# Hyena latent item: the 3x48 serialized short-conv global loads issued back-to-back into own registers, consumers deferred behind one wait (bit-identical arithmetic order)
# speedup vs baseline: 1.1411x; 1.0245x over previous
.LBB0_817:
	s_or_b64 exec, exec, s[0:1]
	v_and_b32_e32 v3, 0x7fffffff, v3
	v_and_b32_e32 v5, 0x7fffffff, v5
	v_and_b32_e32 v7, 0x7fffffff, v7
	v_add_f32_e32 v3, v3, v5
	v_and_b32_e32 v9, 0x7fffffff, v9
	v_add_f32_e32 v3, v3, v7
	v_and_b32_e32 v11, 0x7fffffff, v11
	v_add_f32_e32 v3, v3, v9
	v_and_b32_e32 v13, 0x7fffffff, v13
	v_add_f32_e32 v3, v3, v11
	v_and_b32_e32 v14, 0x7fffffff, v15
	v_add_f32_e32 v3, v3, v13
	v_and_b32_e32 v15, 0x7fffffff, v17
	v_add_f32_e32 v3, v3, v14
	v_and_b32_e32 v16, 0x7fffffff, v19
	v_add_f32_e32 v3, v3, v15
	v_and_b32_e32 v17, 0x7fffffff, v21
	v_add_f32_e32 v3, v3, v16
	s_waitcnt lgkmcnt(0)
	v_and_b32_e32 v18, 0x7fffffff, v23
	v_add_f32_e32 v3, v3, v17
	v_and_b32_e32 v19, 0x7fffffff, v25
	v_add_f32_e32 v3, v3, v18
	v_and_b32_e32 v20, 0x7fffffff, v27
	v_add_f32_e32 v3, v3, v19
	v_and_b32_e32 v21, 0x7fffffff, v29
	v_add_f32_e32 v3, v3, v20
	v_and_b32_e32 v22, 0x7fffffff, v31
	v_add_f32_e32 v3, v3, v21
	v_and_b32_e32 v23, 0x7fffffff, v33
	v_add_f32_e32 v3, v3, v22
	v_add_f32_e32 v3, v3, v23
	ds_bpermute_b32 v2, v2, v3
	s_waitcnt lgkmcnt(0)
	s_barrier
	ds_read_b128 v[46:49], v1 offset:32
	ds_read_b128 v[42:45], v1 offset:48
	v_add_f32_e32 v2, v3, v2
	ds_bpermute_b32 v3, v4, v2
	v_mov_b32_e32 v5, v135
	s_waitcnt lgkmcnt(0)
	v_add_f32_e32 v2, v2, v3
	ds_bpermute_b32 v3, v6, v2
	v_and_b32_e32 v5, 63, v5
	v_cmp_eq_u32_e32 vcc, 0, v5
	s_waitcnt lgkmcnt(0)
	v_add_f32_e32 v2, v2, v3
	ds_bpermute_b32 v3, v8, v2
	s_waitcnt lgkmcnt(0)
	v_add_f32_e32 v3, v2, v3
	ds_bpermute_b32 v4, v10, v3
	v_mov_b32_e32 v2, v135
	s_waitcnt lgkmcnt(0)
	s_barrier
	v_add_f32_e32 v3, v3, v4
	ds_bpermute_b32 v4, v12, v3
	s_waitcnt lgkmcnt(0)
	s_and_saveexec_b64 s[0:1], vcc
	v_ashrrev_i32_e32 v2, 6, v2
	v_add_f32_e32 v3, v3, v4
	v_lshlrev_b32_e32 v2, 2, v2
	ds_write_b32 v2, v3 offset:32
	s_or_b64 exec, exec, s[0:1]
	v_mov_b32_e32 v2, v135
	s_waitcnt lgkmcnt(0)
	s_barrier
	ds_read_b128 v[18:21], v1 offset:32
	ds_read_b128 v[14:17], v1 offset:48
	v_bfrev_b32_e32 v0, v0
	v_lshlrev_b32_e32 v3, 3, v2
	v_ashrrev_i32_e32 v10, 6, v2
	v_add_u32_e32 v11, 0x50, v3
	v_lshlrev_b32_e32 v8, 3, v10
	ds_read2st64_b64 v[4:7], v11 offset1:8
	ds_read2st64_b64 v[22:25], v11 offset0:64 offset1:72
	v_add3_u32 v3, s85, v3, v8
	ds_read_b64 v[8:9], v3
	v_add_u32_e32 v66, 0x200, v2
	v_add_u32_e32 v68, 0x400, v2
	s_waitcnt lgkmcnt(1)
	v_pk_add_f32 v[12:13], v[4:5], v[22:23]
	v_pk_add_f32 v[4:5], v[4:5], v[22:23] neg_lo:[0,1] neg_hi:[0,1]
	ds_write_b64 v11, v[12:13]
	s_waitcnt lgkmcnt(1)
	v_pk_mul_f32 v[12:13], v[4:5], v[8:9] op_sel:[1,1] op_sel_hi:[1,0]
	v_add_u32_e32 v69, 0x600, v2
	v_pk_fma_f32 v[22:23], v[4:5], v[8:9], v[12:13] neg_lo:[0,0,1] neg_hi:[0,0,1]
	v_pk_fma_f32 v[4:5], v[4:5], v[8:9], v[12:13] op_sel_hi:[0,1,1]
	v_ashrrev_i32_e32 v9, 6, v66
	v_mov_b32_e32 v23, v5
	v_lshlrev_b32_e32 v3, 3, v9
	v_lshlrev_b32_e32 v4, 3, v66
	ds_write_b64 v11, v[22:23] offset:32768
	v_add3_u32 v3, s85, v3, v4
	ds_read_b64 v[4:5], v3
	v_pk_add_f32 v[12:13], v[6:7], v[24:25]
	v_pk_add_f32 v[6:7], v[6:7], v[24:25] neg_lo:[0,1] neg_hi:[0,1]
	ds_write_b64 v11, v[12:13] offset:4096
	v_ashrrev_i32_e32 v8, 6, v68
	s_waitcnt lgkmcnt(1)
	v_pk_mul_f32 v[12:13], v[6:7], v[4:5] op_sel:[1,1] op_sel_hi:[1,0]
	v_lshlrev_b32_e32 v3, 3, v8
	v_pk_fma_f32 v[22:23], v[6:7], v[4:5], v[12:13] neg_lo:[0,0,1] neg_hi:[0,0,1]
	v_pk_fma_f32 v[4:5], v[6:7], v[4:5], v[12:13] op_sel_hi:[0,1,1]
	v_mov_b32_e32 v23, v5
	ds_write_b64 v11, v[22:23] offset:36864
	v_lshlrev_b32_e32 v4, 3, v68
	ds_read2st64_b64 v[22:25], v11 offset0:16 offset1:24
	ds_read2st64_b64 v[26:29], v11 offset0:80 offset1:88
	v_add3_u32 v3, s85, v3, v4
	ds_read_b64 v[4:5], v3
	v_lshrrev_b32_e32 v0, 19, v0
	v_sub_u32_e32 v0, 0, v0
	s_waitcnt lgkmcnt(1)
	v_pk_add_f32 v[6:7], v[22:23], v[26:27]
	v_pk_add_f32 v[12:13], v[22:23], v[26:27] neg_lo:[0,1] neg_hi:[0,1]
	ds_write_b64 v11, v[6:7] offset:8192
	s_waitcnt lgkmcnt(1)
	v_pk_mul_f32 v[6:7], v[12:13], v[4:5] op_sel:[1,1] op_sel_hi:[1,0]
	v_and_b32_e32 v0, 0x1fff, v0
	v_pk_fma_f32 v[22:23], v[12:13], v[4:5], v[6:7] neg_lo:[0,0,1] neg_hi:[0,0,1]
	v_pk_fma_f32 v[4:5], v[12:13], v[4:5], v[6:7] op_sel_hi:[0,1,1]
	v_ashrrev_i32_e32 v7, 6, v69
	v_mov_b32_e32 v23, v5
	v_lshlrev_b32_e32 v3, 3, v7
	v_lshlrev_b32_e32 v4, 3, v69
	ds_write_b64 v11, v[22:23] offset:40960
	v_add3_u32 v3, s85, v3, v4
	ds_read_b64 v[4:5], v3
	v_pk_add_f32 v[12:13], v[24:25], v[28:29]
	v_pk_add_f32 v[22:23], v[24:25], v[28:29] neg_lo:[0,1] neg_hi:[0,1]
	ds_write_b64 v11, v[12:13] offset:12288
	v_add_u32_e32 v3, 0x800, v2
	s_waitcnt lgkmcnt(1)
	v_pk_mul_f32 v[12:13], v[22:23], v[4:5] op_sel:[1,1] op_sel_hi:[1,0]
	v_and_b32_e32 v6, 0x3ff, v2
	v_pk_fma_f32 v[24:25], v[22:23], v[4:5], v[12:13] neg_lo:[0,0,1] neg_hi:[0,0,1]
	v_pk_fma_f32 v[4:5], v[22:23], v[4:5], v[12:13] op_sel_hi:[0,1,1]
	v_mov_b32_e32 v25, v5
	v_ashrrev_i32_e32 v4, 6, v3
	ds_write_b64 v11, v[24:25] offset:45056
	v_lshlrev_b32_e32 v4, 3, v4
	v_lshlrev_b32_e32 v3, 3, v3
	ds_read2st64_b64 v[22:25], v11 offset0:32 offset1:40
	ds_read2st64_b64 v[26:29], v11 offset0:96 offset1:104
	v_add3_u32 v3, s85, v4, v3
	ds_read_b64 v[4:5], v3
	v_add_u32_e32 v3, 0xa00, v2
	v_bfrev_b32_e32 v0, v0
	s_waitcnt lgkmcnt(1)
	v_pk_add_f32 v[12:13], v[22:23], v[26:27]
	v_pk_add_f32 v[22:23], v[22:23], v[26:27] neg_lo:[0,1] neg_hi:[0,1]
	ds_write_b64 v11, v[12:13] offset:16384
	s_waitcnt lgkmcnt(1)
	v_pk_mul_f32 v[12:13], v[22:23], v[4:5] op_sel:[1,1] op_sel_hi:[1,0]
	v_add_u32_sdwa v0, s70, v0 dst_sel:DWORD dst_unused:UNUSED_PAD src0_sel:DWORD src1_sel:WORD_1
	v_pk_fma_f32 v[26:27], v[22:23], v[4:5], v[12:13] neg_lo:[0,0,1] neg_hi:[0,0,1]
	v_pk_fma_f32 v[4:5], v[22:23], v[4:5], v[12:13] op_sel_hi:[0,1,1]
	v_ashrrev_i32_e32 v4, 6, v3
	v_mov_b32_e32 v27, v5
	v_lshlrev_b32_e32 v4, 3, v4
	v_lshlrev_b32_e32 v3, 3, v3
	ds_write_b64 v11, v[26:27] offset:49152
	v_add3_u32 v3, s85, v4, v3
	ds_read_b64 v[4:5], v3
	v_pk_add_f32 v[12:13], v[24:25], v[28:29]
	v_pk_add_f32 v[22:23], v[24:25], v[28:29] neg_lo:[0,1] neg_hi:[0,1]
	ds_write_b64 v11, v[12:13] offset:20480
	v_add_u32_e32 v3, 0xc00, v2
	s_waitcnt lgkmcnt(1)
	v_pk_mul_f32 v[12:13], v[22:23], v[4:5] op_sel:[1,1] op_sel_hi:[1,0]
	s_mul_i32 s1, s86, 0xc000
	v_pk_fma_f32 v[24:25], v[22:23], v[4:5], v[12:13] neg_lo:[0,0,1] neg_hi:[0,0,1]
	v_pk_fma_f32 v[4:5], v[22:23], v[4:5], v[12:13] op_sel_hi:[0,1,1]
	v_mov_b32_e32 v25, v5
	v_ashrrev_i32_e32 v4, 6, v3
	ds_write_b64 v11, v[24:25] offset:53248
	v_lshlrev_b32_e32 v4, 3, v4
	v_lshlrev_b32_e32 v3, 3, v3
	ds_read2st64_b64 v[22:25], v11 offset0:48 offset1:56
	ds_read2st64_b64 v[26:29], v11 offset0:112 offset1:120
	v_add3_u32 v3, s85, v4, v3
	ds_read_b64 v[4:5], v3
	v_add_u32_e32 v3, 0xe00, v2
	v_readlane_b32 s20, v251, 39
	s_waitcnt lgkmcnt(1)
	v_pk_add_f32 v[12:13], v[22:23], v[26:27]
	v_pk_add_f32 v[22:23], v[22:23], v[26:27] neg_lo:[0,1] neg_hi:[0,1]
	ds_write_b64 v11, v[12:13] offset:24576
	s_waitcnt lgkmcnt(1)
	v_pk_mul_f32 v[12:13], v[22:23], v[4:5] op_sel:[1,1] op_sel_hi:[1,0]
	s_mul_hi_i32 s0, s86, 0xc000
	v_pk_fma_f32 v[26:27], v[22:23], v[4:5], v[12:13] neg_lo:[0,0,1] neg_hi:[0,0,1]
	v_pk_fma_f32 v[4:5], v[22:23], v[4:5], v[12:13] op_sel_hi:[0,1,1]
	v_ashrrev_i32_e32 v4, 6, v3
	v_mov_b32_e32 v27, v5
	v_lshlrev_b32_e32 v4, 3, v4
	v_lshlrev_b32_e32 v3, 3, v3
	ds_write_b64 v11, v[26:27] offset:57344
	v_add3_u32 v3, s85, v4, v3
	ds_read_b64 v[4:5], v3
	v_pk_add_f32 v[12:13], v[24:25], v[28:29]
	v_pk_add_f32 v[22:23], v[24:25], v[28:29] neg_lo:[0,1] neg_hi:[0,1]
	ds_write_b64 v11, v[12:13] offset:28672
	v_lshlrev_b32_e32 v3, 2, v2
	s_waitcnt lgkmcnt(1)
	v_pk_mul_f32 v[12:13], v[22:23], v[4:5] op_sel:[1,1] op_sel_hi:[1,0]
	v_readlane_b32 s21, v251, 40
	v_pk_fma_f32 v[24:25], v[22:23], v[4:5], v[12:13] neg_lo:[0,0,1] neg_hi:[0,0,1]
	v_pk_fma_f32 v[4:5], v[22:23], v[4:5], v[12:13] op_sel_hi:[0,1,1]
	v_mov_b32_e32 v25, v5
	v_and_or_b32 v4, v3, s26, v6
	v_lshrrev_b32_e32 v5, 2, v2
	ds_write_b64 v11, v[24:25] offset:61440
	v_lshl_add_u32 v11, v4, 3, v205
	v_lshlrev_b32_e32 v4, 4, v6
	v_and_b32_e32 v5, 0xf8, v5
	v_add3_u32 v70, s85, v4, v5
	v_lshrrev_b32_e32 v5, 1, v2
	s_waitcnt lgkmcnt(0)
	s_barrier
	ds_read2st64_b64 v[22:25], v11 offset1:16
	ds_read2st64_b64 v[26:29], v11 offset0:32 offset1:48
	v_lshlrev_b32_e32 v4, 5, v6
	v_and_b32_e32 v5, 0x1f8, v5
	v_add3_u32 v71, s85, v4, v5
	ds_read_b64 v[12:13], v71
	s_waitcnt lgkmcnt(1)
	v_pk_add_f32 v[4:5], v[22:23], v[26:27]
	v_pk_add_f32 v[30:31], v[24:25], v[28:29]
	v_mov_b32_e32 v38, v28
	v_pk_add_f32 v[32:33], v[4:5], v[30:31]
	v_pk_add_f32 v[4:5], v[4:5], v[30:31] neg_lo:[0,1] neg_hi:[0,1]
	ds_read_b64 v[30:31], v70
	s_waitcnt lgkmcnt(1)
	v_pk_mul_f32 v[34:35], v[4:5], v[12:13] op_sel:[1,1] op_sel_hi:[1,0]
	v_mov_b32_e32 v39, v27
	v_pk_fma_f32 v[36:37], v[4:5], v[12:13], v[34:35] neg_lo:[0,0,1] neg_hi:[0,0,1]
	v_pk_fma_f32 v[4:5], v[4:5], v[12:13], v[34:35] op_sel_hi:[0,1,1]
	v_mov_b32_e32 v37, v5
	v_mov_b32_e32 v4, v22
	v_mov_b32_e32 v5, v24
	v_mov_b32_e32 v34, v26
	v_mov_b32_e32 v35, v28
	v_pk_add_f32 v[4:5], v[4:5], v[34:35] neg_lo:[0,1] neg_hi:[0,1]
	v_mov_b32_e32 v34, v24
	v_mov_b32_e32 v35, v23
	v_pk_add_f32 v[34:35], v[34:35], v[38:39] neg_lo:[0,1] neg_hi:[0,1]
	v_pk_mov_b32 v[38:39], v[24:25], v[22:23] op_sel:[1,0]
	v_pk_mov_b32 v[40:41], v[28:29], v[26:27] op_sel:[1,0]
	v_mov_b32_e32 v24, v23
	v_mov_b32_e32 v28, v27
	v_pk_add_f32 v[22:23], v[24:25], v[28:29] neg_lo:[0,1] neg_hi:[0,1]
	v_pk_add_f32 v[38:39], v[38:39], v[40:41] neg_lo:[0,1] neg_hi:[0,1]
	s_waitcnt lgkmcnt(0)
	v_pk_mul_f32 v[22:23], v[22:23], v[30:31] op_sel:[0,1]
	ds_write2st64_b64 v11, v[32:33], v[36:37] offset1:16
	v_pk_fma_f32 v[4:5], v[4:5], v[30:31], v[22:23] op_sel_hi:[1,0,1] neg_lo:[0,0,1] neg_hi:[0,0,1]
	v_pk_mul_f32 v[22:23], v[38:39], v[30:31]
	s_add_u32 s23, s20, s1
	v_pk_fma_f32 v[22:23], v[34:35], v[30:31], v[22:23] op_sel:[0,1,0] op_sel_hi:[1,0,1]
	s_addc_u32 s25, s21, s0
	v_pk_add_f32 v[24:25], v[22:23], v[4:5]
	v_pk_add_f32 v[26:27], v[22:23], v[4:5] neg_lo:[0,1] neg_hi:[0,1]
	v_pk_add_f32 v[4:5], v[4:5], v[22:23] neg_lo:[0,1] neg_hi:[0,1]
	v_pk_mul_f32 v[22:23], v[12:13], v[24:25] op_sel:[1,1] op_sel_hi:[0,1]
	v_mov_b32_e32 v26, v24
	v_pk_fma_f32 v[24:25], v[12:13], v[4:5], v[22:23] neg_lo:[0,0,1] neg_hi:[0,0,1]
	v_pk_fma_f32 v[4:5], v[12:13], v[4:5], v[22:23] op_sel_hi:[1,0,1]
	v_lshrrev_b32_e32 v13, 2, v66
	v_mov_b32_e32 v25, v5
	v_and_b32_e32 v5, 0x3ff, v66
	v_lshlrev_b32_e32 v4, 2, v66
	ds_write2st64_b64 v11, v[26:27], v[24:25] offset0:32 offset1:48
	v_and_or_b32 v11, v4, s26, v5
	v_lshlrev_b32_e32 v12, 4, v5
	v_and_b32_e32 v13, 0xf8, v13
	v_lshl_add_u32 v11, v11, 3, v205
	v_add3_u32 v36, s85, v12, v13
	v_lshrrev_b32_e32 v12, 1, v66
	ds_read2st64_b64 v[22:25], v11 offset1:16
	ds_read2st64_b64 v[26:29], v11 offset0:32 offset1:48
	v_lshlrev_b32_e32 v5, 5, v5
	v_and_b32_e32 v12, 0x1f8, v12
	v_add3_u32 v5, s85, v5, v12
	ds_read_b64 v[30:31], v5
	s_waitcnt lgkmcnt(1)
	v_pk_add_f32 v[12:13], v[22:23], v[26:27]
	v_pk_add_f32 v[32:33], v[24:25], v[28:29]
	v_mov_b32_e32 v40, v28
	v_pk_add_f32 v[34:35], v[12:13], v[32:33]
	v_pk_add_f32 v[12:13], v[12:13], v[32:33] neg_lo:[0,1] neg_hi:[0,1]
	ds_read_b64 v[32:33], v36
	s_waitcnt lgkmcnt(1)
	v_pk_mul_f32 v[36:37], v[12:13], v[30:31] op_sel:[1,1] op_sel_hi:[1,0]
	v_mov_b32_e32 v41, v27
	v_pk_fma_f32 v[38:39], v[12:13], v[30:31], v[36:37] neg_lo:[0,0,1] neg_hi:[0,0,1]
	v_pk_fma_f32 v[12:13], v[12:13], v[30:31], v[36:37] op_sel_hi:[0,1,1]
	v_mov_b32_e32 v39, v13
	v_mov_b32_e32 v12, v22
	v_mov_b32_e32 v13, v24
	v_mov_b32_e32 v36, v26
	v_mov_b32_e32 v37, v28
	v_pk_add_f32 v[12:13], v[12:13], v[36:37] neg_lo:[0,1] neg_hi:[0,1]
	v_mov_b32_e32 v36, v24
	v_mov_b32_e32 v37, v23
	v_pk_add_f32 v[36:37], v[36:37], v[40:41] neg_lo:[0,1] neg_hi:[0,1]
	v_pk_mov_b32 v[40:41], v[24:25], v[22:23] op_sel:[1,0]
	v_pk_mov_b32 v[66:67], v[28:29], v[26:27] op_sel:[1,0]
	v_mov_b32_e32 v24, v23
	v_mov_b32_e32 v28, v27
	v_pk_add_f32 v[22:23], v[24:25], v[28:29] neg_lo:[0,1] neg_hi:[0,1]
	v_pk_add_f32 v[40:41], v[40:41], v[66:67] neg_lo:[0,1] neg_hi:[0,1]
	s_waitcnt lgkmcnt(0)
	v_pk_mul_f32 v[22:23], v[22:23], v[32:33] op_sel:[0,1]
	v_lshlrev_b32_e32 v5, 2, v68
	v_pk_fma_f32 v[12:13], v[12:13], v[32:33], v[22:23] op_sel_hi:[1,0,1] neg_lo:[0,0,1] neg_hi:[0,0,1]
	v_pk_mul_f32 v[22:23], v[40:41], v[32:33]
	v_and_or_b32 v6, v5, s26, v6
	v_pk_fma_f32 v[22:23], v[36:37], v[32:33], v[22:23] op_sel:[0,1,0] op_sel_hi:[1,0,1]
	ds_write2st64_b64 v11, v[34:35], v[38:39] offset1:16
	v_pk_add_f32 v[24:25], v[22:23], v[12:13]
	v_pk_add_f32 v[26:27], v[22:23], v[12:13] neg_lo:[0,1] neg_hi:[0,1]
	v_pk_add_f32 v[12:13], v[12:13], v[22:23] neg_lo:[0,1] neg_hi:[0,1]
	v_pk_mul_f32 v[22:23], v[30:31], v[24:25] op_sel:[1,1] op_sel_hi:[0,1]
	v_mov_b32_e32 v26, v24
	v_pk_fma_f32 v[24:25], v[30:31], v[12:13], v[22:23] neg_lo:[0,0,1] neg_hi:[0,0,1]
	v_pk_fma_f32 v[12:13], v[30:31], v[12:13], v[22:23] op_sel_hi:[1,0,1]
	v_lshl_add_u32 v6, v6, 3, v205
	v_mov_b32_e32 v25, v13
	ds_write2st64_b64 v11, v[26:27], v[24:25] offset0:32 offset1:48
	ds_read2st64_b64 v[22:25], v6 offset1:16
	ds_read2st64_b64 v[26:29], v6 offset0:32 offset1:48
	ds_read_b64 v[30:31], v71
	v_and_b32_e32 v11, 0x3ff, v69
	s_add_u32 s66, s23, 0x4000
	s_addc_u32 s67, s25, 0
	s_waitcnt lgkmcnt(1)
	v_pk_add_f32 v[12:13], v[22:23], v[26:27]
	v_pk_add_f32 v[32:33], v[24:25], v[28:29]
	v_mov_b32_e32 v40, v28
	v_pk_add_f32 v[34:35], v[12:13], v[32:33]
	v_pk_add_f32 v[12:13], v[12:13], v[32:33] neg_lo:[0,1] neg_hi:[0,1]
	ds_read_b64 v[32:33], v70
	s_waitcnt lgkmcnt(1)
	v_pk_mul_f32 v[36:37], v[12:13], v[30:31] op_sel:[1,1] op_sel_hi:[1,0]
	v_mov_b32_e32 v41, v27
	v_pk_fma_f32 v[38:39], v[12:13], v[30:31], v[36:37] neg_lo:[0,0,1] neg_hi:[0,0,1]
	v_pk_fma_f32 v[12:13], v[12:13], v[30:31], v[36:37] op_sel_hi:[0,1,1]
	v_mov_b32_e32 v39, v13
	v_mov_b32_e32 v12, v22
	v_mov_b32_e32 v13, v24
	v_mov_b32_e32 v36, v26
	v_mov_b32_e32 v37, v28
	v_pk_add_f32 v[12:13], v[12:13], v[36:37] neg_lo:[0,1] neg_hi:[0,1]
	v_mov_b32_e32 v36, v24
	v_mov_b32_e32 v37, v23
	v_pk_add_f32 v[36:37], v[36:37], v[40:41] neg_lo:[0,1] neg_hi:[0,1]
	v_pk_mov_b32 v[40:41], v[24:25], v[22:23] op_sel:[1,0]
	v_pk_mov_b32 v[66:67], v[28:29], v[26:27] op_sel:[1,0]
	v_mov_b32_e32 v24, v23
	v_mov_b32_e32 v28, v27
	v_pk_add_f32 v[22:23], v[24:25], v[28:29] neg_lo:[0,1] neg_hi:[0,1]
	v_pk_add_f32 v[40:41], v[40:41], v[66:67] neg_lo:[0,1] neg_hi:[0,1]
	s_waitcnt lgkmcnt(0)
	v_pk_mul_f32 v[22:23], v[22:23], v[32:33] op_sel:[0,1]
	ds_write2st64_b64 v6, v[34:35], v[38:39] offset1:16
	v_pk_fma_f32 v[12:13], v[12:13], v[32:33], v[22:23] op_sel_hi:[1,0,1] neg_lo:[0,0,1] neg_hi:[0,0,1]
	v_pk_mul_f32 v[22:23], v[40:41], v[32:33]
	s_lshl_b64 s[0:1], s[86:87], 2
	v_pk_fma_f32 v[22:23], v[36:37], v[32:33], v[22:23] op_sel:[0,1,0] op_sel_hi:[1,0,1]
	v_readlane_b32 s4, v249, 61
	v_pk_add_f32 v[24:25], v[22:23], v[12:13]
	v_pk_add_f32 v[26:27], v[22:23], v[12:13] neg_lo:[0,1] neg_hi:[0,1]
	v_pk_add_f32 v[12:13], v[12:13], v[22:23] neg_lo:[0,1] neg_hi:[0,1]
	v_pk_mul_f32 v[22:23], v[30:31], v[24:25] op_sel:[1,1] op_sel_hi:[0,1]
	v_mov_b32_e32 v26, v24
	v_pk_fma_f32 v[24:25], v[30:31], v[12:13], v[22:23] neg_lo:[0,0,1] neg_hi:[0,0,1]
	v_pk_fma_f32 v[12:13], v[30:31], v[12:13], v[22:23] op_sel_hi:[1,0,1]
	s_add_u32 s20, s4, s0
	v_mov_b32_e32 v25, v13
	ds_write2st64_b64 v6, v[26:27], v[24:25] offset0:32 offset1:48
	v_lshlrev_b32_e32 v6, 2, v69
	v_and_or_b32 v12, v6, s26, v11
	v_lshrrev_b32_e32 v13, 2, v69
	v_lshl_add_u32 v68, v12, 3, v205
	v_lshlrev_b32_e32 v12, 4, v11
	v_and_b32_e32 v13, 0xf8, v13
	v_add3_u32 v36, s85, v12, v13
	v_lshrrev_b32_e32 v12, 1, v69
	ds_read2st64_b64 v[22:25], v68 offset1:16
	ds_read2st64_b64 v[26:29], v68 offset0:32 offset1:48
	v_lshlrev_b32_e32 v11, 5, v11
	v_and_b32_e32 v12, 0x1f8, v12
	v_add3_u32 v11, s85, v11, v12
	ds_read_b64 v[30:31], v11
	s_waitcnt lgkmcnt(1)
	v_pk_add_f32 v[12:13], v[22:23], v[26:27]
	v_pk_add_f32 v[32:33], v[24:25], v[28:29]
	v_mov_b32_e32 v40, v28
	v_pk_add_f32 v[34:35], v[12:13], v[32:33]
	v_pk_add_f32 v[12:13], v[12:13], v[32:33] neg_lo:[0,1] neg_hi:[0,1]
	ds_read_b64 v[32:33], v36
	s_waitcnt lgkmcnt(1)
	v_pk_mul_f32 v[36:37], v[12:13], v[30:31] op_sel:[1,1] op_sel_hi:[1,0]
	v_mov_b32_e32 v41, v27
	v_pk_fma_f32 v[38:39], v[12:13], v[30:31], v[36:37] neg_lo:[0,0,1] neg_hi:[0,0,1]
	v_pk_fma_f32 v[12:13], v[12:13], v[30:31], v[36:37] op_sel_hi:[0,1,1]
	v_mov_b32_e32 v39, v13
	v_mov_b32_e32 v12, v22
	v_mov_b32_e32 v13, v24
	v_mov_b32_e32 v36, v26
	v_mov_b32_e32 v37, v28
	v_pk_add_f32 v[12:13], v[12:13], v[36:37] neg_lo:[0,1] neg_hi:[0,1]
	v_mov_b32_e32 v36, v24
	v_mov_b32_e32 v37, v23
	v_pk_add_f32 v[36:37], v[36:37], v[40:41] neg_lo:[0,1] neg_hi:[0,1]
	v_pk_mov_b32 v[40:41], v[24:25], v[22:23] op_sel:[1,0]
	v_pk_mov_b32 v[66:67], v[28:29], v[26:27] op_sel:[1,0]
	v_mov_b32_e32 v24, v23
	v_mov_b32_e32 v28, v27
	v_pk_add_f32 v[22:23], v[24:25], v[28:29] neg_lo:[0,1] neg_hi:[0,1]
	v_pk_add_f32 v[40:41], v[40:41], v[66:67] neg_lo:[0,1] neg_hi:[0,1]
	s_waitcnt lgkmcnt(0)
	v_pk_mul_f32 v[22:23], v[22:23], v[32:33] op_sel:[0,1]
	v_and_b32_e32 v11, 0xff, v2
	v_pk_fma_f32 v[12:13], v[12:13], v[32:33], v[22:23] op_sel_hi:[1,0,1] neg_lo:[0,0,1] neg_hi:[0,0,1]
	v_pk_mul_f32 v[22:23], v[40:41], v[32:33]
	ds_write2st64_b64 v68, v[34:35], v[38:39] offset1:16
	v_pk_fma_f32 v[22:23], v[36:37], v[32:33], v[22:23] op_sel:[0,1,0] op_sel_hi:[1,0,1]
	v_readlane_b32 s4, v249, 62
	v_pk_add_f32 v[24:25], v[22:23], v[12:13]
	v_pk_add_f32 v[26:27], v[22:23], v[12:13] neg_lo:[0,1] neg_hi:[0,1]
	v_pk_add_f32 v[12:13], v[12:13], v[22:23] neg_lo:[0,1] neg_hi:[0,1]
	v_pk_mul_f32 v[22:23], v[30:31], v[24:25] op_sel:[1,1] op_sel_hi:[0,1]
	v_mov_b32_e32 v26, v24
	v_pk_fma_f32 v[24:25], v[30:31], v[12:13], v[22:23] neg_lo:[0,0,1] neg_hi:[0,0,1]
	v_pk_fma_f32 v[12:13], v[30:31], v[12:13], v[22:23] op_sel_hi:[1,0,1]
	s_addc_u32 s21, s4, s1
	v_mov_b32_e32 v25, v13
	v_and_or_b32 v12, v3, s34, v11
	ds_write2st64_b64 v68, v[26:27], v[24:25] offset0:32 offset1:48
	v_lshl_add_u32 v68, v12, 3, v205
	v_lshlrev_b32_e32 v12, 6, v11
	v_and_b32_e32 v13, 0xf8, v2
	v_add3_u32 v69, s85, v12, v13
	v_lshlrev_b32_e32 v13, 1, v2
	s_waitcnt lgkmcnt(0)
	s_barrier
	ds_read2st64_b64 v[22:25], v68 offset1:4
	ds_read2st64_b64 v[26:29], v68 offset0:8 offset1:12
	v_lshlrev_b32_e32 v12, 7, v11
	v_and_b32_e32 v13, 0x1f8, v13
	v_add3_u32 v70, s85, v12, v13
	ds_read_b64 v[30:31], v70
	s_waitcnt lgkmcnt(1)
	v_pk_add_f32 v[12:13], v[22:23], v[26:27]
	v_pk_add_f32 v[32:33], v[24:25], v[28:29]
	v_mov_b32_e32 v40, v28
	v_pk_add_f32 v[34:35], v[12:13], v[32:33]
	v_pk_add_f32 v[12:13], v[12:13], v[32:33] neg_lo:[0,1] neg_hi:[0,1]
	ds_read_b64 v[32:33], v69
	s_waitcnt lgkmcnt(1)
	v_pk_mul_f32 v[36:37], v[12:13], v[30:31] op_sel:[1,1] op_sel_hi:[1,0]
	v_mov_b32_e32 v41, v27
	v_pk_fma_f32 v[38:39], v[12:13], v[30:31], v[36:37] neg_lo:[0,0,1] neg_hi:[0,0,1]
	v_pk_fma_f32 v[12:13], v[12:13], v[30:31], v[36:37] op_sel_hi:[0,1,1]
	v_mov_b32_e32 v39, v13
	v_mov_b32_e32 v12, v22
	v_mov_b32_e32 v13, v24
	v_mov_b32_e32 v36, v26
	v_mov_b32_e32 v37, v28
	v_pk_add_f32 v[12:13], v[12:13], v[36:37] neg_lo:[0,1] neg_hi:[0,1]
	v_mov_b32_e32 v36, v24
	v_mov_b32_e32 v37, v23
	v_pk_add_f32 v[36:37], v[36:37], v[40:41] neg_lo:[0,1] neg_hi:[0,1]
	v_pk_mov_b32 v[40:41], v[24:25], v[22:23] op_sel:[1,0]
	v_pk_mov_b32 v[66:67], v[28:29], v[26:27] op_sel:[1,0]
	v_mov_b32_e32 v24, v23
	v_mov_b32_e32 v28, v27
	v_pk_add_f32 v[22:23], v[24:25], v[28:29] neg_lo:[0,1] neg_hi:[0,1]
	v_pk_add_f32 v[40:41], v[40:41], v[66:67] neg_lo:[0,1] neg_hi:[0,1]
	s_waitcnt lgkmcnt(0)
	v_pk_mul_f32 v[22:23], v[22:23], v[32:33] op_sel:[0,1]
	ds_write2st64_b64 v68, v[34:35], v[38:39] offset1:4
	v_pk_fma_f32 v[12:13], v[12:13], v[32:33], v[22:23] op_sel_hi:[1,0,1] neg_lo:[0,0,1] neg_hi:[0,0,1]
	v_pk_mul_f32 v[22:23], v[40:41], v[32:33]
	v_readlane_b32 s4, v249, 52
	v_pk_fma_f32 v[22:23], v[36:37], v[32:33], v[22:23] op_sel:[0,1,0] op_sel_hi:[1,0,1]
	s_add_u32 s0, s4, s0
	v_pk_add_f32 v[24:25], v[22:23], v[12:13]
	v_pk_add_f32 v[26:27], v[22:23], v[12:13] neg_lo:[0,1] neg_hi:[0,1]
	v_pk_add_f32 v[12:13], v[12:13], v[22:23] neg_lo:[0,1] neg_hi:[0,1]
	v_pk_mul_f32 v[22:23], v[30:31], v[24:25] op_sel:[1,1] op_sel_hi:[0,1]
	v_mov_b32_e32 v26, v24
	v_pk_fma_f32 v[24:25], v[30:31], v[12:13], v[22:23] neg_lo:[0,0,1] neg_hi:[0,0,1]
	v_pk_fma_f32 v[12:13], v[30:31], v[12:13], v[22:23] op_sel_hi:[1,0,1]
	v_readlane_b32 s4, v249, 60
	v_mov_b32_e32 v25, v13
	v_and_or_b32 v12, v4, s34, v11
	ds_write2st64_b64 v68, v[26:27], v[24:25] offset0:8 offset1:12
	v_lshl_add_u32 v68, v12, 3, v205
	ds_read2st64_b64 v[22:25], v68 offset1:4
	ds_read2st64_b64 v[26:29], v68 offset0:8 offset1:12
	ds_read_b64 v[30:31], v70
	v_lshl_add_u64 v[116:117], v[50:51], 2, s[66:67]
	s_addc_u32 s1, s4, s1
	v_cmp_lt_i32_e64 s[40:41], 0, v50
	s_waitcnt lgkmcnt(1)
	v_pk_add_f32 v[12:13], v[22:23], v[26:27]
	v_pk_add_f32 v[32:33], v[24:25], v[28:29]
	v_mov_b32_e32 v40, v28
	v_pk_add_f32 v[34:35], v[12:13], v[32:33]
	v_pk_add_f32 v[12:13], v[12:13], v[32:33] neg_lo:[0,1] neg_hi:[0,1]
	ds_read_b64 v[32:33], v69
	s_waitcnt lgkmcnt(1)
	v_pk_mul_f32 v[36:37], v[12:13], v[30:31] op_sel:[1,1] op_sel_hi:[1,0]
	v_mov_b32_e32 v41, v27
	v_pk_fma_f32 v[38:39], v[12:13], v[30:31], v[36:37] neg_lo:[0,0,1] neg_hi:[0,0,1]
	v_pk_fma_f32 v[12:13], v[12:13], v[30:31], v[36:37] op_sel_hi:[0,1,1]
	v_mov_b32_e32 v39, v13
	v_mov_b32_e32 v12, v22
	v_mov_b32_e32 v13, v24
	v_mov_b32_e32 v36, v26
	v_mov_b32_e32 v37, v28
	v_pk_add_f32 v[12:13], v[12:13], v[36:37] neg_lo:[0,1] neg_hi:[0,1]
	v_mov_b32_e32 v36, v24
	v_mov_b32_e32 v37, v23
	v_pk_add_f32 v[36:37], v[36:37], v[40:41] neg_lo:[0,1] neg_hi:[0,1]
	v_pk_mov_b32 v[40:41], v[24:25], v[22:23] op_sel:[1,0]
	v_pk_mov_b32 v[66:67], v[28:29], v[26:27] op_sel:[1,0]
	v_mov_b32_e32 v24, v23
	v_mov_b32_e32 v28, v27
	v_pk_add_f32 v[22:23], v[24:25], v[28:29] neg_lo:[0,1] neg_hi:[0,1]
	v_pk_add_f32 v[40:41], v[40:41], v[66:67] neg_lo:[0,1] neg_hi:[0,1]
	s_waitcnt lgkmcnt(0)
	v_pk_mul_f32 v[22:23], v[22:23], v[32:33] op_sel:[0,1]
	ds_write2st64_b64 v68, v[34:35], v[38:39] offset1:4
	v_pk_fma_f32 v[12:13], v[12:13], v[32:33], v[22:23] op_sel_hi:[1,0,1] neg_lo:[0,0,1] neg_hi:[0,0,1]
	v_pk_mul_f32 v[22:23], v[40:41], v[32:33]
	s_nop 0
	v_pk_fma_f32 v[22:23], v[36:37], v[32:33], v[22:23] op_sel:[0,1,0] op_sel_hi:[1,0,1]
	s_nop 0
	v_pk_add_f32 v[24:25], v[22:23], v[12:13]
	v_pk_add_f32 v[26:27], v[22:23], v[12:13] neg_lo:[0,1] neg_hi:[0,1]
	v_pk_add_f32 v[12:13], v[12:13], v[22:23] neg_lo:[0,1] neg_hi:[0,1]
	v_pk_mul_f32 v[22:23], v[30:31], v[24:25] op_sel:[1,1] op_sel_hi:[0,1]
	v_mov_b32_e32 v26, v24
	v_pk_fma_f32 v[24:25], v[30:31], v[12:13], v[22:23] neg_lo:[0,0,1] neg_hi:[0,0,1]
	v_pk_fma_f32 v[12:13], v[30:31], v[12:13], v[22:23] op_sel_hi:[1,0,1]
	s_nop 0
	v_mov_b32_e32 v25, v13
	v_and_or_b32 v12, v5, s34, v11
	ds_write2st64_b64 v68, v[26:27], v[24:25] offset0:8 offset1:12
	v_lshl_add_u32 v68, v12, 3, v205
	ds_read2st64_b64 v[22:25], v68 offset1:4
	ds_read2st64_b64 v[26:29], v68 offset0:8 offset1:12
	ds_read_b64 v[30:31], v70
	v_and_or_b32 v11, v6, s34, v11
	v_lshl_add_u32 v11, v11, 3, v205
	s_waitcnt lgkmcnt(1)
	v_pk_add_f32 v[12:13], v[22:23], v[26:27]
	v_pk_add_f32 v[32:33], v[24:25], v[28:29]
	v_mov_b32_e32 v40, v28
	v_pk_add_f32 v[34:35], v[12:13], v[32:33]
	v_pk_add_f32 v[12:13], v[12:13], v[32:33] neg_lo:[0,1] neg_hi:[0,1]
	ds_read_b64 v[32:33], v69
	s_waitcnt lgkmcnt(1)
	v_pk_mul_f32 v[36:37], v[12:13], v[30:31] op_sel:[1,1] op_sel_hi:[1,0]
	v_mov_b32_e32 v41, v27
	v_pk_fma_f32 v[38:39], v[12:13], v[30:31], v[36:37] neg_lo:[0,0,1] neg_hi:[0,0,1]
	v_pk_fma_f32 v[12:13], v[12:13], v[30:31], v[36:37] op_sel_hi:[0,1,1]
	v_mov_b32_e32 v39, v13
	v_mov_b32_e32 v12, v22
	v_mov_b32_e32 v13, v24
	v_mov_b32_e32 v36, v26
	v_mov_b32_e32 v37, v28
	v_pk_add_f32 v[12:13], v[12:13], v[36:37] neg_lo:[0,1] neg_hi:[0,1]
	v_mov_b32_e32 v36, v24
	v_mov_b32_e32 v37, v23
	v_pk_add_f32 v[36:37], v[36:37], v[40:41] neg_lo:[0,1] neg_hi:[0,1]
	v_pk_mov_b32 v[40:41], v[24:25], v[22:23] op_sel:[1,0]
	v_pk_mov_b32 v[66:67], v[28:29], v[26:27] op_sel:[1,0]
	v_mov_b32_e32 v24, v23
	v_mov_b32_e32 v28, v27
	v_pk_add_f32 v[22:23], v[24:25], v[28:29] neg_lo:[0,1] neg_hi:[0,1]
	v_pk_add_f32 v[40:41], v[40:41], v[66:67] neg_lo:[0,1] neg_hi:[0,1]
	s_waitcnt lgkmcnt(0)
	v_pk_mul_f32 v[22:23], v[22:23], v[32:33] op_sel:[0,1]
	ds_write2st64_b64 v68, v[34:35], v[38:39] offset1:4
	v_pk_fma_f32 v[12:13], v[12:13], v[32:33], v[22:23] op_sel_hi:[1,0,1] neg_lo:[0,0,1] neg_hi:[0,0,1]
	v_pk_mul_f32 v[22:23], v[40:41], v[32:33]
	s_nop 0
	v_pk_fma_f32 v[22:23], v[36:37], v[32:33], v[22:23] op_sel:[0,1,0] op_sel_hi:[1,0,1]
	s_nop 0
	v_pk_add_f32 v[24:25], v[22:23], v[12:13]
	v_pk_add_f32 v[26:27], v[22:23], v[12:13] neg_lo:[0,1] neg_hi:[0,1]
	v_pk_add_f32 v[12:13], v[12:13], v[22:23] neg_lo:[0,1] neg_hi:[0,1]
	v_pk_mul_f32 v[22:23], v[30:31], v[24:25] op_sel:[1,1] op_sel_hi:[0,1]
	v_mov_b32_e32 v26, v24
	v_pk_fma_f32 v[24:25], v[30:31], v[12:13], v[22:23] neg_lo:[0,0,1] neg_hi:[0,0,1]
	v_pk_fma_f32 v[12:13], v[30:31], v[12:13], v[22:23] op_sel_hi:[1,0,1]
	s_nop 0
	v_mov_b32_e32 v25, v13
	ds_write2st64_b64 v68, v[26:27], v[24:25] offset0:8 offset1:12
	ds_read2st64_b64 v[22:25], v11 offset1:4
	ds_read2st64_b64 v[26:29], v11 offset0:8 offset1:12
	ds_read_b64 v[30:31], v70
	s_waitcnt lgkmcnt(1)
	v_pk_add_f32 v[12:13], v[22:23], v[26:27]
	v_pk_add_f32 v[32:33], v[24:25], v[28:29]
	v_mov_b32_e32 v40, v28
	v_pk_add_f32 v[34:35], v[12:13], v[32:33]
	v_pk_add_f32 v[12:13], v[12:13], v[32:33] neg_lo:[0,1] neg_hi:[0,1]
	ds_read_b64 v[32:33], v69
	s_waitcnt lgkmcnt(1)
	v_pk_mul_f32 v[36:37], v[12:13], v[30:31] op_sel:[1,1] op_sel_hi:[1,0]
	v_mov_b32_e32 v41, v27
	v_pk_fma_f32 v[38:39], v[12:13], v[30:31], v[36:37] neg_lo:[0,0,1] neg_hi:[0,0,1]
	v_pk_fma_f32 v[12:13], v[12:13], v[30:31], v[36:37] op_sel_hi:[0,1,1]
	v_mov_b32_e32 v39, v13
	v_mov_b32_e32 v12, v22
	v_mov_b32_e32 v13, v24
	v_mov_b32_e32 v36, v26
	v_mov_b32_e32 v37, v28
	v_pk_add_f32 v[12:13], v[12:13], v[36:37] neg_lo:[0,1] neg_hi:[0,1]
	v_mov_b32_e32 v36, v24
	v_mov_b32_e32 v37, v23
	v_pk_add_f32 v[36:37], v[36:37], v[40:41] neg_lo:[0,1] neg_hi:[0,1]
	v_pk_mov_b32 v[40:41], v[24:25], v[22:23] op_sel:[1,0]
	v_pk_mov_b32 v[66:67], v[28:29], v[26:27] op_sel:[1,0]
	v_mov_b32_e32 v24, v23
	v_mov_b32_e32 v28, v27
	v_pk_add_f32 v[22:23], v[24:25], v[28:29] neg_lo:[0,1] neg_hi:[0,1]
	v_pk_add_f32 v[40:41], v[40:41], v[66:67] neg_lo:[0,1] neg_hi:[0,1]
	s_waitcnt lgkmcnt(0)
	v_pk_mul_f32 v[22:23], v[22:23], v[32:33] op_sel:[0,1]
	ds_write2st64_b64 v11, v[34:35], v[38:39] offset1:4
	v_pk_fma_f32 v[12:13], v[12:13], v[32:33], v[22:23] op_sel_hi:[1,0,1] neg_lo:[0,0,1] neg_hi:[0,0,1]
	v_pk_mul_f32 v[22:23], v[40:41], v[32:33]
	v_and_b32_e32 v28, 0xf8, v3
	v_pk_fma_f32 v[22:23], v[36:37], v[32:33], v[22:23] op_sel:[0,1,0] op_sel_hi:[1,0,1]
	s_nop 0
	v_pk_add_f32 v[24:25], v[22:23], v[12:13]
	v_pk_add_f32 v[26:27], v[22:23], v[12:13] neg_lo:[0,1] neg_hi:[0,1]
	v_pk_add_f32 v[12:13], v[12:13], v[22:23] neg_lo:[0,1] neg_hi:[0,1]
	v_pk_mul_f32 v[22:23], v[30:31], v[24:25] op_sel:[1,1] op_sel_hi:[0,1]
	v_mov_b32_e32 v26, v24
	v_pk_fma_f32 v[24:25], v[30:31], v[12:13], v[22:23] neg_lo:[0,0,1] neg_hi:[0,0,1]
	v_pk_fma_f32 v[12:13], v[30:31], v[12:13], v[22:23] op_sel_hi:[1,0,1]
	s_nop 0
	v_mov_b32_e32 v25, v13
	ds_write2st64_b64 v11, v[26:27], v[24:25] offset0:8 offset1:12
	v_and_b32_e32 v26, 63, v2
	v_lshlrev_b32_e32 v66, 3, v26
	v_lshl_or_b32 v10, v10, 11, v66
	v_add_u32_e32 v67, 0x50, v10
	s_waitcnt lgkmcnt(0)
	s_barrier
	v_lshlrev_b32_e32 v27, 8, v26
	ds_read2st64_b64 v[10:13], v67 offset1:1
	ds_read2st64_b64 v[22:25], v67 offset0:2 offset1:3
	v_lshlrev_b32_e32 v26, 9, v26
	v_add3_u32 v69, s85, v26, v66
	v_add3_u32 v68, s85, v27, v28
	ds_read_b64 v[28:29], v69
	s_waitcnt lgkmcnt(1)
	v_pk_add_f32 v[26:27], v[10:11], v[22:23]
	v_pk_add_f32 v[30:31], v[12:13], v[24:25]
	v_mov_b32_e32 v38, v24
	v_pk_add_f32 v[32:33], v[26:27], v[30:31]
	v_pk_add_f32 v[26:27], v[26:27], v[30:31] neg_lo:[0,1] neg_hi:[0,1]
	ds_read_b64 v[30:31], v68
	s_waitcnt lgkmcnt(1)
	v_pk_mul_f32 v[34:35], v[26:27], v[28:29] op_sel:[1,1] op_sel_hi:[1,0]
	v_mov_b32_e32 v39, v23
	v_pk_fma_f32 v[36:37], v[26:27], v[28:29], v[34:35] neg_lo:[0,0,1] neg_hi:[0,0,1]
	v_pk_fma_f32 v[26:27], v[26:27], v[28:29], v[34:35] op_sel_hi:[0,1,1]
	v_mov_b32_e32 v37, v27
	v_mov_b32_e32 v26, v10
	v_mov_b32_e32 v27, v12
	v_mov_b32_e32 v34, v22
	v_mov_b32_e32 v35, v24
	v_pk_add_f32 v[26:27], v[26:27], v[34:35] neg_lo:[0,1] neg_hi:[0,1]
	v_mov_b32_e32 v34, v12
	v_mov_b32_e32 v35, v11
	v_pk_add_f32 v[34:35], v[34:35], v[38:39] neg_lo:[0,1] neg_hi:[0,1]
	v_pk_mov_b32 v[38:39], v[12:13], v[10:11] op_sel:[1,0]
	v_pk_mov_b32 v[40:41], v[24:25], v[22:23] op_sel:[1,0]
	v_mov_b32_e32 v12, v11
	v_mov_b32_e32 v24, v23
	v_pk_add_f32 v[38:39], v[38:39], v[40:41] neg_lo:[0,1] neg_hi:[0,1]
	v_pk_add_f32 v[10:11], v[12:13], v[24:25] neg_lo:[0,1] neg_hi:[0,1]
	s_waitcnt lgkmcnt(0)
	v_pk_mul_f32 v[12:13], v[38:39], v[30:31]
	v_pk_mul_f32 v[10:11], v[10:11], v[30:31] op_sel:[0,1]
	v_pk_fma_f32 v[12:13], v[34:35], v[30:31], v[12:13] op_sel:[0,1,0] op_sel_hi:[1,0,1]
	v_pk_fma_f32 v[10:11], v[26:27], v[30:31], v[10:11] op_sel_hi:[1,0,1] neg_lo:[0,0,1] neg_hi:[0,0,1]
	v_lshl_or_b32 v9, v9, 11, v66
	v_pk_add_f32 v[22:23], v[12:13], v[10:11]
	v_pk_add_f32 v[24:25], v[12:13], v[10:11] neg_lo:[0,1] neg_hi:[0,1]
	v_pk_add_f32 v[10:11], v[10:11], v[12:13] neg_lo:[0,1] neg_hi:[0,1]
	v_pk_mul_f32 v[12:13], v[28:29], v[22:23] op_sel:[1,1] op_sel_hi:[0,1]
	v_mov_b32_e32 v24, v22
	v_pk_fma_f32 v[22:23], v[28:29], v[10:11], v[12:13] neg_lo:[0,0,1] neg_hi:[0,0,1]
	v_pk_fma_f32 v[10:11], v[28:29], v[10:11], v[12:13] op_sel_hi:[1,0,1]
	ds_write2st64_b64 v67, v[32:33], v[36:37] offset1:1
	v_mov_b32_e32 v23, v11
	ds_write2st64_b64 v67, v[24:25], v[22:23] offset0:2 offset1:3
	v_add_u32_e32 v9, 0x50, v9
	ds_read2st64_b64 v[10:13], v9 offset1:1
	ds_read2st64_b64 v[22:25], v9 offset0:2 offset1:3
	ds_read_b64 v[28:29], v69
	v_lshl_or_b32 v8, v8, 11, v66
	v_lshl_or_b32 v7, v7, 11, v66
	v_add_u32_e32 v7, 0x50, v7
	s_waitcnt lgkmcnt(1)
	v_pk_add_f32 v[26:27], v[10:11], v[22:23]
	v_pk_add_f32 v[30:31], v[12:13], v[24:25]
	v_mov_b32_e32 v38, v24
	v_pk_add_f32 v[32:33], v[26:27], v[30:31]
	v_pk_add_f32 v[26:27], v[26:27], v[30:31] neg_lo:[0,1] neg_hi:[0,1]
	ds_read_b64 v[30:31], v68
	s_waitcnt lgkmcnt(1)
	v_pk_mul_f32 v[34:35], v[26:27], v[28:29] op_sel:[1,1] op_sel_hi:[1,0]
	v_mov_b32_e32 v39, v23
	v_pk_fma_f32 v[36:37], v[26:27], v[28:29], v[34:35] neg_lo:[0,0,1] neg_hi:[0,0,1]
	v_pk_fma_f32 v[26:27], v[26:27], v[28:29], v[34:35] op_sel_hi:[0,1,1]
	v_mov_b32_e32 v37, v27
	v_mov_b32_e32 v26, v10
	v_mov_b32_e32 v27, v12
	v_mov_b32_e32 v34, v22
	v_mov_b32_e32 v35, v24
	v_pk_add_f32 v[26:27], v[26:27], v[34:35] neg_lo:[0,1] neg_hi:[0,1]
	v_mov_b32_e32 v34, v12
	v_mov_b32_e32 v35, v11
	v_pk_add_f32 v[34:35], v[34:35], v[38:39] neg_lo:[0,1] neg_hi:[0,1]
	v_pk_mov_b32 v[38:39], v[12:13], v[10:11] op_sel:[1,0]
	v_pk_mov_b32 v[40:41], v[24:25], v[22:23] op_sel:[1,0]
	v_mov_b32_e32 v12, v11
	v_mov_b32_e32 v24, v23
	v_pk_add_f32 v[38:39], v[38:39], v[40:41] neg_lo:[0,1] neg_hi:[0,1]
	v_pk_add_f32 v[10:11], v[12:13], v[24:25] neg_lo:[0,1] neg_hi:[0,1]
	s_waitcnt lgkmcnt(0)
	v_pk_mul_f32 v[12:13], v[38:39], v[30:31]
	v_pk_mul_f32 v[10:11], v[10:11], v[30:31] op_sel:[0,1]
	v_pk_fma_f32 v[12:13], v[34:35], v[30:31], v[12:13] op_sel:[0,1,0] op_sel_hi:[1,0,1]
	v_pk_fma_f32 v[10:11], v[26:27], v[30:31], v[10:11] op_sel_hi:[1,0,1] neg_lo:[0,0,1] neg_hi:[0,0,1]
	ds_write2st64_b64 v9, v[32:33], v[36:37] offset1:1
	v_pk_add_f32 v[22:23], v[12:13], v[10:11]
	v_pk_add_f32 v[24:25], v[12:13], v[10:11] neg_lo:[0,1] neg_hi:[0,1]
	v_pk_add_f32 v[10:11], v[10:11], v[12:13] neg_lo:[0,1] neg_hi:[0,1]
	v_pk_mul_f32 v[12:13], v[28:29], v[22:23] op_sel:[1,1] op_sel_hi:[0,1]
	v_mov_b32_e32 v24, v22
	v_pk_fma_f32 v[22:23], v[28:29], v[10:11], v[12:13] neg_lo:[0,0,1] neg_hi:[0,0,1]
	v_pk_fma_f32 v[10:11], v[28:29], v[10:11], v[12:13] op_sel_hi:[1,0,1]
	v_add_u32_e32 v40, 0x50, v8
	v_mov_b32_e32 v23, v11
	ds_write2st64_b64 v9, v[24:25], v[22:23] offset0:2 offset1:3
	ds_read2st64_b64 v[8:11], v40 offset1:1
	ds_read2st64_b64 v[22:25], v40 offset0:2 offset1:3
	ds_read_b64 v[26:27], v69
	s_waitcnt lgkmcnt(1)
	v_pk_add_f32 v[12:13], v[8:9], v[22:23]
	v_pk_add_f32 v[28:29], v[10:11], v[24:25]
	v_mov_b32_e32 v36, v24
	v_pk_add_f32 v[30:31], v[12:13], v[28:29]
	v_pk_add_f32 v[12:13], v[12:13], v[28:29] neg_lo:[0,1] neg_hi:[0,1]
	ds_read_b64 v[28:29], v68
	s_waitcnt lgkmcnt(1)
	v_pk_mul_f32 v[32:33], v[12:13], v[26:27] op_sel:[1,1] op_sel_hi:[1,0]
	v_mov_b32_e32 v37, v23
	v_pk_fma_f32 v[34:35], v[12:13], v[26:27], v[32:33] neg_lo:[0,0,1] neg_hi:[0,0,1]
	v_pk_fma_f32 v[12:13], v[12:13], v[26:27], v[32:33] op_sel_hi:[0,1,1]
	v_mov_b32_e32 v35, v13
	v_mov_b32_e32 v12, v8
	v_mov_b32_e32 v13, v10
	v_mov_b32_e32 v32, v22
	v_mov_b32_e32 v33, v24
	v_pk_add_f32 v[12:13], v[12:13], v[32:33] neg_lo:[0,1] neg_hi:[0,1]
	v_mov_b32_e32 v32, v10
	v_mov_b32_e32 v33, v9
	v_pk_add_f32 v[32:33], v[32:33], v[36:37] neg_lo:[0,1] neg_hi:[0,1]
	v_pk_mov_b32 v[36:37], v[10:11], v[8:9] op_sel:[1,0]
	v_pk_mov_b32 v[38:39], v[24:25], v[22:23] op_sel:[1,0]
	v_mov_b32_e32 v10, v9
	v_mov_b32_e32 v24, v23
	v_pk_add_f32 v[36:37], v[36:37], v[38:39] neg_lo:[0,1] neg_hi:[0,1]
	v_pk_add_f32 v[8:9], v[10:11], v[24:25] neg_lo:[0,1] neg_hi:[0,1]
	s_waitcnt lgkmcnt(0)
	v_pk_mul_f32 v[10:11], v[36:37], v[28:29]
	v_pk_mul_f32 v[8:9], v[8:9], v[28:29] op_sel:[0,1]
	v_pk_fma_f32 v[10:11], v[32:33], v[28:29], v[10:11] op_sel:[0,1,0] op_sel_hi:[1,0,1]
	v_pk_fma_f32 v[8:9], v[12:13], v[28:29], v[8:9] op_sel_hi:[1,0,1] neg_lo:[0,0,1] neg_hi:[0,0,1]
	ds_write2st64_b64 v40, v[30:31], v[34:35] offset1:1
	v_pk_add_f32 v[12:13], v[10:11], v[8:9]
	v_pk_add_f32 v[22:23], v[10:11], v[8:9] neg_lo:[0,1] neg_hi:[0,1]
	v_pk_add_f32 v[8:9], v[8:9], v[10:11] neg_lo:[0,1] neg_hi:[0,1]
	v_pk_mul_f32 v[10:11], v[26:27], v[12:13] op_sel:[1,1] op_sel_hi:[0,1]
	v_mov_b32_e32 v22, v12
	v_pk_fma_f32 v[12:13], v[26:27], v[8:9], v[10:11] neg_lo:[0,0,1] neg_hi:[0,0,1]
	v_pk_fma_f32 v[8:9], v[26:27], v[8:9], v[10:11] op_sel_hi:[1,0,1]
	s_nop 0
	v_mov_b32_e32 v13, v9
	ds_write2st64_b64 v40, v[22:23], v[12:13] offset0:2 offset1:3
	ds_read2st64_b64 v[8:11], v7 offset1:1
	ds_read2st64_b64 v[22:25], v7 offset0:2 offset1:3
	ds_read_b64 v[26:27], v69
	s_waitcnt lgkmcnt(1)
	v_pk_add_f32 v[12:13], v[8:9], v[22:23]
	v_pk_add_f32 v[28:29], v[10:11], v[24:25]
	v_mov_b32_e32 v36, v24
	v_pk_add_f32 v[30:31], v[12:13], v[28:29]
	v_pk_add_f32 v[12:13], v[12:13], v[28:29] neg_lo:[0,1] neg_hi:[0,1]
	ds_read_b64 v[28:29], v68
	s_waitcnt lgkmcnt(1)
	v_pk_mul_f32 v[32:33], v[12:13], v[26:27] op_sel:[1,1] op_sel_hi:[1,0]
	v_mov_b32_e32 v37, v23
	v_pk_fma_f32 v[34:35], v[12:13], v[26:27], v[32:33] neg_lo:[0,0,1] neg_hi:[0,0,1]
	v_pk_fma_f32 v[12:13], v[12:13], v[26:27], v[32:33] op_sel_hi:[0,1,1]
	v_mov_b32_e32 v35, v13
	v_mov_b32_e32 v12, v8
	v_mov_b32_e32 v13, v10
	v_mov_b32_e32 v32, v22
	v_mov_b32_e32 v33, v24
	v_pk_add_f32 v[12:13], v[12:13], v[32:33] neg_lo:[0,1] neg_hi:[0,1]
	v_mov_b32_e32 v32, v10
	v_mov_b32_e32 v33, v9
	v_pk_add_f32 v[32:33], v[32:33], v[36:37] neg_lo:[0,1] neg_hi:[0,1]
	v_pk_mov_b32 v[36:37], v[10:11], v[8:9] op_sel:[1,0]
	v_pk_mov_b32 v[38:39], v[24:25], v[22:23] op_sel:[1,0]
	v_mov_b32_e32 v10, v9
	v_mov_b32_e32 v24, v23
	v_pk_add_f32 v[36:37], v[36:37], v[38:39] neg_lo:[0,1] neg_hi:[0,1]
	v_pk_add_f32 v[8:9], v[10:11], v[24:25] neg_lo:[0,1] neg_hi:[0,1]
	s_waitcnt lgkmcnt(0)
	v_pk_mul_f32 v[10:11], v[36:37], v[28:29]
	v_pk_mul_f32 v[8:9], v[8:9], v[28:29] op_sel:[0,1]
	v_pk_fma_f32 v[10:11], v[32:33], v[28:29], v[10:11] op_sel:[0,1,0] op_sel_hi:[1,0,1]
	v_pk_fma_f32 v[8:9], v[12:13], v[28:29], v[8:9] op_sel_hi:[1,0,1] neg_lo:[0,0,1] neg_hi:[0,0,1]
	ds_write2st64_b64 v7, v[30:31], v[34:35] offset1:1
	v_pk_add_f32 v[12:13], v[10:11], v[8:9]
	v_pk_add_f32 v[22:23], v[10:11], v[8:9] neg_lo:[0,1] neg_hi:[0,1]
	v_pk_add_f32 v[8:9], v[8:9], v[10:11] neg_lo:[0,1] neg_hi:[0,1]
	v_pk_mul_f32 v[10:11], v[26:27], v[12:13] op_sel:[1,1] op_sel_hi:[0,1]
	v_mov_b32_e32 v22, v12
	v_pk_fma_f32 v[12:13], v[26:27], v[8:9], v[10:11] neg_lo:[0,0,1] neg_hi:[0,0,1]
	v_pk_fma_f32 v[8:9], v[26:27], v[8:9], v[10:11] op_sel_hi:[1,0,1]
	s_nop 0
	v_mov_b32_e32 v13, v9
	ds_write2st64_b64 v7, v[22:23], v[12:13] offset0:2 offset1:3
	v_and_b32_e32 v7, 15, v2
	v_and_or_b32 v8, v3, s35, v7
	v_lshl_add_u32 v40, v8, 3, v205
	v_lshlrev_b32_e32 v12, 10, v7
	v_lshlrev_b32_e32 v13, 4, v7
	s_waitcnt lgkmcnt(0)
	s_barrier
	ds_read2_b64 v[8:11], v40 offset1:16
	ds_read2_b64 v[22:25], v40 offset0:32 offset1:48
	v_add3_u32 v41, s85, v12, v13
	v_lshlrev_b32_e32 v12, 11, v7
	v_lshlrev_b32_e32 v13, 5, v7
	v_add3_u32 v66, s85, v12, v13
	ds_read_b64 v[26:27], v66
	s_waitcnt lgkmcnt(1)
	v_pk_add_f32 v[12:13], v[8:9], v[22:23]
	v_pk_add_f32 v[28:29], v[10:11], v[24:25]
	v_mov_b32_e32 v36, v24
	v_pk_add_f32 v[30:31], v[12:13], v[28:29]
	v_pk_add_f32 v[12:13], v[12:13], v[28:29] neg_lo:[0,1] neg_hi:[0,1]
	ds_read_b64 v[28:29], v41
	s_waitcnt lgkmcnt(1)
	v_pk_mul_f32 v[32:33], v[12:13], v[26:27] op_sel:[1,1] op_sel_hi:[1,0]
	v_mov_b32_e32 v37, v23
	v_pk_fma_f32 v[34:35], v[12:13], v[26:27], v[32:33] neg_lo:[0,0,1] neg_hi:[0,0,1]
	v_pk_fma_f32 v[12:13], v[12:13], v[26:27], v[32:33] op_sel_hi:[0,1,1]
	v_mov_b32_e32 v35, v13
	v_mov_b32_e32 v12, v8
	v_mov_b32_e32 v13, v10
	v_mov_b32_e32 v32, v22
	v_mov_b32_e32 v33, v24
	v_pk_add_f32 v[12:13], v[12:13], v[32:33] neg_lo:[0,1] neg_hi:[0,1]
	v_mov_b32_e32 v32, v10
	v_mov_b32_e32 v33, v9
	v_pk_add_f32 v[32:33], v[32:33], v[36:37] neg_lo:[0,1] neg_hi:[0,1]
	v_pk_mov_b32 v[36:37], v[10:11], v[8:9] op_sel:[1,0]
	v_pk_mov_b32 v[38:39], v[24:25], v[22:23] op_sel:[1,0]
	v_mov_b32_e32 v10, v9
	v_mov_b32_e32 v24, v23
	v_pk_add_f32 v[36:37], v[36:37], v[38:39] neg_lo:[0,1] neg_hi:[0,1]
	v_pk_add_f32 v[8:9], v[10:11], v[24:25] neg_lo:[0,1] neg_hi:[0,1]
	s_waitcnt lgkmcnt(0)
	v_pk_mul_f32 v[10:11], v[36:37], v[28:29]
	v_pk_mul_f32 v[8:9], v[8:9], v[28:29] op_sel:[0,1]
	v_pk_fma_f32 v[10:11], v[32:33], v[28:29], v[10:11] op_sel:[0,1,0] op_sel_hi:[1,0,1]
	v_pk_fma_f32 v[8:9], v[12:13], v[28:29], v[8:9] op_sel_hi:[1,0,1] neg_lo:[0,0,1] neg_hi:[0,0,1]
	ds_write2_b64 v40, v[30:31], v[34:35] offset1:16
	v_pk_add_f32 v[12:13], v[10:11], v[8:9]
	v_pk_add_f32 v[22:23], v[10:11], v[8:9] neg_lo:[0,1] neg_hi:[0,1]
	v_pk_add_f32 v[8:9], v[8:9], v[10:11] neg_lo:[0,1] neg_hi:[0,1]
	v_pk_mul_f32 v[10:11], v[26:27], v[12:13] op_sel:[1,1] op_sel_hi:[0,1]
	v_mov_b32_e32 v22, v12
	v_pk_fma_f32 v[12:13], v[26:27], v[8:9], v[10:11] neg_lo:[0,0,1] neg_hi:[0,0,1]
	v_pk_fma_f32 v[8:9], v[26:27], v[8:9], v[10:11] op_sel_hi:[1,0,1]
	s_nop 0
	v_mov_b32_e32 v13, v9
	v_and_or_b32 v8, v4, s35, v7
	ds_write2_b64 v40, v[22:23], v[12:13] offset0:32 offset1:48
	v_lshl_add_u32 v40, v8, 3, v205
	ds_read2_b64 v[8:11], v40 offset1:16
	ds_read2_b64 v[22:25], v40 offset0:32 offset1:48
	ds_read_b64 v[26:27], v66
	s_waitcnt lgkmcnt(1)
	v_pk_add_f32 v[12:13], v[8:9], v[22:23]
	v_pk_add_f32 v[28:29], v[10:11], v[24:25]
	v_mov_b32_e32 v36, v24
	v_pk_add_f32 v[30:31], v[12:13], v[28:29]
	v_pk_add_f32 v[12:13], v[12:13], v[28:29] neg_lo:[0,1] neg_hi:[0,1]
	ds_read_b64 v[28:29], v41
	s_waitcnt lgkmcnt(1)
	v_pk_mul_f32 v[32:33], v[12:13], v[26:27] op_sel:[1,1] op_sel_hi:[1,0]
	v_mov_b32_e32 v37, v23
	v_pk_fma_f32 v[34:35], v[12:13], v[26:27], v[32:33] neg_lo:[0,0,1] neg_hi:[0,0,1]
	v_pk_fma_f32 v[12:13], v[12:13], v[26:27], v[32:33] op_sel_hi:[0,1,1]
	v_mov_b32_e32 v35, v13
	v_mov_b32_e32 v12, v8
	v_mov_b32_e32 v13, v10
	v_mov_b32_e32 v32, v22
	v_mov_b32_e32 v33, v24
	v_pk_add_f32 v[12:13], v[12:13], v[32:33] neg_lo:[0,1] neg_hi:[0,1]
	v_mov_b32_e32 v32, v10
	v_mov_b32_e32 v33, v9
	v_pk_add_f32 v[32:33], v[32:33], v[36:37] neg_lo:[0,1] neg_hi:[0,1]
	v_pk_mov_b32 v[36:37], v[10:11], v[8:9] op_sel:[1,0]
	v_pk_mov_b32 v[38:39], v[24:25], v[22:23] op_sel:[1,0]
	v_mov_b32_e32 v10, v9
	v_mov_b32_e32 v24, v23
	v_pk_add_f32 v[36:37], v[36:37], v[38:39] neg_lo:[0,1] neg_hi:[0,1]
	v_pk_add_f32 v[8:9], v[10:11], v[24:25] neg_lo:[0,1] neg_hi:[0,1]
	s_waitcnt lgkmcnt(0)
	v_pk_mul_f32 v[10:11], v[36:37], v[28:29]
	v_pk_mul_f32 v[8:9], v[8:9], v[28:29] op_sel:[0,1]
	v_pk_fma_f32 v[10:11], v[32:33], v[28:29], v[10:11] op_sel:[0,1,0] op_sel_hi:[1,0,1]
	v_pk_fma_f32 v[8:9], v[12:13], v[28:29], v[8:9] op_sel_hi:[1,0,1] neg_lo:[0,0,1] neg_hi:[0,0,1]
	ds_write2_b64 v40, v[30:31], v[34:35] offset1:16
	v_pk_add_f32 v[12:13], v[10:11], v[8:9]
	v_pk_add_f32 v[22:23], v[10:11], v[8:9] neg_lo:[0,1] neg_hi:[0,1]
	v_pk_add_f32 v[8:9], v[8:9], v[10:11] neg_lo:[0,1] neg_hi:[0,1]
	v_pk_mul_f32 v[10:11], v[26:27], v[12:13] op_sel:[1,1] op_sel_hi:[0,1]
	v_mov_b32_e32 v22, v12
	v_pk_fma_f32 v[12:13], v[26:27], v[8:9], v[10:11] neg_lo:[0,0,1] neg_hi:[0,0,1]
	v_pk_fma_f32 v[8:9], v[26:27], v[8:9], v[10:11] op_sel_hi:[1,0,1]
	s_nop 0
	v_mov_b32_e32 v13, v9
	v_and_or_b32 v8, v5, s35, v7
	ds_write2_b64 v40, v[22:23], v[12:13] offset0:32 offset1:48
	v_lshl_add_u32 v40, v8, 3, v205
	ds_read2_b64 v[8:11], v40 offset1:16
	ds_read2_b64 v[22:25], v40 offset0:32 offset1:48
	ds_read_b64 v[26:27], v66
	v_and_or_b32 v7, v6, s35, v7
	v_lshl_add_u32 v7, v7, 3, v205
	s_waitcnt lgkmcnt(1)
	v_pk_add_f32 v[12:13], v[8:9], v[22:23]
	v_pk_add_f32 v[28:29], v[10:11], v[24:25]
	v_mov_b32_e32 v36, v24
	v_pk_add_f32 v[30:31], v[12:13], v[28:29]
	v_pk_add_f32 v[12:13], v[12:13], v[28:29] neg_lo:[0,1] neg_hi:[0,1]
	ds_read_b64 v[28:29], v41
	s_waitcnt lgkmcnt(1)
	v_pk_mul_f32 v[32:33], v[12:13], v[26:27] op_sel:[1,1] op_sel_hi:[1,0]
	v_mov_b32_e32 v37, v23
	v_pk_fma_f32 v[34:35], v[12:13], v[26:27], v[32:33] neg_lo:[0,0,1] neg_hi:[0,0,1]
	v_pk_fma_f32 v[12:13], v[12:13], v[26:27], v[32:33] op_sel_hi:[0,1,1]
	v_mov_b32_e32 v35, v13
	v_mov_b32_e32 v12, v8
	v_mov_b32_e32 v13, v10
	v_mov_b32_e32 v32, v22
	v_mov_b32_e32 v33, v24
	v_pk_add_f32 v[12:13], v[12:13], v[32:33] neg_lo:[0,1] neg_hi:[0,1]
	v_mov_b32_e32 v32, v10
	v_mov_b32_e32 v33, v9
	v_pk_add_f32 v[32:33], v[32:33], v[36:37] neg_lo:[0,1] neg_hi:[0,1]
	v_pk_mov_b32 v[36:37], v[10:11], v[8:9] op_sel:[1,0]
	v_pk_mov_b32 v[38:39], v[24:25], v[22:23] op_sel:[1,0]
	v_mov_b32_e32 v10, v9
	v_mov_b32_e32 v24, v23
	v_pk_add_f32 v[36:37], v[36:37], v[38:39] neg_lo:[0,1] neg_hi:[0,1]
	v_pk_add_f32 v[8:9], v[10:11], v[24:25] neg_lo:[0,1] neg_hi:[0,1]
	s_waitcnt lgkmcnt(0)
	v_pk_mul_f32 v[10:11], v[36:37], v[28:29]
	v_pk_mul_f32 v[8:9], v[8:9], v[28:29] op_sel:[0,1]
	v_pk_fma_f32 v[10:11], v[32:33], v[28:29], v[10:11] op_sel:[0,1,0] op_sel_hi:[1,0,1]
	v_pk_fma_f32 v[8:9], v[12:13], v[28:29], v[8:9] op_sel_hi:[1,0,1] neg_lo:[0,0,1] neg_hi:[0,0,1]
	ds_write2_b64 v40, v[30:31], v[34:35] offset1:16
	v_pk_add_f32 v[12:13], v[10:11], v[8:9]
	v_pk_add_f32 v[22:23], v[10:11], v[8:9] neg_lo:[0,1] neg_hi:[0,1]
	v_pk_add_f32 v[8:9], v[8:9], v[10:11] neg_lo:[0,1] neg_hi:[0,1]
	v_pk_mul_f32 v[10:11], v[26:27], v[12:13] op_sel:[1,1] op_sel_hi:[0,1]
	v_mov_b32_e32 v22, v12
	v_pk_fma_f32 v[12:13], v[26:27], v[8:9], v[10:11] neg_lo:[0,0,1] neg_hi:[0,0,1]
	v_pk_fma_f32 v[8:9], v[26:27], v[8:9], v[10:11] op_sel_hi:[1,0,1]
	s_nop 0
	v_mov_b32_e32 v13, v9
	ds_write2_b64 v40, v[22:23], v[12:13] offset0:32 offset1:48
	ds_read2_b64 v[8:11], v7 offset1:16
	ds_read2_b64 v[22:25], v7 offset0:32 offset1:48
	ds_read_b64 v[26:27], v66
	s_waitcnt lgkmcnt(1)
	v_pk_add_f32 v[12:13], v[8:9], v[22:23]
	v_pk_add_f32 v[28:29], v[10:11], v[24:25]
	v_mov_b32_e32 v36, v24
	v_pk_add_f32 v[30:31], v[12:13], v[28:29]
	v_pk_add_f32 v[12:13], v[12:13], v[28:29] neg_lo:[0,1] neg_hi:[0,1]
	ds_read_b64 v[28:29], v41
	s_waitcnt lgkmcnt(1)
	v_pk_mul_f32 v[32:33], v[12:13], v[26:27] op_sel:[1,1] op_sel_hi:[1,0]
	v_mov_b32_e32 v37, v23
	v_pk_fma_f32 v[34:35], v[12:13], v[26:27], v[32:33] neg_lo:[0,0,1] neg_hi:[0,0,1]
	v_pk_fma_f32 v[12:13], v[12:13], v[26:27], v[32:33] op_sel_hi:[0,1,1]
	v_mov_b32_e32 v35, v13
	v_mov_b32_e32 v12, v8
	v_mov_b32_e32 v13, v10
	v_mov_b32_e32 v32, v22
	v_mov_b32_e32 v33, v24
	v_pk_add_f32 v[12:13], v[12:13], v[32:33] neg_lo:[0,1] neg_hi:[0,1]
	v_mov_b32_e32 v32, v10
	v_mov_b32_e32 v33, v9
	v_pk_add_f32 v[32:33], v[32:33], v[36:37] neg_lo:[0,1] neg_hi:[0,1]
	v_pk_mov_b32 v[36:37], v[10:11], v[8:9] op_sel:[1,0]
	v_pk_mov_b32 v[38:39], v[24:25], v[22:23] op_sel:[1,0]
	v_mov_b32_e32 v10, v9
	v_mov_b32_e32 v24, v23
	v_pk_add_f32 v[36:37], v[36:37], v[38:39] neg_lo:[0,1] neg_hi:[0,1]
	v_pk_add_f32 v[8:9], v[10:11], v[24:25] neg_lo:[0,1] neg_hi:[0,1]
	s_waitcnt lgkmcnt(0)
	v_pk_mul_f32 v[10:11], v[36:37], v[28:29]
	v_pk_mul_f32 v[8:9], v[8:9], v[28:29] op_sel:[0,1]
	v_pk_fma_f32 v[10:11], v[32:33], v[28:29], v[10:11] op_sel:[0,1,0] op_sel_hi:[1,0,1]
	v_pk_fma_f32 v[8:9], v[12:13], v[28:29], v[8:9] op_sel_hi:[1,0,1] neg_lo:[0,0,1] neg_hi:[0,0,1]
	ds_write2_b64 v7, v[30:31], v[34:35] offset1:16
	v_pk_add_f32 v[12:13], v[10:11], v[8:9]
	v_pk_add_f32 v[22:23], v[10:11], v[8:9] neg_lo:[0,1] neg_hi:[0,1]
	v_pk_add_f32 v[8:9], v[8:9], v[10:11] neg_lo:[0,1] neg_hi:[0,1]
	v_pk_mul_f32 v[10:11], v[26:27], v[12:13] op_sel:[1,1] op_sel_hi:[0,1]
	v_mov_b32_e32 v22, v12
	v_pk_fma_f32 v[12:13], v[26:27], v[8:9], v[10:11] neg_lo:[0,0,1] neg_hi:[0,0,1]
	v_pk_fma_f32 v[8:9], v[26:27], v[8:9], v[10:11] op_sel_hi:[1,0,1]
	s_nop 0
	v_mov_b32_e32 v13, v9
	ds_write2_b64 v7, v[22:23], v[12:13] offset0:32 offset1:48
	v_and_b32_e32 v7, 3, v2
	v_and_or_b32 v3, v3, s5, v7
	v_lshl_add_u32 v3, v3, 3, v205
	v_lshlrev_b32_e32 v12, 12, v7
	v_lshlrev_b32_e32 v13, 6, v7
	s_waitcnt lgkmcnt(0)
	s_barrier
	ds_read2_b64 v[8:11], v3 offset1:4
	ds_read2_b64 v[22:25], v3 offset0:8 offset1:12
	v_add3_u32 v40, s85, v12, v13
	v_lshlrev_b32_e32 v12, 13, v7
	v_lshlrev_b32_e32 v13, 7, v7
	v_add3_u32 v41, s85, v12, v13
	ds_read_b64 v[26:27], v41
	s_waitcnt lgkmcnt(1)
	v_pk_add_f32 v[12:13], v[8:9], v[22:23]
	v_pk_add_f32 v[28:29], v[10:11], v[24:25]
	v_mov_b32_e32 v36, v24
	v_pk_add_f32 v[30:31], v[12:13], v[28:29]
	v_pk_add_f32 v[12:13], v[12:13], v[28:29] neg_lo:[0,1] neg_hi:[0,1]
	ds_read_b64 v[28:29], v40
	s_waitcnt lgkmcnt(1)
	v_pk_mul_f32 v[32:33], v[12:13], v[26:27] op_sel:[1,1] op_sel_hi:[1,0]
	v_mov_b32_e32 v37, v23
	v_pk_fma_f32 v[34:35], v[12:13], v[26:27], v[32:33] neg_lo:[0,0,1] neg_hi:[0,0,1]
	v_pk_fma_f32 v[12:13], v[12:13], v[26:27], v[32:33] op_sel_hi:[0,1,1]
	v_mov_b32_e32 v35, v13
	v_mov_b32_e32 v12, v8
	v_mov_b32_e32 v13, v10
	v_mov_b32_e32 v32, v22
	v_mov_b32_e32 v33, v24
	v_pk_add_f32 v[12:13], v[12:13], v[32:33] neg_lo:[0,1] neg_hi:[0,1]
	v_mov_b32_e32 v32, v10
	v_mov_b32_e32 v33, v9
	v_pk_add_f32 v[32:33], v[32:33], v[36:37] neg_lo:[0,1] neg_hi:[0,1]
	v_pk_mov_b32 v[36:37], v[10:11], v[8:9] op_sel:[1,0]
	v_pk_mov_b32 v[38:39], v[24:25], v[22:23] op_sel:[1,0]
	v_mov_b32_e32 v10, v9
	v_mov_b32_e32 v24, v23
	v_pk_add_f32 v[36:37], v[36:37], v[38:39] neg_lo:[0,1] neg_hi:[0,1]
	v_pk_add_f32 v[8:9], v[10:11], v[24:25] neg_lo:[0,1] neg_hi:[0,1]
	s_waitcnt lgkmcnt(0)
	v_pk_mul_f32 v[10:11], v[36:37], v[28:29]
	v_pk_mul_f32 v[8:9], v[8:9], v[28:29] op_sel:[0,1]
	v_pk_fma_f32 v[10:11], v[32:33], v[28:29], v[10:11] op_sel:[0,1,0] op_sel_hi:[1,0,1]
	v_pk_fma_f32 v[8:9], v[12:13], v[28:29], v[8:9] op_sel_hi:[1,0,1] neg_lo:[0,0,1] neg_hi:[0,0,1]
	ds_write2_b64 v3, v[30:31], v[34:35] offset1:4
	v_pk_add_f32 v[12:13], v[10:11], v[8:9]
	v_pk_add_f32 v[22:23], v[10:11], v[8:9] neg_lo:[0,1] neg_hi:[0,1]
	v_pk_add_f32 v[8:9], v[8:9], v[10:11] neg_lo:[0,1] neg_hi:[0,1]
	v_pk_mul_f32 v[10:11], v[26:27], v[12:13] op_sel:[1,1] op_sel_hi:[0,1]
	v_mov_b32_e32 v22, v12
	v_pk_fma_f32 v[12:13], v[26:27], v[8:9], v[10:11] neg_lo:[0,0,1] neg_hi:[0,0,1]
	v_pk_fma_f32 v[8:9], v[26:27], v[8:9], v[10:11] op_sel_hi:[1,0,1]
	s_nop 0
	v_mov_b32_e32 v13, v9
	ds_write2_b64 v3, v[22:23], v[12:13] offset0:8 offset1:12
	v_and_or_b32 v3, v4, s5, v7
	v_lshl_add_u32 v3, v3, 3, v205
	ds_read2_b64 v[8:11], v3 offset1:4
	ds_read2_b64 v[22:25], v3 offset0:8 offset1:12
	ds_read_b64 v[26:27], v41
	s_waitcnt lgkmcnt(1)
	v_pk_add_f32 v[12:13], v[8:9], v[22:23]
	v_pk_add_f32 v[28:29], v[10:11], v[24:25]
	v_mov_b32_e32 v36, v24
	v_pk_add_f32 v[30:31], v[12:13], v[28:29]
	v_pk_add_f32 v[12:13], v[12:13], v[28:29] neg_lo:[0,1] neg_hi:[0,1]
	ds_read_b64 v[28:29], v40
	s_waitcnt lgkmcnt(1)
	v_pk_mul_f32 v[32:33], v[12:13], v[26:27] op_sel:[1,1] op_sel_hi:[1,0]
	v_mov_b32_e32 v37, v23
	v_pk_fma_f32 v[34:35], v[12:13], v[26:27], v[32:33] neg_lo:[0,0,1] neg_hi:[0,0,1]
	v_pk_fma_f32 v[12:13], v[12:13], v[26:27], v[32:33] op_sel_hi:[0,1,1]
	v_mov_b32_e32 v35, v13
	v_mov_b32_e32 v12, v8
	v_mov_b32_e32 v13, v10
	v_mov_b32_e32 v32, v22
	v_mov_b32_e32 v33, v24
	v_pk_add_f32 v[12:13], v[12:13], v[32:33] neg_lo:[0,1] neg_hi:[0,1]
	v_mov_b32_e32 v32, v10
	v_mov_b32_e32 v33, v9
	v_pk_add_f32 v[32:33], v[32:33], v[36:37] neg_lo:[0,1] neg_hi:[0,1]
	v_pk_mov_b32 v[36:37], v[10:11], v[8:9] op_sel:[1,0]
	v_pk_mov_b32 v[38:39], v[24:25], v[22:23] op_sel:[1,0]
	v_mov_b32_e32 v10, v9
	v_mov_b32_e32 v24, v23
	v_pk_add_f32 v[36:37], v[36:37], v[38:39] neg_lo:[0,1] neg_hi:[0,1]
	v_pk_add_f32 v[8:9], v[10:11], v[24:25] neg_lo:[0,1] neg_hi:[0,1]
	s_waitcnt lgkmcnt(0)
	v_pk_mul_f32 v[10:11], v[36:37], v[28:29]
	v_pk_mul_f32 v[8:9], v[8:9], v[28:29] op_sel:[0,1]
	v_pk_fma_f32 v[10:11], v[32:33], v[28:29], v[10:11] op_sel:[0,1,0] op_sel_hi:[1,0,1]
	v_pk_fma_f32 v[8:9], v[12:13], v[28:29], v[8:9] op_sel_hi:[1,0,1] neg_lo:[0,0,1] neg_hi:[0,0,1]
	ds_write2_b64 v3, v[30:31], v[34:35] offset1:4
	v_pk_add_f32 v[12:13], v[10:11], v[8:9]
	v_pk_add_f32 v[22:23], v[10:11], v[8:9] neg_lo:[0,1] neg_hi:[0,1]
	v_pk_add_f32 v[8:9], v[8:9], v[10:11] neg_lo:[0,1] neg_hi:[0,1]
	v_pk_mul_f32 v[10:11], v[26:27], v[12:13] op_sel:[1,1] op_sel_hi:[0,1]
	v_mov_b32_e32 v22, v12
	v_pk_fma_f32 v[12:13], v[26:27], v[8:9], v[10:11] neg_lo:[0,0,1] neg_hi:[0,0,1]
	v_pk_fma_f32 v[8:9], v[26:27], v[8:9], v[10:11] op_sel_hi:[1,0,1]
	s_nop 0
	v_mov_b32_e32 v13, v9
	ds_write2_b64 v3, v[22:23], v[12:13] offset0:8 offset1:12
	v_and_or_b32 v3, v5, s5, v7
	v_lshl_add_u32 v3, v3, 3, v205
	ds_read2_b64 v[8:11], v3 offset1:4
	ds_read2_b64 v[22:25], v3 offset0:8 offset1:12
	ds_read_b64 v[12:13], v41
	s_waitcnt lgkmcnt(1)
	v_pk_add_f32 v[4:5], v[8:9], v[22:23]
	v_pk_add_f32 v[26:27], v[10:11], v[24:25]
	v_mov_b32_e32 v34, v24
	v_pk_add_f32 v[28:29], v[4:5], v[26:27]
	v_pk_add_f32 v[4:5], v[4:5], v[26:27] neg_lo:[0,1] neg_hi:[0,1]
	ds_read_b64 v[26:27], v40
	s_waitcnt lgkmcnt(1)
	v_pk_mul_f32 v[30:31], v[4:5], v[12:13] op_sel:[1,1] op_sel_hi:[1,0]
	v_mov_b32_e32 v35, v23
	v_pk_fma_f32 v[32:33], v[4:5], v[12:13], v[30:31] neg_lo:[0,0,1] neg_hi:[0,0,1]
	v_pk_fma_f32 v[4:5], v[4:5], v[12:13], v[30:31] op_sel_hi:[0,1,1]
	v_mov_b32_e32 v33, v5
	v_mov_b32_e32 v4, v8
	v_mov_b32_e32 v5, v10
	v_mov_b32_e32 v30, v22
	v_mov_b32_e32 v31, v24
	v_pk_add_f32 v[4:5], v[4:5], v[30:31] neg_lo:[0,1] neg_hi:[0,1]
	v_mov_b32_e32 v30, v10
	v_mov_b32_e32 v31, v9
	v_pk_add_f32 v[30:31], v[30:31], v[34:35] neg_lo:[0,1] neg_hi:[0,1]
	v_pk_mov_b32 v[34:35], v[10:11], v[8:9] op_sel:[1,0]
	v_pk_mov_b32 v[36:37], v[24:25], v[22:23] op_sel:[1,0]
	v_mov_b32_e32 v10, v9
	v_mov_b32_e32 v24, v23
	v_pk_add_f32 v[8:9], v[10:11], v[24:25] neg_lo:[0,1] neg_hi:[0,1]
	v_pk_add_f32 v[34:35], v[34:35], v[36:37] neg_lo:[0,1] neg_hi:[0,1]
	s_waitcnt lgkmcnt(0)
	v_pk_mul_f32 v[8:9], v[8:9], v[26:27] op_sel:[0,1]
	ds_write2_b64 v3, v[28:29], v[32:33] offset1:4
	v_pk_fma_f32 v[4:5], v[4:5], v[26:27], v[8:9] op_sel_hi:[1,0,1] neg_lo:[0,0,1] neg_hi:[0,0,1]
	v_pk_mul_f32 v[8:9], v[34:35], v[26:27]
	s_nop 0
	v_pk_fma_f32 v[8:9], v[30:31], v[26:27], v[8:9] op_sel:[0,1,0] op_sel_hi:[1,0,1]
	s_nop 0
	v_pk_add_f32 v[10:11], v[8:9], v[4:5]
	v_pk_add_f32 v[22:23], v[8:9], v[4:5] neg_lo:[0,1] neg_hi:[0,1]
	v_pk_add_f32 v[4:5], v[4:5], v[8:9] neg_lo:[0,1] neg_hi:[0,1]
	v_pk_mul_f32 v[8:9], v[12:13], v[10:11] op_sel:[1,1] op_sel_hi:[0,1]
	v_mov_b32_e32 v22, v10
	v_pk_fma_f32 v[10:11], v[12:13], v[4:5], v[8:9] neg_lo:[0,0,1] neg_hi:[0,0,1]
	v_pk_fma_f32 v[4:5], v[12:13], v[4:5], v[8:9] op_sel_hi:[1,0,1]
	s_nop 0
	v_mov_b32_e32 v11, v5
	ds_write2_b64 v3, v[22:23], v[10:11] offset0:8 offset1:12
	v_and_or_b32 v3, v6, s5, v7
	v_lshl_add_u32 v3, v3, 3, v205
	ds_read2_b64 v[4:7], v3 offset1:4
	ds_read2_b64 v[8:11], v3 offset0:8 offset1:12
	ds_read_b64 v[22:23], v41
	s_waitcnt lgkmcnt(1)
	v_pk_add_f32 v[12:13], v[4:5], v[8:9]
	v_pk_add_f32 v[24:25], v[6:7], v[10:11]
	v_mov_b32_e32 v32, v10
	v_pk_add_f32 v[26:27], v[12:13], v[24:25]
	v_pk_add_f32 v[12:13], v[12:13], v[24:25] neg_lo:[0,1] neg_hi:[0,1]
	ds_read_b64 v[24:25], v40
	s_waitcnt lgkmcnt(1)
	v_pk_mul_f32 v[28:29], v[12:13], v[22:23] op_sel:[1,1] op_sel_hi:[1,0]
	v_mov_b32_e32 v33, v9
	v_pk_fma_f32 v[30:31], v[12:13], v[22:23], v[28:29] neg_lo:[0,0,1] neg_hi:[0,0,1]
	v_pk_fma_f32 v[12:13], v[12:13], v[22:23], v[28:29] op_sel_hi:[0,1,1]
	v_mov_b32_e32 v31, v13
	v_mov_b32_e32 v12, v4
	v_mov_b32_e32 v13, v6
	v_mov_b32_e32 v28, v8
	v_mov_b32_e32 v29, v10
	v_pk_add_f32 v[12:13], v[12:13], v[28:29] neg_lo:[0,1] neg_hi:[0,1]
	v_mov_b32_e32 v28, v6
	v_mov_b32_e32 v29, v5
	v_pk_add_f32 v[28:29], v[28:29], v[32:33] neg_lo:[0,1] neg_hi:[0,1]
	v_pk_mov_b32 v[32:33], v[6:7], v[4:5] op_sel:[1,0]
	v_pk_mov_b32 v[34:35], v[10:11], v[8:9] op_sel:[1,0]
	v_mov_b32_e32 v6, v5
	v_mov_b32_e32 v10, v9
	v_pk_add_f32 v[32:33], v[32:33], v[34:35] neg_lo:[0,1] neg_hi:[0,1]
	v_pk_add_f32 v[4:5], v[6:7], v[10:11] neg_lo:[0,1] neg_hi:[0,1]
	s_waitcnt lgkmcnt(0)
	v_pk_mul_f32 v[6:7], v[32:33], v[24:25]
	v_pk_mul_f32 v[4:5], v[4:5], v[24:25] op_sel:[0,1]
	v_pk_fma_f32 v[6:7], v[28:29], v[24:25], v[6:7] op_sel:[0,1,0] op_sel_hi:[1,0,1]
	v_pk_fma_f32 v[4:5], v[12:13], v[24:25], v[4:5] op_sel_hi:[1,0,1] neg_lo:[0,0,1] neg_hi:[0,0,1]
	v_lshl_add_u32 v24, v2, 5, v205
	v_pk_add_f32 v[8:9], v[6:7], v[4:5]
	v_pk_add_f32 v[10:11], v[6:7], v[4:5] neg_lo:[0,1] neg_hi:[0,1]
	v_pk_add_f32 v[4:5], v[4:5], v[6:7] neg_lo:[0,1] neg_hi:[0,1]
	v_pk_mul_f32 v[6:7], v[22:23], v[8:9] op_sel:[1,1] op_sel_hi:[0,1]
	v_mov_b32_e32 v10, v8
	v_pk_fma_f32 v[8:9], v[22:23], v[4:5], v[6:7] neg_lo:[0,0,1] neg_hi:[0,0,1]
	v_pk_fma_f32 v[4:5], v[22:23], v[4:5], v[6:7] op_sel_hi:[1,0,1]
	ds_write2_b64 v3, v[26:27], v[30:31] offset1:4
	v_mov_b32_e32 v9, v5
	ds_write2_b64 v3, v[10:11], v[8:9] offset0:8 offset1:12
	s_waitcnt lgkmcnt(0)
	s_barrier
	ds_read_b128 v[2:5], v24
	ds_read_b128 v[6:9], v24 offset:16
	s_waitcnt lgkmcnt(0)
	v_pk_add_f32 v[12:13], v[2:3], v[6:7]
	v_pk_add_f32 v[22:23], v[4:5], v[8:9]
	v_pk_add_f32 v[2:3], v[2:3], v[6:7] neg_lo:[0,1] neg_hi:[0,1]
	v_pk_add_f32 v[10:11], v[12:13], v[22:23]
	v_pk_add_f32 v[12:13], v[12:13], v[22:23] neg_lo:[0,1] neg_hi:[0,1]
	ds_write_b128 v24, v[10:13]
	v_pk_add_f32 v[4:5], v[4:5], v[8:9] neg_lo:[0,1] neg_hi:[0,1]
	ds_read_b128 v[6:9], v24 offset:16384
	ds_read_b128 v[10:13], v24 offset:16400
	v_pk_add_f32 v[22:23], v[2:3], v[4:5] op_sel:[0,1] op_sel_hi:[1,0]
	v_pk_add_f32 v[4:5], v[2:3], v[4:5] op_sel:[0,1] op_sel_hi:[1,0] neg_lo:[0,1] neg_hi:[0,1]
	v_mov_b32_e32 v2, v22
	v_mov_b32_e32 v3, v5
	v_mov_b32_e32 v5, v23
	ds_write_b128 v24, v[2:5] offset:16
	s_waitcnt lgkmcnt(1)
	v_pk_add_f32 v[4:5], v[6:7], v[10:11]
	v_pk_add_f32 v[22:23], v[8:9], v[12:13]
	s_nop 0
	v_pk_add_f32 v[2:3], v[4:5], v[22:23]
	v_pk_add_f32 v[4:5], v[4:5], v[22:23] neg_lo:[0,1] neg_hi:[0,1]
	ds_write_b128 v24, v[2:5] offset:16384
	v_pk_add_f32 v[2:3], v[6:7], v[10:11] neg_lo:[0,1] neg_hi:[0,1]
	v_pk_add_f32 v[4:5], v[8:9], v[12:13] neg_lo:[0,1] neg_hi:[0,1]
	ds_read_b128 v[6:9], v24 offset:32768
	ds_read_b128 v[10:13], v24 offset:32784
	v_pk_add_f32 v[22:23], v[2:3], v[4:5] op_sel:[0,1] op_sel_hi:[1,0]
	v_pk_add_f32 v[4:5], v[2:3], v[4:5] op_sel:[0,1] op_sel_hi:[1,0] neg_lo:[0,1] neg_hi:[0,1]
	v_mov_b32_e32 v2, v22
	v_mov_b32_e32 v3, v5
	v_mov_b32_e32 v5, v23
	ds_write_b128 v24, v[2:5] offset:16400
	s_waitcnt lgkmcnt(1)
	v_pk_add_f32 v[4:5], v[6:7], v[10:11]
	v_pk_add_f32 v[22:23], v[8:9], v[12:13]
	s_nop 0
	v_pk_add_f32 v[2:3], v[4:5], v[22:23]
	v_pk_add_f32 v[4:5], v[4:5], v[22:23] neg_lo:[0,1] neg_hi:[0,1]
	ds_write_b128 v24, v[2:5] offset:32768
	v_pk_add_f32 v[2:3], v[6:7], v[10:11] neg_lo:[0,1] neg_hi:[0,1]
	v_pk_add_f32 v[4:5], v[8:9], v[12:13] neg_lo:[0,1] neg_hi:[0,1]
	ds_read_b128 v[6:9], v24 offset:49152
	ds_read_b128 v[10:13], v24 offset:49168
	v_pk_add_f32 v[22:23], v[2:3], v[4:5] op_sel:[0,1] op_sel_hi:[1,0]
	v_pk_add_f32 v[4:5], v[2:3], v[4:5] op_sel:[0,1] op_sel_hi:[1,0] neg_lo:[0,1] neg_hi:[0,1]
	v_mov_b32_e32 v2, v22
	v_mov_b32_e32 v3, v5
	v_mov_b32_e32 v5, v23
	ds_write_b128 v24, v[2:5] offset:32784
	s_waitcnt lgkmcnt(1)
	v_pk_add_f32 v[4:5], v[6:7], v[10:11]
	v_pk_add_f32 v[22:23], v[8:9], v[12:13]
	s_nop 0
	v_pk_add_f32 v[2:3], v[4:5], v[22:23]
	v_pk_add_f32 v[4:5], v[4:5], v[22:23] neg_lo:[0,1] neg_hi:[0,1]
	ds_write_b128 v24, v[2:5] offset:49152
	v_pk_add_f32 v[2:3], v[6:7], v[10:11] neg_lo:[0,1] neg_hi:[0,1]
	v_pk_add_f32 v[4:5], v[8:9], v[12:13] neg_lo:[0,1] neg_hi:[0,1]
	s_nop 0
	v_pk_add_f32 v[6:7], v[2:3], v[4:5] op_sel:[0,1] op_sel_hi:[1,0]
	v_pk_add_f32 v[4:5], v[2:3], v[4:5] op_sel:[0,1] op_sel_hi:[1,0] neg_lo:[0,1] neg_hi:[0,1]
	v_mov_b32_e32 v2, v6
	v_mov_b32_e32 v3, v5
	v_mov_b32_e32 v5, v7
	ds_write_b128 v24, v[2:5] offset:49168
	v_bfrev_b32_e32 v2, v50
	v_lshrrev_b32_e32 v2, 19, v2
	v_bfrev_b32_e32 v3, v52
	v_bfrev_b32_e32 v4, v54
	v_bfrev_b32_e32 v5, v56
	v_sub_u32_e32 v2, 0, v2
	v_lshrrev_b32_e32 v3, 19, v3
	v_lshrrev_b32_e32 v4, 19, v4
	v_lshrrev_b32_e32 v5, 19, v5
	v_and_b32_e32 v2, 0x1fff, v2
	v_sub_u32_e32 v3, 0, v3
	v_sub_u32_e32 v4, 0, v4
	v_sub_u32_e32 v5, 0, v5
	v_bfrev_b32_e32 v2, v2
	v_and_b32_e32 v3, 0x1fff, v3
	v_and_b32_e32 v4, 0x1fff, v4
	v_and_b32_e32 v5, 0x1fff, v5
	v_add_u32_sdwa v2, s70, v2 dst_sel:DWORD dst_unused:UNUSED_PAD src0_sel:DWORD src1_sel:WORD_1
	v_bfrev_b32_e32 v3, v3
	v_bfrev_b32_e32 v4, v4
	v_bfrev_b32_e32 v5, v5
	s_waitcnt lgkmcnt(0)
	s_barrier
	ds_read2st64_b64 v[38:41], v148 offset1:8
	v_add_u32_sdwa v3, s70, v3 dst_sel:DWORD dst_unused:UNUSED_PAD src0_sel:DWORD src1_sel:WORD_1
	ds_read2st64_b64 v[34:37], v148 offset0:16 offset1:24
	v_add_u32_sdwa v4, s70, v4 dst_sel:DWORD dst_unused:UNUSED_PAD src0_sel:DWORD src1_sel:WORD_1
	v_add_u32_sdwa v5, s70, v5 dst_sel:DWORD dst_unused:UNUSED_PAD src0_sel:DWORD src1_sel:WORD_1
	ds_read_b64 v[96:97], v2
	ds_read_b64 v[94:95], v3
	ds_read_b64 v[92:93], v4
	ds_read_b64 v[90:91], v5
	v_bfrev_b32_e32 v2, v58
	v_lshrrev_b32_e32 v2, 19, v2
	v_bfrev_b32_e32 v3, v60
	v_bfrev_b32_e32 v4, v62
	v_bfrev_b32_e32 v5, v64
	v_sub_u32_e32 v2, 0, v2
	v_lshrrev_b32_e32 v3, 19, v3
	v_lshrrev_b32_e32 v4, 19, v4
	v_lshrrev_b32_e32 v5, 19, v5
	v_and_b32_e32 v2, 0x1fff, v2
	v_sub_u32_e32 v3, 0, v3
	v_sub_u32_e32 v4, 0, v4
	v_sub_u32_e32 v5, 0, v5
	v_bfrev_b32_e32 v2, v2
	v_and_b32_e32 v3, 0x1fff, v3
	v_and_b32_e32 v4, 0x1fff, v4
	v_and_b32_e32 v5, 0x1fff, v5
	v_add_u32_sdwa v2, s70, v2 dst_sel:DWORD dst_unused:UNUSED_PAD src0_sel:DWORD src1_sel:WORD_1
	v_bfrev_b32_e32 v3, v3
	v_bfrev_b32_e32 v4, v4
	v_bfrev_b32_e32 v5, v5
	ds_read2st64_b64 v[30:33], v148 offset0:32 offset1:40
	v_add_u32_sdwa v3, s70, v3 dst_sel:DWORD dst_unused:UNUSED_PAD src0_sel:DWORD src1_sel:WORD_1
	ds_read2st64_b64 v[26:29], v148 offset0:48 offset1:56
	v_add_u32_sdwa v4, s70, v4 dst_sel:DWORD dst_unused:UNUSED_PAD src0_sel:DWORD src1_sel:WORD_1
	v_add_u32_sdwa v5, s70, v5 dst_sel:DWORD dst_unused:UNUSED_PAD src0_sel:DWORD src1_sel:WORD_1
	ds_read_b64 v[88:89], v2
	ds_read_b64 v[86:87], v3
	ds_read_b64 v[84:85], v4
	ds_read_b64 v[82:83], v5
	v_bfrev_b32_e32 v2, v53
	v_lshrrev_b32_e32 v2, 19, v2
	v_bfrev_b32_e32 v3, v55
	v_bfrev_b32_e32 v4, v57
	v_sub_u32_e32 v2, 0, v2
	v_lshrrev_b32_e32 v3, 19, v3
	v_lshrrev_b32_e32 v4, 19, v4
	v_and_b32_e32 v2, 0x1fff, v2
	v_sub_u32_e32 v3, 0, v3
	v_sub_u32_e32 v4, 0, v4
	v_bfrev_b32_e32 v2, v2
	v_and_b32_e32 v3, 0x1fff, v3
	v_and_b32_e32 v4, 0x1fff, v4
	v_add_u32_sdwa v2, s70, v2 dst_sel:DWORD dst_unused:UNUSED_PAD src0_sel:DWORD src1_sel:WORD_1
	v_bfrev_b32_e32 v3, v3
	v_bfrev_b32_e32 v4, v4
	ds_read2st64_b64 v[22:25], v148 offset0:64 offset1:72
	ds_read2st64_b64 v[10:13], v148 offset0:80 offset1:88
	v_add_u32_sdwa v3, s70, v3 dst_sel:DWORD dst_unused:UNUSED_PAD src0_sel:DWORD src1_sel:WORD_1
	v_add_u32_sdwa v4, s70, v4 dst_sel:DWORD dst_unused:UNUSED_PAD src0_sel:DWORD src1_sel:WORD_1
	ds_read_b64 v[80:81], v0
	ds_read_b64 v[78:79], v2
	ds_read_b64 v[76:77], v3
	ds_read_b64 v[74:75], v4
	v_bfrev_b32_e32 v2, v61
	v_lshrrev_b32_e32 v2, 19, v2
	v_sub_u32_e32 v2, 0, v2
	v_and_b32_e32 v2, 0x1fff, v2
	v_bfrev_b32_e32 v0, v59
	v_bfrev_b32_e32 v2, v2
	v_lshrrev_b32_e32 v0, 19, v0
	v_add_u32_sdwa v53, s70, v2 dst_sel:DWORD dst_unused:UNUSED_PAD src0_sel:DWORD src1_sel:WORD_1
	v_bfrev_b32_e32 v2, v63
	v_bfrev_b32_e32 v57, v65
	v_sub_u32_e32 v0, 0, v0
	v_lshrrev_b32_e32 v2, 19, v2
	v_lshrrev_b32_e32 v57, 19, v57
	v_and_b32_e32 v0, 0x1fff, v0
	v_sub_u32_e32 v2, 0, v2
	v_sub_u32_e32 v57, 0, v57
	v_bfrev_b32_e32 v0, v0
	v_and_b32_e32 v2, 0x1fff, v2
	v_and_b32_e32 v57, 0x1fff, v57
	v_add_u32_sdwa v0, s70, v0 dst_sel:DWORD dst_unused:UNUSED_PAD src0_sel:DWORD src1_sel:WORD_1
	v_bfrev_b32_e32 v55, v2
	v_bfrev_b32_e32 v57, v57
	ds_read2st64_b64 v[6:9], v148 offset0:96 offset1:104
	ds_read2st64_b64 v[2:5], v148 offset0:112 offset1:120
	v_add_u32_sdwa v55, s70, v55 dst_sel:DWORD dst_unused:UNUSED_PAD src0_sel:DWORD src1_sel:WORD_1
	v_add_u32_sdwa v57, s70, v57 dst_sel:DWORD dst_unused:UNUSED_PAD src0_sel:DWORD src1_sel:WORD_1
	ds_read_b64 v[72:73], v0
	ds_read_b64 v[70:71], v53
	ds_read_b64 v[68:69], v55
	ds_read_b64 v[66:67], v57
	s_waitcnt lgkmcnt(0)
	s_barrier
	global_load_dword v168, v[116:117], off
	global_load_dword v120, v1, s[0:1] offset:3072
	global_load_dword v99, v1, s[20:21]
	global_load_dword v119, v1, s[0:1]
	global_load_dword v118, v202, s[0:1] offset:2048
	s_and_saveexec_b64 s[36:37], s[40:41]
	s_cbranch_execz .LBB0_821
	v_mov_b32_e32 v0, v50
	v_lshl_add_u64 v[102:103], v[0:1], 2, s[66:67]
	global_load_dword v169, v[102:103], off offset:-4
.LBB0_821:
	s_or_b64 exec, exec, s[36:37]
	v_cmp_gt_i32_e64 s[42:43], s33, v50
	s_and_saveexec_b64 s[36:37], s[42:43]
	s_cbranch_execz .LBB0_823
	global_load_dword v170, v[116:117], off offset:4
.LBB0_823:
	s_or_b64 exec, exec, s[36:37]
	s_add_u32 s68, s23, 0x8000
	s_addc_u32 s69, s25, 0
	v_lshl_add_u64 v[114:115], v[50:51], 2, s[68:69]
	global_load_dword v171, v[114:115], off
	s_and_saveexec_b64 s[36:37], s[40:41]
	s_cbranch_execz .LBB0_825
	v_mov_b32_e32 v0, v50
	v_lshl_add_u64 v[102:103], v[0:1], 2, s[68:69]
	global_load_dword v172, v[102:103], off offset:-4
.LBB0_825:
	s_or_b64 exec, exec, s[36:37]
	s_and_saveexec_b64 s[36:37], s[42:43]
	s_cbranch_execz .LBB0_827
	global_load_dword v173, v[114:115], off offset:4
.LBB0_827:
	s_or_b64 exec, exec, s[36:37]
	global_load_dword v174, v[116:117], off offset:2048
	s_movk_i32 s23, 0xfe00
	v_cmp_lt_i32_e64 s[54:55], s23, v50
	s_and_saveexec_b64 s[36:37], s[54:55]
	s_cbranch_execz .LBB0_829
	v_mov_b32_e32 v53, v1
	v_lshl_add_u64 v[104:105], v[52:53], 2, s[66:67]
	global_load_dword v175, v[104:105], off offset:-4
.LBB0_829:
	s_or_b64 exec, exec, s[36:37]
	v_cmp_gt_i32_e64 s[58:59], s3, v50
	s_and_saveexec_b64 s[36:37], s[58:59]
	s_cbranch_execz .LBB0_831
	global_load_dword v176, v[116:117], off offset:2052
.LBB0_831:
	s_or_b64 exec, exec, s[36:37]
	global_load_dword v177, v[114:115], off offset:2048
	s_and_saveexec_b64 s[36:37], s[54:55]
	s_cbranch_execz .LBB0_833
	v_mov_b32_e32 v53, v1
	v_lshl_add_u64 v[104:105], v[52:53], 2, s[68:69]
	global_load_dword v178, v[104:105], off offset:-4
.LBB0_833:
	s_or_b64 exec, exec, s[36:37]
	s_and_saveexec_b64 s[36:37], s[58:59]
	s_cbranch_execz .LBB0_835
	global_load_dword v179, v[114:115], off offset:2052
.LBB0_835:
	s_or_b64 exec, exec, s[36:37]
	v_add_co_u32_e32 v104, vcc, 0x1000, v116
	s_movk_i32 s4, 0xfc00
	s_nop 0
	v_addc_co_u32_e32 v105, vcc, 0, v117, vcc
	global_load_dword v180, v[104:105], off
	v_cmp_lt_i32_e64 s[36:37], s4, v50
	s_and_saveexec_b64 s[38:39], s[36:37]
	s_cbranch_execz .LBB0_837
	v_mov_b32_e32 v55, v1
	v_lshl_add_u64 v[106:107], v[54:55], 2, s[66:67]
	global_load_dword v181, v[106:107], off offset:-4
.LBB0_837:
	s_or_b64 exec, exec, s[38:39]
	v_cmp_gt_i32_e64 s[38:39], s84, v50
	s_and_saveexec_b64 s[44:45], s[38:39]
	s_cbranch_execz .LBB0_839
	s_mov_b64 s[16:17], 0x1000
	v_lshl_add_u64 v[106:107], v[116:117], 0, s[16:17]
	global_load_dword v182, v[106:107], off offset:4
.LBB0_839:
	s_or_b64 exec, exec, s[44:45]
	v_add_co_u32_e32 v106, vcc, 0x1000, v114
	s_nop 1
	v_addc_co_u32_e32 v107, vcc, 0, v115, vcc
	global_load_dword v183, v[106:107], off
	s_and_saveexec_b64 s[44:45], s[36:37]
	s_cbranch_execz .LBB0_841
	v_mov_b32_e32 v55, v1
	v_lshl_add_u64 v[106:107], v[54:55], 2, s[68:69]
	global_load_dword v184, v[106:107], off offset:-4
.LBB0_841:
	s_or_b64 exec, exec, s[44:45]
	s_and_saveexec_b64 s[44:45], s[38:39]
	s_cbranch_execz .LBB0_843
	s_mov_b64 s[16:17], 0x1000
	v_lshl_add_u64 v[106:107], v[114:115], 0, s[16:17]
	global_load_dword v185, v[106:107], off offset:4
.LBB0_843:
	s_or_b64 exec, exec, s[44:45]
	v_add_co_u32_e32 v106, vcc, 0x1000, v116
	s_movk_i32 s23, 0xfa00
	s_nop 0
	v_addc_co_u32_e32 v107, vcc, 0, v117, vcc
	global_load_dword v186, v[106:107], off offset:2048
	v_cmp_lt_i32_e64 s[44:45], s23, v50
	s_and_saveexec_b64 s[46:47], s[44:45]
	s_cbranch_execz .LBB0_845
	v_mov_b32_e32 v57, v1
	v_lshl_add_u64 v[108:109], v[56:57], 2, s[66:67]
	global_load_dword v187, v[108:109], off offset:-4
.LBB0_845:
	s_or_b64 exec, exec, s[46:47]
	s_movk_i32 s4, 0x9ff
	v_cmp_gt_i32_e64 s[46:47], s4, v50
	s_and_saveexec_b64 s[48:49], s[46:47]
	s_cbranch_execz .LBB0_847
	s_mov_b64 s[16:17], 0x1800
	v_lshl_add_u64 v[108:109], v[116:117], 0, s[16:17]
	global_load_dword v188, v[108:109], off offset:4
.LBB0_847:
	s_or_b64 exec, exec, s[48:49]
	v_add_co_u32_e32 v108, vcc, 0x1000, v114
	s_nop 1
	v_addc_co_u32_e32 v109, vcc, 0, v115, vcc
	global_load_dword v189, v[108:109], off offset:2048
	s_and_saveexec_b64 s[48:49], s[44:45]
	s_cbranch_execz .LBB0_849
	v_mov_b32_e32 v57, v1
	v_lshl_add_u64 v[108:109], v[56:57], 2, s[68:69]
	global_load_dword v190, v[108:109], off offset:-4
.LBB0_849:
	s_or_b64 exec, exec, s[48:49]
	s_and_saveexec_b64 s[48:49], s[46:47]
	s_cbranch_execz .LBB0_851
	s_mov_b64 s[16:17], 0x1800
	v_lshl_add_u64 v[108:109], v[114:115], 0, s[16:17]
	global_load_dword v191, v[108:109], off offset:4
.LBB0_851:
	s_or_b64 exec, exec, s[48:49]
	v_add_co_u32_e32 v108, vcc, 0x2000, v116
	s_movk_i32 s23, 0xf800
	s_nop 0
	v_addc_co_u32_e32 v109, vcc, 0, v117, vcc
	global_load_dword v192, v[108:109], off
	v_cmp_lt_i32_e64 s[48:49], s23, v50
	s_and_saveexec_b64 s[50:51], s[48:49]
	s_cbranch_execz .LBB0_853
	v_mov_b32_e32 v59, v1
	v_lshl_add_u64 v[110:111], v[58:59], 2, s[66:67]
	global_load_dword v193, v[110:111], off offset:-4
.LBB0_853:
	s_or_b64 exec, exec, s[50:51]
	s_movk_i32 s4, 0x7ff
	v_cmp_gt_i32_e64 s[50:51], s4, v50
	s_and_saveexec_b64 s[52:53], s[50:51]
	s_cbranch_execz .LBB0_855
	s_mov_b64 s[16:17], 0x2000
	v_lshl_add_u64 v[110:111], v[116:117], 0, s[16:17]
	global_load_dword v194, v[110:111], off offset:4
.LBB0_855:
	s_or_b64 exec, exec, s[52:53]
	v_add_co_u32_e32 v110, vcc, 0x2000, v114
	s_nop 1
	v_addc_co_u32_e32 v111, vcc, 0, v115, vcc
	global_load_dword v195, v[110:111], off
	s_and_saveexec_b64 s[52:53], s[48:49]
	s_cbranch_execz .LBB0_857
	v_mov_b32_e32 v59, v1
	v_lshl_add_u64 v[110:111], v[58:59], 2, s[68:69]
	global_load_dword v196, v[110:111], off offset:-4
.LBB0_857:
	s_or_b64 exec, exec, s[52:53]
	s_and_saveexec_b64 s[52:53], s[50:51]
	s_cbranch_execz .LBB0_859
	s_mov_b64 s[16:17], 0x2000
	v_lshl_add_u64 v[110:111], v[114:115], 0, s[16:17]
	global_load_dword v197, v[110:111], off offset:4
.LBB0_859:
	s_or_b64 exec, exec, s[52:53]
	v_add_co_u32_e32 v110, vcc, 0x2000, v116
	s_movk_i32 s23, 0xf600
	s_nop 0
	v_addc_co_u32_e32 v111, vcc, 0, v117, vcc
	global_load_dword v224, v[110:111], off offset:2048
	v_cmp_lt_i32_e64 s[52:53], s23, v50
	s_and_saveexec_b64 s[56:57], s[52:53]
	s_cbranch_execz .LBB0_861
	v_mov_b32_e32 v61, v1
	v_lshl_add_u64 v[112:113], v[60:61], 2, s[66:67]
	global_load_dword v225, v[112:113], off offset:-4
.LBB0_861:
	s_or_b64 exec, exec, s[56:57]
	v_cmp_gt_i32_e64 s[56:57], s22, v50
	s_and_saveexec_b64 s[60:61], s[56:57]
	s_cbranch_execz .LBB0_863
	s_mov_b64 s[16:17], 0x2800
	v_lshl_add_u64 v[112:113], v[116:117], 0, s[16:17]
	global_load_dword v226, v[112:113], off offset:4
.LBB0_863:
	s_or_b64 exec, exec, s[60:61]
	v_add_co_u32_e32 v112, vcc, 0x2000, v114
	s_nop 1
	v_addc_co_u32_e32 v113, vcc, 0, v115, vcc
	global_load_dword v227, v[112:113], off offset:2048
	s_and_saveexec_b64 s[60:61], s[52:53]
	s_cbranch_execz .LBB0_865
	v_mov_b32_e32 v61, v1
	v_lshl_add_u64 v[112:113], v[60:61], 2, s[68:69]
	global_load_dword v228, v[112:113], off offset:-4
.LBB0_865:
	s_or_b64 exec, exec, s[60:61]
	s_and_saveexec_b64 s[60:61], s[56:57]
	s_cbranch_execz .LBB0_867
	s_mov_b64 s[16:17], 0x2800
	v_lshl_add_u64 v[112:113], v[114:115], 0, s[16:17]
	global_load_dword v229, v[112:113], off offset:4
.LBB0_867:
	s_or_b64 exec, exec, s[60:61]
	v_add_co_u32_e32 v112, vcc, 0x3000, v116
	s_movk_i32 s23, 0xf400
	s_nop 0
	v_addc_co_u32_e32 v113, vcc, 0, v117, vcc
	global_load_dword v230, v[112:113], off
	v_cmp_lt_i32_e64 s[60:61], s23, v50
	s_and_saveexec_b64 s[62:63], s[60:61]
	s_cbranch_execz .LBB0_869
	v_mov_b32_e32 v63, v1
	v_lshl_add_u64 v[122:123], v[62:63], 2, s[66:67]
	global_load_dword v231, v[122:123], off offset:-4
.LBB0_869:
	s_or_b64 exec, exec, s[62:63]
	v_cmp_gt_i32_e64 s[62:63], s71, v50
	s_and_saveexec_b64 s[64:65], s[62:63]
	s_cbranch_execz .LBB0_871
	s_mov_b64 s[16:17], 0x3000
	v_lshl_add_u64 v[122:123], v[116:117], 0, s[16:17]
	global_load_dword v232, v[122:123], off offset:4
.LBB0_871:
	s_or_b64 exec, exec, s[64:65]
	v_add_co_u32_e32 v122, vcc, 0x3000, v114
	s_nop 1
	v_addc_co_u32_e32 v123, vcc, 0, v115, vcc
	global_load_dword v233, v[122:123], off
	s_and_saveexec_b64 s[64:65], s[60:61]
	s_cbranch_execz .LBB0_873
	v_mov_b32_e32 v63, v1
	v_lshl_add_u64 v[122:123], v[62:63], 2, s[68:69]
	global_load_dword v234, v[122:123], off offset:-4
.LBB0_873:
	s_or_b64 exec, exec, s[64:65]
	s_and_saveexec_b64 s[64:65], s[62:63]
	s_cbranch_execz .LBB0_875
	s_mov_b64 s[16:17], 0x3000
	v_lshl_add_u64 v[122:123], v[114:115], 0, s[16:17]
	global_load_dword v235, v[122:123], off offset:4
.LBB0_875:
	s_or_b64 exec, exec, s[64:65]
	v_add_co_u32_e32 v122, vcc, 0x3000, v116
	s_movk_i32 s23, 0xf200
	s_nop 0
	v_addc_co_u32_e32 v123, vcc, 0, v117, vcc
	global_load_dword v236, v[122:123], off offset:2048
	v_cmp_lt_i32_e64 s[64:65], s23, v50
	s_and_saveexec_b64 s[78:79], s[64:65]
	s_cbranch_execz .LBB0_877
	v_mov_b32_e32 v65, v1
	v_lshl_add_u64 v[122:123], v[64:65], 2, s[66:67]
	global_load_dword v237, v[122:123], off offset:-4
.LBB0_877:
	s_or_b64 exec, exec, s[78:79]
	v_cmp_gt_i32_e64 s[66:67], s29, v50
	s_and_saveexec_b64 s[78:79], s[66:67]
	s_cbranch_execz .LBB0_879
	s_mov_b64 s[16:17], 0x3800
	v_lshl_add_u64 v[116:117], v[116:117], 0, s[16:17]
	global_load_dword v238, v[116:117], off offset:4
.LBB0_879:
	s_or_b64 exec, exec, s[78:79]
	v_add_co_u32_e32 v116, vcc, 0x3000, v114
	s_nop 1
	v_addc_co_u32_e32 v117, vcc, 0, v115, vcc
	global_load_dword v239, v[116:117], off offset:2048
	s_and_saveexec_b64 s[78:79], s[64:65]
	s_cbranch_execz .LBB0_881
	v_mov_b32_e32 v65, v1
	v_lshl_add_u64 v[116:117], v[64:65], 2, s[68:69]
	global_load_dword v240, v[116:117], off offset:-4
.LBB0_881:
	s_or_b64 exec, exec, s[78:79]
	s_and_saveexec_b64 s[68:69], s[66:67]
	s_cbranch_execz .LBB0_883
	s_mov_b64 s[16:17], 0x3800
	v_lshl_add_u64 v[114:115], v[114:115], 0, s[16:17]
	global_load_dword v241, v[114:115], off offset:4
.LBB0_883:
	s_or_b64 exec, exec, s[68:69]
	s_waitcnt vmcnt(0)
	v_fma_f32 v100, v120, v168, v99
	s_and_saveexec_b64 s[98:99], s[40:41]
	v_fmac_f32_e32 v100, v119, v169
	s_or_b64 exec, exec, s[98:99]
	s_and_saveexec_b64 s[98:99], s[42:43]
	v_fmac_f32_e32 v100, v118, v170
	s_or_b64 exec, exec, s[98:99]
	v_fma_f32 v101, v120, v171, v99
	s_and_saveexec_b64 s[98:99], s[40:41]
	v_fmac_f32_e32 v101, v119, v172
	s_or_b64 exec, exec, s[98:99]
	s_and_saveexec_b64 s[98:99], s[42:43]
	v_fmac_f32_e32 v101, v118, v173
	s_or_b64 exec, exec, s[98:99]
	v_fma_f32 v102, v120, v174, v99
	s_and_saveexec_b64 s[98:99], s[54:55]
	v_fmac_f32_e32 v102, v119, v175
	s_or_b64 exec, exec, s[98:99]
	s_and_saveexec_b64 s[98:99], s[58:59]
	v_fmac_f32_e32 v102, v118, v176
	s_or_b64 exec, exec, s[98:99]
	v_fma_f32 v103, v120, v177, v99
	s_and_saveexec_b64 s[98:99], s[54:55]
	v_fmac_f32_e32 v103, v119, v178
	s_or_b64 exec, exec, s[98:99]
	s_and_saveexec_b64 s[98:99], s[58:59]
	v_fmac_f32_e32 v103, v118, v179
	s_or_b64 exec, exec, s[98:99]
	v_fma_f32 v104, v120, v180, v99
	s_and_saveexec_b64 s[98:99], s[36:37]
	v_fmac_f32_e32 v104, v119, v181
	s_or_b64 exec, exec, s[98:99]
	s_and_saveexec_b64 s[98:99], s[38:39]
	v_fmac_f32_e32 v104, v118, v182
	s_or_b64 exec, exec, s[98:99]
	v_fma_f32 v105, v120, v183, v99
	s_and_saveexec_b64 s[98:99], s[36:37]
	v_fmac_f32_e32 v105, v119, v184
	s_or_b64 exec, exec, s[98:99]
	s_and_saveexec_b64 s[98:99], s[38:39]
	v_fmac_f32_e32 v105, v118, v185
	s_or_b64 exec, exec, s[98:99]
	v_fma_f32 v106, v120, v186, v99
	s_and_saveexec_b64 s[98:99], s[44:45]
	v_fmac_f32_e32 v106, v119, v187
	s_or_b64 exec, exec, s[98:99]
	s_and_saveexec_b64 s[98:99], s[46:47]
	v_fmac_f32_e32 v106, v118, v188
	s_or_b64 exec, exec, s[98:99]
	v_fma_f32 v107, v120, v189, v99
	s_and_saveexec_b64 s[98:99], s[44:45]
	v_fmac_f32_e32 v107, v119, v190
	s_or_b64 exec, exec, s[98:99]
	s_and_saveexec_b64 s[98:99], s[46:47]
	v_fmac_f32_e32 v107, v118, v191
	s_or_b64 exec, exec, s[98:99]
	v_fma_f32 v108, v120, v192, v99
	s_and_saveexec_b64 s[98:99], s[48:49]
	v_fmac_f32_e32 v108, v119, v193
	s_or_b64 exec, exec, s[98:99]
	s_and_saveexec_b64 s[98:99], s[50:51]
	v_fmac_f32_e32 v108, v118, v194
	s_or_b64 exec, exec, s[98:99]
	v_fma_f32 v109, v120, v195, v99
	s_and_saveexec_b64 s[98:99], s[48:49]
	v_fmac_f32_e32 v109, v119, v196
	s_or_b64 exec, exec, s[98:99]
	s_and_saveexec_b64 s[98:99], s[50:51]
	v_fmac_f32_e32 v109, v118, v197
	s_or_b64 exec, exec, s[98:99]
	v_fma_f32 v110, v120, v224, v99
	s_and_saveexec_b64 s[98:99], s[52:53]
	v_fmac_f32_e32 v110, v119, v225
	s_or_b64 exec, exec, s[98:99]
	s_and_saveexec_b64 s[98:99], s[56:57]
	v_fmac_f32_e32 v110, v118, v226
	s_or_b64 exec, exec, s[98:99]
	v_fma_f32 v111, v120, v227, v99
	s_and_saveexec_b64 s[98:99], s[52:53]
	v_fmac_f32_e32 v111, v119, v228
	s_or_b64 exec, exec, s[98:99]
	s_and_saveexec_b64 s[98:99], s[56:57]
	v_fmac_f32_e32 v111, v118, v229
	s_or_b64 exec, exec, s[98:99]
	v_fma_f32 v112, v120, v230, v99
	s_and_saveexec_b64 s[98:99], s[60:61]
	v_fmac_f32_e32 v112, v119, v231
	s_or_b64 exec, exec, s[98:99]
	s_and_saveexec_b64 s[98:99], s[62:63]
	v_fmac_f32_e32 v112, v118, v232
	s_or_b64 exec, exec, s[98:99]
	v_fma_f32 v113, v120, v233, v99
	s_and_saveexec_b64 s[98:99], s[60:61]
	v_fmac_f32_e32 v113, v119, v234
	s_or_b64 exec, exec, s[98:99]
	s_and_saveexec_b64 s[98:99], s[62:63]
	v_fmac_f32_e32 v113, v118, v235
	s_or_b64 exec, exec, s[98:99]
	v_fma_f32 v98, v120, v236, v99
	s_and_saveexec_b64 s[98:99], s[64:65]
	v_fmac_f32_e32 v98, v119, v237
	s_or_b64 exec, exec, s[98:99]
	s_and_saveexec_b64 s[98:99], s[66:67]
	v_fmac_f32_e32 v98, v118, v238
	s_or_b64 exec, exec, s[98:99]
	v_fmac_f32_e32 v99, v120, v239
	s_and_saveexec_b64 s[98:99], s[64:65]
	v_fmac_f32_e32 v99, v119, v240
	s_or_b64 exec, exec, s[98:99]
	s_and_saveexec_b64 s[98:99], s[66:67]
	v_fmac_f32_e32 v99, v118, v241
	s_or_b64 exec, exec, s[98:99]
	s_mov_b32 s74, s75
	v_mov_b32_e32 v53, v135
	v_add_f32_e32 v0, 0, v46
	v_mov_b64_e32 v[114:115], s[74:75]
	ds_write2st64_b64 v148, v[100:101], v[102:103] offset1:8
	ds_write2st64_b64 v148, v[114:115], v[114:115] offset0:64 offset1:72
	ds_write2st64_b64 v148, v[104:105], v[106:107] offset0:16 offset1:24
	ds_write2st64_b64 v148, v[114:115], v[114:115] offset0:80 offset1:88
	ds_write2st64_b64 v148, v[108:109], v[110:111] offset0:32 offset1:40
	ds_write2st64_b64 v148, v[114:115], v[114:115] offset0:96 offset1:104
	ds_write2st64_b64 v148, v[112:113], v[98:99] offset0:48 offset1:56
	ds_write2st64_b64 v148, v[114:115], v[114:115] offset0:112 offset1:120
	s_waitcnt lgkmcnt(0)
	s_barrier
	v_add_f32_e32 v0, v0, v47
	v_lshlrev_b32_e32 v46, 3, v53
	v_ashrrev_i32_e32 v57, 6, v53
	v_add_u32_e32 v59, 0x50, v46
	v_lshlrev_b32_e32 v55, 3, v57
	ds_read2st64_b64 v[114:117], v59 offset1:8
	ds_read2st64_b64 v[118:121], v59 offset0:64 offset1:72
	v_add3_u32 v46, s85, v46, v55
	ds_read_b64 v[122:123], v46
	v_add_u32_e32 v61, 0x200, v53
	v_ashrrev_i32_e32 v55, 6, v61
	s_waitcnt lgkmcnt(1)
	v_pk_add_f32 v[46:47], v[114:115], v[118:119]
	v_pk_add_f32 v[114:115], v[114:115], v[118:119] neg_lo:[0,1] neg_hi:[0,1]
	ds_write_b64 v59, v[46:47]
	s_waitcnt lgkmcnt(1)
	v_pk_mul_f32 v[46:47], v[114:115], v[122:123] op_sel:[1,1] op_sel_hi:[1,0]
	v_add_u32_e32 v63, 0x400, v53
	v_pk_fma_f32 v[118:119], v[114:115], v[122:123], v[46:47] neg_lo:[0,0,1] neg_hi:[0,0,1]
	v_pk_fma_f32 v[46:47], v[114:115], v[122:123], v[46:47] op_sel_hi:[0,1,1]
	v_mov_b32_e32 v119, v47
	v_lshlrev_b32_e32 v46, 3, v55
	v_lshlrev_b32_e32 v47, 3, v61
	ds_write_b64 v59, v[118:119] offset:32768
	v_add3_u32 v46, s85, v46, v47
	ds_read_b64 v[46:47], v46
	v_pk_add_f32 v[114:115], v[116:117], v[120:121]
	v_pk_add_f32 v[116:117], v[116:117], v[120:121] neg_lo:[0,1] neg_hi:[0,1]
	ds_write_b64 v59, v[114:115] offset:4096
	v_add_f32_e32 v48, v0, v48
	s_waitcnt lgkmcnt(1)
	v_pk_mul_f32 v[114:115], v[116:117], v[46:47] op_sel:[1,1] op_sel_hi:[1,0]
	v_ashrrev_i32_e32 v0, 6, v63
	v_pk_fma_f32 v[118:119], v[116:117], v[46:47], v[114:115] neg_lo:[0,0,1] neg_hi:[0,0,1]
	v_pk_fma_f32 v[46:47], v[116:117], v[46:47], v[114:115] op_sel_hi:[0,1,1]
	v_mov_b32_e32 v119, v47
	ds_write_b64 v59, v[118:119] offset:36864
	v_lshlrev_b32_e32 v46, 3, v0
	v_lshlrev_b32_e32 v47, 3, v63
	ds_read2st64_b64 v[114:117], v59 offset0:16 offset1:24
	ds_read2st64_b64 v[118:121], v59 offset0:80 offset1:88
	v_add3_u32 v46, s85, v46, v47
	ds_read_b64 v[46:47], v46
	v_add_f32_e32 v65, v48, v49
	v_add_u32_e32 v142, 0x600, v53
	s_waitcnt lgkmcnt(1)
	v_pk_add_f32 v[48:49], v[114:115], v[118:119]
	v_pk_add_f32 v[114:115], v[114:115], v[118:119] neg_lo:[0,1] neg_hi:[0,1]
	ds_write_b64 v59, v[48:49] offset:8192
	s_waitcnt lgkmcnt(1)
	v_pk_mul_f32 v[48:49], v[114:115], v[46:47] op_sel:[1,1] op_sel_hi:[1,0]
	v_add_f32_e32 v42, v65, v42
	v_pk_fma_f32 v[118:119], v[114:115], v[46:47], v[48:49] neg_lo:[0,0,1] neg_hi:[0,0,1]
	v_pk_fma_f32 v[46:47], v[114:115], v[46:47], v[48:49] op_sel_hi:[0,1,1]
	v_ashrrev_i32_e32 v46, 6, v142
	v_mov_b32_e32 v119, v47
	v_lshlrev_b32_e32 v47, 3, v46
	v_lshlrev_b32_e32 v48, 3, v142
	ds_write_b64 v59, v[118:119] offset:40960
	v_add3_u32 v47, s85, v47, v48
	ds_read_b64 v[48:49], v47
	v_pk_add_f32 v[114:115], v[116:117], v[120:121]
	v_pk_add_f32 v[116:117], v[116:117], v[120:121] neg_lo:[0,1] neg_hi:[0,1]
	ds_write_b64 v59, v[114:115] offset:12288
	v_add_u32_e32 v47, 0x800, v53
	s_waitcnt lgkmcnt(1)
	v_pk_mul_f32 v[114:115], v[116:117], v[48:49] op_sel:[1,1] op_sel_hi:[1,0]
	v_readlane_b32 s4, v249, 50
	v_pk_fma_f32 v[118:119], v[116:117], v[48:49], v[114:115] neg_lo:[0,0,1] neg_hi:[0,0,1]
	v_pk_fma_f32 v[48:49], v[116:117], v[48:49], v[114:115] op_sel_hi:[0,1,1]
	v_mov_b32_e32 v119, v49
	v_ashrrev_i32_e32 v48, 6, v47
	ds_write_b64 v59, v[118:119] offset:45056
	v_lshlrev_b32_e32 v48, 3, v48
	v_lshlrev_b32_e32 v47, 3, v47
	ds_read2st64_b64 v[114:117], v59 offset0:32 offset1:40
	ds_read2st64_b64 v[118:121], v59 offset0:96 offset1:104
	v_add3_u32 v47, s85, v48, v47
	ds_read_b64 v[48:49], v47
	v_add_f32_e32 v47, v42, v43
	v_add_f32_e32 v44, v47, v44
	s_waitcnt lgkmcnt(1)
	v_pk_add_f32 v[42:43], v[114:115], v[118:119]
	v_pk_add_f32 v[114:115], v[114:115], v[118:119] neg_lo:[0,1] neg_hi:[0,1]
	ds_write_b64 v59, v[42:43] offset:16384
	s_waitcnt lgkmcnt(1)
	v_pk_mul_f32 v[42:43], v[114:115], v[48:49] op_sel:[1,1] op_sel_hi:[1,0]
	v_add_f32_e32 v47, v44, v45
	v_pk_fma_f32 v[118:119], v[114:115], v[48:49], v[42:43] neg_lo:[0,0,1] neg_hi:[0,0,1]
	v_pk_fma_f32 v[42:43], v[114:115], v[48:49], v[42:43] op_sel_hi:[0,1,1]
	v_add_u32_e32 v42, 0xa00, v53
	v_mov_b32_e32 v119, v43
	v_ashrrev_i32_e32 v43, 6, v42
	v_lshlrev_b32_e32 v43, 3, v43
	v_lshlrev_b32_e32 v42, 3, v42
	ds_write_b64 v59, v[118:119] offset:49152
	v_add3_u32 v42, s85, v43, v42
	ds_read_b64 v[42:43], v42
	v_pk_add_f32 v[48:49], v[116:117], v[120:121]
	v_pk_add_f32 v[114:115], v[116:117], v[120:121] neg_lo:[0,1] neg_hi:[0,1]
	ds_write_b64 v59, v[48:49] offset:20480
	s_mul_i32 s23, s24, 0xc000
	s_waitcnt lgkmcnt(1)
	v_pk_mul_f32 v[48:49], v[114:115], v[42:43] op_sel:[1,1] op_sel_hi:[1,0]
	s_mul_hi_i32 s25, s24, 0xc000
	v_pk_fma_f32 v[116:117], v[114:115], v[42:43], v[48:49] neg_lo:[0,0,1] neg_hi:[0,0,1]
	v_pk_fma_f32 v[42:43], v[114:115], v[42:43], v[48:49] op_sel_hi:[0,1,1]
	v_add_u32_e32 v42, 0xc00, v53
	v_mov_b32_e32 v117, v43
	v_ashrrev_i32_e32 v43, 6, v42
	ds_write_b64 v59, v[116:117] offset:53248
	v_lshlrev_b32_e32 v43, 3, v43
	v_lshlrev_b32_e32 v42, 3, v42
	ds_read2st64_b64 v[114:117], v59 offset0:48 offset1:56
	ds_read2st64_b64 v[118:121], v59 offset0:112 offset1:120
	v_add3_u32 v42, s85, v43, v42
	ds_read_b64 v[42:43], v42
	s_waitcnt lgkmcnt(1)
	v_pk_add_f32 v[44:45], v[114:115], v[118:119]
	v_pk_add_f32 v[48:49], v[114:115], v[118:119] neg_lo:[0,1] neg_hi:[0,1]
	ds_write_b64 v59, v[44:45] offset:24576
	s_waitcnt lgkmcnt(1)
	v_pk_mul_f32 v[44:45], v[48:49], v[42:43] op_sel:[1,1] op_sel_hi:[1,0]
	s_nop 0
	v_pk_fma_f32 v[114:115], v[48:49], v[42:43], v[44:45] neg_lo:[0,0,1] neg_hi:[0,0,1]
	v_pk_fma_f32 v[42:43], v[48:49], v[42:43], v[44:45] op_sel_hi:[0,1,1]
	v_add_u32_e32 v42, 0xe00, v53
	v_mov_b32_e32 v115, v43
	v_ashrrev_i32_e32 v43, 6, v42
	v_lshlrev_b32_e32 v43, 3, v43
	v_lshlrev_b32_e32 v42, 3, v42
	ds_write_b64 v59, v[114:115] offset:57344
	v_add3_u32 v42, s85, v43, v42
	ds_read_b64 v[44:45], v42
	v_pk_add_f32 v[48:49], v[116:117], v[120:121]
	v_pk_add_f32 v[114:115], v[116:117], v[120:121] neg_lo:[0,1] neg_hi:[0,1]
	ds_write_b64 v59, v[48:49] offset:28672
	v_mul_f32_e32 v42, 0x46000000, v47
	s_waitcnt lgkmcnt(1)
	v_pk_mul_f32 v[48:49], v[114:115], v[44:45] op_sel:[1,1] op_sel_hi:[1,0]
	v_and_b32_e32 v47, 0x3ff, v53
	v_pk_fma_f32 v[116:117], v[114:115], v[44:45], v[48:49] neg_lo:[0,0,1] neg_hi:[0,0,1]
	v_pk_fma_f32 v[44:45], v[114:115], v[44:45], v[48:49] op_sel_hi:[0,1,1]
	v_lshlrev_b32_e32 v43, 2, v53
	v_mov_b32_e32 v117, v45
	v_and_or_b32 v44, v43, s26, v47
	v_lshrrev_b32_e32 v45, 2, v53
	ds_write_b64 v59, v[116:117] offset:61440
	v_lshl_add_u32 v59, v44, 3, v205
	v_lshlrev_b32_e32 v44, 4, v47
	v_and_b32_e32 v45, 0xf8, v45
	v_add3_u32 v65, s85, v44, v45
	v_lshrrev_b32_e32 v45, 1, v53
	s_waitcnt lgkmcnt(0)
	s_barrier
	v_lshlrev_b32_e32 v44, 5, v47
	ds_read2st64_b64 v[114:117], v59 offset1:16
	ds_read2st64_b64 v[118:121], v59 offset0:32 offset1:48
	v_and_b32_e32 v45, 0x1f8, v45
	v_add3_u32 v140, s85, v44, v45
	ds_read_b64 v[44:45], v140
	s_waitcnt lgkmcnt(1)
	v_pk_add_f32 v[48:49], v[114:115], v[118:119]
	v_pk_add_f32 v[122:123], v[116:117], v[120:121]
	v_mov_b32_e32 v128, v118
	v_pk_add_f32 v[124:125], v[48:49], v[122:123]
	v_pk_add_f32 v[48:49], v[48:49], v[122:123] neg_lo:[0,1] neg_hi:[0,1]
	v_mov_b32_e32 v129, v120
	s_waitcnt lgkmcnt(0)
	v_pk_mul_f32 v[122:123], v[48:49], v[44:45] op_sel:[1,1] op_sel_hi:[1,0]
	v_mov_b32_e32 v130, v120
	v_pk_fma_f32 v[126:127], v[48:49], v[44:45], v[122:123] neg_lo:[0,0,1] neg_hi:[0,0,1]
	v_pk_fma_f32 v[48:49], v[48:49], v[44:45], v[122:123] op_sel_hi:[0,1,1]
	v_mov_b32_e32 v127, v49
	ds_read_b64 v[48:49], v65
	v_mov_b32_e32 v122, v114
	v_mov_b32_e32 v123, v116
	v_pk_add_f32 v[122:123], v[122:123], v[128:129] neg_lo:[0,1] neg_hi:[0,1]
	v_mov_b32_e32 v128, v116
	v_mov_b32_e32 v129, v115
	v_mov_b32_e32 v131, v119
	v_pk_add_f32 v[128:129], v[128:129], v[130:131] neg_lo:[0,1] neg_hi:[0,1]
	v_pk_mov_b32 v[130:131], v[116:117], v[114:115] op_sel:[1,0]
	v_pk_mov_b32 v[132:133], v[120:121], v[118:119] op_sel:[1,0]
	v_mov_b32_e32 v116, v115
	v_mov_b32_e32 v120, v119
	v_pk_add_f32 v[130:131], v[130:131], v[132:133] neg_lo:[0,1] neg_hi:[0,1]
	v_pk_add_f32 v[114:115], v[116:117], v[120:121] neg_lo:[0,1] neg_hi:[0,1]
	s_waitcnt lgkmcnt(0)
	v_pk_mul_f32 v[116:117], v[130:131], v[48:49]
	v_pk_mul_f32 v[114:115], v[114:115], v[48:49] op_sel:[0,1]
	ds_write2st64_b64 v59, v[124:125], v[126:127] offset1:16
	v_pk_fma_f32 v[114:115], v[122:123], v[48:49], v[114:115] op_sel_hi:[1,0,1] neg_lo:[0,0,1] neg_hi:[0,0,1]
	v_pk_fma_f32 v[48:49], v[128:129], v[48:49], v[116:117] op_sel:[0,1,0] op_sel_hi:[1,0,1]
	s_nop 0
	v_pk_add_f32 v[116:117], v[48:49], v[114:115]
	v_pk_add_f32 v[118:119], v[48:49], v[114:115] neg_lo:[0,1] neg_hi:[0,1]
	v_pk_add_f32 v[48:49], v[114:115], v[48:49] neg_lo:[0,1] neg_hi:[0,1]
	v_pk_mul_f32 v[114:115], v[44:45], v[116:117] op_sel:[1,1] op_sel_hi:[0,1]
	v_mov_b32_e32 v118, v116
	v_pk_fma_f32 v[116:117], v[44:45], v[48:49], v[114:115] neg_lo:[0,0,1] neg_hi:[0,0,1]
	v_pk_fma_f32 v[44:45], v[44:45], v[48:49], v[114:115] op_sel_hi:[1,0,1]
	v_lshrrev_b32_e32 v49, 2, v61
	v_mov_b32_e32 v117, v45
	v_and_b32_e32 v44, 0x3ff, v61
	v_lshlrev_b32_e32 v45, 2, v61
	v_and_or_b32 v48, v45, s26, v44
	ds_write2st64_b64 v59, v[118:119], v[116:117] offset0:32 offset1:48
	v_lshl_add_u32 v59, v48, 3, v205
	v_lshlrev_b32_e32 v48, 4, v44
	v_and_b32_e32 v49, 0xf8, v49
	v_add3_u32 v130, s85, v48, v49
	v_lshrrev_b32_e32 v48, 1, v61
	v_lshlrev_b32_e32 v44, 5, v44
	ds_read2st64_b64 v[114:117], v59 offset1:16
	ds_read2st64_b64 v[118:121], v59 offset0:32 offset1:48
	v_and_b32_e32 v48, 0x1f8, v48
	v_add3_u32 v44, s85, v44, v48
	ds_read_b64 v[48:49], v44
	s_waitcnt lgkmcnt(1)
	v_pk_add_f32 v[122:123], v[114:115], v[118:119]
	v_pk_add_f32 v[124:125], v[116:117], v[120:121]
	v_mov_b32_e32 v131, v120
	v_pk_add_f32 v[126:127], v[122:123], v[124:125]
	v_pk_add_f32 v[122:123], v[122:123], v[124:125] neg_lo:[0,1] neg_hi:[0,1]
	v_mov_b32_e32 v132, v120
	s_waitcnt lgkmcnt(0)
	v_pk_mul_f32 v[124:125], v[122:123], v[48:49] op_sel:[1,1] op_sel_hi:[1,0]
	v_mov_b32_e32 v133, v119
	v_pk_fma_f32 v[128:129], v[122:123], v[48:49], v[124:125] neg_lo:[0,0,1] neg_hi:[0,0,1]
	v_pk_fma_f32 v[122:123], v[122:123], v[48:49], v[124:125] op_sel_hi:[0,1,1]
	v_mov_b32_e32 v129, v123
	ds_read_b64 v[122:123], v130
	v_mov_b32_e32 v124, v114
	v_mov_b32_e32 v125, v116
	v_mov_b32_e32 v130, v118
	v_pk_add_f32 v[124:125], v[124:125], v[130:131] neg_lo:[0,1] neg_hi:[0,1]
	v_mov_b32_e32 v130, v116
	v_mov_b32_e32 v131, v115
	v_pk_add_f32 v[130:131], v[130:131], v[132:133] neg_lo:[0,1] neg_hi:[0,1]
	v_pk_mov_b32 v[132:133], v[116:117], v[114:115] op_sel:[1,0]
	v_pk_mov_b32 v[138:139], v[120:121], v[118:119] op_sel:[1,0]
	v_mov_b32_e32 v116, v115
	v_mov_b32_e32 v120, v119
	v_pk_add_f32 v[132:133], v[132:133], v[138:139] neg_lo:[0,1] neg_hi:[0,1]
	v_pk_add_f32 v[114:115], v[116:117], v[120:121] neg_lo:[0,1] neg_hi:[0,1]
	s_waitcnt lgkmcnt(0)
	v_pk_mul_f32 v[116:117], v[132:133], v[122:123]
	v_pk_mul_f32 v[114:115], v[114:115], v[122:123] op_sel:[0,1]
	v_pk_fma_f32 v[116:117], v[130:131], v[122:123], v[116:117] op_sel:[0,1,0] op_sel_hi:[1,0,1]
	v_pk_fma_f32 v[114:115], v[124:125], v[122:123], v[114:115] op_sel_hi:[1,0,1] neg_lo:[0,0,1] neg_hi:[0,0,1]
	ds_write2st64_b64 v59, v[126:127], v[128:129] offset1:16
	v_pk_add_f32 v[118:119], v[116:117], v[114:115]
	v_pk_add_f32 v[120:121], v[116:117], v[114:115] neg_lo:[0,1] neg_hi:[0,1]
	v_pk_add_f32 v[114:115], v[114:115], v[116:117] neg_lo:[0,1] neg_hi:[0,1]
	v_pk_mul_f32 v[116:117], v[48:49], v[118:119] op_sel:[1,1] op_sel_hi:[0,1]
	v_mov_b32_e32 v120, v118
	v_pk_fma_f32 v[118:119], v[48:49], v[114:115], v[116:117] neg_lo:[0,0,1] neg_hi:[0,0,1]
	v_pk_fma_f32 v[48:49], v[48:49], v[114:115], v[116:117] op_sel_hi:[1,0,1]
	s_nop 0
	v_mov_b32_e32 v119, v49
	v_lshlrev_b32_e32 v49, 2, v63
	v_and_or_b32 v44, v49, s26, v47
	ds_write2st64_b64 v59, v[120:121], v[118:119] offset0:32 offset1:48
	v_lshl_add_u32 v47, v44, 3, v205
	ds_read2st64_b64 v[114:117], v47 offset1:16
	ds_read2st64_b64 v[118:121], v47 offset0:32 offset1:48
	ds_read_b64 v[122:123], v140
	v_and_b32_e32 v59, 0x3ff, v142
	v_lshlrev_b32_e32 v63, 4, v59
	v_div_scale_f32 v48, s[30:31], v42, v42, 0.5
	s_waitcnt lgkmcnt(1)
	v_pk_add_f32 v[124:125], v[114:115], v[118:119]
	v_pk_add_f32 v[126:127], v[116:117], v[120:121]
	v_mov_b32_e32 v132, v118
	v_pk_add_f32 v[128:129], v[124:125], v[126:127]
	v_pk_add_f32 v[124:125], v[124:125], v[126:127] neg_lo:[0,1] neg_hi:[0,1]
	v_mov_b32_e32 v133, v120
	s_waitcnt lgkmcnt(0)
	v_pk_mul_f32 v[126:127], v[124:125], v[122:123] op_sel:[1,1] op_sel_hi:[1,0]
	v_mov_b32_e32 v138, v120
	v_pk_fma_f32 v[130:131], v[124:125], v[122:123], v[126:127] neg_lo:[0,0,1] neg_hi:[0,0,1]
	v_pk_fma_f32 v[124:125], v[124:125], v[122:123], v[126:127] op_sel_hi:[0,1,1]
	v_mov_b32_e32 v131, v125
	ds_read_b64 v[124:125], v65
	v_mov_b32_e32 v126, v114
	v_mov_b32_e32 v127, v116
	v_pk_add_f32 v[126:127], v[126:127], v[132:133] neg_lo:[0,1] neg_hi:[0,1]
	v_mov_b32_e32 v132, v116
	v_mov_b32_e32 v133, v115
	v_mov_b32_e32 v139, v119
	v_pk_add_f32 v[132:133], v[132:133], v[138:139] neg_lo:[0,1] neg_hi:[0,1]
	v_pk_mov_b32 v[138:139], v[116:117], v[114:115] op_sel:[1,0]
	v_pk_mov_b32 v[140:141], v[120:121], v[118:119] op_sel:[1,0]
	v_mov_b32_e32 v116, v115
	v_mov_b32_e32 v120, v119
	v_pk_add_f32 v[138:139], v[138:139], v[140:141] neg_lo:[0,1] neg_hi:[0,1]
	v_pk_add_f32 v[114:115], v[116:117], v[120:121] neg_lo:[0,1] neg_hi:[0,1]
	s_waitcnt lgkmcnt(0)
	v_pk_mul_f32 v[116:117], v[138:139], v[124:125]
	v_pk_mul_f32 v[114:115], v[114:115], v[124:125] op_sel:[0,1]
	v_pk_fma_f32 v[116:117], v[132:133], v[124:125], v[116:117] op_sel:[0,1,0] op_sel_hi:[1,0,1]
	v_pk_fma_f32 v[114:115], v[126:127], v[124:125], v[114:115] op_sel_hi:[1,0,1] neg_lo:[0,0,1] neg_hi:[0,0,1]
	ds_write2st64_b64 v47, v[128:129], v[130:131] offset1:16
	v_pk_add_f32 v[118:119], v[116:117], v[114:115]
	v_pk_add_f32 v[120:121], v[116:117], v[114:115] neg_lo:[0,1] neg_hi:[0,1]
	v_pk_add_f32 v[114:115], v[114:115], v[116:117] neg_lo:[0,1] neg_hi:[0,1]
	v_pk_mul_f32 v[116:117], v[122:123], v[118:119] op_sel:[1,1] op_sel_hi:[0,1]
	v_mov_b32_e32 v120, v118
	v_pk_fma_f32 v[118:119], v[122:123], v[114:115], v[116:117] neg_lo:[0,0,1] neg_hi:[0,0,1]
	v_pk_fma_f32 v[114:115], v[122:123], v[114:115], v[116:117] op_sel_hi:[1,0,1]
	v_lshrrev_b32_e32 v65, 2, v142
	v_mov_b32_e32 v119, v115
	ds_write2st64_b64 v47, v[120:121], v[118:119] offset0:32 offset1:48
	v_lshlrev_b32_e32 v47, 2, v142
	v_and_or_b32 v61, v47, s26, v59
	v_and_b32_e32 v65, 0xf8, v65
	v_lshl_add_u32 v61, v61, 3, v205
	v_add3_u32 v63, s85, v63, v65
	v_lshrrev_b32_e32 v65, 1, v142
	v_lshlrev_b32_e32 v59, 5, v59
	ds_read2st64_b64 v[114:117], v61 offset1:16
	ds_read2st64_b64 v[118:121], v61 offset0:32 offset1:48
	v_and_b32_e32 v65, 0x1f8, v65
	v_add3_u32 v59, s85, v59, v65
	ds_read_b64 v[122:123], v59
	v_and_b32_e32 v59, 0xff, v53
	s_waitcnt lgkmcnt(1)
	v_pk_add_f32 v[124:125], v[114:115], v[118:119]
	v_pk_add_f32 v[126:127], v[116:117], v[120:121]
	v_mov_b32_e32 v132, v118
	v_pk_add_f32 v[128:129], v[124:125], v[126:127]
	v_pk_add_f32 v[124:125], v[124:125], v[126:127] neg_lo:[0,1] neg_hi:[0,1]
	v_mov_b32_e32 v133, v120
	s_waitcnt lgkmcnt(0)
	v_pk_mul_f32 v[126:127], v[124:125], v[122:123] op_sel:[1,1] op_sel_hi:[1,0]
	v_mov_b32_e32 v138, v120
	v_pk_fma_f32 v[130:131], v[124:125], v[122:123], v[126:127] neg_lo:[0,0,1] neg_hi:[0,0,1]
	v_pk_fma_f32 v[124:125], v[124:125], v[122:123], v[126:127] op_sel_hi:[0,1,1]
	v_mov_b32_e32 v131, v125
	ds_read_b64 v[124:125], v63
	v_mov_b32_e32 v126, v114
	v_mov_b32_e32 v127, v116
	v_pk_add_f32 v[126:127], v[126:127], v[132:133] neg_lo:[0,1] neg_hi:[0,1]
	v_mov_b32_e32 v132, v116
	v_mov_b32_e32 v133, v115
	v_mov_b32_e32 v139, v119
	v_pk_add_f32 v[132:133], v[132:133], v[138:139] neg_lo:[0,1] neg_hi:[0,1]
	v_pk_mov_b32 v[138:139], v[116:117], v[114:115] op_sel:[1,0]
	v_pk_mov_b32 v[140:141], v[120:121], v[118:119] op_sel:[1,0]
	v_mov_b32_e32 v116, v115
	v_mov_b32_e32 v120, v119
	v_pk_add_f32 v[138:139], v[138:139], v[140:141] neg_lo:[0,1] neg_hi:[0,1]
	v_pk_add_f32 v[114:115], v[116:117], v[120:121] neg_lo:[0,1] neg_hi:[0,1]
	s_waitcnt lgkmcnt(0)
	v_pk_mul_f32 v[116:117], v[138:139], v[124:125]
	v_pk_mul_f32 v[114:115], v[114:115], v[124:125] op_sel:[0,1]
	v_pk_fma_f32 v[116:117], v[132:133], v[124:125], v[116:117] op_sel:[0,1,0] op_sel_hi:[1,0,1]
	v_pk_fma_f32 v[114:115], v[126:127], v[124:125], v[114:115] op_sel_hi:[1,0,1] neg_lo:[0,0,1] neg_hi:[0,0,1]
	ds_write2st64_b64 v61, v[128:129], v[130:131] offset1:16
	v_pk_add_f32 v[118:119], v[116:117], v[114:115]
	v_pk_add_f32 v[120:121], v[116:117], v[114:115] neg_lo:[0,1] neg_hi:[0,1]
	v_pk_add_f32 v[114:115], v[114:115], v[116:117] neg_lo:[0,1] neg_hi:[0,1]
	v_pk_mul_f32 v[116:117], v[122:123], v[118:119] op_sel:[1,1] op_sel_hi:[0,1]
	v_mov_b32_e32 v120, v118
	v_pk_fma_f32 v[118:119], v[122:123], v[114:115], v[116:117] neg_lo:[0,0,1] neg_hi:[0,0,1]
	v_pk_fma_f32 v[114:115], v[122:123], v[114:115], v[116:117] op_sel_hi:[1,0,1]
	v_lshlrev_b32_e32 v63, 6, v59
	v_mov_b32_e32 v119, v115
	ds_write2st64_b64 v61, v[120:121], v[118:119] offset0:32 offset1:48
	v_and_or_b32 v61, v43, s34, v59
	v_lshl_add_u32 v61, v61, 3, v205
	v_and_b32_e32 v65, 0xf8, v53
	v_lshlrev_b32_e32 v122, 1, v53
	s_waitcnt lgkmcnt(0)
	s_barrier
	v_add3_u32 v63, s85, v63, v65
	v_lshlrev_b32_e32 v65, 7, v59
	ds_read2st64_b64 v[114:117], v61 offset1:4
	ds_read2st64_b64 v[118:121], v61 offset0:8 offset1:12
	v_and_b32_e32 v122, 0x1f8, v122
	v_add3_u32 v65, s85, v65, v122
	ds_read_b64 v[122:123], v65
	v_rcp_f32_e32 v44, v48
	s_waitcnt lgkmcnt(1)
	v_pk_add_f32 v[124:125], v[114:115], v[118:119]
	v_pk_add_f32 v[126:127], v[116:117], v[120:121]
	v_mov_b32_e32 v132, v118
	v_pk_add_f32 v[128:129], v[124:125], v[126:127]
	v_pk_add_f32 v[124:125], v[124:125], v[126:127] neg_lo:[0,1] neg_hi:[0,1]
	v_mov_b32_e32 v133, v120
	s_waitcnt lgkmcnt(0)
	v_pk_mul_f32 v[126:127], v[124:125], v[122:123] op_sel:[1,1] op_sel_hi:[1,0]
	v_mov_b32_e32 v138, v120
	v_pk_fma_f32 v[130:131], v[124:125], v[122:123], v[126:127] neg_lo:[0,0,1] neg_hi:[0,0,1]
	v_pk_fma_f32 v[124:125], v[124:125], v[122:123], v[126:127] op_sel_hi:[0,1,1]
	v_mov_b32_e32 v131, v125
	ds_read_b64 v[124:125], v63
	v_mov_b32_e32 v126, v114
	v_mov_b32_e32 v127, v116
	v_pk_add_f32 v[126:127], v[126:127], v[132:133] neg_lo:[0,1] neg_hi:[0,1]
	v_mov_b32_e32 v132, v116
	v_mov_b32_e32 v133, v115
	v_mov_b32_e32 v139, v119
	v_pk_add_f32 v[132:133], v[132:133], v[138:139] neg_lo:[0,1] neg_hi:[0,1]
	v_pk_mov_b32 v[138:139], v[116:117], v[114:115] op_sel:[1,0]
	v_pk_mov_b32 v[140:141], v[120:121], v[118:119] op_sel:[1,0]
	v_mov_b32_e32 v116, v115
	v_mov_b32_e32 v120, v119
	v_pk_add_f32 v[138:139], v[138:139], v[140:141] neg_lo:[0,1] neg_hi:[0,1]
	v_pk_add_f32 v[114:115], v[116:117], v[120:121] neg_lo:[0,1] neg_hi:[0,1]
	s_waitcnt lgkmcnt(0)
	v_pk_mul_f32 v[116:117], v[138:139], v[124:125]
	v_pk_mul_f32 v[114:115], v[114:115], v[124:125] op_sel:[0,1]
	v_pk_fma_f32 v[116:117], v[132:133], v[124:125], v[116:117] op_sel:[0,1,0] op_sel_hi:[1,0,1]
	v_pk_fma_f32 v[114:115], v[126:127], v[124:125], v[114:115] op_sel_hi:[1,0,1] neg_lo:[0,0,1] neg_hi:[0,0,1]
	ds_write2st64_b64 v61, v[128:129], v[130:131] offset1:4
	v_pk_add_f32 v[118:119], v[116:117], v[114:115]
	v_pk_add_f32 v[120:121], v[116:117], v[114:115] neg_lo:[0,1] neg_hi:[0,1]
	v_pk_add_f32 v[114:115], v[114:115], v[116:117] neg_lo:[0,1] neg_hi:[0,1]
	v_pk_mul_f32 v[116:117], v[122:123], v[118:119] op_sel:[1,1] op_sel_hi:[0,1]
	v_mov_b32_e32 v120, v118
	v_pk_fma_f32 v[118:119], v[122:123], v[114:115], v[116:117] neg_lo:[0,0,1] neg_hi:[0,0,1]
	v_pk_fma_f32 v[114:115], v[122:123], v[114:115], v[116:117] op_sel_hi:[1,0,1]
	v_fma_f32 v122, -v48, v44, 1.0
	v_mov_b32_e32 v119, v115
	ds_write2st64_b64 v61, v[120:121], v[118:119] offset0:8 offset1:12
	v_and_or_b32 v61, v45, s34, v59
	v_lshl_add_u32 v61, v61, 3, v205
	ds_read2st64_b64 v[114:117], v61 offset1:4
	ds_read2st64_b64 v[118:121], v61 offset0:8 offset1:12
	v_fmac_f32_e32 v44, v122, v44
	ds_read_b64 v[122:123], v65
	v_div_scale_f32 v142, vcc, 0.5, v42, 0.5
	s_waitcnt lgkmcnt(1)
	v_pk_add_f32 v[124:125], v[114:115], v[118:119]
	v_pk_add_f32 v[126:127], v[116:117], v[120:121]
	v_mov_b32_e32 v132, v118
	v_pk_add_f32 v[128:129], v[124:125], v[126:127]
	v_pk_add_f32 v[124:125], v[124:125], v[126:127] neg_lo:[0,1] neg_hi:[0,1]
	v_mov_b32_e32 v133, v120
	s_waitcnt lgkmcnt(0)
	v_pk_mul_f32 v[126:127], v[124:125], v[122:123] op_sel:[1,1] op_sel_hi:[1,0]
	v_mov_b32_e32 v138, v120
	v_pk_fma_f32 v[130:131], v[124:125], v[122:123], v[126:127] neg_lo:[0,0,1] neg_hi:[0,0,1]
	v_pk_fma_f32 v[124:125], v[124:125], v[122:123], v[126:127] op_sel_hi:[0,1,1]
	v_mov_b32_e32 v131, v125
	ds_read_b64 v[124:125], v63
	v_mov_b32_e32 v126, v114
	v_mov_b32_e32 v127, v116
	v_pk_add_f32 v[126:127], v[126:127], v[132:133] neg_lo:[0,1] neg_hi:[0,1]
	v_mov_b32_e32 v132, v116
	v_mov_b32_e32 v133, v115
	v_mov_b32_e32 v139, v119
	v_pk_add_f32 v[132:133], v[132:133], v[138:139] neg_lo:[0,1] neg_hi:[0,1]
	v_pk_mov_b32 v[138:139], v[116:117], v[114:115] op_sel:[1,0]
	v_pk_mov_b32 v[140:141], v[120:121], v[118:119] op_sel:[1,0]
	v_mov_b32_e32 v116, v115
	v_mov_b32_e32 v120, v119
	v_pk_add_f32 v[138:139], v[138:139], v[140:141] neg_lo:[0,1] neg_hi:[0,1]
	v_pk_add_f32 v[114:115], v[116:117], v[120:121] neg_lo:[0,1] neg_hi:[0,1]
	s_waitcnt lgkmcnt(0)
	v_pk_mul_f32 v[116:117], v[138:139], v[124:125]
	v_pk_mul_f32 v[114:115], v[114:115], v[124:125] op_sel:[0,1]
	v_pk_fma_f32 v[116:117], v[132:133], v[124:125], v[116:117] op_sel:[0,1,0] op_sel_hi:[1,0,1]
	v_pk_fma_f32 v[114:115], v[126:127], v[124:125], v[114:115] op_sel_hi:[1,0,1] neg_lo:[0,0,1] neg_hi:[0,0,1]
	ds_write2st64_b64 v61, v[128:129], v[130:131] offset1:4
	v_pk_add_f32 v[118:119], v[116:117], v[114:115]
	v_pk_add_f32 v[120:121], v[116:117], v[114:115] neg_lo:[0,1] neg_hi:[0,1]
	v_pk_add_f32 v[114:115], v[114:115], v[116:117] neg_lo:[0,1] neg_hi:[0,1]
	v_pk_mul_f32 v[116:117], v[122:123], v[118:119] op_sel:[1,1] op_sel_hi:[0,1]
	v_mov_b32_e32 v120, v118
	v_pk_fma_f32 v[118:119], v[122:123], v[114:115], v[116:117] neg_lo:[0,0,1] neg_hi:[0,0,1]
	v_pk_fma_f32 v[114:115], v[122:123], v[114:115], v[116:117] op_sel_hi:[1,0,1]
	v_mul_f32_e32 v143, v142, v44
	v_mov_b32_e32 v119, v115
	ds_write2st64_b64 v61, v[120:121], v[118:119] offset0:8 offset1:12
	v_and_or_b32 v61, v49, s34, v59
	v_lshl_add_u32 v61, v61, 3, v205
	ds_read2st64_b64 v[114:117], v61 offset1:4
	ds_read2st64_b64 v[118:121], v61 offset0:8 offset1:12
	ds_read_b64 v[122:123], v65
	v_and_or_b32 v59, v47, s34, v59
	v_lshl_add_u32 v59, v59, 3, v205
	s_add_i32 s30, s86, s4
	s_waitcnt lgkmcnt(1)
	v_pk_add_f32 v[124:125], v[114:115], v[118:119]
	v_pk_add_f32 v[126:127], v[116:117], v[120:121]
	v_mov_b32_e32 v132, v118
	v_pk_add_f32 v[128:129], v[124:125], v[126:127]
	v_pk_add_f32 v[124:125], v[124:125], v[126:127] neg_lo:[0,1] neg_hi:[0,1]
	v_mov_b32_e32 v133, v120
	s_waitcnt lgkmcnt(0)
	v_pk_mul_f32 v[126:127], v[124:125], v[122:123] op_sel:[1,1] op_sel_hi:[1,0]
	v_mov_b32_e32 v138, v120
	v_pk_fma_f32 v[130:131], v[124:125], v[122:123], v[126:127] neg_lo:[0,0,1] neg_hi:[0,0,1]
	v_pk_fma_f32 v[124:125], v[124:125], v[122:123], v[126:127] op_sel_hi:[0,1,1]
	v_mov_b32_e32 v131, v125
	ds_read_b64 v[124:125], v63
	v_mov_b32_e32 v126, v114
	v_mov_b32_e32 v127, v116
	v_pk_add_f32 v[126:127], v[126:127], v[132:133] neg_lo:[0,1] neg_hi:[0,1]
	v_mov_b32_e32 v132, v116
	v_mov_b32_e32 v133, v115
	v_mov_b32_e32 v139, v119
	v_pk_add_f32 v[132:133], v[132:133], v[138:139] neg_lo:[0,1] neg_hi:[0,1]
	v_pk_mov_b32 v[138:139], v[116:117], v[114:115] op_sel:[1,0]
	v_pk_mov_b32 v[140:141], v[120:121], v[118:119] op_sel:[1,0]
	v_mov_b32_e32 v116, v115
	v_mov_b32_e32 v120, v119
	v_pk_add_f32 v[138:139], v[138:139], v[140:141] neg_lo:[0,1] neg_hi:[0,1]
	v_pk_add_f32 v[114:115], v[116:117], v[120:121] neg_lo:[0,1] neg_hi:[0,1]
	s_waitcnt lgkmcnt(0)
	v_pk_mul_f32 v[116:117], v[138:139], v[124:125]
	v_pk_mul_f32 v[114:115], v[114:115], v[124:125] op_sel:[0,1]
	v_pk_fma_f32 v[116:117], v[132:133], v[124:125], v[116:117] op_sel:[0,1,0] op_sel_hi:[1,0,1]
	v_pk_fma_f32 v[114:115], v[126:127], v[124:125], v[114:115] op_sel_hi:[1,0,1] neg_lo:[0,0,1] neg_hi:[0,0,1]
	ds_write2st64_b64 v61, v[128:129], v[130:131] offset1:4
	v_pk_add_f32 v[118:119], v[116:117], v[114:115]
	v_pk_add_f32 v[120:121], v[116:117], v[114:115] neg_lo:[0,1] neg_hi:[0,1]
	v_pk_add_f32 v[114:115], v[114:115], v[116:117] neg_lo:[0,1] neg_hi:[0,1]
	v_pk_mul_f32 v[116:117], v[122:123], v[118:119] op_sel:[1,1] op_sel_hi:[0,1]
	v_mov_b32_e32 v120, v118
	v_pk_fma_f32 v[118:119], v[122:123], v[114:115], v[116:117] neg_lo:[0,0,1] neg_hi:[0,0,1]
	v_pk_fma_f32 v[114:115], v[122:123], v[114:115], v[116:117] op_sel_hi:[1,0,1]
	s_nop 0
	v_mov_b32_e32 v119, v115
	ds_write2st64_b64 v61, v[120:121], v[118:119] offset0:8 offset1:12
	ds_read2st64_b64 v[114:117], v59 offset1:4
	ds_read2st64_b64 v[118:121], v59 offset0:8 offset1:12
	ds_read_b64 v[122:123], v65
	v_fma_f32 v61, -v48, v143, v142
	v_fmac_f32_e32 v143, v61, v44
	v_and_b32_e32 v65, 0xf8, v43
	s_waitcnt lgkmcnt(1)
	v_pk_add_f32 v[124:125], v[114:115], v[118:119]
	v_pk_add_f32 v[126:127], v[116:117], v[120:121]
	v_mov_b32_e32 v132, v118
	v_pk_add_f32 v[128:129], v[124:125], v[126:127]
	v_pk_add_f32 v[124:125], v[124:125], v[126:127] neg_lo:[0,1] neg_hi:[0,1]
	v_mov_b32_e32 v133, v120
	s_waitcnt lgkmcnt(0)
	v_pk_mul_f32 v[126:127], v[124:125], v[122:123] op_sel:[1,1] op_sel_hi:[1,0]
	v_mov_b32_e32 v138, v120
	v_pk_fma_f32 v[130:131], v[124:125], v[122:123], v[126:127] neg_lo:[0,0,1] neg_hi:[0,0,1]
	v_pk_fma_f32 v[124:125], v[124:125], v[122:123], v[126:127] op_sel_hi:[0,1,1]
	v_mov_b32_e32 v131, v125
	ds_read_b64 v[124:125], v63
	v_mov_b32_e32 v126, v114
	v_mov_b32_e32 v127, v116
	v_pk_add_f32 v[126:127], v[126:127], v[132:133] neg_lo:[0,1] neg_hi:[0,1]
	v_mov_b32_e32 v132, v116
	v_mov_b32_e32 v133, v115
	v_mov_b32_e32 v139, v119
	v_pk_add_f32 v[132:133], v[132:133], v[138:139] neg_lo:[0,1] neg_hi:[0,1]
	v_pk_mov_b32 v[138:139], v[116:117], v[114:115] op_sel:[1,0]
	v_pk_mov_b32 v[140:141], v[120:121], v[118:119] op_sel:[1,0]
	v_mov_b32_e32 v116, v115
	v_mov_b32_e32 v120, v119
	v_pk_add_f32 v[138:139], v[138:139], v[140:141] neg_lo:[0,1] neg_hi:[0,1]
	v_pk_add_f32 v[114:115], v[116:117], v[120:121] neg_lo:[0,1] neg_hi:[0,1]
	s_waitcnt lgkmcnt(0)
	v_pk_mul_f32 v[116:117], v[138:139], v[124:125]
	v_pk_mul_f32 v[114:115], v[114:115], v[124:125] op_sel:[0,1]
	v_pk_fma_f32 v[116:117], v[132:133], v[124:125], v[116:117] op_sel:[0,1,0] op_sel_hi:[1,0,1]
	v_pk_fma_f32 v[114:115], v[126:127], v[124:125], v[114:115] op_sel_hi:[1,0,1] neg_lo:[0,0,1] neg_hi:[0,0,1]
	ds_write2st64_b64 v59, v[128:129], v[130:131] offset1:4
	v_pk_add_f32 v[118:119], v[116:117], v[114:115]
	v_pk_add_f32 v[120:121], v[116:117], v[114:115] neg_lo:[0,1] neg_hi:[0,1]
	v_pk_add_f32 v[114:115], v[114:115], v[116:117] neg_lo:[0,1] neg_hi:[0,1]
	v_pk_mul_f32 v[116:117], v[122:123], v[118:119] op_sel:[1,1] op_sel_hi:[0,1]
	v_mov_b32_e32 v120, v118
	v_pk_fma_f32 v[118:119], v[122:123], v[114:115], v[116:117] neg_lo:[0,0,1] neg_hi:[0,0,1]
	v_pk_fma_f32 v[114:115], v[122:123], v[114:115], v[116:117] op_sel_hi:[1,0,1]
	v_fma_f32 v48, -v48, v143, v142
	v_mov_b32_e32 v119, v115
	ds_write2st64_b64 v59, v[120:121], v[118:119] offset0:8 offset1:12
	v_and_b32_e32 v59, 63, v53
	v_lshlrev_b32_e32 v61, 3, v59
	v_lshl_or_b32 v57, v57, 11, v61
	v_add_u32_e32 v57, 0x50, v57
	s_waitcnt lgkmcnt(0)
	s_barrier
	v_lshlrev_b32_e32 v63, 8, v59
	ds_read2st64_b64 v[114:117], v57 offset1:1
	ds_read2st64_b64 v[118:121], v57 offset0:2 offset1:3
	v_lshlrev_b32_e32 v59, 9, v59
	v_add3_u32 v59, s85, v59, v61
	ds_read_b64 v[122:123], v59
	v_add3_u32 v63, s85, v63, v65
	s_waitcnt lgkmcnt(1)
	v_pk_add_f32 v[124:125], v[114:115], v[118:119]
	v_pk_add_f32 v[126:127], v[116:117], v[120:121]
	v_mov_b32_e32 v132, v118
	v_pk_add_f32 v[128:129], v[124:125], v[126:127]
	v_pk_add_f32 v[124:125], v[124:125], v[126:127] neg_lo:[0,1] neg_hi:[0,1]
	v_mov_b32_e32 v133, v120
	s_waitcnt lgkmcnt(0)
	v_pk_mul_f32 v[126:127], v[124:125], v[122:123] op_sel:[1,1] op_sel_hi:[1,0]
	v_mov_b32_e32 v138, v120
	v_pk_fma_f32 v[130:131], v[124:125], v[122:123], v[126:127] neg_lo:[0,0,1] neg_hi:[0,0,1]
	v_pk_fma_f32 v[124:125], v[124:125], v[122:123], v[126:127] op_sel_hi:[0,1,1]
	v_mov_b32_e32 v131, v125
	ds_read_b64 v[124:125], v63
	v_mov_b32_e32 v126, v114
	v_mov_b32_e32 v127, v116
	v_pk_add_f32 v[126:127], v[126:127], v[132:133] neg_lo:[0,1] neg_hi:[0,1]
	v_mov_b32_e32 v132, v116
	v_mov_b32_e32 v133, v115
	v_mov_b32_e32 v139, v119
	v_pk_add_f32 v[132:133], v[132:133], v[138:139] neg_lo:[0,1] neg_hi:[0,1]
	v_pk_mov_b32 v[138:139], v[116:117], v[114:115] op_sel:[1,0]
	v_pk_mov_b32 v[140:141], v[120:121], v[118:119] op_sel:[1,0]
	v_mov_b32_e32 v116, v115
	v_mov_b32_e32 v120, v119
	v_pk_add_f32 v[138:139], v[138:139], v[140:141] neg_lo:[0,1] neg_hi:[0,1]
	v_pk_add_f32 v[114:115], v[116:117], v[120:121] neg_lo:[0,1] neg_hi:[0,1]
	s_waitcnt lgkmcnt(0)
	v_pk_mul_f32 v[116:117], v[138:139], v[124:125]
	v_pk_mul_f32 v[114:115], v[114:115], v[124:125] op_sel:[0,1]
	v_pk_fma_f32 v[116:117], v[132:133], v[124:125], v[116:117] op_sel:[0,1,0] op_sel_hi:[1,0,1]
	v_pk_fma_f32 v[114:115], v[126:127], v[124:125], v[114:115] op_sel_hi:[1,0,1] neg_lo:[0,0,1] neg_hi:[0,0,1]
	v_lshl_or_b32 v55, v55, 11, v61
	v_pk_add_f32 v[118:119], v[116:117], v[114:115]
	v_pk_add_f32 v[120:121], v[116:117], v[114:115] neg_lo:[0,1] neg_hi:[0,1]
	v_pk_add_f32 v[114:115], v[114:115], v[116:117] neg_lo:[0,1] neg_hi:[0,1]
	v_pk_mul_f32 v[116:117], v[122:123], v[118:119] op_sel:[1,1] op_sel_hi:[0,1]
	v_mov_b32_e32 v120, v118
	v_pk_fma_f32 v[118:119], v[122:123], v[114:115], v[116:117] neg_lo:[0,0,1] neg_hi:[0,0,1]
	v_pk_fma_f32 v[114:115], v[122:123], v[114:115], v[116:117] op_sel_hi:[1,0,1]
	ds_write2st64_b64 v57, v[128:129], v[130:131] offset1:1
	v_mov_b32_e32 v119, v115
	ds_write2st64_b64 v57, v[120:121], v[118:119] offset0:2 offset1:3
	v_add_u32_e32 v57, 0x50, v55
	ds_read2st64_b64 v[114:117], v57 offset1:1
	ds_read2st64_b64 v[118:121], v57 offset0:2 offset1:3
	ds_read_b64 v[122:123], v59
	v_div_fmas_f32 v44, v48, v44, v143
	v_lshl_or_b32 v0, v0, 11, v61
	v_div_fixup_f32 v55, v44, v42, 0.5
	s_waitcnt lgkmcnt(1)
	v_pk_add_f32 v[124:125], v[114:115], v[118:119]
	v_pk_add_f32 v[126:127], v[116:117], v[120:121]
	v_mov_b32_e32 v132, v118
	v_pk_add_f32 v[128:129], v[124:125], v[126:127]
	v_pk_add_f32 v[124:125], v[124:125], v[126:127] neg_lo:[0,1] neg_hi:[0,1]
	v_mov_b32_e32 v133, v120
	s_waitcnt lgkmcnt(0)
	v_pk_mul_f32 v[126:127], v[124:125], v[122:123] op_sel:[1,1] op_sel_hi:[1,0]
	v_mov_b32_e32 v138, v120
	v_pk_fma_f32 v[130:131], v[124:125], v[122:123], v[126:127] neg_lo:[0,0,1] neg_hi:[0,0,1]
	v_pk_fma_f32 v[124:125], v[124:125], v[122:123], v[126:127] op_sel_hi:[0,1,1]
	v_mov_b32_e32 v131, v125
	ds_read_b64 v[124:125], v63
	v_mov_b32_e32 v126, v114
	v_mov_b32_e32 v127, v116
	v_pk_add_f32 v[126:127], v[126:127], v[132:133] neg_lo:[0,1] neg_hi:[0,1]
	v_mov_b32_e32 v132, v116
	v_mov_b32_e32 v133, v115
	v_mov_b32_e32 v139, v119
	v_pk_add_f32 v[132:133], v[132:133], v[138:139] neg_lo:[0,1] neg_hi:[0,1]
	v_pk_mov_b32 v[138:139], v[116:117], v[114:115] op_sel:[1,0]
	v_pk_mov_b32 v[140:141], v[120:121], v[118:119] op_sel:[1,0]
	v_mov_b32_e32 v116, v115
	v_mov_b32_e32 v120, v119
	v_pk_add_f32 v[138:139], v[138:139], v[140:141] neg_lo:[0,1] neg_hi:[0,1]
	v_pk_add_f32 v[114:115], v[116:117], v[120:121] neg_lo:[0,1] neg_hi:[0,1]
	s_waitcnt lgkmcnt(0)
	v_pk_mul_f32 v[116:117], v[138:139], v[124:125]
	v_pk_mul_f32 v[114:115], v[114:115], v[124:125] op_sel:[0,1]
	v_pk_fma_f32 v[116:117], v[132:133], v[124:125], v[116:117] op_sel:[0,1,0] op_sel_hi:[1,0,1]
	v_pk_fma_f32 v[114:115], v[126:127], v[124:125], v[114:115] op_sel_hi:[1,0,1] neg_lo:[0,0,1] neg_hi:[0,0,1]
	ds_write2st64_b64 v57, v[128:129], v[130:131] offset1:1
	v_pk_add_f32 v[118:119], v[116:117], v[114:115]
	v_pk_add_f32 v[120:121], v[116:117], v[114:115] neg_lo:[0,1] neg_hi:[0,1]
	v_pk_add_f32 v[114:115], v[114:115], v[116:117] neg_lo:[0,1] neg_hi:[0,1]
	v_pk_mul_f32 v[116:117], v[122:123], v[118:119] op_sel:[1,1] op_sel_hi:[0,1]
	v_mov_b32_e32 v120, v118
	v_pk_fma_f32 v[118:119], v[122:123], v[114:115], v[116:117] neg_lo:[0,0,1] neg_hi:[0,0,1]
	v_pk_fma_f32 v[114:115], v[122:123], v[114:115], v[116:117] op_sel_hi:[1,0,1]
	v_add_u32_e32 v42, 0x50, v0
	v_mov_b32_e32 v119, v115
	ds_write2st64_b64 v57, v[120:121], v[118:119] offset0:2 offset1:3
	ds_read2st64_b64 v[114:117], v42 offset1:1
	ds_read2st64_b64 v[118:121], v42 offset0:2 offset1:3
	ds_read_b64 v[122:123], v59
	v_and_b32_e32 v57, 15, v53
	v_lshlrev_b32_e32 v48, 10, v57
	v_sub_f32_e32 v44, v39, v97
	s_waitcnt lgkmcnt(1)
	v_pk_add_f32 v[124:125], v[114:115], v[118:119]
	v_pk_add_f32 v[126:127], v[116:117], v[120:121]
	v_mov_b32_e32 v132, v118
	v_pk_add_f32 v[128:129], v[124:125], v[126:127]
	v_pk_add_f32 v[124:125], v[124:125], v[126:127] neg_lo:[0,1] neg_hi:[0,1]
	v_mov_b32_e32 v133, v120
	s_waitcnt lgkmcnt(0)
	v_pk_mul_f32 v[126:127], v[124:125], v[122:123] op_sel:[1,1] op_sel_hi:[1,0]
	v_mov_b32_e32 v138, v120
	v_pk_fma_f32 v[130:131], v[124:125], v[122:123], v[126:127] neg_lo:[0,0,1] neg_hi:[0,0,1]
	v_pk_fma_f32 v[124:125], v[124:125], v[122:123], v[126:127] op_sel_hi:[0,1,1]
	v_mov_b32_e32 v131, v125
	ds_read_b64 v[124:125], v63
	v_mov_b32_e32 v126, v114
	v_mov_b32_e32 v127, v116
	v_pk_add_f32 v[126:127], v[126:127], v[132:133] neg_lo:[0,1] neg_hi:[0,1]
	v_mov_b32_e32 v132, v116
	v_mov_b32_e32 v133, v115
	v_mov_b32_e32 v139, v119
	v_pk_add_f32 v[132:133], v[132:133], v[138:139] neg_lo:[0,1] neg_hi:[0,1]
	v_pk_mov_b32 v[138:139], v[116:117], v[114:115] op_sel:[1,0]
	v_pk_mov_b32 v[140:141], v[120:121], v[118:119] op_sel:[1,0]
	v_mov_b32_e32 v116, v115
	v_mov_b32_e32 v120, v119
	v_pk_add_f32 v[138:139], v[138:139], v[140:141] neg_lo:[0,1] neg_hi:[0,1]
	v_pk_add_f32 v[114:115], v[116:117], v[120:121] neg_lo:[0,1] neg_hi:[0,1]
	s_waitcnt lgkmcnt(0)
	v_pk_mul_f32 v[116:117], v[138:139], v[124:125]
	v_pk_mul_f32 v[114:115], v[114:115], v[124:125] op_sel:[0,1]
	v_pk_fma_f32 v[116:117], v[132:133], v[124:125], v[116:117] op_sel:[0,1,0] op_sel_hi:[1,0,1]
	v_pk_fma_f32 v[114:115], v[126:127], v[124:125], v[114:115] op_sel_hi:[1,0,1] neg_lo:[0,0,1] neg_hi:[0,0,1]
	ds_write2st64_b64 v42, v[128:129], v[130:131] offset1:1
	v_pk_add_f32 v[118:119], v[116:117], v[114:115]
	v_pk_add_f32 v[120:121], v[116:117], v[114:115] neg_lo:[0,1] neg_hi:[0,1]
	v_pk_add_f32 v[114:115], v[114:115], v[116:117] neg_lo:[0,1] neg_hi:[0,1]
	v_pk_mul_f32 v[116:117], v[122:123], v[118:119] op_sel:[1,1] op_sel_hi:[0,1]
	v_mov_b32_e32 v120, v118
	v_pk_fma_f32 v[118:119], v[122:123], v[114:115], v[116:117] neg_lo:[0,0,1] neg_hi:[0,0,1]
	v_pk_fma_f32 v[114:115], v[122:123], v[114:115], v[116:117] op_sel_hi:[1,0,1]
	v_add_f32_e32 v0, v38, v96
	v_mov_b32_e32 v119, v115
	ds_write2st64_b64 v42, v[120:121], v[118:119] offset0:2 offset1:3
	v_lshl_or_b32 v42, v46, 11, v61
	v_add_u32_e32 v46, 0x50, v42
	ds_read2st64_b64 v[114:117], v46 offset1:1
	ds_read2st64_b64 v[118:121], v46 offset0:2 offset1:3
	ds_read_b64 v[122:123], v59
	v_lshlrev_b32_e32 v59, 4, v57
	v_add3_u32 v59, s85, v48, v59
	v_lshlrev_b32_e32 v48, 11, v57
	s_waitcnt lgkmcnt(1)
	v_pk_add_f32 v[124:125], v[114:115], v[118:119]
	v_pk_add_f32 v[126:127], v[116:117], v[120:121]
	v_mov_b32_e32 v132, v118
	v_pk_add_f32 v[128:129], v[124:125], v[126:127]
	v_pk_add_f32 v[124:125], v[124:125], v[126:127] neg_lo:[0,1] neg_hi:[0,1]
	v_mov_b32_e32 v133, v120
	s_waitcnt lgkmcnt(0)
	v_pk_mul_f32 v[126:127], v[124:125], v[122:123] op_sel:[1,1] op_sel_hi:[1,0]
	v_mov_b32_e32 v138, v120
	v_pk_fma_f32 v[130:131], v[124:125], v[122:123], v[126:127] neg_lo:[0,0,1] neg_hi:[0,0,1]
	v_pk_fma_f32 v[124:125], v[124:125], v[122:123], v[126:127] op_sel_hi:[0,1,1]
	v_mov_b32_e32 v131, v125
	ds_read_b64 v[124:125], v63
	v_mov_b32_e32 v126, v114
	v_mov_b32_e32 v127, v116
	v_pk_add_f32 v[126:127], v[126:127], v[132:133] neg_lo:[0,1] neg_hi:[0,1]
	v_mov_b32_e32 v132, v116
	v_mov_b32_e32 v133, v115
	v_mov_b32_e32 v139, v119
	v_pk_add_f32 v[132:133], v[132:133], v[138:139] neg_lo:[0,1] neg_hi:[0,1]
	v_pk_mov_b32 v[138:139], v[116:117], v[114:115] op_sel:[1,0]
	v_pk_mov_b32 v[140:141], v[120:121], v[118:119] op_sel:[1,0]
	v_mov_b32_e32 v116, v115
	v_mov_b32_e32 v120, v119
	v_pk_add_f32 v[138:139], v[138:139], v[140:141] neg_lo:[0,1] neg_hi:[0,1]
	v_pk_add_f32 v[114:115], v[116:117], v[120:121] neg_lo:[0,1] neg_hi:[0,1]
	s_waitcnt lgkmcnt(0)
	v_pk_mul_f32 v[116:117], v[138:139], v[124:125]
	v_pk_mul_f32 v[114:115], v[114:115], v[124:125] op_sel:[0,1]
	v_pk_fma_f32 v[116:117], v[132:133], v[124:125], v[116:117] op_sel:[0,1,0] op_sel_hi:[1,0,1]
	v_pk_fma_f32 v[114:115], v[126:127], v[124:125], v[114:115] op_sel_hi:[1,0,1] neg_lo:[0,0,1] neg_hi:[0,0,1]
	ds_write2st64_b64 v46, v[128:129], v[130:131] offset1:1
	v_pk_add_f32 v[118:119], v[116:117], v[114:115]
	v_pk_add_f32 v[120:121], v[116:117], v[114:115] neg_lo:[0,1] neg_hi:[0,1]
	v_pk_add_f32 v[114:115], v[114:115], v[116:117] neg_lo:[0,1] neg_hi:[0,1]
	v_pk_mul_f32 v[116:117], v[122:123], v[118:119] op_sel:[1,1] op_sel_hi:[0,1]
	v_mov_b32_e32 v120, v118
	v_pk_fma_f32 v[118:119], v[122:123], v[114:115], v[116:117] neg_lo:[0,0,1] neg_hi:[0,0,1]
	v_pk_fma_f32 v[114:115], v[122:123], v[114:115], v[116:117] op_sel_hi:[1,0,1]
	v_lshlrev_b32_e32 v61, 5, v57
	v_mov_b32_e32 v119, v115
	ds_write2st64_b64 v46, v[120:121], v[118:119] offset0:2 offset1:3
	v_and_or_b32 v46, v43, s35, v57
	v_lshl_add_u32 v46, v46, 3, v205
	s_waitcnt lgkmcnt(0)
	s_barrier
	ds_read2_b64 v[114:117], v46 offset1:16
	ds_read2_b64 v[118:121], v46 offset0:32 offset1:48
	v_add3_u32 v61, s85, v48, v61
	ds_read_b64 v[122:123], v61
	v_mul_f32_e32 v44, v55, v44
	v_mul_f32_e32 v0, v55, v0
	s_waitcnt lgkmcnt(1)
	v_pk_add_f32 v[124:125], v[114:115], v[118:119]
	v_pk_add_f32 v[126:127], v[116:117], v[120:121]
	v_mov_b32_e32 v132, v118
	v_pk_add_f32 v[128:129], v[124:125], v[126:127]
	v_pk_add_f32 v[124:125], v[124:125], v[126:127] neg_lo:[0,1] neg_hi:[0,1]
	v_mov_b32_e32 v133, v120
	s_waitcnt lgkmcnt(0)
	v_pk_mul_f32 v[126:127], v[124:125], v[122:123] op_sel:[1,1] op_sel_hi:[1,0]
	v_mov_b32_e32 v138, v120
	v_pk_fma_f32 v[130:131], v[124:125], v[122:123], v[126:127] neg_lo:[0,0,1] neg_hi:[0,0,1]
	v_pk_fma_f32 v[124:125], v[124:125], v[122:123], v[126:127] op_sel_hi:[0,1,1]
	v_mov_b32_e32 v131, v125
	ds_read_b64 v[124:125], v59
	v_mov_b32_e32 v126, v114
	v_mov_b32_e32 v127, v116
	v_pk_add_f32 v[126:127], v[126:127], v[132:133] neg_lo:[0,1] neg_hi:[0,1]
	v_mov_b32_e32 v132, v116
	v_mov_b32_e32 v133, v115
	v_mov_b32_e32 v139, v119
	v_pk_add_f32 v[132:133], v[132:133], v[138:139] neg_lo:[0,1] neg_hi:[0,1]
	v_pk_mov_b32 v[138:139], v[116:117], v[114:115] op_sel:[1,0]
	v_pk_mov_b32 v[140:141], v[120:121], v[118:119] op_sel:[1,0]
	v_mov_b32_e32 v116, v115
	v_mov_b32_e32 v120, v119
	v_pk_add_f32 v[138:139], v[138:139], v[140:141] neg_lo:[0,1] neg_hi:[0,1]
	v_pk_add_f32 v[114:115], v[116:117], v[120:121] neg_lo:[0,1] neg_hi:[0,1]
	s_waitcnt lgkmcnt(0)
	v_pk_mul_f32 v[116:117], v[138:139], v[124:125]
	v_pk_mul_f32 v[114:115], v[114:115], v[124:125] op_sel:[0,1]
	v_pk_fma_f32 v[116:117], v[132:133], v[124:125], v[116:117] op_sel:[0,1,0] op_sel_hi:[1,0,1]
	v_pk_fma_f32 v[114:115], v[126:127], v[124:125], v[114:115] op_sel_hi:[1,0,1] neg_lo:[0,0,1] neg_hi:[0,0,1]
	ds_write2_b64 v46, v[128:129], v[130:131] offset1:16
	v_pk_add_f32 v[118:119], v[116:117], v[114:115]
	v_pk_add_f32 v[120:121], v[116:117], v[114:115] neg_lo:[0,1] neg_hi:[0,1]
	v_pk_add_f32 v[114:115], v[114:115], v[116:117] neg_lo:[0,1] neg_hi:[0,1]
	v_pk_mul_f32 v[116:117], v[122:123], v[118:119] op_sel:[1,1] op_sel_hi:[0,1]
	v_mov_b32_e32 v120, v118
	v_pk_fma_f32 v[118:119], v[122:123], v[114:115], v[116:117] neg_lo:[0,0,1] neg_hi:[0,0,1]
	v_pk_fma_f32 v[114:115], v[122:123], v[114:115], v[116:117] op_sel_hi:[1,0,1]
	v_add_f32_e32 v42, v40, v94
	v_mov_b32_e32 v119, v115
	ds_write2_b64 v46, v[120:121], v[118:119] offset0:32 offset1:48
	v_and_or_b32 v46, v45, s35, v57
	v_lshl_add_u32 v48, v46, 3, v205
	ds_read2_b64 v[114:117], v48 offset1:16
	ds_read2_b64 v[118:121], v48 offset0:32 offset1:48
	ds_read_b64 v[122:123], v61
	v_sub_f32_e32 v46, v41, v95
	v_mul_f32_e32 v46, v55, v46
	v_mul_f32_e32 v42, v55, v42
	s_waitcnt lgkmcnt(1)
	v_pk_add_f32 v[124:125], v[114:115], v[118:119]
	v_pk_add_f32 v[126:127], v[116:117], v[120:121]
	v_mov_b32_e32 v132, v118
	v_pk_add_f32 v[128:129], v[124:125], v[126:127]
	v_pk_add_f32 v[124:125], v[124:125], v[126:127] neg_lo:[0,1] neg_hi:[0,1]
	v_mov_b32_e32 v133, v120
	s_waitcnt lgkmcnt(0)
	v_pk_mul_f32 v[126:127], v[124:125], v[122:123] op_sel:[1,1] op_sel_hi:[1,0]
	v_mov_b32_e32 v138, v120
	v_pk_fma_f32 v[130:131], v[124:125], v[122:123], v[126:127] neg_lo:[0,0,1] neg_hi:[0,0,1]
	v_pk_fma_f32 v[124:125], v[124:125], v[122:123], v[126:127] op_sel_hi:[0,1,1]
	v_mov_b32_e32 v131, v125
	ds_read_b64 v[124:125], v59
	v_mov_b32_e32 v126, v114
	v_mov_b32_e32 v127, v116
	v_pk_add_f32 v[126:127], v[126:127], v[132:133] neg_lo:[0,1] neg_hi:[0,1]
	v_mov_b32_e32 v132, v116
	v_mov_b32_e32 v133, v115
	v_mov_b32_e32 v139, v119
	v_pk_add_f32 v[132:133], v[132:133], v[138:139] neg_lo:[0,1] neg_hi:[0,1]
	v_pk_mov_b32 v[138:139], v[116:117], v[114:115] op_sel:[1,0]
	v_pk_mov_b32 v[140:141], v[120:121], v[118:119] op_sel:[1,0]
	v_mov_b32_e32 v116, v115
	v_mov_b32_e32 v120, v119
	v_pk_add_f32 v[138:139], v[138:139], v[140:141] neg_lo:[0,1] neg_hi:[0,1]
	v_pk_add_f32 v[114:115], v[116:117], v[120:121] neg_lo:[0,1] neg_hi:[0,1]
	s_waitcnt lgkmcnt(0)
	v_pk_mul_f32 v[116:117], v[138:139], v[124:125]
	v_pk_mul_f32 v[114:115], v[114:115], v[124:125] op_sel:[0,1]
	v_pk_fma_f32 v[116:117], v[132:133], v[124:125], v[116:117] op_sel:[0,1,0] op_sel_hi:[1,0,1]
	v_pk_fma_f32 v[114:115], v[126:127], v[124:125], v[114:115] op_sel_hi:[1,0,1] neg_lo:[0,0,1] neg_hi:[0,0,1]
	ds_write2_b64 v48, v[128:129], v[130:131] offset1:16
	v_pk_add_f32 v[118:119], v[116:117], v[114:115]
	v_pk_add_f32 v[120:121], v[116:117], v[114:115] neg_lo:[0,1] neg_hi:[0,1]
	v_pk_add_f32 v[114:115], v[114:115], v[116:117] neg_lo:[0,1] neg_hi:[0,1]
	v_pk_mul_f32 v[116:117], v[122:123], v[118:119] op_sel:[1,1] op_sel_hi:[0,1]
	v_mov_b32_e32 v120, v118
	v_pk_fma_f32 v[118:119], v[122:123], v[114:115], v[116:117] neg_lo:[0,0,1] neg_hi:[0,0,1]
	v_pk_fma_f32 v[114:115], v[122:123], v[114:115], v[116:117] op_sel_hi:[1,0,1]
	v_add_f32_e32 v63, v34, v92
	v_mov_b32_e32 v119, v115
	ds_write2_b64 v48, v[120:121], v[118:119] offset0:32 offset1:48
	v_and_or_b32 v48, v49, s35, v57
	v_lshl_add_u32 v65, v48, 3, v205
	ds_read2_b64 v[116:119], v65 offset1:16
	ds_read2_b64 v[120:123], v65 offset0:32 offset1:48
	ds_read_b64 v[124:125], v61
	v_and_or_b32 v57, v47, s35, v57
	v_lshl_add_u32 v57, v57, 3, v205
	v_mul_f32_e32 v48, v55, v63
	s_waitcnt lgkmcnt(1)
	v_pk_add_f32 v[126:127], v[116:117], v[120:121]
	v_pk_add_f32 v[128:129], v[118:119], v[122:123]
	v_mov_b32_e32 v138, v120
	v_pk_add_f32 v[130:131], v[126:127], v[128:129]
	v_pk_add_f32 v[126:127], v[126:127], v[128:129] neg_lo:[0,1] neg_hi:[0,1]
	v_mov_b32_e32 v139, v122
	s_waitcnt lgkmcnt(0)
	v_pk_mul_f32 v[128:129], v[126:127], v[124:125] op_sel:[1,1] op_sel_hi:[1,0]
	v_mov_b32_e32 v140, v122
	v_pk_fma_f32 v[132:133], v[126:127], v[124:125], v[128:129] neg_lo:[0,0,1] neg_hi:[0,0,1]
	v_pk_fma_f32 v[126:127], v[126:127], v[124:125], v[128:129] op_sel_hi:[0,1,1]
	v_mov_b32_e32 v133, v127
	ds_read_b64 v[126:127], v59
	v_mov_b32_e32 v128, v116
	v_mov_b32_e32 v129, v118
	v_pk_add_f32 v[128:129], v[128:129], v[138:139] neg_lo:[0,1] neg_hi:[0,1]
	v_mov_b32_e32 v138, v118
	v_mov_b32_e32 v139, v117
	v_mov_b32_e32 v141, v121
	v_pk_add_f32 v[138:139], v[138:139], v[140:141] neg_lo:[0,1] neg_hi:[0,1]
	v_pk_mov_b32 v[140:141], v[118:119], v[116:117] op_sel:[1,0]
	v_pk_mov_b32 v[142:143], v[122:123], v[120:121] op_sel:[1,0]
	v_mov_b32_e32 v118, v117
	v_mov_b32_e32 v122, v121
	v_pk_add_f32 v[140:141], v[140:141], v[142:143] neg_lo:[0,1] neg_hi:[0,1]
	v_pk_add_f32 v[116:117], v[118:119], v[122:123] neg_lo:[0,1] neg_hi:[0,1]
	s_waitcnt lgkmcnt(0)
	v_pk_mul_f32 v[118:119], v[140:141], v[126:127]
	v_pk_mul_f32 v[116:117], v[116:117], v[126:127] op_sel:[0,1]
	v_pk_fma_f32 v[118:119], v[138:139], v[126:127], v[118:119] op_sel:[0,1,0] op_sel_hi:[1,0,1]
	v_pk_fma_f32 v[116:117], v[128:129], v[126:127], v[116:117] op_sel_hi:[1,0,1] neg_lo:[0,0,1] neg_hi:[0,0,1]
	ds_write2_b64 v65, v[130:131], v[132:133] offset1:16
	v_pk_add_f32 v[120:121], v[118:119], v[116:117]
	v_pk_add_f32 v[122:123], v[118:119], v[116:117] neg_lo:[0,1] neg_hi:[0,1]
	v_pk_add_f32 v[116:117], v[116:117], v[118:119] neg_lo:[0,1] neg_hi:[0,1]
	v_pk_mul_f32 v[118:119], v[124:125], v[120:121] op_sel:[1,1] op_sel_hi:[0,1]
	v_mov_b32_e32 v122, v120
	v_pk_fma_f32 v[120:121], v[124:125], v[116:117], v[118:119] neg_lo:[0,0,1] neg_hi:[0,0,1]
	v_pk_fma_f32 v[116:117], v[124:125], v[116:117], v[118:119] op_sel_hi:[1,0,1]
	v_sub_f32_e32 v63, v35, v93
	v_mov_b32_e32 v121, v117
	ds_write2_b64 v65, v[122:123], v[120:121] offset0:32 offset1:48
	ds_read2_b64 v[118:121], v57 offset1:16
	ds_read2_b64 v[122:125], v57 offset0:32 offset1:48
	ds_read_b64 v[126:127], v61
	v_mul_f32_e32 v114, v55, v63
	v_add_f32_e32 v63, v36, v90
	v_mul_f32_e32 v116, v55, v63
	s_waitcnt lgkmcnt(1)
	v_pk_add_f32 v[128:129], v[118:119], v[122:123]
	v_pk_add_f32 v[130:131], v[120:121], v[124:125]
	v_mov_b32_e32 v140, v122
	v_pk_add_f32 v[132:133], v[128:129], v[130:131]
	v_pk_add_f32 v[128:129], v[128:129], v[130:131] neg_lo:[0,1] neg_hi:[0,1]
	v_mov_b32_e32 v141, v124
	s_waitcnt lgkmcnt(0)
	v_pk_mul_f32 v[130:131], v[128:129], v[126:127] op_sel:[1,1] op_sel_hi:[1,0]
	v_mov_b32_e32 v142, v124
	v_pk_fma_f32 v[138:139], v[128:129], v[126:127], v[130:131] neg_lo:[0,0,1] neg_hi:[0,0,1]
	v_pk_fma_f32 v[128:129], v[128:129], v[126:127], v[130:131] op_sel_hi:[0,1,1]
	v_mov_b32_e32 v139, v129
	ds_read_b64 v[128:129], v59
	v_mov_b32_e32 v130, v118
	v_mov_b32_e32 v131, v120
	v_pk_add_f32 v[130:131], v[130:131], v[140:141] neg_lo:[0,1] neg_hi:[0,1]
	v_mov_b32_e32 v140, v120
	v_mov_b32_e32 v141, v119
	v_mov_b32_e32 v143, v123
	v_pk_add_f32 v[140:141], v[140:141], v[142:143] neg_lo:[0,1] neg_hi:[0,1]
	v_pk_mov_b32 v[142:143], v[120:121], v[118:119] op_sel:[1,0]
	v_pk_mov_b32 v[144:145], v[124:125], v[122:123] op_sel:[1,0]
	v_mov_b32_e32 v120, v119
	v_mov_b32_e32 v124, v123
	v_pk_add_f32 v[142:143], v[142:143], v[144:145] neg_lo:[0,1] neg_hi:[0,1]
	v_pk_add_f32 v[118:119], v[120:121], v[124:125] neg_lo:[0,1] neg_hi:[0,1]
	s_waitcnt lgkmcnt(0)
	v_pk_mul_f32 v[120:121], v[142:143], v[128:129]
	v_pk_mul_f32 v[118:119], v[118:119], v[128:129] op_sel:[0,1]
	v_pk_fma_f32 v[120:121], v[140:141], v[128:129], v[120:121] op_sel:[0,1,0] op_sel_hi:[1,0,1]
	v_pk_fma_f32 v[118:119], v[130:131], v[128:129], v[118:119] op_sel_hi:[1,0,1] neg_lo:[0,0,1] neg_hi:[0,0,1]
	ds_write2_b64 v57, v[132:133], v[138:139] offset1:16
	v_pk_add_f32 v[122:123], v[120:121], v[118:119]
	v_pk_add_f32 v[124:125], v[120:121], v[118:119] neg_lo:[0,1] neg_hi:[0,1]
	v_pk_add_f32 v[118:119], v[118:119], v[120:121] neg_lo:[0,1] neg_hi:[0,1]
	v_pk_mul_f32 v[120:121], v[126:127], v[122:123] op_sel:[1,1] op_sel_hi:[0,1]
	v_mov_b32_e32 v124, v122
	v_pk_fma_f32 v[122:123], v[126:127], v[118:119], v[120:121] neg_lo:[0,0,1] neg_hi:[0,0,1]
	v_pk_fma_f32 v[118:119], v[126:127], v[118:119], v[120:121] op_sel_hi:[1,0,1]
	v_sub_f32_e32 v63, v37, v91
	v_mov_b32_e32 v123, v119
	ds_write2_b64 v57, v[124:125], v[122:123] offset0:32 offset1:48
	v_and_b32_e32 v57, 3, v53
	v_and_or_b32 v43, v43, s5, v57
	v_lshl_add_u32 v43, v43, 3, v205
	v_lshlrev_b32_e32 v59, 12, v57
	v_lshlrev_b32_e32 v61, 6, v57
	s_waitcnt lgkmcnt(0)
	s_barrier
	v_add3_u32 v59, s85, v59, v61
	ds_read2_b64 v[118:121], v43 offset1:4
	ds_read2_b64 v[122:125], v43 offset0:8 offset1:12
	v_lshlrev_b32_e32 v61, 13, v57
	v_lshlrev_b32_e32 v65, 7, v57
	v_add3_u32 v61, s85, v61, v65
	ds_read_b64 v[126:127], v61
	s_waitcnt lgkmcnt(1)
	v_pk_add_f32 v[128:129], v[118:119], v[122:123]
	v_pk_add_f32 v[130:131], v[120:121], v[124:125]
	v_mov_b32_e32 v140, v122
	v_pk_add_f32 v[132:133], v[128:129], v[130:131]
	v_pk_add_f32 v[128:129], v[128:129], v[130:131] neg_lo:[0,1] neg_hi:[0,1]
	v_mov_b32_e32 v141, v124
	s_waitcnt lgkmcnt(0)
	v_pk_mul_f32 v[130:131], v[128:129], v[126:127] op_sel:[1,1] op_sel_hi:[1,0]
	v_mov_b32_e32 v142, v124
	v_pk_fma_f32 v[138:139], v[128:129], v[126:127], v[130:131] neg_lo:[0,0,1] neg_hi:[0,0,1]
	v_pk_fma_f32 v[128:129], v[128:129], v[126:127], v[130:131] op_sel_hi:[0,1,1]
	v_mov_b32_e32 v139, v129
	ds_read_b64 v[128:129], v59
	v_mov_b32_e32 v130, v118
	v_mov_b32_e32 v131, v120
	v_pk_add_f32 v[130:131], v[130:131], v[140:141] neg_lo:[0,1] neg_hi:[0,1]
	v_mov_b32_e32 v140, v120
	v_mov_b32_e32 v141, v119
	v_mov_b32_e32 v143, v123
	v_pk_add_f32 v[140:141], v[140:141], v[142:143] neg_lo:[0,1] neg_hi:[0,1]
	v_pk_mov_b32 v[142:143], v[120:121], v[118:119] op_sel:[1,0]
	v_pk_mov_b32 v[144:145], v[124:125], v[122:123] op_sel:[1,0]
	v_mov_b32_e32 v120, v119
	v_mov_b32_e32 v124, v123
	v_pk_add_f32 v[142:143], v[142:143], v[144:145] neg_lo:[0,1] neg_hi:[0,1]
	v_pk_add_f32 v[118:119], v[120:121], v[124:125] neg_lo:[0,1] neg_hi:[0,1]
	s_waitcnt lgkmcnt(0)
	v_pk_mul_f32 v[120:121], v[142:143], v[128:129]
	v_pk_mul_f32 v[118:119], v[118:119], v[128:129] op_sel:[0,1]
	v_pk_fma_f32 v[120:121], v[140:141], v[128:129], v[120:121] op_sel:[0,1,0] op_sel_hi:[1,0,1]
	v_pk_fma_f32 v[118:119], v[130:131], v[128:129], v[118:119] op_sel_hi:[1,0,1] neg_lo:[0,0,1] neg_hi:[0,0,1]
	ds_write2_b64 v43, v[132:133], v[138:139] offset1:4
	v_pk_add_f32 v[122:123], v[120:121], v[118:119]
	v_pk_add_f32 v[124:125], v[120:121], v[118:119] neg_lo:[0,1] neg_hi:[0,1]
	v_pk_add_f32 v[118:119], v[118:119], v[120:121] neg_lo:[0,1] neg_hi:[0,1]
	v_pk_mul_f32 v[120:121], v[126:127], v[122:123] op_sel:[1,1] op_sel_hi:[0,1]
	v_mov_b32_e32 v124, v122
	v_pk_fma_f32 v[122:123], v[126:127], v[118:119], v[120:121] neg_lo:[0,0,1] neg_hi:[0,0,1]
	v_pk_fma_f32 v[118:119], v[126:127], v[118:119], v[120:121] op_sel_hi:[1,0,1]
	v_mul_f32_e32 v120, v55, v63
	v_mov_b32_e32 v123, v119
	ds_write2_b64 v43, v[124:125], v[122:123] offset0:8 offset1:12
	v_and_or_b32 v43, v45, s5, v57
	v_lshl_add_u32 v43, v43, 3, v205
	ds_read2_b64 v[122:125], v43 offset1:4
	ds_read2_b64 v[126:129], v43 offset0:8 offset1:12
	ds_read_b64 v[130:131], v61
	v_add_f32_e32 v45, v30, v88
	v_mul_f32_e32 v118, v55, v45
	v_sub_f32_e32 v45, v31, v89
	s_waitcnt lgkmcnt(1)
	v_pk_add_f32 v[132:133], v[122:123], v[126:127]
	v_pk_add_f32 v[138:139], v[124:125], v[128:129]
	v_mov_b32_e32 v144, v126
	v_pk_add_f32 v[140:141], v[132:133], v[138:139]
	v_pk_add_f32 v[132:133], v[132:133], v[138:139] neg_lo:[0,1] neg_hi:[0,1]
	v_mov_b32_e32 v145, v128
	s_waitcnt lgkmcnt(0)
	v_pk_mul_f32 v[138:139], v[132:133], v[130:131] op_sel:[1,1] op_sel_hi:[1,0]
	v_mov_b32_e32 v146, v128
	v_pk_fma_f32 v[142:143], v[132:133], v[130:131], v[138:139] neg_lo:[0,0,1] neg_hi:[0,0,1]
	v_pk_fma_f32 v[132:133], v[132:133], v[130:131], v[138:139] op_sel_hi:[0,1,1]
	v_mov_b32_e32 v143, v133
	ds_read_b64 v[132:133], v59
	v_mov_b32_e32 v138, v122
	v_mov_b32_e32 v139, v124
	v_pk_add_f32 v[138:139], v[138:139], v[144:145] neg_lo:[0,1] neg_hi:[0,1]
	v_mov_b32_e32 v144, v124
	v_mov_b32_e32 v145, v123
	v_mov_b32_e32 v147, v127
	v_pk_add_f32 v[144:145], v[144:145], v[146:147] neg_lo:[0,1] neg_hi:[0,1]
	v_pk_mov_b32 v[146:147], v[124:125], v[122:123] op_sel:[1,0]
	v_pk_mov_b32 v[150:151], v[128:129], v[126:127] op_sel:[1,0]
	v_mov_b32_e32 v124, v123
	v_mov_b32_e32 v128, v127
	v_pk_add_f32 v[146:147], v[146:147], v[150:151] neg_lo:[0,1] neg_hi:[0,1]
	v_pk_add_f32 v[122:123], v[124:125], v[128:129] neg_lo:[0,1] neg_hi:[0,1]
	s_waitcnt lgkmcnt(0)
	v_pk_mul_f32 v[124:125], v[146:147], v[132:133]
	v_pk_mul_f32 v[122:123], v[122:123], v[132:133] op_sel:[0,1]
	v_pk_fma_f32 v[124:125], v[144:145], v[132:133], v[124:125] op_sel:[0,1,0] op_sel_hi:[1,0,1]
	v_pk_fma_f32 v[122:123], v[138:139], v[132:133], v[122:123] op_sel_hi:[1,0,1] neg_lo:[0,0,1] neg_hi:[0,0,1]
	ds_write2_b64 v43, v[140:141], v[142:143] offset1:4
	v_pk_add_f32 v[126:127], v[124:125], v[122:123]
	v_pk_add_f32 v[128:129], v[124:125], v[122:123] neg_lo:[0,1] neg_hi:[0,1]
	v_pk_add_f32 v[122:123], v[122:123], v[124:125] neg_lo:[0,1] neg_hi:[0,1]
	v_pk_mul_f32 v[124:125], v[130:131], v[126:127] op_sel:[1,1] op_sel_hi:[0,1]
	v_mov_b32_e32 v128, v126
	v_pk_fma_f32 v[126:127], v[130:131], v[122:123], v[124:125] neg_lo:[0,0,1] neg_hi:[0,0,1]
	v_pk_fma_f32 v[122:123], v[130:131], v[122:123], v[124:125] op_sel_hi:[1,0,1]
	s_nop 0
	v_mov_b32_e32 v127, v123
	ds_write2_b64 v43, v[128:129], v[126:127] offset0:8 offset1:12
	v_and_or_b32 v43, v49, s5, v57
	v_lshl_add_u32 v43, v43, 3, v205
	ds_read2_b64 v[124:127], v43 offset1:4
	ds_read2_b64 v[128:131], v43 offset0:8 offset1:12
	ds_read_b64 v[132:133], v61
	v_mul_f32_e32 v122, v55, v45
	v_add_f32_e32 v45, v32, v86
	s_waitcnt lgkmcnt(1)
	v_pk_add_f32 v[138:139], v[124:125], v[128:129]
	v_pk_add_f32 v[140:141], v[126:127], v[130:131]
	v_mov_b32_e32 v146, v128
	v_pk_add_f32 v[142:143], v[138:139], v[140:141]
	v_pk_add_f32 v[138:139], v[138:139], v[140:141] neg_lo:[0,1] neg_hi:[0,1]
	v_mov_b32_e32 v147, v130
	s_waitcnt lgkmcnt(0)
	v_pk_mul_f32 v[140:141], v[138:139], v[132:133] op_sel:[1,1] op_sel_hi:[1,0]
	v_mov_b32_e32 v150, v130
	v_pk_fma_f32 v[144:145], v[138:139], v[132:133], v[140:141] neg_lo:[0,0,1] neg_hi:[0,0,1]
	v_pk_fma_f32 v[138:139], v[138:139], v[132:133], v[140:141] op_sel_hi:[0,1,1]
	v_mov_b32_e32 v145, v139
	ds_read_b64 v[138:139], v59
	v_mov_b32_e32 v140, v124
	v_mov_b32_e32 v141, v126
	v_pk_add_f32 v[140:141], v[140:141], v[146:147] neg_lo:[0,1] neg_hi:[0,1]
	v_mov_b32_e32 v146, v126
	v_mov_b32_e32 v147, v125
	v_mov_b32_e32 v151, v129
	v_pk_add_f32 v[146:147], v[146:147], v[150:151] neg_lo:[0,1] neg_hi:[0,1]
	v_pk_mov_b32 v[150:151], v[126:127], v[124:125] op_sel:[1,0]
	v_pk_mov_b32 v[152:153], v[130:131], v[128:129] op_sel:[1,0]
	v_mov_b32_e32 v126, v125
	v_mov_b32_e32 v130, v129
	v_pk_add_f32 v[150:151], v[150:151], v[152:153] neg_lo:[0,1] neg_hi:[0,1]
	v_pk_add_f32 v[124:125], v[126:127], v[130:131] neg_lo:[0,1] neg_hi:[0,1]
	s_waitcnt lgkmcnt(0)
	v_pk_mul_f32 v[126:127], v[150:151], v[138:139]
	v_pk_mul_f32 v[124:125], v[124:125], v[138:139] op_sel:[0,1]
	v_pk_fma_f32 v[126:127], v[146:147], v[138:139], v[126:127] op_sel:[0,1,0] op_sel_hi:[1,0,1]
	v_pk_fma_f32 v[124:125], v[140:141], v[138:139], v[124:125] op_sel_hi:[1,0,1] neg_lo:[0,0,1] neg_hi:[0,0,1]
	ds_write2_b64 v43, v[142:143], v[144:145] offset1:4
	v_pk_add_f32 v[128:129], v[126:127], v[124:125]
	v_pk_add_f32 v[130:131], v[126:127], v[124:125] neg_lo:[0,1] neg_hi:[0,1]
	v_pk_add_f32 v[124:125], v[124:125], v[126:127] neg_lo:[0,1] neg_hi:[0,1]
	v_pk_mul_f32 v[126:127], v[132:133], v[128:129] op_sel:[1,1] op_sel_hi:[0,1]
	v_mov_b32_e32 v130, v128
	v_pk_fma_f32 v[128:129], v[132:133], v[124:125], v[126:127] neg_lo:[0,0,1] neg_hi:[0,0,1]
	v_pk_fma_f32 v[124:125], v[132:133], v[124:125], v[126:127] op_sel_hi:[1,0,1]
	s_nop 0
	v_mov_b32_e32 v129, v125
	ds_write2_b64 v43, v[130:131], v[128:129] offset0:8 offset1:12
	v_and_or_b32 v43, v47, s5, v57
	v_lshl_add_u32 v43, v43, 3, v205
	ds_read2_b64 v[128:131], v43 offset1:4
	ds_read2_b64 v[138:141], v43 offset0:8 offset1:12
	v_mul_f32_e32 v124, v55, v45
	v_sub_f32_e32 v45, v33, v87
	v_mul_f32_e32 v126, v55, v45
	s_waitcnt lgkmcnt(1)
	v_mov_b32_e32 v146, v128
	s_waitcnt lgkmcnt(0)
	v_pk_add_f32 v[132:133], v[128:129], v[138:139]
	v_pk_add_f32 v[142:143], v[130:131], v[140:141]
	v_mov_b32_e32 v147, v130
	v_mov_b32_e32 v151, v140
	v_mov_b32_e32 v150, v138
	v_pk_add_f32 v[144:145], v[132:133], v[142:143]
	v_pk_add_f32 v[132:133], v[132:133], v[142:143] neg_lo:[0,1] neg_hi:[0,1]
	ds_read_b64 v[142:143], v61
	v_pk_add_f32 v[146:147], v[146:147], v[150:151] neg_lo:[0,1] neg_hi:[0,1]
	ds_read_b64 v[150:151], v59
	v_mov_b32_e32 v152, v130
	v_mov_b32_e32 v154, v140
	v_pk_mov_b32 v[156:157], v[130:131], v[128:129] op_sel:[1,0]
	v_pk_mov_b32 v[158:159], v[140:141], v[138:139] op_sel:[1,0]
	v_mov_b32_e32 v130, v129
	v_mov_b32_e32 v140, v139
	v_mov_b32_e32 v153, v129
	v_pk_add_f32 v[140:141], v[130:131], v[140:141] neg_lo:[0,1] neg_hi:[0,1]
	v_mov_b32_e32 v155, v139
	s_waitcnt lgkmcnt(1)
	v_pk_mul_f32 v[128:129], v[132:133], v[142:143] op_sel:[1,1] op_sel_hi:[1,0]
	v_pk_add_f32 v[152:153], v[152:153], v[154:155] neg_lo:[0,1] neg_hi:[0,1]
	v_pk_add_f32 v[154:155], v[156:157], v[158:159] neg_lo:[0,1] neg_hi:[0,1]
	s_waitcnt lgkmcnt(0)
	v_pk_mul_f32 v[140:141], v[140:141], v[150:151] op_sel:[0,1]
	v_pk_fma_f32 v[160:161], v[132:133], v[142:143], v[128:129] neg_lo:[0,0,1] neg_hi:[0,0,1]
	v_pk_fma_f32 v[128:129], v[132:133], v[142:143], v[128:129] op_sel_hi:[0,1,1]
	v_pk_fma_f32 v[140:141], v[146:147], v[150:151], v[140:141] op_sel_hi:[1,0,1] neg_lo:[0,0,1] neg_hi:[0,0,1]
	v_pk_mul_f32 v[146:147], v[154:155], v[150:151]
	v_mov_b32_e32 v161, v129
	v_pk_fma_f32 v[146:147], v[152:153], v[150:151], v[146:147] op_sel:[0,1,0] op_sel_hi:[1,0,1]
	ds_write2_b64 v43, v[144:145], v[160:161] offset1:4
	v_pk_add_f32 v[144:145], v[146:147], v[140:141]
	v_pk_add_f32 v[150:151], v[146:147], v[140:141] neg_lo:[0,1] neg_hi:[0,1]
	v_pk_add_f32 v[140:141], v[140:141], v[146:147] neg_lo:[0,1] neg_hi:[0,1]
	v_mov_b32_e32 v150, v144
	v_pk_mul_f32 v[144:145], v[142:143], v[144:145] op_sel:[1,1] op_sel_hi:[0,1]
	v_pk_fma_f32 v[146:147], v[142:143], v[140:141], v[144:145] neg_lo:[0,0,1] neg_hi:[0,0,1]
	v_pk_fma_f32 v[140:141], v[142:143], v[140:141], v[144:145] op_sel_hi:[1,0,1]
	v_add_f32_e32 v45, v26, v84
	v_mov_b32_e32 v147, v141
	ds_write2_b64 v43, v[150:151], v[146:147] offset0:8 offset1:12
	v_lshl_add_u32 v43, v53, 5, v205
	s_waitcnt lgkmcnt(0)
	s_barrier
	ds_read_b128 v[144:147], v43
	ds_read_b128 v[150:153], v43 offset:16
	v_mul_f32_e32 v130, v55, v45
	v_sub_f32_e32 v45, v27, v85
	v_mul_f32_e32 v132, v55, v45
	v_add_f32_e32 v45, v28, v82
	s_waitcnt lgkmcnt(0)
	v_pk_add_f32 v[156:157], v[144:145], v[150:151]
	v_pk_add_f32 v[158:159], v[146:147], v[152:153]
	v_pk_add_f32 v[144:145], v[144:145], v[150:151] neg_lo:[0,1] neg_hi:[0,1]
	v_pk_add_f32 v[154:155], v[156:157], v[158:159]
	v_pk_add_f32 v[156:157], v[156:157], v[158:159] neg_lo:[0,1] neg_hi:[0,1]
	ds_write_b128 v43, v[154:157]
	v_pk_add_f32 v[146:147], v[146:147], v[152:153] neg_lo:[0,1] neg_hi:[0,1]
	ds_read_b128 v[150:153], v43 offset:16384
	ds_read_b128 v[154:157], v43 offset:16400
	v_pk_add_f32 v[158:159], v[144:145], v[146:147] op_sel:[0,1] op_sel_hi:[1,0]
	v_pk_add_f32 v[146:147], v[144:145], v[146:147] op_sel:[0,1] op_sel_hi:[1,0] neg_lo:[0,1] neg_hi:[0,1]
	v_mov_b32_e32 v144, v158
	v_mov_b32_e32 v145, v147
	v_mov_b32_e32 v147, v159
	ds_write_b128 v43, v[144:147] offset:16
	s_waitcnt lgkmcnt(1)
	v_pk_add_f32 v[146:147], v[150:151], v[154:155]
	v_pk_add_f32 v[158:159], v[152:153], v[156:157]
	v_mul_f32_e32 v128, v55, v45
	v_pk_add_f32 v[144:145], v[146:147], v[158:159]
	v_pk_add_f32 v[146:147], v[146:147], v[158:159] neg_lo:[0,1] neg_hi:[0,1]
	ds_write_b128 v43, v[144:147] offset:16384
	v_pk_add_f32 v[144:145], v[150:151], v[154:155] neg_lo:[0,1] neg_hi:[0,1]
	v_pk_add_f32 v[146:147], v[152:153], v[156:157] neg_lo:[0,1] neg_hi:[0,1]
	ds_read_b128 v[150:153], v43 offset:32768
	ds_read_b128 v[154:157], v43 offset:32784
	v_pk_add_f32 v[158:159], v[144:145], v[146:147] op_sel:[0,1] op_sel_hi:[1,0]
	v_pk_add_f32 v[146:147], v[144:145], v[146:147] op_sel:[0,1] op_sel_hi:[1,0] neg_lo:[0,1] neg_hi:[0,1]
	v_mov_b32_e32 v144, v158
	v_mov_b32_e32 v145, v147
	v_mov_b32_e32 v147, v159
	ds_write_b128 v43, v[144:147] offset:16400
	s_waitcnt lgkmcnt(1)
	v_pk_add_f32 v[146:147], v[150:151], v[154:155]
	v_pk_add_f32 v[158:159], v[152:153], v[156:157]
	v_sub_f32_e32 v45, v29, v83
	v_pk_add_f32 v[144:145], v[146:147], v[158:159]
	v_pk_add_f32 v[146:147], v[146:147], v[158:159] neg_lo:[0,1] neg_hi:[0,1]
	ds_write_b128 v43, v[144:147] offset:32768
	v_pk_add_f32 v[144:145], v[150:151], v[154:155] neg_lo:[0,1] neg_hi:[0,1]
	v_pk_add_f32 v[146:147], v[152:153], v[156:157] neg_lo:[0,1] neg_hi:[0,1]
	ds_read_b128 v[150:153], v43 offset:49152
	ds_read_b128 v[154:157], v43 offset:49168
	v_pk_add_f32 v[158:159], v[144:145], v[146:147] op_sel:[0,1] op_sel_hi:[1,0]
	v_pk_add_f32 v[146:147], v[144:145], v[146:147] op_sel:[0,1] op_sel_hi:[1,0] neg_lo:[0,1] neg_hi:[0,1]
	v_mov_b32_e32 v144, v158
	v_mov_b32_e32 v145, v147
	v_mov_b32_e32 v147, v159
	ds_write_b128 v43, v[144:147] offset:32784
	s_waitcnt lgkmcnt(1)
	v_pk_add_f32 v[144:145], v[150:151], v[154:155]
	v_pk_add_f32 v[146:147], v[152:153], v[156:157]
	v_pk_add_f32 v[150:151], v[150:151], v[154:155] neg_lo:[0,1] neg_hi:[0,1]
	v_pk_add_f32 v[152:153], v[152:153], v[156:157] neg_lo:[0,1] neg_hi:[0,1]
	v_pk_add_f32 v[158:159], v[144:145], v[146:147]
	v_pk_add_f32 v[154:155], v[150:151], v[152:153] op_sel:[0,1] op_sel_hi:[1,0]
	v_pk_add_f32 v[152:153], v[150:151], v[152:153] op_sel:[0,1] op_sel_hi:[1,0] neg_lo:[0,1] neg_hi:[0,1]
	v_pk_add_f32 v[160:161], v[144:145], v[146:147] neg_lo:[0,1] neg_hi:[0,1]
	v_mov_b32_e32 v150, v154
	v_mov_b32_e32 v151, v153
	v_mov_b32_e32 v153, v155
	ds_write_b128 v43, v[158:161] offset:49152
	ds_write_b128 v43, v[150:153] offset:49168
	s_waitcnt lgkmcnt(0)
	s_barrier
	ds_read2st64_b64 v[150:153], v148 offset1:8
	v_mul_f32_e32 v138, v55, v45
	v_add_f32_e32 v45, v22, v80
	v_mul_f32_e32 v140, v55, v45
	v_sub_f32_e32 v45, v23, v81
	v_mul_f32_e32 v142, v55, v45
	v_add_f32_e32 v45, v24, v78
	v_mul_f32_e32 v144, v55, v45
	v_sub_f32_e32 v45, v25, v79
	v_mul_f32_e32 v146, v55, v45
	v_add_f32_e32 v43, v10, v76
	s_waitcnt lgkmcnt(0)
	v_pk_mul_f32 v[44:45], v[44:45], v[150:151] op_sel:[0,1] op_sel_hi:[0,0]
	v_mul_f32_e32 v154, v55, v43
	v_sub_f32_e32 v43, v11, v77
	v_pk_fma_f32 v[158:159], v[0:1], v[150:151], v[44:45] neg_lo:[0,0,1] neg_hi:[0,0,1]
	v_pk_fma_f32 v[150:151], v[0:1], v[150:151], v[44:45] op_sel_hi:[0,1,1]
	v_pk_mul_f32 v[44:45], v[46:47], v[152:153] op_sel:[0,1] op_sel_hi:[0,0]
	v_mul_f32_e32 v156, v55, v43
	v_pk_fma_f32 v[46:47], v[42:43], v[152:153], v[44:45] neg_lo:[0,0,1] neg_hi:[0,0,1]
	v_pk_fma_f32 v[152:153], v[42:43], v[152:153], v[44:45] op_sel_hi:[0,1,1]
	ds_read2st64_b64 v[42:45], v148 offset0:16 offset1:24
	v_sub_f32_e32 v47, v13, v75
	v_mul_f32_e32 v150, v55, v47
	v_mov_b32_e32 v159, v151
	v_mov_b32_e32 v47, v153
	s_waitcnt lgkmcnt(0)
	v_pk_mul_f32 v[114:115], v[114:115], v[42:43] op_sel:[0,1] op_sel_hi:[0,0]
	v_pk_fma_f32 v[160:161], v[48:49], v[42:43], v[114:115] neg_lo:[0,0,1] neg_hi:[0,0,1]
	v_pk_fma_f32 v[42:43], v[48:49], v[42:43], v[114:115] op_sel_hi:[0,1,1]
	v_pk_mul_f32 v[48:49], v[120:121], v[44:45] op_sel:[0,1] op_sel_hi:[0,0]
	v_add_f32_e32 v42, v6, v72
	v_pk_fma_f32 v[114:115], v[116:117], v[44:45], v[48:49] neg_lo:[0,0,1] neg_hi:[0,0,1]
	v_pk_fma_f32 v[44:45], v[116:117], v[44:45], v[48:49] op_sel_hi:[0,1,1]
	v_mul_f32_e32 v116, v55, v42
	v_sub_f32_e32 v42, v7, v73
	v_mul_f32_e32 v120, v55, v42
	v_add_f32_e32 v42, v8, v70
	v_mul_f32_e32 v152, v55, v42
	v_sub_f32_e32 v42, v9, v71
	v_mul_f32_e32 v162, v55, v42
	v_add_f32_e32 v42, v2, v68
	v_mul_f32_e32 v164, v55, v42
	v_sub_f32_e32 v42, v3, v69
	ds_write2st64_b64 v148, v[158:159], v[46:47] offset1:8
	v_mul_f32_e32 v158, v55, v42
	v_mov_b32_e32 v161, v43
	v_mov_b32_e32 v115, v45
	ds_read2st64_b64 v[42:45], v148 offset0:32 offset1:40
	v_add_f32_e32 v46, v4, v66
	v_mul_f32_e32 v166, v55, v46
	ds_write2st64_b64 v148, v[160:161], v[114:115] offset0:16 offset1:24
	v_add_f32_e32 v0, v12, v74
	s_waitcnt lgkmcnt(1)
	v_pk_mul_f32 v[46:47], v[122:123], v[42:43] op_sel:[0,1] op_sel_hi:[0,0]
	v_pk_fma_f32 v[48:49], v[118:119], v[42:43], v[46:47] neg_lo:[0,0,1] neg_hi:[0,0,1]
	v_pk_fma_f32 v[46:47], v[118:119], v[42:43], v[46:47] op_sel_hi:[0,1,1]
	v_pk_mul_f32 v[42:43], v[126:127], v[44:45] op_sel:[0,1] op_sel_hi:[0,0]
	v_pk_fma_f32 v[114:115], v[124:125], v[44:45], v[42:43] neg_lo:[0,0,1] neg_hi:[0,0,1]
	v_pk_fma_f32 v[118:119], v[124:125], v[44:45], v[42:43] op_sel_hi:[0,1,1]
	ds_read2st64_b64 v[42:45], v148 offset0:48 offset1:56
	v_mov_b32_e32 v49, v47
	v_mov_b32_e32 v115, v119
	ds_write2st64_b64 v148, v[48:49], v[114:115] offset0:32 offset1:40
	v_mul_f32_e32 v0, v55, v0
	s_waitcnt lgkmcnt(1)
	v_pk_mul_f32 v[46:47], v[132:133], v[42:43] op_sel:[0,1] op_sel_hi:[0,0]
	v_pk_fma_f32 v[114:115], v[130:131], v[42:43], v[46:47] neg_lo:[0,0,1] neg_hi:[0,0,1]
	v_pk_fma_f32 v[42:43], v[130:131], v[42:43], v[46:47] op_sel_hi:[0,1,1]
	ds_read2st64_b64 v[46:49], v148 offset0:64 offset1:72
	v_mov_b32_e32 v115, v43
	v_pk_mul_f32 v[42:43], v[138:139], v[44:45] op_sel:[0,1] op_sel_hi:[0,0]
	v_pk_fma_f32 v[122:123], v[128:129], v[44:45], v[42:43] neg_lo:[0,0,1] neg_hi:[0,0,1]
	v_pk_fma_f32 v[42:43], v[128:129], v[44:45], v[42:43] op_sel_hi:[0,1,1]
	v_mov_b32_e32 v123, v43
	s_waitcnt lgkmcnt(0)
	v_pk_mul_f32 v[42:43], v[142:143], v[46:47] op_sel:[0,1] op_sel_hi:[0,0]
	ds_write2st64_b64 v148, v[114:115], v[122:123] offset0:48 offset1:56
	v_pk_fma_f32 v[114:115], v[140:141], v[46:47], v[42:43] neg_lo:[0,0,1] neg_hi:[0,0,1]
	v_pk_fma_f32 v[42:43], v[140:141], v[46:47], v[42:43] op_sel_hi:[0,1,1]
	v_mov_b32_e32 v115, v43
	ds_read2st64_b64 v[42:45], v148 offset0:80 offset1:88
	v_pk_mul_f32 v[46:47], v[146:147], v[48:49] op_sel:[0,1] op_sel_hi:[0,0]
	v_pk_fma_f32 v[122:123], v[144:145], v[48:49], v[46:47] neg_lo:[0,0,1] neg_hi:[0,0,1]
	v_pk_fma_f32 v[46:47], v[144:145], v[48:49], v[46:47] op_sel_hi:[0,1,1]
	v_mov_b32_e32 v123, v47
	s_waitcnt lgkmcnt(0)
	v_pk_mul_f32 v[46:47], v[156:157], v[42:43] op_sel:[0,1] op_sel_hi:[0,0]
	ds_write2st64_b64 v148, v[114:115], v[122:123] offset0:64 offset1:72
	v_pk_fma_f32 v[114:115], v[154:155], v[42:43], v[46:47] neg_lo:[0,0,1] neg_hi:[0,0,1]
	v_pk_fma_f32 v[42:43], v[154:155], v[42:43], v[46:47] op_sel_hi:[0,1,1]
	ds_read2st64_b64 v[46:49], v148 offset0:96 offset1:104
	v_mov_b32_e32 v115, v43
	v_pk_mul_f32 v[42:43], v[150:151], v[44:45] op_sel:[0,1] op_sel_hi:[0,0]
	v_pk_fma_f32 v[122:123], v[0:1], v[44:45], v[42:43] neg_lo:[0,0,1] neg_hi:[0,0,1]
	v_pk_fma_f32 v[42:43], v[0:1], v[44:45], v[42:43] op_sel_hi:[0,1,1]
	v_mov_b32_e32 v123, v43
	s_waitcnt lgkmcnt(0)
	v_pk_mul_f32 v[42:43], v[120:121], v[46:47] op_sel:[0,1] op_sel_hi:[0,0]
	ds_write2st64_b64 v148, v[114:115], v[122:123] offset0:80 offset1:88
	v_pk_fma_f32 v[114:115], v[116:117], v[46:47], v[42:43] neg_lo:[0,0,1] neg_hi:[0,0,1]
	v_pk_fma_f32 v[42:43], v[116:117], v[46:47], v[42:43] op_sel_hi:[0,1,1]
	v_mov_b32_e32 v115, v43
	ds_read2st64_b64 v[42:45], v148 offset0:112 offset1:120
	v_pk_mul_f32 v[46:47], v[162:163], v[48:49] op_sel:[0,1] op_sel_hi:[0,0]
	v_pk_fma_f32 v[116:117], v[152:153], v[48:49], v[46:47] neg_lo:[0,0,1] neg_hi:[0,0,1]
	v_pk_fma_f32 v[46:47], v[152:153], v[48:49], v[46:47] op_sel_hi:[0,1,1]
	v_sub_f32_e32 v53, v5, v67
	v_mov_b32_e32 v117, v47
	s_waitcnt lgkmcnt(0)
	v_pk_mul_f32 v[46:47], v[158:159], v[42:43] op_sel:[0,1] op_sel_hi:[0,0]
	v_mul_f32_e32 v118, v55, v53
	v_pk_fma_f32 v[48:49], v[164:165], v[42:43], v[46:47] neg_lo:[0,0,1] neg_hi:[0,0,1]
	v_pk_fma_f32 v[42:43], v[164:165], v[42:43], v[46:47] op_sel_hi:[0,1,1]
	v_mov_b32_e32 v49, v43
	v_pk_mul_f32 v[42:43], v[118:119], v[44:45] op_sel:[0,1] op_sel_hi:[0,0]
	v_pk_fma_f32 v[46:47], v[166:167], v[44:45], v[42:43] neg_lo:[0,0,1] neg_hi:[0,0,1]
	v_pk_fma_f32 v[42:43], v[166:167], v[44:45], v[42:43] op_sel_hi:[0,1,1]
	v_mov_b32_e32 v47, v43
	v_mov_b32_e32 v0, v135
	ds_write2st64_b64 v148, v[114:115], v[116:117] offset0:96 offset1:104
	ds_write2st64_b64 v148, v[48:49], v[46:47] offset0:112 offset1:120
	s_waitcnt lgkmcnt(0)
	s_barrier
	s_nop 0
	v_lshl_add_u32 v53, v0, 5, v205
	ds_read_b128 v[42:45], v53
	ds_read_b128 v[46:49], v53 offset:16
	s_waitcnt lgkmcnt(1)
	v_pk_add_f32 v[118:119], v[42:43], v[44:45]
	v_pk_add_f32 v[42:43], v[42:43], v[44:45] neg_lo:[0,1] neg_hi:[0,1]
	s_waitcnt lgkmcnt(0)
	v_pk_add_f32 v[44:45], v[46:47], v[48:49] neg_lo:[0,1] neg_hi:[0,1]
	v_pk_add_f32 v[120:121], v[46:47], v[48:49]
	v_pk_add_f32 v[122:123], v[42:43], v[44:45] op_sel:[0,1] op_sel_hi:[1,0] neg_lo:[0,1] neg_hi:[0,1]
	v_pk_add_f32 v[44:45], v[42:43], v[44:45] op_sel:[0,1] op_sel_hi:[1,0]
	v_pk_add_f32 v[114:115], v[118:119], v[120:121]
	v_mov_b32_e32 v116, v122
	v_mov_b32_e32 v117, v45
	ds_write_b128 v53, v[114:117]
	ds_read_b128 v[46:49], v53 offset:16384
	ds_read_b128 v[114:117], v53 offset:16400
	v_pk_add_f32 v[42:43], v[118:119], v[120:121] neg_lo:[0,1] neg_hi:[0,1]
	v_mov_b32_e32 v45, v123
	ds_write_b128 v53, v[42:45] offset:16
	s_waitcnt lgkmcnt(2)
	v_pk_add_f32 v[122:123], v[46:47], v[48:49]
	v_pk_add_f32 v[44:45], v[46:47], v[48:49] neg_lo:[0,1] neg_hi:[0,1]
	s_waitcnt lgkmcnt(1)
	v_pk_add_f32 v[46:47], v[114:115], v[116:117] neg_lo:[0,1] neg_hi:[0,1]
	v_pk_add_f32 v[124:125], v[114:115], v[116:117]
	v_pk_add_f32 v[48:49], v[44:45], v[46:47] op_sel:[0,1] op_sel_hi:[1,0] neg_lo:[0,1] neg_hi:[0,1]
	v_pk_add_f32 v[46:47], v[44:45], v[46:47] op_sel:[0,1] op_sel_hi:[1,0]
	v_pk_add_f32 v[42:43], v[122:123], v[124:125]
	v_mov_b32_e32 v44, v48
	v_mov_b32_e32 v45, v47
	ds_write_b128 v53, v[42:45] offset:16384
	ds_read_b128 v[114:117], v53 offset:32768
	ds_read_b128 v[118:121], v53 offset:32784
	v_pk_add_f32 v[44:45], v[122:123], v[124:125] neg_lo:[0,1] neg_hi:[0,1]
	v_mov_b32_e32 v47, v49
	ds_write_b128 v53, v[44:47] offset:16400
	s_waitcnt lgkmcnt(2)
	v_pk_add_f32 v[44:45], v[114:115], v[116:117] neg_lo:[0,1] neg_hi:[0,1]
	s_waitcnt lgkmcnt(1)
	v_pk_add_f32 v[46:47], v[118:119], v[120:121] neg_lo:[0,1] neg_hi:[0,1]
	v_pk_add_f32 v[48:49], v[114:115], v[116:117]
	v_pk_add_f32 v[122:123], v[118:119], v[120:121]
	v_pk_add_f32 v[124:125], v[44:45], v[46:47] op_sel:[0,1] op_sel_hi:[1,0] neg_lo:[0,1] neg_hi:[0,1]
	v_pk_add_f32 v[46:47], v[44:45], v[46:47] op_sel:[0,1] op_sel_hi:[1,0]
	v_pk_add_f32 v[42:43], v[48:49], v[122:123]
	v_mov_b32_e32 v44, v124
	v_mov_b32_e32 v45, v47
	ds_write_b128 v53, v[42:45] offset:32768
	ds_read_b128 v[114:117], v53 offset:49152
	ds_read_b128 v[118:121], v53 offset:49168
	v_pk_add_f32 v[44:45], v[48:49], v[122:123] neg_lo:[0,1] neg_hi:[0,1]
	v_mov_b32_e32 v47, v125
	ds_write_b128 v53, v[44:47] offset:32784
	s_waitcnt lgkmcnt(2)
	v_pk_add_f32 v[44:45], v[114:115], v[116:117] neg_lo:[0,1] neg_hi:[0,1]
	s_waitcnt lgkmcnt(1)
	v_pk_add_f32 v[46:47], v[118:119], v[120:121] neg_lo:[0,1] neg_hi:[0,1]
	v_pk_add_f32 v[48:49], v[114:115], v[116:117]
	v_pk_add_f32 v[122:123], v[118:119], v[120:121]
	v_pk_add_f32 v[114:115], v[44:45], v[46:47] op_sel:[0,1] op_sel_hi:[1,0] neg_lo:[0,1] neg_hi:[0,1]
	v_pk_add_f32 v[46:47], v[44:45], v[46:47] op_sel:[0,1] op_sel_hi:[1,0]
	v_pk_add_f32 v[42:43], v[48:49], v[122:123]
	v_mov_b32_e32 v44, v114
	v_mov_b32_e32 v45, v47
	ds_write_b128 v53, v[42:45] offset:49152
	v_pk_add_f32 v[44:45], v[48:49], v[122:123] neg_lo:[0,1] neg_hi:[0,1]
	v_mov_b32_e32 v47, v115
	v_and_b32_e32 v49, 3, v0
	v_lshlrev_b32_e32 v48, 2, v0
	ds_write_b128 v53, v[44:47] offset:49168
	v_and_or_b32 v42, v48, s5, v49
	v_lshlrev_b32_e32 v46, 13, v49
	v_lshlrev_b32_e32 v47, 7, v49
	v_lshl_add_u32 v53, v42, 3, v205
	v_add3_u32 v55, s85, v46, v47
	s_waitcnt lgkmcnt(0)
	s_barrier
	ds_read2_b64 v[42:45], v53 offset0:8 offset1:12
	ds_read_b64 v[114:115], v55
	v_lshlrev_b32_e32 v46, 12, v49
	v_lshlrev_b32_e32 v47, 6, v49
	v_add3_u32 v57, s85, v46, v47
	ds_read_b64 v[122:123], v57
	s_waitcnt lgkmcnt(1)
	v_pk_mul_f32 v[46:47], v[44:45], v[114:115]
	v_pk_mul_f32 v[44:45], v[44:45], v[114:115] op_sel:[1,0] op_sel_hi:[0,1]
	v_add_f32_e32 v59, v46, v47
	v_sub_f32_e32 v61, v44, v45
	ds_read2_b64 v[44:47], v53 offset1:4
	v_add_f32_e32 v116, v42, v59
	v_add_f32_e32 v118, v43, v61
	v_sub_f32_e32 v42, v42, v59
	v_sub_f32_e32 v120, v43, v61
	s_waitcnt lgkmcnt(0)
	v_pk_mul_f32 v[124:125], v[46:47], v[114:115] op_sel:[1,1] op_sel_hi:[0,1]
	v_pk_fma_f32 v[126:127], v[46:47], v[114:115], v[124:125]
	v_pk_fma_f32 v[46:47], v[46:47], v[114:115], v[124:125] op_sel_hi:[1,0,1] neg_lo:[0,0,1] neg_hi:[0,0,1]
	v_pk_mul_f32 v[114:115], v[122:123], v[116:117] op_sel_hi:[1,0]
	v_mov_b32_e32 v127, v47
	v_pk_fma_f32 v[116:117], v[122:123], v[118:119], v[114:115] op_sel:[1,0,0] op_sel_hi:[0,1,1]
	v_pk_fma_f32 v[114:115], v[122:123], v[118:119], v[114:115] op_sel:[1,0,0] op_sel_hi:[0,0,1] neg_lo:[0,0,1] neg_hi:[0,0,1]
	v_pk_add_f32 v[46:47], v[44:45], v[126:127]
	v_mov_b32_e32 v117, v115
	v_pk_mul_f32 v[42:43], v[122:123], v[42:43] op_sel:[1,0] op_sel_hi:[0,0]
	v_pk_add_f32 v[114:115], v[46:47], v[116:117]
	v_pk_add_f32 v[46:47], v[46:47], v[116:117] neg_lo:[0,1] neg_hi:[0,1]
	v_pk_fma_f32 v[116:117], v[122:123], v[120:121], v[42:43] neg_lo:[0,0,1] neg_hi:[0,0,1]
	v_pk_fma_f32 v[42:43], v[122:123], v[120:121], v[42:43] op_sel_hi:[1,0,1]
	v_pk_add_f32 v[44:45], v[44:45], v[126:127] neg_lo:[0,1] neg_hi:[0,1]
	v_mov_b32_e32 v117, v43
	v_pk_add_f32 v[42:43], v[44:45], v[116:117] neg_lo:[0,1] neg_hi:[0,1]
	v_pk_add_f32 v[44:45], v[44:45], v[116:117]
	v_mov_b32_e32 v116, v42
	v_mov_b32_e32 v117, v45
	v_mov_b32_e32 v45, v43
	v_add_u32_e32 v42, 0x200, v0
	ds_write2_b64 v53, v[46:47], v[44:45] offset0:8 offset1:12
	v_lshlrev_b32_e32 v47, 2, v42
	v_and_or_b32 v43, v47, s5, v49
	ds_write2_b64 v53, v[114:115], v[116:117] offset1:4
	v_lshl_add_u32 v43, v43, 3, v205
	ds_read2_b64 v[114:117], v43 offset0:8 offset1:12
	ds_read_b64 v[44:45], v55
	ds_read_b64 v[124:125], v57
	s_waitcnt lgkmcnt(1)
	v_pk_mul_f32 v[118:119], v[116:117], v[44:45]
	v_pk_mul_f32 v[116:117], v[116:117], v[44:45] op_sel:[1,0] op_sel_hi:[0,1]
	v_add_f32_e32 v53, v118, v119
	v_sub_f32_e32 v59, v116, v117
	ds_read2_b64 v[116:119], v43 offset1:4
	v_add_f32_e32 v46, v114, v53
	v_sub_f32_e32 v114, v114, v53
	v_add_f32_e32 v120, v115, v59
	v_sub_f32_e32 v122, v115, v59
	s_waitcnt lgkmcnt(0)
	v_pk_mul_f32 v[126:127], v[118:119], v[44:45] op_sel:[1,1] op_sel_hi:[0,1]
	v_pk_fma_f32 v[128:129], v[118:119], v[44:45], v[126:127]
	v_pk_fma_f32 v[44:45], v[118:119], v[44:45], v[126:127] op_sel_hi:[1,0,1] neg_lo:[0,0,1] neg_hi:[0,0,1]
	v_pk_mul_f32 v[118:119], v[124:125], v[46:47] op_sel_hi:[1,0]
	v_pk_mul_f32 v[114:115], v[124:125], v[114:115] op_sel:[1,0] op_sel_hi:[0,0]
	v_mov_b32_e32 v129, v45
	v_pk_fma_f32 v[126:127], v[124:125], v[120:121], v[118:119] op_sel:[1,0,0] op_sel_hi:[0,1,1]
	v_pk_fma_f32 v[118:119], v[124:125], v[120:121], v[118:119] op_sel:[1,0,0] op_sel_hi:[0,0,1] neg_lo:[0,0,1] neg_hi:[0,0,1]
	v_pk_fma_f32 v[120:121], v[124:125], v[122:123], v[114:115] neg_lo:[0,0,1] neg_hi:[0,0,1]
	v_pk_fma_f32 v[114:115], v[124:125], v[122:123], v[114:115] op_sel_hi:[1,0,1]
	v_pk_add_f32 v[44:45], v[116:117], v[128:129]
	v_pk_add_f32 v[116:117], v[116:117], v[128:129] neg_lo:[0,1] neg_hi:[0,1]
	v_mov_b32_e32 v121, v115
	v_mov_b32_e32 v127, v119
	v_pk_add_f32 v[114:115], v[116:117], v[120:121] neg_lo:[0,1] neg_hi:[0,1]
	v_pk_add_f32 v[116:117], v[116:117], v[120:121]
	v_pk_add_f32 v[118:119], v[44:45], v[126:127]
	v_pk_add_f32 v[44:45], v[44:45], v[126:127] neg_lo:[0,1] neg_hi:[0,1]
	v_mov_b32_e32 v120, v114
	v_mov_b32_e32 v121, v117
	v_mov_b32_e32 v117, v115
	ds_write2_b64 v43, v[118:119], v[120:121] offset1:4
	ds_write2_b64 v43, v[44:45], v[116:117] offset0:8 offset1:12
	v_add_u32_e32 v43, 0x400, v0
	v_lshlrev_b32_e32 v45, 2, v43
	v_and_or_b32 v44, v45, s5, v49
	v_lshl_add_u32 v53, v44, 3, v205
	ds_read2_b64 v[114:117], v53 offset0:8 offset1:12
	ds_read_b64 v[120:121], v55
	ds_read_b64 v[124:125], v57
	s_waitcnt lgkmcnt(1)
	v_pk_mul_f32 v[118:119], v[116:117], v[120:121]
	v_pk_mul_f32 v[116:117], v[116:117], v[120:121] op_sel:[1,0] op_sel_hi:[0,1]
	v_add_f32_e32 v59, v118, v119
	v_sub_f32_e32 v61, v116, v117
	ds_read2_b64 v[116:119], v53 offset1:4
	v_add_f32_e32 v44, v114, v59
	v_add_f32_e32 v46, v115, v61
	v_sub_f32_e32 v114, v114, v59
	v_sub_f32_e32 v122, v115, v61
	s_waitcnt lgkmcnt(0)
	v_pk_mul_f32 v[126:127], v[118:119], v[120:121] op_sel:[1,1] op_sel_hi:[0,1]
	v_pk_fma_f32 v[128:129], v[118:119], v[120:121], v[126:127]
	v_pk_fma_f32 v[118:119], v[118:119], v[120:121], v[126:127] op_sel_hi:[1,0,1] neg_lo:[0,0,1] neg_hi:[0,0,1]
	v_pk_mul_f32 v[120:121], v[124:125], v[44:45] op_sel_hi:[1,0]
	v_mov_b32_e32 v129, v119
	v_pk_fma_f32 v[126:127], v[124:125], v[46:47], v[120:121] op_sel:[1,0,0] op_sel_hi:[0,1,1]
	v_pk_fma_f32 v[120:121], v[124:125], v[46:47], v[120:121] op_sel:[1,0,0] op_sel_hi:[0,0,1] neg_lo:[0,0,1] neg_hi:[0,0,1]
	v_pk_add_f32 v[118:119], v[116:117], v[128:129]
	v_mov_b32_e32 v127, v121
	v_pk_mul_f32 v[114:115], v[124:125], v[114:115] op_sel:[1,0] op_sel_hi:[0,0]
	v_pk_add_f32 v[120:121], v[118:119], v[126:127]
	v_pk_add_f32 v[118:119], v[118:119], v[126:127] neg_lo:[0,1] neg_hi:[0,1]
	v_pk_fma_f32 v[126:127], v[124:125], v[122:123], v[114:115] neg_lo:[0,0,1] neg_hi:[0,0,1]
	v_pk_fma_f32 v[114:115], v[124:125], v[122:123], v[114:115] op_sel_hi:[1,0,1]
	v_pk_add_f32 v[116:117], v[116:117], v[128:129] neg_lo:[0,1] neg_hi:[0,1]
	v_mov_b32_e32 v127, v115
	v_add_u32_e32 v44, 0x600, v0
	v_pk_add_f32 v[114:115], v[116:117], v[126:127] neg_lo:[0,1] neg_hi:[0,1]
	v_pk_add_f32 v[116:117], v[116:117], v[126:127]
	v_lshlrev_b32_e32 v46, 2, v44
	v_mov_b32_e32 v122, v114
	v_mov_b32_e32 v123, v117
	v_mov_b32_e32 v117, v115
	v_and_or_b32 v49, v46, s5, v49
	ds_write2_b64 v53, v[120:121], v[122:123] offset1:4
	ds_write2_b64 v53, v[118:119], v[116:117] offset0:8 offset1:12
	v_lshl_add_u32 v49, v49, 3, v205
	ds_read2_b64 v[114:117], v49 offset0:8 offset1:12
	ds_read_b64 v[120:121], v55
	ds_read_b64 v[128:129], v57
	v_readlane_b32 s4, v250, 59
	v_readlane_b32 s14, v249, 5
	v_readlane_b32 s15, v249, 6
	s_waitcnt lgkmcnt(1)
	v_pk_mul_f32 v[118:119], v[116:117], v[120:121]
	v_pk_mul_f32 v[116:117], v[116:117], v[120:121] op_sel:[1,0] op_sel_hi:[0,1]
	v_add_f32_e32 v53, v118, v119
	v_sub_f32_e32 v55, v116, v117
	ds_read2_b64 v[116:119], v49 offset1:4
	v_add_f32_e32 v122, v114, v53
	v_add_f32_e32 v124, v115, v55
	v_sub_f32_e32 v114, v114, v53
	v_sub_f32_e32 v126, v115, v55
	s_waitcnt lgkmcnt(0)
	v_pk_mul_f32 v[130:131], v[118:119], v[120:121] op_sel:[1,1] op_sel_hi:[0,1]
	v_pk_fma_f32 v[132:133], v[118:119], v[120:121], v[130:131]
	v_pk_fma_f32 v[118:119], v[118:119], v[120:121], v[130:131] op_sel_hi:[1,0,1] neg_lo:[0,0,1] neg_hi:[0,0,1]
	v_pk_mul_f32 v[120:121], v[128:129], v[122:123] op_sel_hi:[1,0]
	v_mov_b32_e32 v133, v119
	v_pk_fma_f32 v[122:123], v[128:129], v[124:125], v[120:121] op_sel:[1,0,0] op_sel_hi:[0,1,1]
	v_pk_fma_f32 v[120:121], v[128:129], v[124:125], v[120:121] op_sel:[1,0,0] op_sel_hi:[0,0,1] neg_lo:[0,0,1] neg_hi:[0,0,1]
	v_pk_add_f32 v[118:119], v[116:117], v[132:133]
	v_mov_b32_e32 v123, v121
	v_pk_mul_f32 v[114:115], v[128:129], v[114:115] op_sel:[1,0] op_sel_hi:[0,0]
	v_pk_add_f32 v[120:121], v[118:119], v[122:123]
	v_pk_add_f32 v[118:119], v[118:119], v[122:123] neg_lo:[0,1] neg_hi:[0,1]
	v_pk_fma_f32 v[122:123], v[128:129], v[126:127], v[114:115] neg_lo:[0,0,1] neg_hi:[0,0,1]
	v_pk_fma_f32 v[114:115], v[128:129], v[126:127], v[114:115] op_sel_hi:[1,0,1]
	v_pk_add_f32 v[116:117], v[116:117], v[132:133] neg_lo:[0,1] neg_hi:[0,1]
	v_mov_b32_e32 v123, v115
	v_pk_add_f32 v[114:115], v[116:117], v[122:123] neg_lo:[0,1] neg_hi:[0,1]
	v_pk_add_f32 v[116:117], v[116:117], v[122:123]
	v_mov_b32_e32 v122, v114
	v_mov_b32_e32 v123, v117
	v_mov_b32_e32 v117, v115
	ds_write2_b64 v49, v[120:121], v[122:123] offset1:4
	ds_write2_b64 v49, v[118:119], v[116:117] offset0:8 offset1:12
	v_and_b32_e32 v49, 15, v0
	v_and_or_b32 v53, v48, s35, v49
	v_lshlrev_b32_e32 v55, 11, v49
	v_lshlrev_b32_e32 v57, 5, v49
	v_lshl_add_u32 v53, v53, 3, v205
	v_add3_u32 v55, s85, v55, v57
	s_waitcnt lgkmcnt(0)
	s_barrier
	ds_read2_b64 v[114:117], v53 offset0:32 offset1:48
	ds_read_b64 v[120:121], v55
	v_lshlrev_b32_e32 v57, 10, v49
	v_lshlrev_b32_e32 v59, 4, v49
	v_add3_u32 v57, s85, v57, v59
	ds_read_b64 v[128:129], v57
	s_waitcnt lgkmcnt(1)
	v_pk_mul_f32 v[118:119], v[116:117], v[120:121]
	v_pk_mul_f32 v[116:117], v[116:117], v[120:121] op_sel:[1,0] op_sel_hi:[0,1]
	v_add_f32_e32 v59, v118, v119
	v_sub_f32_e32 v61, v116, v117
	ds_read2_b64 v[116:119], v53 offset1:16
	v_add_f32_e32 v122, v114, v59
	v_add_f32_e32 v124, v115, v61
	v_sub_f32_e32 v114, v114, v59
	v_sub_f32_e32 v126, v115, v61
	s_waitcnt lgkmcnt(0)
	v_pk_mul_f32 v[130:131], v[118:119], v[120:121] op_sel:[1,1] op_sel_hi:[0,1]
	v_pk_fma_f32 v[132:133], v[118:119], v[120:121], v[130:131]
	v_pk_fma_f32 v[118:119], v[118:119], v[120:121], v[130:131] op_sel_hi:[1,0,1] neg_lo:[0,0,1] neg_hi:[0,0,1]
	v_pk_mul_f32 v[120:121], v[128:129], v[122:123] op_sel_hi:[1,0]
	v_mov_b32_e32 v133, v119
	v_pk_fma_f32 v[122:123], v[128:129], v[124:125], v[120:121] op_sel:[1,0,0] op_sel_hi:[0,1,1]
	v_pk_fma_f32 v[120:121], v[128:129], v[124:125], v[120:121] op_sel:[1,0,0] op_sel_hi:[0,0,1] neg_lo:[0,0,1] neg_hi:[0,0,1]
	v_pk_add_f32 v[118:119], v[116:117], v[132:133]
	v_mov_b32_e32 v123, v121
	v_pk_mul_f32 v[114:115], v[128:129], v[114:115] op_sel:[1,0] op_sel_hi:[0,0]
	v_pk_add_f32 v[120:121], v[118:119], v[122:123]
	v_pk_add_f32 v[118:119], v[118:119], v[122:123] neg_lo:[0,1] neg_hi:[0,1]
	v_pk_fma_f32 v[122:123], v[128:129], v[126:127], v[114:115] neg_lo:[0,0,1] neg_hi:[0,0,1]
	v_pk_fma_f32 v[114:115], v[128:129], v[126:127], v[114:115] op_sel_hi:[1,0,1]
	v_pk_add_f32 v[116:117], v[116:117], v[132:133] neg_lo:[0,1] neg_hi:[0,1]
	v_mov_b32_e32 v123, v115
	v_pk_add_f32 v[114:115], v[116:117], v[122:123] neg_lo:[0,1] neg_hi:[0,1]
	v_pk_add_f32 v[116:117], v[116:117], v[122:123]
	v_mov_b32_e32 v122, v114
	v_mov_b32_e32 v123, v117
	v_mov_b32_e32 v117, v115
	ds_write2_b64 v53, v[120:121], v[122:123] offset1:16
	ds_write2_b64 v53, v[118:119], v[116:117] offset0:32 offset1:48
	v_and_or_b32 v53, v47, s35, v49
	v_lshl_add_u32 v53, v53, 3, v205
	ds_read2_b64 v[114:117], v53 offset0:32 offset1:48
	ds_read_b64 v[120:121], v55
	ds_read_b64 v[128:129], v57
	v_readlane_b32 s5, v250, 60
	v_readlane_b32 s6, v250, 61
	v_readlane_b32 s7, v250, 62
	s_waitcnt lgkmcnt(1)
	v_pk_mul_f32 v[118:119], v[116:117], v[120:121]
	v_pk_mul_f32 v[116:117], v[116:117], v[120:121] op_sel:[1,0] op_sel_hi:[0,1]
	v_add_f32_e32 v59, v118, v119
	v_sub_f32_e32 v61, v116, v117
	ds_read2_b64 v[116:119], v53 offset1:16
	v_add_f32_e32 v122, v114, v59
	v_add_f32_e32 v124, v115, v61
	v_sub_f32_e32 v114, v114, v59
	v_sub_f32_e32 v126, v115, v61
	s_waitcnt lgkmcnt(0)
	v_pk_mul_f32 v[130:131], v[118:119], v[120:121] op_sel:[1,1] op_sel_hi:[0,1]
	v_pk_fma_f32 v[132:133], v[118:119], v[120:121], v[130:131]
	v_pk_fma_f32 v[118:119], v[118:119], v[120:121], v[130:131] op_sel_hi:[1,0,1] neg_lo:[0,0,1] neg_hi:[0,0,1]
	v_pk_mul_f32 v[120:121], v[128:129], v[122:123] op_sel_hi:[1,0]
	v_mov_b32_e32 v133, v119
	v_pk_fma_f32 v[122:123], v[128:129], v[124:125], v[120:121] op_sel:[1,0,0] op_sel_hi:[0,1,1]
	v_pk_fma_f32 v[120:121], v[128:129], v[124:125], v[120:121] op_sel:[1,0,0] op_sel_hi:[0,0,1] neg_lo:[0,0,1] neg_hi:[0,0,1]
	v_pk_add_f32 v[118:119], v[116:117], v[132:133]
	v_mov_b32_e32 v123, v121
	v_pk_mul_f32 v[114:115], v[128:129], v[114:115] op_sel:[1,0] op_sel_hi:[0,0]
	v_pk_add_f32 v[120:121], v[118:119], v[122:123]
	v_pk_add_f32 v[118:119], v[118:119], v[122:123] neg_lo:[0,1] neg_hi:[0,1]
	v_pk_fma_f32 v[122:123], v[128:129], v[126:127], v[114:115] neg_lo:[0,0,1] neg_hi:[0,0,1]
	v_pk_fma_f32 v[114:115], v[128:129], v[126:127], v[114:115] op_sel_hi:[1,0,1]
	v_pk_add_f32 v[116:117], v[116:117], v[132:133] neg_lo:[0,1] neg_hi:[0,1]
	v_mov_b32_e32 v123, v115
	v_pk_add_f32 v[114:115], v[116:117], v[122:123] neg_lo:[0,1] neg_hi:[0,1]
	v_pk_add_f32 v[116:117], v[116:117], v[122:123]
	v_mov_b32_e32 v122, v114
	v_mov_b32_e32 v123, v117
	v_mov_b32_e32 v117, v115
	ds_write2_b64 v53, v[120:121], v[122:123] offset1:16
	ds_write2_b64 v53, v[118:119], v[116:117] offset0:32 offset1:48
	v_and_or_b32 v53, v45, s35, v49
	v_lshl_add_u32 v53, v53, 3, v205
	ds_read2_b64 v[114:117], v53 offset0:32 offset1:48
	ds_read_b64 v[120:121], v55
	ds_read_b64 v[128:129], v57
	v_and_or_b32 v49, v46, s35, v49
	v_lshl_add_u32 v49, v49, 3, v205
	v_readlane_b32 s8, v250, 63
	s_waitcnt lgkmcnt(1)
	v_pk_mul_f32 v[118:119], v[116:117], v[120:121]
	v_pk_mul_f32 v[116:117], v[116:117], v[120:121] op_sel:[1,0] op_sel_hi:[0,1]
	v_add_f32_e32 v59, v118, v119
	v_sub_f32_e32 v61, v116, v117
	ds_read2_b64 v[116:119], v53 offset1:16
	v_add_f32_e32 v122, v114, v59
	v_add_f32_e32 v124, v115, v61
	v_sub_f32_e32 v114, v114, v59
	v_sub_f32_e32 v126, v115, v61
	s_waitcnt lgkmcnt(0)
	v_pk_mul_f32 v[130:131], v[118:119], v[120:121] op_sel:[1,1] op_sel_hi:[0,1]
	v_pk_fma_f32 v[132:133], v[118:119], v[120:121], v[130:131]
	v_pk_fma_f32 v[118:119], v[118:119], v[120:121], v[130:131] op_sel_hi:[1,0,1] neg_lo:[0,0,1] neg_hi:[0,0,1]
	v_pk_mul_f32 v[120:121], v[128:129], v[122:123] op_sel_hi:[1,0]
	v_mov_b32_e32 v133, v119
	v_pk_fma_f32 v[122:123], v[128:129], v[124:125], v[120:121] op_sel:[1,0,0] op_sel_hi:[0,1,1]
	v_pk_fma_f32 v[120:121], v[128:129], v[124:125], v[120:121] op_sel:[1,0,0] op_sel_hi:[0,0,1] neg_lo:[0,0,1] neg_hi:[0,0,1]
	v_pk_add_f32 v[118:119], v[116:117], v[132:133]
	v_mov_b32_e32 v123, v121
	v_pk_mul_f32 v[114:115], v[128:129], v[114:115] op_sel:[1,0] op_sel_hi:[0,0]
	v_pk_add_f32 v[120:121], v[118:119], v[122:123]
	v_pk_add_f32 v[118:119], v[118:119], v[122:123] neg_lo:[0,1] neg_hi:[0,1]
	v_pk_fma_f32 v[122:123], v[128:129], v[126:127], v[114:115] neg_lo:[0,0,1] neg_hi:[0,0,1]
	v_pk_fma_f32 v[114:115], v[128:129], v[126:127], v[114:115] op_sel_hi:[1,0,1]
	v_pk_add_f32 v[116:117], v[116:117], v[132:133] neg_lo:[0,1] neg_hi:[0,1]
	v_mov_b32_e32 v123, v115
	v_pk_add_f32 v[114:115], v[116:117], v[122:123] neg_lo:[0,1] neg_hi:[0,1]
	v_pk_add_f32 v[116:117], v[116:117], v[122:123]
	v_mov_b32_e32 v122, v114
	v_mov_b32_e32 v123, v117
	v_mov_b32_e32 v117, v115
	ds_write2_b64 v53, v[120:121], v[122:123] offset1:16
	ds_write2_b64 v53, v[118:119], v[116:117] offset0:32 offset1:48
	ds_read2_b64 v[114:117], v49 offset0:32 offset1:48
	ds_read_b64 v[120:121], v55
	ds_read_b64 v[128:129], v57
	v_readlane_b32 s9, v249, 0
	v_readlane_b32 s10, v249, 1
	v_readlane_b32 s11, v249, 2
	s_waitcnt lgkmcnt(1)
	v_pk_mul_f32 v[118:119], v[116:117], v[120:121]
	v_pk_mul_f32 v[116:117], v[116:117], v[120:121] op_sel:[1,0] op_sel_hi:[0,1]
	v_add_f32_e32 v53, v118, v119
	v_sub_f32_e32 v55, v116, v117
	ds_read2_b64 v[116:119], v49 offset1:16
	v_add_f32_e32 v122, v114, v53
	v_add_f32_e32 v124, v115, v55
	v_sub_f32_e32 v114, v114, v53
	v_sub_f32_e32 v126, v115, v55
	s_waitcnt lgkmcnt(0)
	v_pk_mul_f32 v[130:131], v[118:119], v[120:121] op_sel:[1,1] op_sel_hi:[0,1]
	v_pk_fma_f32 v[132:133], v[118:119], v[120:121], v[130:131]
	v_pk_fma_f32 v[118:119], v[118:119], v[120:121], v[130:131] op_sel_hi:[1,0,1] neg_lo:[0,0,1] neg_hi:[0,0,1]
	v_pk_mul_f32 v[120:121], v[128:129], v[122:123] op_sel_hi:[1,0]
	v_mov_b32_e32 v133, v119
	v_pk_fma_f32 v[122:123], v[128:129], v[124:125], v[120:121] op_sel:[1,0,0] op_sel_hi:[0,1,1]
	v_pk_fma_f32 v[120:121], v[128:129], v[124:125], v[120:121] op_sel:[1,0,0] op_sel_hi:[0,0,1] neg_lo:[0,0,1] neg_hi:[0,0,1]
	v_pk_add_f32 v[118:119], v[116:117], v[132:133]
	v_mov_b32_e32 v123, v121
	v_pk_mul_f32 v[114:115], v[128:129], v[114:115] op_sel:[1,0] op_sel_hi:[0,0]
	v_pk_add_f32 v[120:121], v[118:119], v[122:123]
	v_pk_add_f32 v[118:119], v[118:119], v[122:123] neg_lo:[0,1] neg_hi:[0,1]
	v_pk_fma_f32 v[122:123], v[128:129], v[126:127], v[114:115] neg_lo:[0,0,1] neg_hi:[0,0,1]
	v_pk_fma_f32 v[114:115], v[128:129], v[126:127], v[114:115] op_sel_hi:[1,0,1]
	v_pk_add_f32 v[116:117], v[116:117], v[132:133] neg_lo:[0,1] neg_hi:[0,1]
	v_mov_b32_e32 v123, v115
	v_pk_add_f32 v[114:115], v[116:117], v[122:123] neg_lo:[0,1] neg_hi:[0,1]
	v_pk_add_f32 v[116:117], v[116:117], v[122:123]
	v_mov_b32_e32 v122, v114
	v_mov_b32_e32 v123, v117
	v_mov_b32_e32 v117, v115
	v_and_b32_e32 v53, 63, v0
	ds_write2_b64 v49, v[120:121], v[122:123] offset1:16
	ds_write2_b64 v49, v[118:119], v[116:117] offset0:32 offset1:48
	v_ashrrev_i32_e32 v49, 6, v0
	v_lshlrev_b32_e32 v59, 3, v53
	v_lshl_or_b32 v55, v49, 11, v59
	v_lshlrev_b32_e32 v57, 9, v53
	v_add_u32_e32 v55, 0x50, v55
	v_add3_u32 v61, s85, v57, v59
	s_waitcnt lgkmcnt(0)
	s_barrier
	ds_read2st64_b64 v[114:117], v55 offset0:2 offset1:3
	ds_read_b64 v[120:121], v61
	v_lshlrev_b32_e32 v53, 8, v53
	v_and_b32_e32 v57, 0xf8, v48
	v_add3_u32 v63, s85, v53, v57
	ds_read_b64 v[128:129], v63
	s_waitcnt lgkmcnt(1)
	v_pk_mul_f32 v[118:119], v[116:117], v[120:121]
	v_pk_mul_f32 v[116:117], v[116:117], v[120:121] op_sel:[1,0] op_sel_hi:[0,1]
	v_add_f32_e32 v53, v118, v119
	v_sub_f32_e32 v57, v116, v117
	ds_read2st64_b64 v[116:119], v55 offset1:1
	v_add_f32_e32 v122, v114, v53
	v_add_f32_e32 v124, v115, v57
	v_sub_f32_e32 v114, v114, v53
	v_sub_f32_e32 v126, v115, v57
	s_waitcnt lgkmcnt(0)
	v_pk_mul_f32 v[130:131], v[118:119], v[120:121] op_sel:[1,1] op_sel_hi:[0,1]
	v_pk_fma_f32 v[132:133], v[118:119], v[120:121], v[130:131]
	v_pk_fma_f32 v[118:119], v[118:119], v[120:121], v[130:131] op_sel_hi:[1,0,1] neg_lo:[0,0,1] neg_hi:[0,0,1]
	v_pk_mul_f32 v[120:121], v[128:129], v[122:123] op_sel_hi:[1,0]
	v_mov_b32_e32 v133, v119
	v_pk_fma_f32 v[122:123], v[128:129], v[124:125], v[120:121] op_sel:[1,0,0] op_sel_hi:[0,1,1]
	v_pk_fma_f32 v[120:121], v[128:129], v[124:125], v[120:121] op_sel:[1,0,0] op_sel_hi:[0,0,1] neg_lo:[0,0,1] neg_hi:[0,0,1]
	v_pk_add_f32 v[118:119], v[116:117], v[132:133]
	v_mov_b32_e32 v123, v121
	v_pk_mul_f32 v[114:115], v[128:129], v[114:115] op_sel:[1,0] op_sel_hi:[0,0]
	v_pk_add_f32 v[120:121], v[118:119], v[122:123]
	v_pk_add_f32 v[118:119], v[118:119], v[122:123] neg_lo:[0,1] neg_hi:[0,1]
	v_pk_fma_f32 v[122:123], v[128:129], v[126:127], v[114:115] neg_lo:[0,0,1] neg_hi:[0,0,1]
	v_pk_fma_f32 v[114:115], v[128:129], v[126:127], v[114:115] op_sel_hi:[1,0,1]
	v_pk_add_f32 v[116:117], v[116:117], v[132:133] neg_lo:[0,1] neg_hi:[0,1]
	v_mov_b32_e32 v123, v115
	v_pk_add_f32 v[114:115], v[116:117], v[122:123] neg_lo:[0,1] neg_hi:[0,1]
	v_pk_add_f32 v[116:117], v[116:117], v[122:123]
	v_mov_b32_e32 v122, v114
	v_mov_b32_e32 v123, v117
	v_mov_b32_e32 v117, v115
	v_ashrrev_i32_e32 v53, 6, v42
	ds_write2st64_b64 v55, v[120:121], v[122:123] offset1:1
	ds_write2st64_b64 v55, v[118:119], v[116:117] offset0:2 offset1:3
	v_lshl_or_b32 v55, v53, 11, v59
	v_add_u32_e32 v55, 0x50, v55
	ds_read2st64_b64 v[114:117], v55 offset0:2 offset1:3
	ds_read_b64 v[120:121], v61
	ds_read_b64 v[128:129], v63
	v_readlane_b32 s12, v249, 3
	v_readlane_b32 s13, v249, 4
	v_readlane_b32 s16, v249, 7
	s_waitcnt lgkmcnt(1)
	v_pk_mul_f32 v[118:119], v[116:117], v[120:121]
	v_pk_mul_f32 v[116:117], v[116:117], v[120:121] op_sel:[1,0] op_sel_hi:[0,1]
	v_add_f32_e32 v57, v118, v119
	v_sub_f32_e32 v65, v116, v117
	ds_read2st64_b64 v[116:119], v55 offset1:1
	v_add_f32_e32 v122, v114, v57
	v_add_f32_e32 v124, v115, v65
	v_sub_f32_e32 v114, v114, v57
	v_sub_f32_e32 v126, v115, v65
	s_waitcnt lgkmcnt(0)
	v_pk_mul_f32 v[130:131], v[118:119], v[120:121] op_sel:[1,1] op_sel_hi:[0,1]
	v_pk_fma_f32 v[132:133], v[118:119], v[120:121], v[130:131]
	v_pk_fma_f32 v[118:119], v[118:119], v[120:121], v[130:131] op_sel_hi:[1,0,1] neg_lo:[0,0,1] neg_hi:[0,0,1]
	v_pk_mul_f32 v[120:121], v[128:129], v[122:123] op_sel_hi:[1,0]
	v_mov_b32_e32 v133, v119
	v_pk_fma_f32 v[122:123], v[128:129], v[124:125], v[120:121] op_sel:[1,0,0] op_sel_hi:[0,1,1]
	v_pk_fma_f32 v[120:121], v[128:129], v[124:125], v[120:121] op_sel:[1,0,0] op_sel_hi:[0,0,1] neg_lo:[0,0,1] neg_hi:[0,0,1]
	v_pk_add_f32 v[118:119], v[116:117], v[132:133]
	v_mov_b32_e32 v123, v121
	v_pk_mul_f32 v[114:115], v[128:129], v[114:115] op_sel:[1,0] op_sel_hi:[0,0]
	v_pk_add_f32 v[120:121], v[118:119], v[122:123]
	v_pk_add_f32 v[118:119], v[118:119], v[122:123] neg_lo:[0,1] neg_hi:[0,1]
	v_pk_fma_f32 v[122:123], v[128:129], v[126:127], v[114:115] neg_lo:[0,0,1] neg_hi:[0,0,1]
	v_pk_fma_f32 v[114:115], v[128:129], v[126:127], v[114:115] op_sel_hi:[1,0,1]
	v_pk_add_f32 v[116:117], v[116:117], v[132:133] neg_lo:[0,1] neg_hi:[0,1]
	v_mov_b32_e32 v123, v115
	v_pk_add_f32 v[114:115], v[116:117], v[122:123] neg_lo:[0,1] neg_hi:[0,1]
	v_pk_add_f32 v[116:117], v[116:117], v[122:123]
	v_mov_b32_e32 v122, v114
	v_mov_b32_e32 v123, v117
	v_mov_b32_e32 v117, v115
	ds_write2st64_b64 v55, v[120:121], v[122:123] offset1:1
	ds_write2st64_b64 v55, v[118:119], v[116:117] offset0:2 offset1:3
	v_ashrrev_i32_e32 v55, 6, v43
	v_lshl_or_b32 v57, v55, 11, v59
	v_add_u32_e32 v57, 0x50, v57
	ds_read2st64_b64 v[114:117], v57 offset0:2 offset1:3
	ds_read_b64 v[120:121], v61
	ds_read_b64 v[128:129], v63
	v_lshlrev_b32_e32 v43, 3, v43
	v_readlane_b32 s17, v249, 8
	v_readlane_b32 s18, v249, 9
	s_waitcnt lgkmcnt(1)
	v_pk_mul_f32 v[118:119], v[116:117], v[120:121]
	v_pk_mul_f32 v[116:117], v[116:117], v[120:121] op_sel:[1,0] op_sel_hi:[0,1]
	v_add_f32_e32 v65, v118, v119
	v_sub_f32_e32 v123, v116, v117
	ds_read2st64_b64 v[116:119], v57 offset1:1
	v_add_f32_e32 v122, v114, v65
	v_add_f32_e32 v124, v115, v123
	v_sub_f32_e32 v114, v114, v65
	v_sub_f32_e32 v126, v115, v123
	s_waitcnt lgkmcnt(0)
	v_pk_mul_f32 v[130:131], v[118:119], v[120:121] op_sel:[1,1] op_sel_hi:[0,1]
	v_pk_fma_f32 v[132:133], v[118:119], v[120:121], v[130:131]
	v_pk_fma_f32 v[118:119], v[118:119], v[120:121], v[130:131] op_sel_hi:[1,0,1] neg_lo:[0,0,1] neg_hi:[0,0,1]
	v_pk_mul_f32 v[120:121], v[128:129], v[122:123] op_sel_hi:[1,0]
	v_mov_b32_e32 v133, v119
	v_pk_fma_f32 v[122:123], v[128:129], v[124:125], v[120:121] op_sel:[1,0,0] op_sel_hi:[0,1,1]
	v_pk_fma_f32 v[120:121], v[128:129], v[124:125], v[120:121] op_sel:[1,0,0] op_sel_hi:[0,0,1] neg_lo:[0,0,1] neg_hi:[0,0,1]
	v_pk_add_f32 v[118:119], v[116:117], v[132:133]
	v_mov_b32_e32 v123, v121
	v_pk_mul_f32 v[114:115], v[128:129], v[114:115] op_sel:[1,0] op_sel_hi:[0,0]
	v_pk_add_f32 v[120:121], v[118:119], v[122:123]
	v_pk_add_f32 v[118:119], v[118:119], v[122:123] neg_lo:[0,1] neg_hi:[0,1]
	v_pk_fma_f32 v[122:123], v[128:129], v[126:127], v[114:115] neg_lo:[0,0,1] neg_hi:[0,0,1]
	v_pk_fma_f32 v[114:115], v[128:129], v[126:127], v[114:115] op_sel_hi:[1,0,1]
	v_pk_add_f32 v[116:117], v[116:117], v[132:133] neg_lo:[0,1] neg_hi:[0,1]
	v_mov_b32_e32 v123, v115
	v_pk_add_f32 v[114:115], v[116:117], v[122:123] neg_lo:[0,1] neg_hi:[0,1]
	v_pk_add_f32 v[116:117], v[116:117], v[122:123]
	v_mov_b32_e32 v122, v114
	v_mov_b32_e32 v123, v117
	v_mov_b32_e32 v117, v115
	ds_write2st64_b64 v57, v[120:121], v[122:123] offset1:1
	ds_write2st64_b64 v57, v[118:119], v[116:117] offset0:2 offset1:3
	v_ashrrev_i32_e32 v57, 6, v44
	v_lshl_or_b32 v59, v57, 11, v59
	v_add_u32_e32 v59, 0x50, v59
	ds_read2st64_b64 v[114:117], v59 offset0:2 offset1:3
	ds_read_b64 v[120:121], v61
	ds_read_b64 v[128:129], v63
	v_readlane_b32 s19, v249, 10
	s_waitcnt lgkmcnt(1)
	v_pk_mul_f32 v[118:119], v[116:117], v[120:121]
	v_pk_mul_f32 v[116:117], v[116:117], v[120:121] op_sel:[1,0] op_sel_hi:[0,1]
	v_add_f32_e32 v61, v118, v119
	v_sub_f32_e32 v65, v116, v117
	ds_read2st64_b64 v[116:119], v59 offset1:1
	v_add_f32_e32 v122, v114, v61
	v_add_f32_e32 v124, v115, v65
	v_sub_f32_e32 v114, v114, v61
	v_sub_f32_e32 v126, v115, v65
	s_waitcnt lgkmcnt(0)
	v_pk_mul_f32 v[130:131], v[118:119], v[120:121] op_sel:[1,1] op_sel_hi:[0,1]
	v_pk_fma_f32 v[132:133], v[118:119], v[120:121], v[130:131]
	v_pk_fma_f32 v[118:119], v[118:119], v[120:121], v[130:131] op_sel_hi:[1,0,1] neg_lo:[0,0,1] neg_hi:[0,0,1]
	v_pk_mul_f32 v[120:121], v[128:129], v[122:123] op_sel_hi:[1,0]
	v_mov_b32_e32 v133, v119
	v_pk_fma_f32 v[122:123], v[128:129], v[124:125], v[120:121] op_sel:[1,0,0] op_sel_hi:[0,1,1]
	v_pk_fma_f32 v[120:121], v[128:129], v[124:125], v[120:121] op_sel:[1,0,0] op_sel_hi:[0,0,1] neg_lo:[0,0,1] neg_hi:[0,0,1]
	v_pk_add_f32 v[118:119], v[116:117], v[132:133]
	v_mov_b32_e32 v123, v121
	v_pk_mul_f32 v[114:115], v[128:129], v[114:115] op_sel:[1,0] op_sel_hi:[0,0]
	v_pk_add_f32 v[120:121], v[118:119], v[122:123]
	v_pk_add_f32 v[118:119], v[118:119], v[122:123] neg_lo:[0,1] neg_hi:[0,1]
	v_pk_fma_f32 v[122:123], v[128:129], v[126:127], v[114:115] neg_lo:[0,0,1] neg_hi:[0,0,1]
	v_pk_fma_f32 v[114:115], v[128:129], v[126:127], v[114:115] op_sel_hi:[1,0,1]
	v_pk_add_f32 v[116:117], v[116:117], v[132:133] neg_lo:[0,1] neg_hi:[0,1]
	v_mov_b32_e32 v123, v115
	v_pk_add_f32 v[114:115], v[116:117], v[122:123] neg_lo:[0,1] neg_hi:[0,1]
	v_pk_add_f32 v[116:117], v[116:117], v[122:123]
	v_mov_b32_e32 v122, v114
	v_mov_b32_e32 v123, v117
	v_mov_b32_e32 v117, v115
	ds_write2st64_b64 v59, v[120:121], v[122:123] offset1:1
	ds_write2st64_b64 v59, v[118:119], v[116:117] offset0:2 offset1:3
	v_and_b32_e32 v59, 0xff, v0
	v_lshlrev_b32_e32 v65, 1, v0
	v_and_or_b32 v61, v48, s34, v59
	v_lshlrev_b32_e32 v63, 7, v59
	v_and_b32_e32 v65, 0x1f8, v65
	v_lshl_add_u32 v61, v61, 3, v205
	v_add3_u32 v63, s85, v63, v65
	s_waitcnt lgkmcnt(0)
	s_barrier
	ds_read2st64_b64 v[114:117], v61 offset0:8 offset1:12
	ds_read_b64 v[120:121], v63
	v_lshlrev_b32_e32 v65, 6, v59
	v_and_b32_e32 v118, 0xf8, v0
	v_add3_u32 v65, s85, v65, v118
	ds_read_b64 v[128:129], v65
	s_waitcnt lgkmcnt(1)
	v_pk_mul_f32 v[118:119], v[116:117], v[120:121]
	v_pk_mul_f32 v[116:117], v[116:117], v[120:121] op_sel:[1,0] op_sel_hi:[0,1]
	v_add_f32_e32 v123, v118, v119
	v_sub_f32_e32 v125, v116, v117
	ds_read2st64_b64 v[116:119], v61 offset1:4
	v_add_f32_e32 v122, v114, v123
	v_add_f32_e32 v124, v115, v125
	v_sub_f32_e32 v114, v114, v123
	v_sub_f32_e32 v126, v115, v125
	s_waitcnt lgkmcnt(0)
	v_pk_mul_f32 v[130:131], v[118:119], v[120:121] op_sel:[1,1] op_sel_hi:[0,1]
	v_pk_fma_f32 v[132:133], v[118:119], v[120:121], v[130:131]
	v_pk_fma_f32 v[118:119], v[118:119], v[120:121], v[130:131] op_sel_hi:[1,0,1] neg_lo:[0,0,1] neg_hi:[0,0,1]
	v_pk_mul_f32 v[120:121], v[128:129], v[122:123] op_sel_hi:[1,0]
	v_mov_b32_e32 v133, v119
	v_pk_fma_f32 v[122:123], v[128:129], v[124:125], v[120:121] op_sel:[1,0,0] op_sel_hi:[0,1,1]
	v_pk_fma_f32 v[120:121], v[128:129], v[124:125], v[120:121] op_sel:[1,0,0] op_sel_hi:[0,0,1] neg_lo:[0,0,1] neg_hi:[0,0,1]
	v_pk_add_f32 v[118:119], v[116:117], v[132:133]
	v_mov_b32_e32 v123, v121
	v_pk_mul_f32 v[114:115], v[128:129], v[114:115] op_sel:[1,0] op_sel_hi:[0,0]
	v_pk_add_f32 v[120:121], v[118:119], v[122:123]
	v_pk_add_f32 v[118:119], v[118:119], v[122:123] neg_lo:[0,1] neg_hi:[0,1]
	v_pk_fma_f32 v[122:123], v[128:129], v[126:127], v[114:115] neg_lo:[0,0,1] neg_hi:[0,0,1]
	v_pk_fma_f32 v[114:115], v[128:129], v[126:127], v[114:115] op_sel_hi:[1,0,1]
	v_pk_add_f32 v[116:117], v[116:117], v[132:133] neg_lo:[0,1] neg_hi:[0,1]
	v_mov_b32_e32 v123, v115
	v_pk_add_f32 v[114:115], v[116:117], v[122:123] neg_lo:[0,1] neg_hi:[0,1]
	v_pk_add_f32 v[116:117], v[116:117], v[122:123]
	v_mov_b32_e32 v122, v114
	v_mov_b32_e32 v123, v117
	v_mov_b32_e32 v117, v115
	ds_write2st64_b64 v61, v[120:121], v[122:123] offset1:4
	ds_write2st64_b64 v61, v[118:119], v[116:117] offset0:8 offset1:12
	v_and_or_b32 v61, v47, s34, v59
	v_lshl_add_u32 v61, v61, 3, v205
	ds_read2st64_b64 v[114:117], v61 offset0:8 offset1:12
	ds_read_b64 v[120:121], v63
	ds_read_b64 v[128:129], v65
	s_waitcnt lgkmcnt(1)
	v_pk_mul_f32 v[118:119], v[116:117], v[120:121]
	v_pk_mul_f32 v[116:117], v[116:117], v[120:121] op_sel:[1,0] op_sel_hi:[0,1]
	v_add_f32_e32 v123, v118, v119
	v_sub_f32_e32 v125, v116, v117
	ds_read2st64_b64 v[116:119], v61 offset1:4
	v_add_f32_e32 v122, v114, v123
	v_add_f32_e32 v124, v115, v125
	v_sub_f32_e32 v114, v114, v123
	v_sub_f32_e32 v126, v115, v125
	s_waitcnt lgkmcnt(0)
	v_pk_mul_f32 v[130:131], v[118:119], v[120:121] op_sel:[1,1] op_sel_hi:[0,1]
	v_pk_fma_f32 v[132:133], v[118:119], v[120:121], v[130:131]
	v_pk_fma_f32 v[118:119], v[118:119], v[120:121], v[130:131] op_sel_hi:[1,0,1] neg_lo:[0,0,1] neg_hi:[0,0,1]
	v_pk_mul_f32 v[120:121], v[128:129], v[122:123] op_sel_hi:[1,0]
	v_mov_b32_e32 v133, v119
	v_pk_fma_f32 v[122:123], v[128:129], v[124:125], v[120:121] op_sel:[1,0,0] op_sel_hi:[0,1,1]
	v_pk_fma_f32 v[120:121], v[128:129], v[124:125], v[120:121] op_sel:[1,0,0] op_sel_hi:[0,0,1] neg_lo:[0,0,1] neg_hi:[0,0,1]
	v_pk_add_f32 v[118:119], v[116:117], v[132:133]
	v_mov_b32_e32 v123, v121
	v_pk_mul_f32 v[114:115], v[128:129], v[114:115] op_sel:[1,0] op_sel_hi:[0,0]
	v_pk_add_f32 v[120:121], v[118:119], v[122:123]
	v_pk_add_f32 v[118:119], v[118:119], v[122:123] neg_lo:[0,1] neg_hi:[0,1]
	v_pk_fma_f32 v[122:123], v[128:129], v[126:127], v[114:115] neg_lo:[0,0,1] neg_hi:[0,0,1]
	v_pk_fma_f32 v[114:115], v[128:129], v[126:127], v[114:115] op_sel_hi:[1,0,1]
	v_pk_add_f32 v[116:117], v[116:117], v[132:133] neg_lo:[0,1] neg_hi:[0,1]
	v_mov_b32_e32 v123, v115
	v_pk_add_f32 v[114:115], v[116:117], v[122:123] neg_lo:[0,1] neg_hi:[0,1]
	v_pk_add_f32 v[116:117], v[116:117], v[122:123]
	v_mov_b32_e32 v122, v114
	v_mov_b32_e32 v123, v117
	v_mov_b32_e32 v117, v115
	ds_write2st64_b64 v61, v[120:121], v[122:123] offset1:4
	ds_write2st64_b64 v61, v[118:119], v[116:117] offset0:8 offset1:12
	v_and_or_b32 v61, v45, s34, v59
	v_lshl_add_u32 v61, v61, 3, v205
	ds_read2st64_b64 v[114:117], v61 offset0:8 offset1:12
	ds_read_b64 v[120:121], v63
	ds_read_b64 v[128:129], v65
	v_and_or_b32 v59, v46, s34, v59
	v_lshl_add_u32 v59, v59, 3, v205
	s_add_u32 s34, s0, 0x400
	s_waitcnt lgkmcnt(1)
	v_pk_mul_f32 v[118:119], v[116:117], v[120:121]
	v_pk_mul_f32 v[116:117], v[116:117], v[120:121] op_sel:[1,0] op_sel_hi:[0,1]
	v_add_f32_e32 v123, v118, v119
	v_sub_f32_e32 v125, v116, v117
	ds_read2st64_b64 v[116:119], v61 offset1:4
	v_add_f32_e32 v122, v114, v123
	v_add_f32_e32 v124, v115, v125
	v_sub_f32_e32 v114, v114, v123
	v_sub_f32_e32 v126, v115, v125
	s_waitcnt lgkmcnt(0)
	v_pk_mul_f32 v[130:131], v[118:119], v[120:121] op_sel:[1,1] op_sel_hi:[0,1]
	v_pk_fma_f32 v[132:133], v[118:119], v[120:121], v[130:131]
	v_pk_fma_f32 v[118:119], v[118:119], v[120:121], v[130:131] op_sel_hi:[1,0,1] neg_lo:[0,0,1] neg_hi:[0,0,1]
	v_pk_mul_f32 v[120:121], v[128:129], v[122:123] op_sel_hi:[1,0]
	v_mov_b32_e32 v133, v119
	v_pk_fma_f32 v[122:123], v[128:129], v[124:125], v[120:121] op_sel:[1,0,0] op_sel_hi:[0,1,1]
	v_pk_fma_f32 v[120:121], v[128:129], v[124:125], v[120:121] op_sel:[1,0,0] op_sel_hi:[0,0,1] neg_lo:[0,0,1] neg_hi:[0,0,1]
	v_pk_add_f32 v[118:119], v[116:117], v[132:133]
	v_mov_b32_e32 v123, v121
	v_pk_mul_f32 v[114:115], v[128:129], v[114:115] op_sel:[1,0] op_sel_hi:[0,0]
	v_pk_add_f32 v[120:121], v[118:119], v[122:123]
	v_pk_add_f32 v[118:119], v[118:119], v[122:123] neg_lo:[0,1] neg_hi:[0,1]
	v_pk_fma_f32 v[122:123], v[128:129], v[126:127], v[114:115] neg_lo:[0,0,1] neg_hi:[0,0,1]
	v_pk_fma_f32 v[114:115], v[128:129], v[126:127], v[114:115] op_sel_hi:[1,0,1]
	v_pk_add_f32 v[116:117], v[116:117], v[132:133] neg_lo:[0,1] neg_hi:[0,1]
	v_mov_b32_e32 v123, v115
	v_pk_add_f32 v[114:115], v[116:117], v[122:123] neg_lo:[0,1] neg_hi:[0,1]
	v_pk_add_f32 v[116:117], v[116:117], v[122:123]
	v_mov_b32_e32 v122, v114
	v_mov_b32_e32 v123, v117
	v_mov_b32_e32 v117, v115
	ds_write2st64_b64 v61, v[120:121], v[122:123] offset1:4
	ds_write2st64_b64 v61, v[118:119], v[116:117] offset0:8 offset1:12
	ds_read2st64_b64 v[114:117], v59 offset0:8 offset1:12
	ds_read_b64 v[120:121], v63
	ds_read_b64 v[128:129], v65
	v_lshrrev_b32_e32 v65, 2, v0
	v_and_b32_e32 v65, 0xf8, v65
	s_addc_u32 s35, s1, 0
	s_waitcnt lgkmcnt(1)
	v_pk_mul_f32 v[118:119], v[116:117], v[120:121]
	v_pk_mul_f32 v[116:117], v[116:117], v[120:121] op_sel:[1,0] op_sel_hi:[0,1]
	v_add_f32_e32 v61, v118, v119
	v_sub_f32_e32 v63, v116, v117
	ds_read2st64_b64 v[116:119], v59 offset1:4
	v_add_f32_e32 v122, v114, v61
	v_add_f32_e32 v124, v115, v63
	v_sub_f32_e32 v114, v114, v61
	v_sub_f32_e32 v126, v115, v63
	s_waitcnt lgkmcnt(0)
	v_pk_mul_f32 v[130:131], v[118:119], v[120:121] op_sel:[1,1] op_sel_hi:[0,1]
	v_pk_fma_f32 v[132:133], v[118:119], v[120:121], v[130:131]
	v_pk_fma_f32 v[118:119], v[118:119], v[120:121], v[130:131] op_sel_hi:[1,0,1] neg_lo:[0,0,1] neg_hi:[0,0,1]
	v_pk_mul_f32 v[120:121], v[128:129], v[122:123] op_sel_hi:[1,0]
	v_mov_b32_e32 v133, v119
	v_pk_fma_f32 v[122:123], v[128:129], v[124:125], v[120:121] op_sel:[1,0,0] op_sel_hi:[0,1,1]
	v_pk_fma_f32 v[120:121], v[128:129], v[124:125], v[120:121] op_sel:[1,0,0] op_sel_hi:[0,0,1] neg_lo:[0,0,1] neg_hi:[0,0,1]
	v_pk_add_f32 v[118:119], v[116:117], v[132:133]
	v_mov_b32_e32 v123, v121
	v_pk_mul_f32 v[114:115], v[128:129], v[114:115] op_sel:[1,0] op_sel_hi:[0,0]
	v_pk_add_f32 v[120:121], v[118:119], v[122:123]
	v_pk_add_f32 v[118:119], v[118:119], v[122:123] neg_lo:[0,1] neg_hi:[0,1]
	v_pk_fma_f32 v[122:123], v[128:129], v[126:127], v[114:115] neg_lo:[0,0,1] neg_hi:[0,0,1]
	v_pk_fma_f32 v[114:115], v[128:129], v[126:127], v[114:115] op_sel_hi:[1,0,1]
	v_pk_add_f32 v[116:117], v[116:117], v[132:133] neg_lo:[0,1] neg_hi:[0,1]
	v_mov_b32_e32 v123, v115
	v_pk_add_f32 v[114:115], v[116:117], v[122:123] neg_lo:[0,1] neg_hi:[0,1]
	v_pk_add_f32 v[116:117], v[116:117], v[122:123]
	v_mov_b32_e32 v122, v114
	v_mov_b32_e32 v123, v117
	v_mov_b32_e32 v117, v115
	ds_write2st64_b64 v59, v[120:121], v[122:123] offset1:4
	ds_write2st64_b64 v59, v[118:119], v[116:117] offset0:8 offset1:12
	v_and_b32_e32 v59, 0x3ff, v0
	v_and_or_b32 v48, v48, s26, v59
	v_lshrrev_b32_e32 v63, 1, v0
	v_lshl_add_u32 v61, v48, 3, v205
	v_lshlrev_b32_e32 v48, 5, v59
	v_and_b32_e32 v63, 0x1f8, v63
	v_add3_u32 v63, s85, v48, v63
	s_waitcnt lgkmcnt(0)
	s_barrier
	ds_read2st64_b64 v[114:117], v61 offset0:32 offset1:48
	ds_read_b64 v[120:121], v63
	v_lshlrev_b32_e32 v48, 4, v59
	v_add3_u32 v65, s85, v48, v65
	ds_read_b64 v[126:127], v65
	v_and_or_b32 v45, v45, s26, v59
	s_waitcnt lgkmcnt(1)
	v_pk_mul_f32 v[118:119], v[116:117], v[120:121]
	v_pk_mul_f32 v[116:117], v[116:117], v[120:121] op_sel:[1,0] op_sel_hi:[0,1]
	v_add_f32_e32 v123, v118, v119
	v_sub_f32_e32 v124, v116, v117
	ds_read2st64_b64 v[116:119], v61 offset1:16
	v_add_f32_e32 v48, v114, v123
	v_sub_f32_e32 v114, v114, v123
	v_add_f32_e32 v122, v115, v124
	v_sub_f32_e32 v124, v115, v124
	s_waitcnt lgkmcnt(0)
	v_pk_mul_f32 v[128:129], v[118:119], v[120:121] op_sel:[1,1] op_sel_hi:[0,1]
	v_pk_fma_f32 v[130:131], v[118:119], v[120:121], v[128:129]
	v_pk_fma_f32 v[118:119], v[118:119], v[120:121], v[128:129] op_sel_hi:[1,0,1] neg_lo:[0,0,1] neg_hi:[0,0,1]
	v_pk_mul_f32 v[120:121], v[126:127], v[48:49] op_sel_hi:[1,0]
	v_pk_mul_f32 v[114:115], v[126:127], v[114:115] op_sel:[1,0] op_sel_hi:[0,0]
	v_mov_b32_e32 v131, v119
	v_pk_fma_f32 v[128:129], v[126:127], v[122:123], v[120:121] op_sel:[1,0,0] op_sel_hi:[0,1,1]
	v_pk_fma_f32 v[120:121], v[126:127], v[122:123], v[120:121] op_sel:[1,0,0] op_sel_hi:[0,0,1] neg_lo:[0,0,1] neg_hi:[0,0,1]
	v_pk_fma_f32 v[122:123], v[126:127], v[124:125], v[114:115] neg_lo:[0,0,1] neg_hi:[0,0,1]
	v_pk_fma_f32 v[114:115], v[126:127], v[124:125], v[114:115] op_sel_hi:[1,0,1]
	v_pk_add_f32 v[118:119], v[116:117], v[130:131]
	v_pk_add_f32 v[116:117], v[116:117], v[130:131] neg_lo:[0,1] neg_hi:[0,1]
	v_mov_b32_e32 v123, v115
	v_mov_b32_e32 v129, v121
	v_pk_add_f32 v[114:115], v[116:117], v[122:123] neg_lo:[0,1] neg_hi:[0,1]
	v_pk_add_f32 v[116:117], v[116:117], v[122:123]
	v_pk_add_f32 v[120:121], v[118:119], v[128:129]
	v_pk_add_f32 v[118:119], v[118:119], v[128:129] neg_lo:[0,1] neg_hi:[0,1]
	v_mov_b32_e32 v123, v117
	v_mov_b32_e32 v117, v115
	v_mov_b32_e32 v122, v114
	ds_write2st64_b64 v61, v[118:119], v[116:117] offset0:32 offset1:48
	v_and_b32_e32 v48, 0x3ff, v42
	v_lshrrev_b32_e32 v118, 1, v42
	ds_write2st64_b64 v61, v[120:121], v[122:123] offset1:16
	v_and_or_b32 v47, v47, s26, v48
	v_lshlrev_b32_e32 v61, 5, v48
	v_and_b32_e32 v118, 0x1f8, v118
	v_lshl_add_u32 v47, v47, 3, v205
	v_add3_u32 v61, s85, v61, v118
	ds_read2st64_b64 v[114:117], v47 offset0:32 offset1:48
	ds_read_b64 v[120:121], v61
	v_lshrrev_b32_e32 v61, 2, v42
	v_lshlrev_b32_e32 v48, 4, v48
	v_and_b32_e32 v61, 0xf8, v61
	v_add3_u32 v61, s85, v48, v61
	s_waitcnt lgkmcnt(0)
	v_pk_mul_f32 v[118:119], v[116:117], v[120:121]
	v_pk_mul_f32 v[116:117], v[116:117], v[120:121] op_sel:[1,0] op_sel_hi:[0,1]
	v_add_f32_e32 v123, v118, v119
	v_sub_f32_e32 v124, v116, v117
	ds_read2st64_b64 v[116:119], v47 offset1:16
	ds_read_b64 v[126:127], v61
	v_add_f32_e32 v48, v114, v123
	v_sub_f32_e32 v114, v114, v123
	v_add_f32_e32 v122, v115, v124
	s_waitcnt lgkmcnt(1)
	v_pk_mul_f32 v[128:129], v[118:119], v[120:121] op_sel:[1,1] op_sel_hi:[0,1]
	v_sub_f32_e32 v124, v115, v124
	v_pk_fma_f32 v[130:131], v[118:119], v[120:121], v[128:129]
	v_pk_fma_f32 v[118:119], v[118:119], v[120:121], v[128:129] op_sel_hi:[1,0,1] neg_lo:[0,0,1] neg_hi:[0,0,1]
	s_waitcnt lgkmcnt(0)
	v_pk_mul_f32 v[120:121], v[126:127], v[48:49] op_sel_hi:[1,0]
	v_pk_mul_f32 v[114:115], v[126:127], v[114:115] op_sel:[1,0] op_sel_hi:[0,0]
	v_mov_b32_e32 v131, v119
	v_pk_fma_f32 v[128:129], v[126:127], v[122:123], v[120:121] op_sel:[1,0,0] op_sel_hi:[0,1,1]
	v_pk_fma_f32 v[120:121], v[126:127], v[122:123], v[120:121] op_sel:[1,0,0] op_sel_hi:[0,0,1] neg_lo:[0,0,1] neg_hi:[0,0,1]
	v_pk_fma_f32 v[122:123], v[126:127], v[124:125], v[114:115] neg_lo:[0,0,1] neg_hi:[0,0,1]
	v_pk_fma_f32 v[114:115], v[126:127], v[124:125], v[114:115] op_sel_hi:[1,0,1]
	v_pk_add_f32 v[118:119], v[116:117], v[130:131]
	v_pk_add_f32 v[116:117], v[116:117], v[130:131] neg_lo:[0,1] neg_hi:[0,1]
	v_mov_b32_e32 v123, v115
	v_mov_b32_e32 v129, v121
	v_pk_add_f32 v[114:115], v[116:117], v[122:123] neg_lo:[0,1] neg_hi:[0,1]
	v_pk_add_f32 v[116:117], v[116:117], v[122:123]
	v_pk_add_f32 v[120:121], v[118:119], v[128:129]
	v_pk_add_f32 v[118:119], v[118:119], v[128:129] neg_lo:[0,1] neg_hi:[0,1]
	v_mov_b32_e32 v122, v114
	v_mov_b32_e32 v123, v117
	v_mov_b32_e32 v117, v115
	ds_write2st64_b64 v47, v[120:121], v[122:123] offset1:16
	ds_write2st64_b64 v47, v[118:119], v[116:117] offset0:32 offset1:48
	v_lshl_add_u32 v45, v45, 3, v205
	ds_read2st64_b64 v[114:117], v45 offset0:32 offset1:48
	ds_read_b64 v[120:121], v63
	ds_read_b64 v[126:127], v65
	v_lshlrev_b32_e32 v42, 3, v42
	s_waitcnt lgkmcnt(1)
	v_pk_mul_f32 v[118:119], v[116:117], v[120:121]
	v_pk_mul_f32 v[116:117], v[116:117], v[120:121] op_sel:[1,0] op_sel_hi:[0,1]
	v_add_f32_e32 v47, v118, v119
	v_sub_f32_e32 v59, v116, v117
	ds_read2st64_b64 v[116:119], v45 offset1:16
	v_add_f32_e32 v48, v114, v47
	v_sub_f32_e32 v114, v114, v47
	v_add_f32_e32 v122, v115, v59
	v_sub_f32_e32 v124, v115, v59
	s_waitcnt lgkmcnt(0)
	v_pk_mul_f32 v[128:129], v[118:119], v[120:121] op_sel:[1,1] op_sel_hi:[0,1]
	v_pk_fma_f32 v[130:131], v[118:119], v[120:121], v[128:129]
	v_pk_fma_f32 v[118:119], v[118:119], v[120:121], v[128:129] op_sel_hi:[1,0,1] neg_lo:[0,0,1] neg_hi:[0,0,1]
	v_pk_mul_f32 v[120:121], v[126:127], v[48:49] op_sel_hi:[1,0]
	v_pk_mul_f32 v[114:115], v[126:127], v[114:115] op_sel:[1,0] op_sel_hi:[0,0]
	v_mov_b32_e32 v131, v119
	v_pk_fma_f32 v[128:129], v[126:127], v[122:123], v[120:121] op_sel:[1,0,0] op_sel_hi:[0,1,1]
	v_pk_fma_f32 v[120:121], v[126:127], v[122:123], v[120:121] op_sel:[1,0,0] op_sel_hi:[0,0,1] neg_lo:[0,0,1] neg_hi:[0,0,1]
	v_pk_fma_f32 v[122:123], v[126:127], v[124:125], v[114:115] neg_lo:[0,0,1] neg_hi:[0,0,1]
	v_pk_fma_f32 v[114:115], v[126:127], v[124:125], v[114:115] op_sel_hi:[1,0,1]
	v_pk_add_f32 v[118:119], v[116:117], v[130:131]
	v_pk_add_f32 v[116:117], v[116:117], v[130:131] neg_lo:[0,1] neg_hi:[0,1]
	v_mov_b32_e32 v123, v115
	v_mov_b32_e32 v129, v121
	v_pk_add_f32 v[114:115], v[116:117], v[122:123] neg_lo:[0,1] neg_hi:[0,1]
	v_pk_add_f32 v[116:117], v[116:117], v[122:123]
	v_pk_add_f32 v[120:121], v[118:119], v[128:129]
	v_pk_add_f32 v[118:119], v[118:119], v[128:129] neg_lo:[0,1] neg_hi:[0,1]
	v_mov_b32_e32 v122, v114
	v_mov_b32_e32 v123, v117
	v_mov_b32_e32 v117, v115
	ds_write2st64_b64 v45, v[120:121], v[122:123] offset1:16
	ds_write2st64_b64 v45, v[118:119], v[116:117] offset0:32 offset1:48
	v_and_b32_e32 v45, 0x3ff, v44
	v_and_or_b32 v46, v46, s26, v45
	v_lshrrev_b32_e32 v47, 1, v44
	v_lshl_add_u32 v59, v46, 3, v205
	v_lshlrev_b32_e32 v46, 5, v45
	v_and_b32_e32 v47, 0x1f8, v47
	v_add3_u32 v46, s85, v46, v47
	ds_read2st64_b64 v[114:117], v59 offset0:32 offset1:48
	ds_read_b64 v[46:47], v46
	v_lshrrev_b32_e32 v48, 2, v44
	v_lshlrev_b32_e32 v45, 4, v45
	v_and_b32_e32 v48, 0xf8, v48
	v_add3_u32 v45, s85, v45, v48
	ds_read_b64 v[124:125], v45
	s_waitcnt lgkmcnt(1)
	v_pk_mul_f32 v[118:119], v[116:117], v[46:47]
	v_pk_mul_f32 v[116:117], v[116:117], v[46:47] op_sel:[1,0] op_sel_hi:[0,1]
	v_add_f32_e32 v61, v118, v119
	v_sub_f32_e32 v63, v116, v117
	ds_read2st64_b64 v[116:119], v59 offset1:16
	v_add_f32_e32 v48, v114, v61
	v_sub_f32_e32 v114, v114, v61
	v_add_f32_e32 v120, v115, v63
	v_sub_f32_e32 v122, v115, v63
	s_waitcnt lgkmcnt(0)
	v_pk_mul_f32 v[126:127], v[118:119], v[46:47] op_sel:[1,1] op_sel_hi:[0,1]
	v_pk_fma_f32 v[128:129], v[118:119], v[46:47], v[126:127]
	v_pk_fma_f32 v[46:47], v[118:119], v[46:47], v[126:127] op_sel_hi:[1,0,1] neg_lo:[0,0,1] neg_hi:[0,0,1]
	v_pk_mul_f32 v[118:119], v[124:125], v[48:49] op_sel_hi:[1,0]
	v_pk_mul_f32 v[114:115], v[124:125], v[114:115] op_sel:[1,0] op_sel_hi:[0,0]
	v_mov_b32_e32 v129, v47
	v_pk_fma_f32 v[126:127], v[124:125], v[120:121], v[118:119] op_sel:[1,0,0] op_sel_hi:[0,1,1]
	v_pk_fma_f32 v[118:119], v[124:125], v[120:121], v[118:119] op_sel:[1,0,0] op_sel_hi:[0,0,1] neg_lo:[0,0,1] neg_hi:[0,0,1]
	v_pk_fma_f32 v[120:121], v[124:125], v[122:123], v[114:115] neg_lo:[0,0,1] neg_hi:[0,0,1]
	v_pk_fma_f32 v[114:115], v[124:125], v[122:123], v[114:115] op_sel_hi:[1,0,1]
	v_pk_add_f32 v[46:47], v[116:117], v[128:129]
	v_pk_add_f32 v[116:117], v[116:117], v[128:129] neg_lo:[0,1] neg_hi:[0,1]
	v_mov_b32_e32 v121, v115
	v_mov_b32_e32 v127, v119
	v_pk_add_f32 v[114:115], v[116:117], v[120:121] neg_lo:[0,1] neg_hi:[0,1]
	v_pk_add_f32 v[116:117], v[116:117], v[120:121]
	v_pk_add_f32 v[118:119], v[46:47], v[126:127]
	v_pk_add_f32 v[46:47], v[46:47], v[126:127] neg_lo:[0,1] neg_hi:[0,1]
	v_mov_b32_e32 v121, v117
	v_mov_b32_e32 v117, v115
	ds_write2st64_b64 v59, v[46:47], v[116:117] offset0:32 offset1:48
	v_lshlrev_b32_e32 v45, 3, v0
	v_lshlrev_b32_e32 v46, 3, v49
	v_mov_b32_e32 v120, v114
	v_add3_u32 v46, s85, v45, v46
	ds_write2st64_b64 v59, v[118:119], v[120:121] offset1:16
	s_waitcnt lgkmcnt(0)
	s_barrier
	ds_read_b64 v[118:119], v46
	v_add_u32_e32 v59, 0x50, v45
	ds_read2st64_b64 v[46:49], v59 offset0:64 offset1:72
	ds_read2st64_b64 v[114:117], v59 offset1:8
	v_lshlrev_b32_e32 v45, 3, v53
	v_add3_u32 v42, s85, v45, v42
	s_waitcnt lgkmcnt(1)
	v_pk_mul_f32 v[120:121], v[118:119], v[46:47] op_sel:[1,1] op_sel_hi:[1,0]
	s_nop 0
	v_pk_fma_f32 v[122:123], v[118:119], v[46:47], v[120:121]
	v_pk_fma_f32 v[46:47], v[118:119], v[46:47], v[120:121] op_sel_hi:[0,1,1] neg_lo:[0,0,1] neg_hi:[0,0,1]
	v_mov_b32_e32 v123, v47
	s_waitcnt lgkmcnt(0)
	v_pk_add_f32 v[46:47], v[114:115], v[122:123]
	ds_write_b64 v59, v[46:47]
	v_pk_add_f32 v[46:47], v[114:115], v[122:123] neg_lo:[0,1] neg_hi:[0,1]
	ds_write_b64 v59, v[46:47] offset:32768
	ds_read_b64 v[46:47], v42
	v_lshlrev_b32_e32 v42, 3, v55
	v_add3_u32 v42, s85, v42, v43
	s_waitcnt lgkmcnt(0)
	v_pk_mul_f32 v[114:115], v[46:47], v[48:49] op_sel:[1,1] op_sel_hi:[1,0]
	s_nop 0
	v_pk_fma_f32 v[118:119], v[46:47], v[48:49], v[114:115]
	v_pk_fma_f32 v[46:47], v[46:47], v[48:49], v[114:115] op_sel_hi:[0,1,1] neg_lo:[0,0,1] neg_hi:[0,0,1]
	v_mov_b32_e32 v119, v47
	v_pk_add_f32 v[46:47], v[116:117], v[118:119]
	ds_write_b64 v59, v[46:47] offset:4096
	v_pk_add_f32 v[46:47], v[116:117], v[118:119] neg_lo:[0,1] neg_hi:[0,1]
	ds_write_b64 v59, v[46:47] offset:36864
	ds_read_b64 v[42:43], v42
	ds_read2st64_b64 v[46:49], v59 offset0:80 offset1:88
	ds_read2st64_b64 v[114:117], v59 offset0:16 offset1:24
	s_waitcnt lgkmcnt(1)
	v_pk_mul_f32 v[118:119], v[42:43], v[46:47] op_sel:[1,1] op_sel_hi:[1,0]
	s_nop 0
	v_pk_fma_f32 v[120:121], v[42:43], v[46:47], v[118:119]
	v_pk_fma_f32 v[42:43], v[42:43], v[46:47], v[118:119] op_sel_hi:[0,1,1] neg_lo:[0,0,1] neg_hi:[0,0,1]
	v_mov_b32_e32 v121, v43
	s_waitcnt lgkmcnt(0)
	v_pk_add_f32 v[42:43], v[114:115], v[120:121]
	ds_write_b64 v59, v[42:43] offset:8192
	v_pk_add_f32 v[42:43], v[114:115], v[120:121] neg_lo:[0,1] neg_hi:[0,1]
	ds_write_b64 v59, v[42:43] offset:40960
	v_lshlrev_b32_e32 v42, 3, v57
	v_lshlrev_b32_e32 v43, 3, v44
	v_add3_u32 v42, s85, v42, v43
	ds_read_b64 v[42:43], v42
	s_waitcnt lgkmcnt(0)
	v_pk_mul_f32 v[44:45], v[42:43], v[48:49] op_sel:[1,1] op_sel_hi:[1,0]
	s_nop 0
	v_pk_fma_f32 v[46:47], v[42:43], v[48:49], v[44:45]
	v_pk_fma_f32 v[42:43], v[42:43], v[48:49], v[44:45] op_sel_hi:[0,1,1] neg_lo:[0,0,1] neg_hi:[0,0,1]
	v_mov_b32_e32 v47, v43
	v_pk_add_f32 v[42:43], v[116:117], v[46:47]
	ds_write_b64 v59, v[42:43] offset:12288
	v_pk_add_f32 v[42:43], v[116:117], v[46:47] neg_lo:[0,1] neg_hi:[0,1]
	ds_write_b64 v59, v[42:43] offset:45056
	v_add_u32_e32 v42, 0x800, v0
	v_ashrrev_i32_e32 v43, 6, v42
	v_lshlrev_b32_e32 v43, 3, v43
	v_lshlrev_b32_e32 v42, 3, v42
	v_add3_u32 v42, s85, v43, v42
	ds_read_b64 v[114:115], v42
	ds_read2st64_b64 v[42:45], v59 offset0:96 offset1:104
	ds_read2st64_b64 v[46:49], v59 offset0:32 offset1:40
	s_waitcnt lgkmcnt(1)
	v_pk_mul_f32 v[116:117], v[114:115], v[42:43] op_sel:[1,1] op_sel_hi:[1,0]
	s_nop 0
	v_pk_fma_f32 v[118:119], v[114:115], v[42:43], v[116:117]
	v_pk_fma_f32 v[42:43], v[114:115], v[42:43], v[116:117] op_sel_hi:[0,1,1] neg_lo:[0,0,1] neg_hi:[0,0,1]
	v_mov_b32_e32 v119, v43
	s_waitcnt lgkmcnt(0)
	v_pk_add_f32 v[42:43], v[46:47], v[118:119]
	ds_write_b64 v59, v[42:43] offset:16384
	v_pk_add_f32 v[42:43], v[46:47], v[118:119] neg_lo:[0,1] neg_hi:[0,1]
	ds_write_b64 v59, v[42:43] offset:49152
	v_add_u32_e32 v42, 0xa00, v0
	v_ashrrev_i32_e32 v43, 6, v42
	v_lshlrev_b32_e32 v43, 3, v43
	v_lshlrev_b32_e32 v42, 3, v42
	v_add3_u32 v42, s85, v43, v42
	ds_read_b64 v[42:43], v42
	s_waitcnt lgkmcnt(0)
	v_pk_mul_f32 v[46:47], v[42:43], v[44:45] op_sel:[1,1] op_sel_hi:[1,0]
	s_nop 0
	v_pk_fma_f32 v[114:115], v[42:43], v[44:45], v[46:47]
	v_pk_fma_f32 v[42:43], v[42:43], v[44:45], v[46:47] op_sel_hi:[0,1,1] neg_lo:[0,0,1] neg_hi:[0,0,1]
	v_mov_b32_e32 v115, v43
	v_pk_add_f32 v[42:43], v[48:49], v[114:115]
	ds_write_b64 v59, v[42:43] offset:20480
	v_pk_add_f32 v[42:43], v[48:49], v[114:115] neg_lo:[0,1] neg_hi:[0,1]
	ds_write_b64 v59, v[42:43] offset:53248
	v_add_u32_e32 v42, 0xc00, v0
	v_ashrrev_i32_e32 v43, 6, v42
	v_lshlrev_b32_e32 v43, 3, v43
	v_lshlrev_b32_e32 v42, 3, v42
	v_add3_u32 v42, s85, v43, v42
	ds_read_b64 v[114:115], v42
	ds_read2st64_b64 v[42:45], v59 offset0:112 offset1:120
	ds_read2st64_b64 v[46:49], v59 offset0:48 offset1:56
	v_add_u32_e32 v0, 0xe00, v0
	s_waitcnt lgkmcnt(1)
	v_pk_mul_f32 v[116:117], v[114:115], v[42:43] op_sel:[1,1] op_sel_hi:[1,0]
	s_nop 0
	v_pk_fma_f32 v[118:119], v[114:115], v[42:43], v[116:117]
	v_pk_fma_f32 v[42:43], v[114:115], v[42:43], v[116:117] op_sel_hi:[0,1,1] neg_lo:[0,0,1] neg_hi:[0,0,1]
	v_mov_b32_e32 v119, v43
	s_waitcnt lgkmcnt(0)
	v_pk_add_f32 v[42:43], v[46:47], v[118:119]
	ds_write_b64 v59, v[42:43] offset:24576
	v_pk_add_f32 v[42:43], v[46:47], v[118:119] neg_lo:[0,1] neg_hi:[0,1]
	ds_write_b64 v59, v[42:43] offset:57344
	v_ashrrev_i32_e32 v42, 6, v0
	v_lshlrev_b32_e32 v42, 3, v42
	v_lshlrev_b32_e32 v0, 3, v0
	v_add3_u32 v0, s85, v42, v0
	ds_read_b64 v[42:43], v0
	s_waitcnt lgkmcnt(0)
	v_pk_mul_f32 v[46:47], v[42:43], v[44:45] op_sel:[1,1] op_sel_hi:[1,0]
	s_nop 0
	v_pk_fma_f32 v[114:115], v[42:43], v[44:45], v[46:47]
	v_pk_fma_f32 v[42:43], v[42:43], v[44:45], v[46:47] op_sel_hi:[0,1,1] neg_lo:[0,0,1] neg_hi:[0,0,1]
	v_mov_b32_e32 v115, v43
	v_pk_add_f32 v[42:43], v[48:49], v[114:115]
	ds_write_b64 v59, v[42:43] offset:28672
	v_pk_add_f32 v[42:43], v[48:49], v[114:115] neg_lo:[0,1] neg_hi:[0,1]
	ds_write_b64 v59, v[42:43] offset:61440
	s_waitcnt lgkmcnt(0)
	s_barrier
	global_load_dword v149, v1, s[0:1] offset:1024
	global_load_dword v150, v1, s[34:35] offset:3072
	global_load_dword v117, v202, s[0:1] offset:3072
	global_load_dword v115, v1, s[20:21] offset:1024
	v_readlane_b32 s34, v251, 39
	v_readlane_b32 s35, v251, 40
	s_add_u32 s23, s34, s23
	s_addc_u32 s26, s35, s25
	s_add_u32 s68, s23, 0x4000
	s_addc_u32 s69, s26, 0
	s_ashr_i32 s31, s30, 31
	s_lshl_b64 s[24:25], s[30:31], 2
	s_add_u32 s24, s14, s24
	v_lshl_add_u64 v[42:43], v[50:51], 2, s[68:69]
	s_addc_u32 s25, s15, s25
	global_load_dword v151, v[42:43], off
	global_load_dword v116, v1, s[24:25]
	ds_read_b64 v[118:119], v148
	s_and_saveexec_b64 s[78:79], s[40:41]
	s_cbranch_execz .LBB0_885
	v_mov_b32_e32 v0, v50
	v_lshl_add_u64 v[44:45], v[0:1], 2, s[68:69]
	global_load_dword v154, v[44:45], off offset:-4
.LBB0_885:
	s_or_b64 exec, exec, s[78:79]
	s_and_saveexec_b64 s[78:79], s[42:43]
	s_cbranch_execz .LBB0_887
	global_load_dword v155, v[42:43], off offset:4
.LBB0_887:
	s_or_b64 exec, exec, s[78:79]
	s_add_u32 s78, s23, 0x8000
	s_addc_u32 s79, s26, 0
	v_lshl_add_u64 v[44:45], v[50:51], 2, s[78:79]
	global_load_dword v156, v[44:45], off
	s_and_saveexec_b64 vcc, s[40:41]
	s_mov_b32 s26, 0x1ffff000
	s_mov_b32 s34, 0x1ffffc00
	s_mov_b32 s35, 0x1fffffc0
	s_mov_b32 s5, 0x1ffffff0
	s_cbranch_execz .LBB0_889
	v_mov_b32_e32 v0, v50
	v_lshl_add_u64 v[46:47], v[0:1], 2, s[78:79]
	global_load_dword v157, v[46:47], off offset:-4
.LBB0_889:
	s_or_b64 exec, exec, vcc
	s_and_saveexec_b64 vcc, s[42:43]
	s_cbranch_execz .LBB0_891
	global_load_dword v158, v[44:45], off offset:4
.LBB0_891:
	s_or_b64 exec, exec, vcc
	global_load_dword v159, v[42:43], off offset:2048
	ds_read_b64 v[124:125], v148 offset:4096
	s_and_saveexec_b64 vcc, s[54:55]
	s_cbranch_execz .LBB0_893
	v_mov_b32_e32 v53, v1
	v_lshl_add_u64 v[46:47], v[52:53], 2, s[68:69]
	global_load_dword v160, v[46:47], off offset:-4
.LBB0_893:
	s_or_b64 exec, exec, vcc
	s_and_saveexec_b64 vcc, s[58:59]
	s_cbranch_execz .LBB0_895
	global_load_dword v161, v[42:43], off offset:2052
.LBB0_895:
	s_or_b64 exec, exec, vcc
	global_load_dword v162, v[44:45], off offset:2048
	s_and_saveexec_b64 vcc, s[54:55]
	s_cbranch_execz .LBB0_897
	v_mov_b32_e32 v53, v1
	v_lshl_add_u64 v[46:47], v[52:53], 2, s[78:79]
	global_load_dword v164, v[46:47], off offset:-4
.LBB0_897:
	s_or_b64 exec, exec, vcc
	s_and_saveexec_b64 vcc, s[58:59]
	s_cbranch_execz .LBB0_899
	global_load_dword v166, v[44:45], off offset:2052
.LBB0_899:
	s_or_b64 exec, exec, vcc
	v_add_co_u32_e32 v46, vcc, 0x1000, v42
	ds_read_b64 v[128:129], v148 offset:8192
	s_nop 0
	v_addc_co_u32_e32 v47, vcc, 0, v43, vcc
	global_load_dword v168, v[46:47], off
	s_and_saveexec_b64 vcc, s[36:37]
	s_cbranch_execz .LBB0_901
	v_mov_b32_e32 v55, v1
	v_lshl_add_u64 v[46:47], v[54:55], 2, s[68:69]
	global_load_dword v171, v[46:47], off offset:-4
.LBB0_901:
	s_or_b64 exec, exec, vcc
	s_and_saveexec_b64 vcc, s[38:39]
	s_cbranch_execz .LBB0_903
	s_mov_b64 s[16:17], 0x1000
	v_lshl_add_u64 v[46:47], v[42:43], 0, s[16:17]
	global_load_dword v174, v[46:47], off offset:4
.LBB0_903:
	s_or_b64 exec, exec, vcc
	v_add_co_u32_e32 v46, vcc, 0x1000, v44
	s_nop 1
	v_addc_co_u32_e32 v47, vcc, 0, v45, vcc
	global_load_dword v177, v[46:47], off
	s_and_saveexec_b64 vcc, s[36:37]
	s_cbranch_execz .LBB0_905
	v_mov_b32_e32 v55, v1
	v_lshl_add_u64 v[46:47], v[54:55], 2, s[78:79]
	global_load_dword v180, v[46:47], off offset:-4
.LBB0_905:
	s_or_b64 exec, exec, vcc
	s_and_saveexec_b64 vcc, s[38:39]
	s_cbranch_execz .LBB0_907
	s_mov_b64 s[16:17], 0x1000
	v_lshl_add_u64 v[46:47], v[44:45], 0, s[16:17]
	global_load_dword v183, v[46:47], off offset:4
.LBB0_907:
	s_or_b64 exec, exec, vcc
	v_add_co_u32_e32 v46, vcc, 0x1000, v42
	ds_read_b64 v[130:131], v148 offset:12288
	s_nop 0
	v_addc_co_u32_e32 v47, vcc, 0, v43, vcc
	global_load_dword v186, v[46:47], off offset:2048
	s_and_saveexec_b64 vcc, s[44:45]
	s_cbranch_execz .LBB0_909
	v_mov_b32_e32 v57, v1
	v_lshl_add_u64 v[46:47], v[56:57], 2, s[68:69]
	global_load_dword v189, v[46:47], off offset:-4
.LBB0_909:
	s_or_b64 exec, exec, vcc
	s_and_saveexec_b64 vcc, s[46:47]
	s_cbranch_execz .LBB0_911
	s_mov_b64 s[16:17], 0x1800
	v_lshl_add_u64 v[46:47], v[42:43], 0, s[16:17]
	global_load_dword v192, v[46:47], off offset:4
.LBB0_911:
	s_or_b64 exec, exec, vcc
	v_add_co_u32_e32 v46, vcc, 0x1000, v44
	s_nop 1
	v_addc_co_u32_e32 v47, vcc, 0, v45, vcc
	global_load_dword v195, v[46:47], off offset:2048
	s_and_saveexec_b64 vcc, s[44:45]
	s_cbranch_execz .LBB0_913
	v_mov_b32_e32 v57, v1
	v_lshl_add_u64 v[46:47], v[56:57], 2, s[78:79]
	global_load_dword v217, v[46:47], off offset:-4
.LBB0_913:
	s_or_b64 exec, exec, vcc
	s_and_saveexec_b64 vcc, s[46:47]
	s_cbranch_execz .LBB0_915
	s_mov_b64 s[16:17], 0x1800
	v_lshl_add_u64 v[46:47], v[44:45], 0, s[16:17]
	global_load_dword v218, v[46:47], off offset:4
.LBB0_915:
	s_or_b64 exec, exec, vcc
	v_add_co_u32_e32 v46, vcc, 0x2000, v42
	ds_read_b64 v[132:133], v148 offset:16384
	s_nop 0
	v_addc_co_u32_e32 v47, vcc, 0, v43, vcc
	global_load_dword v219, v[46:47], off
	s_and_saveexec_b64 vcc, s[48:49]
	s_cbranch_execz .LBB0_917
	v_mov_b32_e32 v59, v1
	v_lshl_add_u64 v[138:139], v[58:59], 2, s[68:69]
	global_load_dword v220, v[138:139], off offset:-4
.LBB0_917:
	s_or_b64 exec, exec, vcc
	s_and_saveexec_b64 vcc, s[50:51]
	s_cbranch_execz .LBB0_919
	s_mov_b64 s[16:17], 0x2000
	v_lshl_add_u64 v[138:139], v[42:43], 0, s[16:17]
	global_load_dword v221, v[138:139], off offset:4
.LBB0_919:
	s_or_b64 exec, exec, vcc
	v_add_co_u32_e32 v138, vcc, 0x2000, v44
	s_nop 1
	v_addc_co_u32_e32 v139, vcc, 0, v45, vcc
	global_load_dword v224, v[138:139], off
	s_and_saveexec_b64 vcc, s[48:49]
	s_cbranch_execz .LBB0_921
	v_mov_b32_e32 v59, v1
	v_lshl_add_u64 v[138:139], v[58:59], 2, s[78:79]
	global_load_dword v227, v[138:139], off offset:-4
.LBB0_921:
	s_or_b64 exec, exec, vcc
	s_and_saveexec_b64 vcc, s[50:51]
	s_cbranch_execz .LBB0_923
	s_mov_b64 s[16:17], 0x2000
	v_lshl_add_u64 v[138:139], v[44:45], 0, s[16:17]
	global_load_dword v230, v[138:139], off offset:4
.LBB0_923:
	s_or_b64 exec, exec, vcc
	v_add_co_u32_e32 v138, vcc, 0x2000, v42
	ds_read_b64 v[142:143], v148 offset:20480
	s_nop 0
	v_addc_co_u32_e32 v139, vcc, 0, v43, vcc
	global_load_dword v233, v[138:139], off offset:2048
	s_and_saveexec_b64 vcc, s[52:53]
	s_cbranch_execz .LBB0_925
	v_mov_b32_e32 v61, v1
	v_lshl_add_u64 v[138:139], v[60:61], 2, s[68:69]
	global_load_dword v236, v[138:139], off offset:-4
.LBB0_925:
	s_or_b64 exec, exec, vcc
	s_and_saveexec_b64 vcc, s[56:57]
	s_cbranch_execz .LBB0_927
	s_mov_b64 s[16:17], 0x2800
	v_lshl_add_u64 v[138:139], v[42:43], 0, s[16:17]
	global_load_dword v239, v[138:139], off offset:4
.LBB0_927:
	s_or_b64 exec, exec, vcc
	v_add_co_u32_e32 v138, vcc, 0x2000, v44
	s_nop 1
	v_addc_co_u32_e32 v139, vcc, 0, v45, vcc
	global_load_dword v242, v[138:139], off offset:2048
	s_and_saveexec_b64 vcc, s[52:53]
	s_cbranch_execz .LBB0_929
	v_mov_b32_e32 v61, v1
	v_lshl_add_u64 v[138:139], v[60:61], 2, s[78:79]
	global_load_dword v243, v[138:139], off offset:-4
.LBB0_929:
	s_or_b64 exec, exec, vcc
	s_and_saveexec_b64 vcc, s[56:57]
	s_cbranch_execz .LBB0_931
	s_mov_b64 s[16:17], 0x2800
	v_lshl_add_u64 v[138:139], v[44:45], 0, s[16:17]
	global_load_dword v244, v[138:139], off offset:4
.LBB0_931:
	s_or_b64 exec, exec, vcc
	v_add_co_u32_e32 v138, vcc, 0x3000, v42
	ds_read_b64 v[146:147], v148 offset:24576
	s_nop 0
	v_addc_co_u32_e32 v139, vcc, 0, v43, vcc
	global_load_dword v245, v[138:139], off
	s_and_saveexec_b64 vcc, s[60:61]
	s_cbranch_execz .LBB0_933
	v_mov_b32_e32 v63, v1
	v_lshl_add_u64 v[138:139], v[62:63], 2, s[68:69]
	global_load_dword v246, v[138:139], off offset:-4
.LBB0_933:
	s_or_b64 exec, exec, vcc
	s_and_saveexec_b64 vcc, s[62:63]
	s_cbranch_execz .LBB0_935
	s_mov_b64 s[16:17], 0x3000
	v_lshl_add_u64 v[138:139], v[42:43], 0, s[16:17]
	global_load_dword v247, v[138:139], off offset:4
.LBB0_935:
	s_or_b64 exec, exec, vcc
	v_add_co_u32_e32 v138, vcc, 0x3000, v44
	s_nop 1
	v_addc_co_u32_e32 v139, vcc, 0, v45, vcc
	s_waitcnt vmcnt(0)
	v_fma_f32 v120, v150, v151, v115
	s_and_saveexec_b64 s[98:99], s[40:41]
	v_fmac_f32_e32 v120, v149, v154
	s_or_b64 exec, exec, s[98:99]
	s_and_saveexec_b64 s[98:99], s[42:43]
	v_fmac_f32_e32 v120, v117, v155
	s_or_b64 exec, exec, s[98:99]
	v_fma_f32 v121, v150, v156, v115
	s_and_saveexec_b64 s[98:99], s[40:41]
	v_fmac_f32_e32 v121, v149, v157
	s_or_b64 exec, exec, s[98:99]
	s_and_saveexec_b64 s[98:99], s[42:43]
	v_fmac_f32_e32 v121, v117, v158
	s_or_b64 exec, exec, s[98:99]
	v_fma_f32 v122, v150, v159, v115
	s_and_saveexec_b64 s[98:99], s[54:55]
	v_fmac_f32_e32 v122, v149, v160
	s_or_b64 exec, exec, s[98:99]
	s_and_saveexec_b64 s[98:99], s[58:59]
	v_fmac_f32_e32 v122, v117, v161
	s_or_b64 exec, exec, s[98:99]
	v_fma_f32 v123, v150, v162, v115
	s_and_saveexec_b64 s[98:99], s[54:55]
	v_fmac_f32_e32 v123, v149, v164
	s_or_b64 exec, exec, s[98:99]
	s_and_saveexec_b64 s[98:99], s[58:59]
	v_fmac_f32_e32 v123, v117, v166
	s_or_b64 exec, exec, s[98:99]
	v_fma_f32 v126, v150, v168, v115
	s_and_saveexec_b64 s[98:99], s[36:37]
	v_fmac_f32_e32 v126, v149, v171
	s_or_b64 exec, exec, s[98:99]
	s_and_saveexec_b64 s[98:99], s[38:39]
	v_fmac_f32_e32 v126, v117, v174
	s_or_b64 exec, exec, s[98:99]
	v_fma_f32 v127, v150, v177, v115
	s_and_saveexec_b64 s[98:99], s[36:37]
	v_fmac_f32_e32 v127, v149, v180
	s_or_b64 exec, exec, s[98:99]
	s_and_saveexec_b64 s[98:99], s[38:39]
	v_fmac_f32_e32 v127, v117, v183
	s_or_b64 exec, exec, s[98:99]
	v_fma_f32 v48, v150, v186, v115
	s_and_saveexec_b64 s[98:99], s[44:45]
	v_fmac_f32_e32 v48, v149, v189
	s_or_b64 exec, exec, s[98:99]
	s_and_saveexec_b64 s[98:99], s[46:47]
	v_fmac_f32_e32 v48, v117, v192
	s_or_b64 exec, exec, s[98:99]
	v_fma_f32 v49, v150, v195, v115
	s_and_saveexec_b64 s[98:99], s[44:45]
	v_fmac_f32_e32 v49, v149, v217
	s_or_b64 exec, exec, s[98:99]
	s_and_saveexec_b64 s[98:99], s[46:47]
	v_fmac_f32_e32 v49, v117, v218
	s_or_b64 exec, exec, s[98:99]
	v_fma_f32 v46, v150, v219, v115
	s_and_saveexec_b64 s[98:99], s[48:49]
	v_fmac_f32_e32 v46, v149, v220
	s_or_b64 exec, exec, s[98:99]
	s_and_saveexec_b64 s[98:99], s[50:51]
	v_fmac_f32_e32 v46, v117, v221
	s_or_b64 exec, exec, s[98:99]
	v_fma_f32 v47, v150, v224, v115
	s_and_saveexec_b64 s[98:99], s[48:49]
	v_fmac_f32_e32 v47, v149, v227
	s_or_b64 exec, exec, s[98:99]
	s_and_saveexec_b64 s[98:99], s[50:51]
	v_fmac_f32_e32 v47, v117, v230
	s_or_b64 exec, exec, s[98:99]
	v_fma_f32 v140, v150, v233, v115
	s_and_saveexec_b64 s[98:99], s[52:53]
	v_fmac_f32_e32 v140, v149, v236
	s_or_b64 exec, exec, s[98:99]
	s_and_saveexec_b64 s[98:99], s[56:57]
	v_fmac_f32_e32 v140, v117, v239
	s_or_b64 exec, exec, s[98:99]
	v_fma_f32 v141, v150, v242, v115
	s_and_saveexec_b64 s[98:99], s[52:53]
	v_fmac_f32_e32 v141, v149, v243
	s_or_b64 exec, exec, s[98:99]
	s_and_saveexec_b64 s[98:99], s[56:57]
	v_fmac_f32_e32 v141, v117, v244
	s_or_b64 exec, exec, s[98:99]
	v_fma_f32 v144, v150, v245, v115
	s_and_saveexec_b64 s[98:99], s[60:61]
	v_fmac_f32_e32 v144, v149, v246
	s_or_b64 exec, exec, s[98:99]
	s_and_saveexec_b64 s[98:99], s[62:63]
	v_fmac_f32_e32 v144, v117, v247
	s_or_b64 exec, exec, s[98:99]
	global_load_dword v151, v[138:139], off
	s_and_saveexec_b64 vcc, s[60:61]
	s_cbranch_execz .LBB0_937
	v_mov_b32_e32 v63, v1
	v_lshl_add_u64 v[138:139], v[62:63], 2, s[78:79]
	global_load_dword v154, v[138:139], off offset:-4
.LBB0_937:
	s_or_b64 exec, exec, vcc
	s_and_saveexec_b64 vcc, s[62:63]
	s_cbranch_execz .LBB0_939
	s_mov_b64 s[16:17], 0x3000
	v_lshl_add_u64 v[138:139], v[44:45], 0, s[16:17]
	global_load_dword v155, v[138:139], off offset:4
.LBB0_939:
	s_or_b64 exec, exec, vcc
	v_add_co_u32_e32 v138, vcc, 0x3000, v42
	s_nop 1
	v_addc_co_u32_e32 v139, vcc, 0, v43, vcc
	global_load_dword v156, v[138:139], off offset:2048
	ds_read_b64 v[138:139], v148 offset:28672
	s_and_saveexec_b64 vcc, s[64:65]
	s_cbranch_execz .LBB0_941
	v_mov_b32_e32 v65, v1
	v_lshl_add_u64 v[152:153], v[64:65], 2, s[68:69]
	global_load_dword v157, v[152:153], off offset:-4
.LBB0_941:
	s_or_b64 exec, exec, vcc
	s_and_saveexec_b64 s[68:69], s[66:67]
	s_cbranch_execz .LBB0_943
	s_mov_b64 s[16:17], 0x3800
	v_lshl_add_u64 v[42:43], v[42:43], 0, s[16:17]
	global_load_dword v158, v[42:43], off offset:4
.LBB0_943:
	s_or_b64 exec, exec, s[68:69]
	v_add_co_u32_e32 v42, vcc, 0x3000, v44
	s_nop 1
	v_addc_co_u32_e32 v43, vcc, 0, v45, vcc
	global_load_dword v159, v[42:43], off offset:2048
	s_and_saveexec_b64 s[68:69], s[64:65]
	s_cbranch_execz .LBB0_945
	v_mov_b32_e32 v65, v1
	v_lshl_add_u64 v[42:43], v[64:65], 2, s[78:79]
	global_load_dword v160, v[42:43], off offset:-4
.LBB0_945:
	s_or_b64 exec, exec, s[68:69]
	s_and_saveexec_b64 s[68:69], s[66:67]
	s_cbranch_execz .LBB0_947
	s_mov_b64 s[16:17], 0x3800
	v_lshl_add_u64 v[42:43], v[44:45], 0, s[16:17]
	global_load_dword v161, v[42:43], off offset:4
.LBB0_947:
	s_or_b64 exec, exec, s[68:69]
	s_waitcnt vmcnt(0)
	v_fma_f32 v145, v150, v151, v115
	s_and_saveexec_b64 s[98:99], s[60:61]
	v_fmac_f32_e32 v145, v149, v154
	s_or_b64 exec, exec, s[98:99]
	s_and_saveexec_b64 s[98:99], s[62:63]
	v_fmac_f32_e32 v145, v117, v155
	s_or_b64 exec, exec, s[98:99]
	v_fma_f32 v114, v150, v156, v115
	s_and_saveexec_b64 s[98:99], s[64:65]
	v_fmac_f32_e32 v114, v149, v157
	s_or_b64 exec, exec, s[98:99]
	s_and_saveexec_b64 s[98:99], s[66:67]
	v_fmac_f32_e32 v114, v117, v158
	s_or_b64 exec, exec, s[98:99]
	v_fmac_f32_e32 v115, v150, v159
	s_and_saveexec_b64 s[98:99], s[64:65]
	v_fmac_f32_e32 v115, v149, v160
	s_or_b64 exec, exec, s[98:99]
	s_and_saveexec_b64 s[98:99], s[66:67]
	v_fmac_f32_e32 v115, v117, v161
	s_or_b64 exec, exec, s[98:99]
	v_add_f32_e32 v0, 0, v18
	v_add_f32_e32 v0, v0, v19
	v_add_f32_e32 v0, v0, v20
	v_add_f32_e32 v0, v0, v21
	v_add_f32_e32 v0, v0, v14
	v_add_f32_e32 v0, v0, v15
	v_add_f32_e32 v0, v0, v16
	v_add_f32_e32 v0, v0, v17
	v_mul_f32_e32 v0, 0x46000000, v0
	v_div_scale_f32 v18, s[30:31], v0, v0, 0.5
	v_rcp_f32_e32 v19, v18
	s_waitcnt lgkmcnt(1)
	v_pk_fma_f32 v[42:43], v[112:113], v[116:117], v[146:147] op_sel_hi:[1,0,1]
	v_pk_fma_f32 v[102:103], v[102:103], v[116:117], v[124:125] op_sel_hi:[1,0,1]
	v_pk_fma_f32 v[14:15], v[100:101], v[116:117], v[118:119] op_sel_hi:[1,0,1]
	v_fma_f32 v20, -v18, v19, 1.0
	v_fmac_f32_e32 v19, v20, v19
	v_div_scale_f32 v20, vcc, 0.5, v0, 0.5
	v_mul_f32_e32 v21, v20, v19
	v_fma_f32 v53, -v18, v21, v20
	v_fmac_f32_e32 v21, v53, v19
	v_fma_f32 v18, -v18, v21, v20
	v_div_fmas_f32 v18, v18, v19, v21
	v_div_fixup_f32 v21, v18, v0, 0.5
	v_add_f32_e32 v0, v39, v97
	v_sub_f32_e32 v18, v94, v40
	v_mul_f32_e32 v20, v21, v0
	v_sub_f32_e32 v0, v96, v38
	v_mul_f32_e32 v38, v21, v18
	s_mov_b32 s74, s75
	s_waitcnt lgkmcnt(0)
	v_pk_fma_f32 v[18:19], v[98:99], v[116:117], v[138:139] op_sel_hi:[1,0,1]
	v_pk_mul_f32 v[42:43], v[42:43], v[144:145]
	v_pk_fma_f32 v[44:45], v[110:111], v[116:117], v[142:143] op_sel_hi:[1,0,1]
	v_pk_fma_f32 v[108:109], v[108:109], v[116:117], v[132:133] op_sel_hi:[1,0,1]
	v_pk_fma_f32 v[106:107], v[106:107], v[116:117], v[130:131] op_sel_hi:[1,0,1]
	v_pk_fma_f32 v[104:105], v[104:105], v[116:117], v[128:129] op_sel_hi:[1,0,1]
	v_pk_mul_f32 v[16:17], v[102:103], v[122:123]
	v_pk_mul_f32 v[14:15], v[14:15], v[120:121]
	v_mul_f32_e32 v96, v21, v0
	v_add_f32_e32 v0, v41, v95
	v_add_f32_e32 v39, v35, v93
	v_mov_b64_e32 v[40:41], s[74:75]
	v_pk_mul_f32 v[18:19], v[18:19], v[114:115]
	v_mov_b32_e32 v35, v135
	v_pk_mul_f32 v[44:45], v[44:45], v[140:141]
	v_pk_mul_f32 v[46:47], v[108:109], v[46:47]
	v_pk_mul_f32 v[48:49], v[106:107], v[48:49]
	v_pk_mul_f32 v[104:105], v[104:105], v[126:127]
	s_barrier
	ds_write2st64_b64 v148, v[14:15], v[16:17] offset1:8
	ds_write2st64_b64 v148, v[40:41], v[40:41] offset0:64 offset1:72
	ds_write2st64_b64 v148, v[104:105], v[48:49] offset0:16 offset1:24
	ds_write2st64_b64 v148, v[40:41], v[40:41] offset0:80 offset1:88
	ds_write2st64_b64 v148, v[46:47], v[44:45] offset0:32 offset1:40
	ds_write2st64_b64 v148, v[40:41], v[40:41] offset0:96 offset1:104
	ds_write2st64_b64 v148, v[42:43], v[18:19] offset0:48 offset1:56
	ds_write2st64_b64 v148, v[40:41], v[40:41] offset0:112 offset1:120
	s_waitcnt lgkmcnt(0)
	s_barrier
	v_sub_f32_e32 v34, v92, v34
	v_lshlrev_b32_e32 v40, 3, v35
	v_ashrrev_i32_e32 v59, 6, v35
	v_add_u32_e32 v41, 0x50, v40
	v_lshlrev_b32_e32 v53, 3, v59
	ds_read2st64_b64 v[98:101], v41 offset1:8
	ds_read2st64_b64 v[106:109], v41 offset0:64 offset1:72
	v_add3_u32 v40, s85, v40, v53
	ds_read_b64 v[94:95], v40
	v_mul_f32_e32 v40, v21, v39
	v_add_u32_e32 v39, 0x200, v35
	s_waitcnt lgkmcnt(1)
	v_pk_add_f32 v[102:103], v[98:99], v[106:107]
	v_pk_add_f32 v[98:99], v[98:99], v[106:107] neg_lo:[0,1] neg_hi:[0,1]
	ds_write_b64 v41, v[102:103]
	s_waitcnt lgkmcnt(1)
	v_pk_mul_f32 v[102:103], v[98:99], v[94:95] op_sel:[1,1] op_sel_hi:[1,0]
	v_ashrrev_i32_e32 v57, 6, v39
	v_pk_fma_f32 v[106:107], v[98:99], v[94:95], v[102:103] neg_lo:[0,0,1] neg_hi:[0,0,1]
	v_pk_fma_f32 v[94:95], v[98:99], v[94:95], v[102:103] op_sel_hi:[0,1,1]
	v_mov_b32_e32 v107, v95
	v_lshlrev_b32_e32 v53, 3, v57
	v_lshlrev_b32_e32 v55, 3, v39
	ds_write_b64 v41, v[106:107] offset:32768
	v_add3_u32 v53, s85, v53, v55
	ds_read_b64 v[94:95], v53
	v_pk_add_f32 v[92:93], v[100:101], v[108:109]
	v_pk_add_f32 v[98:99], v[100:101], v[108:109] neg_lo:[0,1] neg_hi:[0,1]
	ds_write_b64 v41, v[92:93] offset:4096
	v_add_u32_e32 v61, 0x400, v35
	s_waitcnt lgkmcnt(1)
	v_pk_mul_f32 v[92:93], v[98:99], v[94:95] op_sel:[1,1] op_sel_hi:[1,0]
	v_ashrrev_i32_e32 v55, 6, v61
	v_pk_fma_f32 v[100:101], v[98:99], v[94:95], v[92:93] neg_lo:[0,0,1] neg_hi:[0,0,1]
	v_pk_fma_f32 v[92:93], v[98:99], v[94:95], v[92:93] op_sel_hi:[0,1,1]
	v_mov_b32_e32 v101, v93
	ds_write_b64 v41, v[100:101] offset:36864
	v_lshlrev_b32_e32 v53, 3, v55
	v_lshlrev_b32_e32 v63, 3, v61
	ds_read2st64_b64 v[92:95], v41 offset0:16 offset1:24
	ds_read2st64_b64 v[98:101], v41 offset0:80 offset1:88
	v_add3_u32 v53, s85, v53, v63
	ds_read_b64 v[102:103], v53
	v_add_u32_e32 v63, 0x600, v35
	v_ashrrev_i32_e32 v53, 6, v63
	s_waitcnt lgkmcnt(1)
	v_pk_add_f32 v[106:107], v[92:93], v[98:99]
	v_pk_add_f32 v[92:93], v[92:93], v[98:99] neg_lo:[0,1] neg_hi:[0,1]
	ds_write_b64 v41, v[106:107] offset:8192
	s_waitcnt lgkmcnt(1)
	v_pk_mul_f32 v[98:99], v[92:93], v[102:103] op_sel:[1,1] op_sel_hi:[1,0]
	v_lshlrev_b32_e32 v65, 3, v53
	v_pk_fma_f32 v[106:107], v[92:93], v[102:103], v[98:99] neg_lo:[0,0,1] neg_hi:[0,0,1]
	v_pk_fma_f32 v[92:93], v[92:93], v[102:103], v[98:99] op_sel_hi:[0,1,1]
	v_mov_b32_e32 v107, v93
	v_lshlrev_b32_e32 v92, 3, v63
	ds_write_b64 v41, v[106:107] offset:40960
	v_add3_u32 v65, s85, v65, v92
	ds_read_b64 v[92:93], v65
	v_pk_add_f32 v[98:99], v[94:95], v[100:101]
	v_pk_add_f32 v[94:95], v[94:95], v[100:101] neg_lo:[0,1] neg_hi:[0,1]
	ds_write_b64 v41, v[98:99] offset:12288
	v_add_u32_e32 v65, 0x800, v35
	s_waitcnt lgkmcnt(1)
	v_pk_mul_f32 v[98:99], v[94:95], v[92:93] op_sel:[1,1] op_sel_hi:[1,0]
	v_add_f32_e32 v37, v37, v91
	v_pk_fma_f32 v[100:101], v[94:95], v[92:93], v[98:99] neg_lo:[0,0,1] neg_hi:[0,0,1]
	v_pk_fma_f32 v[92:93], v[94:95], v[92:93], v[98:99] op_sel_hi:[0,1,1]
	v_mov_b32_e32 v101, v93
	v_ashrrev_i32_e32 v91, 6, v65
	ds_write_b64 v41, v[100:101] offset:45056
	v_lshlrev_b32_e32 v91, 3, v91
	v_lshlrev_b32_e32 v65, 3, v65
	ds_read2st64_b64 v[98:101], v41 offset0:32 offset1:40
	ds_read2st64_b64 v[106:109], v41 offset0:96 offset1:104
	v_add3_u32 v65, s85, v91, v65
	ds_read_b64 v[94:95], v65
	v_mul_f32_e32 v92, v21, v37
	v_add_u32_e32 v37, 0xa00, v35
	s_waitcnt lgkmcnt(1)
	v_pk_add_f32 v[102:103], v[98:99], v[106:107]
	v_pk_add_f32 v[98:99], v[98:99], v[106:107] neg_lo:[0,1] neg_hi:[0,1]
	ds_write_b64 v41, v[102:103] offset:16384
	s_waitcnt lgkmcnt(1)
	v_pk_mul_f32 v[102:103], v[98:99], v[94:95] op_sel:[1,1] op_sel_hi:[1,0]
	v_ashrrev_i32_e32 v65, 6, v37
	v_pk_fma_f32 v[106:107], v[98:99], v[94:95], v[102:103] neg_lo:[0,0,1] neg_hi:[0,0,1]
	v_pk_fma_f32 v[94:95], v[98:99], v[94:95], v[102:103] op_sel_hi:[0,1,1]
	v_mov_b32_e32 v107, v95
	v_lshlrev_b32_e32 v65, 3, v65
	v_lshlrev_b32_e32 v37, 3, v37
	ds_write_b64 v41, v[106:107] offset:49152
	v_add3_u32 v37, s85, v65, v37
	ds_read_b64 v[94:95], v37
	v_sub_f32_e32 v65, v90, v36
	v_pk_add_f32 v[36:37], v[100:101], v[108:109]
	v_pk_add_f32 v[90:91], v[100:101], v[108:109] neg_lo:[0,1] neg_hi:[0,1]
	ds_write_b64 v41, v[36:37] offset:20480
	s_waitcnt lgkmcnt(1)
	v_pk_mul_f32 v[36:37], v[90:91], v[94:95] op_sel:[1,1] op_sel_hi:[1,0]
	v_sub_f32_e32 v30, v88, v30
	v_pk_fma_f32 v[98:99], v[90:91], v[94:95], v[36:37] neg_lo:[0,0,1] neg_hi:[0,0,1]
	v_pk_fma_f32 v[36:37], v[90:91], v[94:95], v[36:37] op_sel_hi:[0,1,1]
	v_add_u32_e32 v36, 0xc00, v35
	v_mov_b32_e32 v99, v37
	v_ashrrev_i32_e32 v37, 6, v36
	ds_write_b64 v41, v[98:99] offset:53248
	v_lshlrev_b32_e32 v37, 3, v37
	v_lshlrev_b32_e32 v36, 3, v36
	ds_read2st64_b64 v[98:101], v41 offset0:48 offset1:56
	ds_read2st64_b64 v[106:109], v41 offset0:112 offset1:120
	v_add3_u32 v36, s85, v37, v36
	ds_read_b64 v[90:91], v36
	v_add_u32_e32 v37, 0xe00, v35
	v_mul_f32_e32 v36, v21, v65
	s_waitcnt lgkmcnt(1)
	v_pk_add_f32 v[94:95], v[98:99], v[106:107]
	v_pk_add_f32 v[98:99], v[98:99], v[106:107] neg_lo:[0,1] neg_hi:[0,1]
	ds_write_b64 v41, v[94:95] offset:24576
	s_waitcnt lgkmcnt(1)
	v_pk_mul_f32 v[94:95], v[98:99], v[90:91] op_sel:[1,1] op_sel_hi:[1,0]
	v_ashrrev_i32_e32 v65, 6, v37
	v_pk_fma_f32 v[102:103], v[98:99], v[90:91], v[94:95] neg_lo:[0,0,1] neg_hi:[0,0,1]
	v_pk_fma_f32 v[90:91], v[98:99], v[90:91], v[94:95] op_sel_hi:[0,1,1]
	v_mov_b32_e32 v103, v91
	v_lshlrev_b32_e32 v65, 3, v65
	v_lshlrev_b32_e32 v37, 3, v37
	ds_write_b64 v41, v[102:103] offset:57344
	v_add3_u32 v37, s85, v65, v37
	ds_read_b64 v[90:91], v37
	v_pk_add_f32 v[94:95], v[100:101], v[108:109]
	v_pk_add_f32 v[98:99], v[100:101], v[108:109] neg_lo:[0,1] neg_hi:[0,1]
	ds_write_b64 v41, v[94:95] offset:28672
	v_add_f32_e32 v65, v31, v89
	s_waitcnt lgkmcnt(1)
	v_pk_mul_f32 v[94:95], v[98:99], v[90:91] op_sel:[1,1] op_sel_hi:[1,0]
	v_lshlrev_b32_e32 v31, 2, v35
	v_pk_fma_f32 v[100:101], v[98:99], v[90:91], v[94:95] neg_lo:[0,0,1] neg_hi:[0,0,1]
	v_pk_fma_f32 v[90:91], v[98:99], v[90:91], v[94:95] op_sel_hi:[0,1,1]
	v_mov_b32_e32 v101, v91
	ds_write_b64 v41, v[100:101] offset:61440
	v_and_b32_e32 v41, 0x3ff, v35
	v_lshrrev_b32_e32 v90, 2, v35
	v_and_or_b32 v37, v31, s26, v41
	v_lshlrev_b32_e32 v89, 4, v41
	v_and_b32_e32 v90, 0xf8, v90
	v_lshl_add_u32 v37, v37, 3, v205
	v_add3_u32 v93, s85, v89, v90
	v_lshrrev_b32_e32 v90, 1, v35
	s_waitcnt lgkmcnt(0)
	s_barrier
	v_lshlrev_b32_e32 v89, 5, v41
	ds_read2st64_b64 v[98:101], v37 offset1:16
	ds_read2st64_b64 v[106:109], v37 offset0:32 offset1:48
	v_and_b32_e32 v90, 0x1f8, v90
	v_add3_u32 v89, s85, v89, v90
	ds_read_b64 v[90:91], v89
	v_add_f32_e32 v33, v33, v87
	s_waitcnt lgkmcnt(1)
	v_pk_add_f32 v[94:95], v[98:99], v[106:107]
	v_pk_add_f32 v[102:103], v[100:101], v[108:109]
	v_mov_b32_e32 v116, v108
	v_pk_add_f32 v[110:111], v[94:95], v[102:103]
	v_pk_add_f32 v[94:95], v[94:95], v[102:103] neg_lo:[0,1] neg_hi:[0,1]
	ds_read_b64 v[102:103], v93
	s_waitcnt lgkmcnt(1)
	v_pk_mul_f32 v[112:113], v[94:95], v[90:91] op_sel:[1,1] op_sel_hi:[1,0]
	v_mov_b32_e32 v117, v107
	v_pk_fma_f32 v[114:115], v[94:95], v[90:91], v[112:113] neg_lo:[0,0,1] neg_hi:[0,0,1]
	v_pk_fma_f32 v[94:95], v[94:95], v[90:91], v[112:113] op_sel_hi:[0,1,1]
	v_mov_b32_e32 v115, v95
	v_mov_b32_e32 v94, v98
	v_mov_b32_e32 v95, v100
	v_mov_b32_e32 v112, v106
	v_mov_b32_e32 v113, v108
	v_pk_add_f32 v[94:95], v[94:95], v[112:113] neg_lo:[0,1] neg_hi:[0,1]
	v_mov_b32_e32 v112, v100
	v_mov_b32_e32 v113, v99
	v_pk_add_f32 v[112:113], v[112:113], v[116:117] neg_lo:[0,1] neg_hi:[0,1]
	v_pk_mov_b32 v[116:117], v[100:101], v[98:99] op_sel:[1,0]
	v_pk_mov_b32 v[118:119], v[108:109], v[106:107] op_sel:[1,0]
	v_mov_b32_e32 v100, v99
	v_mov_b32_e32 v108, v107
	v_pk_add_f32 v[98:99], v[100:101], v[108:109] neg_lo:[0,1] neg_hi:[0,1]
	v_pk_add_f32 v[116:117], v[116:117], v[118:119] neg_lo:[0,1] neg_hi:[0,1]
	s_waitcnt lgkmcnt(0)
	v_pk_mul_f32 v[98:99], v[98:99], v[102:103] op_sel:[0,1]
	ds_write2st64_b64 v37, v[110:111], v[114:115] offset1:16
	v_pk_fma_f32 v[94:95], v[94:95], v[102:103], v[98:99] op_sel_hi:[1,0,1] neg_lo:[0,0,1] neg_hi:[0,0,1]
	v_pk_mul_f32 v[98:99], v[116:117], v[102:103]
	v_add_f32_e32 v27, v27, v85
	v_pk_fma_f32 v[98:99], v[112:113], v[102:103], v[98:99] op_sel:[0,1,0] op_sel_hi:[1,0,1]
	v_sub_f32_e32 v26, v84, v26
	v_pk_add_f32 v[100:101], v[98:99], v[94:95]
	v_pk_add_f32 v[102:103], v[98:99], v[94:95] neg_lo:[0,1] neg_hi:[0,1]
	v_pk_add_f32 v[94:95], v[94:95], v[98:99] neg_lo:[0,1] neg_hi:[0,1]
	v_pk_mul_f32 v[98:99], v[90:91], v[100:101] op_sel:[1,1] op_sel_hi:[0,1]
	v_mov_b32_e32 v102, v100
	v_pk_fma_f32 v[100:101], v[90:91], v[94:95], v[98:99] neg_lo:[0,0,1] neg_hi:[0,0,1]
	v_pk_fma_f32 v[90:91], v[90:91], v[94:95], v[98:99] op_sel_hi:[1,0,1]
	v_lshrrev_b32_e32 v94, 2, v39
	v_mov_b32_e32 v101, v91
	ds_write2st64_b64 v37, v[102:103], v[100:101] offset0:32 offset1:48
	v_and_b32_e32 v90, 0x3ff, v39
	v_lshlrev_b32_e32 v37, 2, v39
	v_and_or_b32 v91, v37, s26, v90
	v_lshl_add_u32 v97, v91, 3, v205
	v_lshrrev_b32_e32 v39, 1, v39
	v_lshlrev_b32_e32 v91, 4, v90
	v_lshlrev_b32_e32 v90, 5, v90
	ds_read2st64_b64 v[98:101], v97 offset1:16
	ds_read2st64_b64 v[106:109], v97 offset0:32 offset1:48
	v_and_b32_e32 v39, 0x1f8, v39
	v_and_b32_e32 v94, 0xf8, v94
	v_add3_u32 v39, s85, v90, v39
	v_add3_u32 v112, s85, v91, v94
	ds_read_b64 v[90:91], v39
	s_waitcnt lgkmcnt(1)
	v_pk_add_f32 v[94:95], v[98:99], v[106:107]
	v_pk_add_f32 v[102:103], v[100:101], v[108:109]
	v_mov_b32_e32 v116, v108
	v_pk_add_f32 v[110:111], v[94:95], v[102:103]
	v_pk_add_f32 v[94:95], v[94:95], v[102:103] neg_lo:[0,1] neg_hi:[0,1]
	ds_read_b64 v[102:103], v112
	s_waitcnt lgkmcnt(1)
	v_pk_mul_f32 v[112:113], v[94:95], v[90:91] op_sel:[1,1] op_sel_hi:[1,0]
	v_mov_b32_e32 v117, v107
	v_pk_fma_f32 v[114:115], v[94:95], v[90:91], v[112:113] neg_lo:[0,0,1] neg_hi:[0,0,1]
	v_pk_fma_f32 v[94:95], v[94:95], v[90:91], v[112:113] op_sel_hi:[0,1,1]
	v_mov_b32_e32 v115, v95
	v_mov_b32_e32 v94, v98
	v_mov_b32_e32 v95, v100
	v_mov_b32_e32 v112, v106
	v_mov_b32_e32 v113, v108
	v_pk_add_f32 v[94:95], v[94:95], v[112:113] neg_lo:[0,1] neg_hi:[0,1]
	v_mov_b32_e32 v112, v100
	v_mov_b32_e32 v113, v99
	v_pk_add_f32 v[112:113], v[112:113], v[116:117] neg_lo:[0,1] neg_hi:[0,1]
	v_pk_mov_b32 v[116:117], v[100:101], v[98:99] op_sel:[1,0]
	v_pk_mov_b32 v[118:119], v[108:109], v[106:107] op_sel:[1,0]
	v_mov_b32_e32 v100, v99
	v_mov_b32_e32 v108, v107
	v_pk_add_f32 v[98:99], v[100:101], v[108:109] neg_lo:[0,1] neg_hi:[0,1]
	v_pk_add_f32 v[116:117], v[116:117], v[118:119] neg_lo:[0,1] neg_hi:[0,1]
	s_waitcnt lgkmcnt(0)
	v_pk_mul_f32 v[98:99], v[98:99], v[102:103] op_sel:[0,1]
	v_lshlrev_b32_e32 v39, 2, v61
	v_pk_fma_f32 v[94:95], v[94:95], v[102:103], v[98:99] op_sel_hi:[1,0,1] neg_lo:[0,0,1] neg_hi:[0,0,1]
	v_pk_mul_f32 v[98:99], v[116:117], v[102:103]
	v_and_or_b32 v41, v39, s26, v41
	v_pk_fma_f32 v[98:99], v[112:113], v[102:103], v[98:99] op_sel:[0,1,0] op_sel_hi:[1,0,1]
	ds_write2st64_b64 v97, v[110:111], v[114:115] offset1:16
	v_pk_add_f32 v[100:101], v[98:99], v[94:95]
	v_pk_add_f32 v[102:103], v[98:99], v[94:95] neg_lo:[0,1] neg_hi:[0,1]
	v_pk_add_f32 v[94:95], v[94:95], v[98:99] neg_lo:[0,1] neg_hi:[0,1]
	v_pk_mul_f32 v[98:99], v[90:91], v[100:101] op_sel:[1,1] op_sel_hi:[0,1]
	v_mov_b32_e32 v102, v100
	v_pk_fma_f32 v[100:101], v[90:91], v[94:95], v[98:99] neg_lo:[0,0,1] neg_hi:[0,0,1]
	v_pk_fma_f32 v[90:91], v[90:91], v[94:95], v[98:99] op_sel_hi:[1,0,1]
	v_lshl_add_u32 v41, v41, 3, v205
	v_mov_b32_e32 v101, v91
	ds_write2st64_b64 v97, v[102:103], v[100:101] offset0:32 offset1:48
	ds_read2st64_b64 v[98:101], v41 offset1:16
	ds_read2st64_b64 v[106:109], v41 offset0:32 offset1:48
	ds_read_b64 v[88:89], v89
	v_and_b32_e32 v61, 0x3ff, v63
	v_mul_f32_e32 v90, v21, v65
	v_add_f32_e32 v29, v29, v83
	s_waitcnt lgkmcnt(1)
	v_pk_add_f32 v[94:95], v[98:99], v[106:107]
	v_pk_add_f32 v[102:103], v[100:101], v[108:109]
	v_mov_b32_e32 v116, v108
	v_pk_add_f32 v[110:111], v[94:95], v[102:103]
	v_pk_add_f32 v[94:95], v[94:95], v[102:103] neg_lo:[0,1] neg_hi:[0,1]
	ds_read_b64 v[102:103], v93
	s_waitcnt lgkmcnt(1)
	v_pk_mul_f32 v[112:113], v[94:95], v[88:89] op_sel:[1,1] op_sel_hi:[1,0]
	v_mov_b32_e32 v117, v107
	v_pk_fma_f32 v[114:115], v[94:95], v[88:89], v[112:113] neg_lo:[0,0,1] neg_hi:[0,0,1]
	v_pk_fma_f32 v[94:95], v[94:95], v[88:89], v[112:113] op_sel_hi:[0,1,1]
	v_mov_b32_e32 v115, v95
	v_mov_b32_e32 v94, v98
	v_mov_b32_e32 v95, v100
	v_mov_b32_e32 v112, v106
	v_mov_b32_e32 v113, v108
	v_pk_add_f32 v[94:95], v[94:95], v[112:113] neg_lo:[0,1] neg_hi:[0,1]
	v_mov_b32_e32 v112, v100
	v_mov_b32_e32 v113, v99
	v_pk_add_f32 v[112:113], v[112:113], v[116:117] neg_lo:[0,1] neg_hi:[0,1]
	v_pk_mov_b32 v[116:117], v[100:101], v[98:99] op_sel:[1,0]
	v_pk_mov_b32 v[118:119], v[108:109], v[106:107] op_sel:[1,0]
	v_mov_b32_e32 v100, v99
	v_mov_b32_e32 v108, v107
	v_pk_add_f32 v[98:99], v[100:101], v[108:109] neg_lo:[0,1] neg_hi:[0,1]
	v_pk_add_f32 v[116:117], v[116:117], v[118:119] neg_lo:[0,1] neg_hi:[0,1]
	s_waitcnt lgkmcnt(0)
	v_pk_mul_f32 v[98:99], v[98:99], v[102:103] op_sel:[0,1]
	ds_write2st64_b64 v41, v[110:111], v[114:115] offset1:16
	v_pk_fma_f32 v[94:95], v[94:95], v[102:103], v[98:99] op_sel_hi:[1,0,1] neg_lo:[0,0,1] neg_hi:[0,0,1]
	v_pk_mul_f32 v[98:99], v[116:117], v[102:103]
	v_sub_f32_e32 v28, v82, v28
	v_pk_fma_f32 v[98:99], v[112:113], v[102:103], v[98:99] op_sel:[0,1,0] op_sel_hi:[1,0,1]
	v_add_f32_e32 v23, v23, v81
	v_pk_add_f32 v[100:101], v[98:99], v[94:95]
	v_pk_add_f32 v[102:103], v[98:99], v[94:95] neg_lo:[0,1] neg_hi:[0,1]
	v_pk_add_f32 v[94:95], v[94:95], v[98:99] neg_lo:[0,1] neg_hi:[0,1]
	v_pk_mul_f32 v[98:99], v[88:89], v[100:101] op_sel:[1,1] op_sel_hi:[0,1]
	v_mov_b32_e32 v102, v100
	v_pk_fma_f32 v[100:101], v[88:89], v[94:95], v[98:99] neg_lo:[0,0,1] neg_hi:[0,0,1]
	v_pk_fma_f32 v[88:89], v[88:89], v[94:95], v[98:99] op_sel_hi:[1,0,1]
	v_sub_f32_e32 v24, v78, v24
	v_mov_b32_e32 v101, v89
	ds_write2st64_b64 v41, v[102:103], v[100:101] offset0:32 offset1:48
	v_lshlrev_b32_e32 v41, 2, v63
	v_and_or_b32 v65, v41, s26, v61
	v_lshl_add_u32 v65, v65, 3, v205
	v_lshrrev_b32_e32 v89, 2, v63
	v_lshrrev_b32_e32 v63, 1, v63
	v_lshlrev_b32_e32 v88, 4, v61
	v_lshlrev_b32_e32 v61, 5, v61
	ds_read2st64_b64 v[98:101], v65 offset1:16
	ds_read2st64_b64 v[106:109], v65 offset0:32 offset1:48
	v_and_b32_e32 v63, 0x1f8, v63
	v_and_b32_e32 v89, 0xf8, v89
	v_add3_u32 v61, s85, v61, v63
	v_add3_u32 v91, s85, v88, v89
	ds_read_b64 v[88:89], v61
	s_waitcnt lgkmcnt(1)
	v_pk_add_f32 v[94:95], v[98:99], v[106:107]
	v_pk_add_f32 v[102:103], v[100:101], v[108:109]
	v_mov_b32_e32 v116, v108
	v_pk_add_f32 v[110:111], v[94:95], v[102:103]
	v_pk_add_f32 v[94:95], v[94:95], v[102:103] neg_lo:[0,1] neg_hi:[0,1]
	ds_read_b64 v[102:103], v91
	s_waitcnt lgkmcnt(1)
	v_pk_mul_f32 v[112:113], v[94:95], v[88:89] op_sel:[1,1] op_sel_hi:[1,0]
	v_mov_b32_e32 v117, v107
	v_pk_fma_f32 v[114:115], v[94:95], v[88:89], v[112:113] neg_lo:[0,0,1] neg_hi:[0,0,1]
	v_pk_fma_f32 v[94:95], v[94:95], v[88:89], v[112:113] op_sel_hi:[0,1,1]
	v_mov_b32_e32 v115, v95
	v_mov_b32_e32 v94, v98
	v_mov_b32_e32 v95, v100
	v_mov_b32_e32 v112, v106
	v_mov_b32_e32 v113, v108
	v_pk_add_f32 v[94:95], v[94:95], v[112:113] neg_lo:[0,1] neg_hi:[0,1]
	v_mov_b32_e32 v112, v100
	v_mov_b32_e32 v113, v99
	v_pk_add_f32 v[112:113], v[112:113], v[116:117] neg_lo:[0,1] neg_hi:[0,1]
	v_pk_mov_b32 v[116:117], v[100:101], v[98:99] op_sel:[1,0]
	v_pk_mov_b32 v[118:119], v[108:109], v[106:107] op_sel:[1,0]
	v_mov_b32_e32 v100, v99
	v_mov_b32_e32 v108, v107
	v_pk_add_f32 v[98:99], v[100:101], v[108:109] neg_lo:[0,1] neg_hi:[0,1]
	v_pk_add_f32 v[116:117], v[116:117], v[118:119] neg_lo:[0,1] neg_hi:[0,1]
	s_waitcnt lgkmcnt(0)
	v_pk_mul_f32 v[98:99], v[98:99], v[102:103] op_sel:[0,1]
	v_and_b32_e32 v61, 0xff, v35
	v_pk_fma_f32 v[94:95], v[94:95], v[102:103], v[98:99] op_sel_hi:[1,0,1] neg_lo:[0,0,1] neg_hi:[0,0,1]
	v_pk_mul_f32 v[98:99], v[116:117], v[102:103]
	v_and_or_b32 v63, v31, s34, v61
	v_pk_fma_f32 v[98:99], v[112:113], v[102:103], v[98:99] op_sel:[0,1,0] op_sel_hi:[1,0,1]
	ds_write2st64_b64 v65, v[110:111], v[114:115] offset1:16
	v_pk_add_f32 v[100:101], v[98:99], v[94:95]
	v_pk_add_f32 v[102:103], v[98:99], v[94:95] neg_lo:[0,1] neg_hi:[0,1]
	v_pk_add_f32 v[94:95], v[94:95], v[98:99] neg_lo:[0,1] neg_hi:[0,1]
	v_pk_mul_f32 v[98:99], v[88:89], v[100:101] op_sel:[1,1] op_sel_hi:[0,1]
	v_mov_b32_e32 v102, v100
	v_pk_fma_f32 v[100:101], v[88:89], v[94:95], v[98:99] neg_lo:[0,0,1] neg_hi:[0,0,1]
	v_pk_fma_f32 v[88:89], v[88:89], v[94:95], v[98:99] op_sel_hi:[1,0,1]
	v_lshl_add_u32 v63, v63, 3, v205
	v_mov_b32_e32 v101, v89
	ds_write2st64_b64 v65, v[102:103], v[100:101] offset0:32 offset1:48
	v_lshlrev_b32_e32 v65, 6, v61
	v_and_b32_e32 v88, 0xf8, v35
	v_lshlrev_b32_e32 v89, 1, v35
	s_waitcnt lgkmcnt(0)
	s_barrier
	v_add3_u32 v65, s85, v65, v88
	v_lshlrev_b32_e32 v88, 7, v61
	ds_read2st64_b64 v[98:101], v63 offset1:4
	ds_read2st64_b64 v[106:109], v63 offset0:8 offset1:12
	v_and_b32_e32 v89, 0x1f8, v89
	v_add3_u32 v91, s85, v88, v89
	ds_read_b64 v[88:89], v91
	v_add_f32_e32 v11, v11, v77
	s_waitcnt lgkmcnt(1)
	v_pk_add_f32 v[94:95], v[98:99], v[106:107]
	v_pk_add_f32 v[102:103], v[100:101], v[108:109]
	v_mov_b32_e32 v116, v108
	v_pk_add_f32 v[110:111], v[94:95], v[102:103]
	v_pk_add_f32 v[94:95], v[94:95], v[102:103] neg_lo:[0,1] neg_hi:[0,1]
	ds_read_b64 v[102:103], v65
	s_waitcnt lgkmcnt(1)
	v_pk_mul_f32 v[112:113], v[94:95], v[88:89] op_sel:[1,1] op_sel_hi:[1,0]
	v_mov_b32_e32 v117, v107
	v_pk_fma_f32 v[114:115], v[94:95], v[88:89], v[112:113] neg_lo:[0,0,1] neg_hi:[0,0,1]
	v_pk_fma_f32 v[94:95], v[94:95], v[88:89], v[112:113] op_sel_hi:[0,1,1]
	v_mov_b32_e32 v115, v95
	v_mov_b32_e32 v94, v98
	v_mov_b32_e32 v95, v100
	v_mov_b32_e32 v112, v106
	v_mov_b32_e32 v113, v108
	v_pk_add_f32 v[94:95], v[94:95], v[112:113] neg_lo:[0,1] neg_hi:[0,1]
	v_mov_b32_e32 v112, v100
	v_mov_b32_e32 v113, v99
	v_pk_add_f32 v[112:113], v[112:113], v[116:117] neg_lo:[0,1] neg_hi:[0,1]
	v_pk_mov_b32 v[116:117], v[100:101], v[98:99] op_sel:[1,0]
	v_pk_mov_b32 v[118:119], v[108:109], v[106:107] op_sel:[1,0]
	v_mov_b32_e32 v100, v99
	v_mov_b32_e32 v108, v107
	v_pk_add_f32 v[98:99], v[100:101], v[108:109] neg_lo:[0,1] neg_hi:[0,1]
	v_pk_add_f32 v[116:117], v[116:117], v[118:119] neg_lo:[0,1] neg_hi:[0,1]
	s_waitcnt lgkmcnt(0)
	v_pk_mul_f32 v[98:99], v[98:99], v[102:103] op_sel:[0,1]
	ds_write2st64_b64 v63, v[110:111], v[114:115] offset1:4
	v_pk_fma_f32 v[94:95], v[94:95], v[102:103], v[98:99] op_sel_hi:[1,0,1] neg_lo:[0,0,1] neg_hi:[0,0,1]
	v_pk_mul_f32 v[98:99], v[116:117], v[102:103]
	v_sub_f32_e32 v10, v76, v10
	v_pk_fma_f32 v[98:99], v[112:113], v[102:103], v[98:99] op_sel:[0,1,0] op_sel_hi:[1,0,1]
	v_add_f32_e32 v13, v13, v75
	v_pk_add_f32 v[100:101], v[98:99], v[94:95]
	v_pk_add_f32 v[102:103], v[98:99], v[94:95] neg_lo:[0,1] neg_hi:[0,1]
	v_pk_add_f32 v[94:95], v[94:95], v[98:99] neg_lo:[0,1] neg_hi:[0,1]
	v_pk_mul_f32 v[98:99], v[88:89], v[100:101] op_sel:[1,1] op_sel_hi:[0,1]
	v_mov_b32_e32 v102, v100
	v_pk_fma_f32 v[100:101], v[88:89], v[94:95], v[98:99] neg_lo:[0,0,1] neg_hi:[0,0,1]
	v_pk_fma_f32 v[88:89], v[88:89], v[94:95], v[98:99] op_sel_hi:[1,0,1]
	v_add_f32_e32 v7, v7, v73
	v_mov_b32_e32 v101, v89
	ds_write2st64_b64 v63, v[102:103], v[100:101] offset0:8 offset1:12
	v_and_or_b32 v63, v37, s34, v61
	v_lshl_add_u32 v63, v63, 3, v205
	ds_read2st64_b64 v[98:101], v63 offset1:4
	ds_read2st64_b64 v[106:109], v63 offset0:8 offset1:12
	v_mul_f32_e32 v88, v21, v33
	v_sub_f32_e32 v89, v86, v32
	ds_read_b64 v[32:33], v91
	v_sub_f32_e32 v6, v72, v6
	s_waitcnt lgkmcnt(1)
	v_pk_add_f32 v[86:87], v[98:99], v[106:107]
	v_pk_add_f32 v[94:95], v[100:101], v[108:109]
	v_mov_b32_e32 v114, v108
	v_pk_add_f32 v[102:103], v[86:87], v[94:95]
	v_pk_add_f32 v[86:87], v[86:87], v[94:95] neg_lo:[0,1] neg_hi:[0,1]
	ds_read_b64 v[94:95], v65
	s_waitcnt lgkmcnt(1)
	v_pk_mul_f32 v[110:111], v[86:87], v[32:33] op_sel:[1,1] op_sel_hi:[1,0]
	v_mov_b32_e32 v115, v107
	v_pk_fma_f32 v[112:113], v[86:87], v[32:33], v[110:111] neg_lo:[0,0,1] neg_hi:[0,0,1]
	v_pk_fma_f32 v[86:87], v[86:87], v[32:33], v[110:111] op_sel_hi:[0,1,1]
	v_mov_b32_e32 v113, v87
	v_mov_b32_e32 v86, v98
	v_mov_b32_e32 v87, v100
	v_mov_b32_e32 v110, v106
	v_mov_b32_e32 v111, v108
	v_pk_add_f32 v[86:87], v[86:87], v[110:111] neg_lo:[0,1] neg_hi:[0,1]
	v_mov_b32_e32 v110, v100
	v_mov_b32_e32 v111, v99
	v_pk_add_f32 v[110:111], v[110:111], v[114:115] neg_lo:[0,1] neg_hi:[0,1]
	v_pk_mov_b32 v[114:115], v[100:101], v[98:99] op_sel:[1,0]
	v_pk_mov_b32 v[116:117], v[108:109], v[106:107] op_sel:[1,0]
	v_mov_b32_e32 v100, v99
	v_mov_b32_e32 v108, v107
	v_pk_add_f32 v[98:99], v[100:101], v[108:109] neg_lo:[0,1] neg_hi:[0,1]
	v_pk_add_f32 v[114:115], v[114:115], v[116:117] neg_lo:[0,1] neg_hi:[0,1]
	s_waitcnt lgkmcnt(0)
	v_pk_mul_f32 v[98:99], v[98:99], v[94:95] op_sel:[0,1]
	ds_write2st64_b64 v63, v[102:103], v[112:113] offset1:4
	v_pk_fma_f32 v[86:87], v[86:87], v[94:95], v[98:99] op_sel_hi:[1,0,1] neg_lo:[0,0,1] neg_hi:[0,0,1]
	v_pk_mul_f32 v[98:99], v[114:115], v[94:95]
	v_add_f32_e32 v9, v9, v71
	v_pk_fma_f32 v[94:95], v[110:111], v[94:95], v[98:99] op_sel:[0,1,0] op_sel_hi:[1,0,1]
	v_sub_f32_e32 v8, v70, v8
	v_pk_add_f32 v[98:99], v[94:95], v[86:87]
	v_pk_add_f32 v[100:101], v[94:95], v[86:87] neg_lo:[0,1] neg_hi:[0,1]
	v_pk_add_f32 v[86:87], v[86:87], v[94:95] neg_lo:[0,1] neg_hi:[0,1]
	v_pk_mul_f32 v[94:95], v[32:33], v[98:99] op_sel:[1,1] op_sel_hi:[0,1]
	v_mov_b32_e32 v100, v98
	v_pk_fma_f32 v[98:99], v[32:33], v[86:87], v[94:95] neg_lo:[0,0,1] neg_hi:[0,0,1]
	v_pk_fma_f32 v[32:33], v[32:33], v[86:87], v[94:95] op_sel_hi:[1,0,1]
	v_add_f32_e32 v3, v3, v69
	v_mov_b32_e32 v99, v33
	v_and_or_b32 v32, v39, s34, v61
	ds_write2st64_b64 v63, v[100:101], v[98:99] offset0:8 offset1:12
	v_lshl_add_u32 v33, v32, 3, v205
	ds_read2st64_b64 v[98:101], v33 offset1:4
	ds_read2st64_b64 v[106:109], v33 offset0:8 offset1:12
	ds_read_b64 v[94:95], v91
	v_mul_f32_e32 v32, v21, v27
	v_and_or_b32 v27, v41, s34, v61
	v_lshl_add_u32 v27, v27, 3, v205
	s_waitcnt lgkmcnt(1)
	v_pk_add_f32 v[102:103], v[98:99], v[106:107]
	v_pk_add_f32 v[110:111], v[100:101], v[108:109]
	v_mov_b32_e32 v118, v108
	v_pk_add_f32 v[112:113], v[102:103], v[110:111]
	v_pk_add_f32 v[102:103], v[102:103], v[110:111] neg_lo:[0,1] neg_hi:[0,1]
	ds_read_b64 v[110:111], v65
	s_waitcnt lgkmcnt(1)
	v_pk_mul_f32 v[114:115], v[102:103], v[94:95] op_sel:[1,1] op_sel_hi:[1,0]
	v_mov_b32_e32 v119, v107
	v_pk_fma_f32 v[116:117], v[102:103], v[94:95], v[114:115] neg_lo:[0,0,1] neg_hi:[0,0,1]
	v_pk_fma_f32 v[102:103], v[102:103], v[94:95], v[114:115] op_sel_hi:[0,1,1]
	v_mov_b32_e32 v117, v103
	v_mov_b32_e32 v102, v98
	v_mov_b32_e32 v103, v100
	v_mov_b32_e32 v114, v106
	v_mov_b32_e32 v115, v108
	v_pk_add_f32 v[102:103], v[102:103], v[114:115] neg_lo:[0,1] neg_hi:[0,1]
	v_mov_b32_e32 v114, v100
	v_mov_b32_e32 v115, v99
	v_pk_add_f32 v[114:115], v[114:115], v[118:119] neg_lo:[0,1] neg_hi:[0,1]
	v_pk_mov_b32 v[118:119], v[100:101], v[98:99] op_sel:[1,0]
	v_pk_mov_b32 v[120:121], v[108:109], v[106:107] op_sel:[1,0]
	v_mov_b32_e32 v100, v99
	v_mov_b32_e32 v108, v107
	v_pk_add_f32 v[118:119], v[118:119], v[120:121] neg_lo:[0,1] neg_hi:[0,1]
	v_pk_add_f32 v[98:99], v[100:101], v[108:109] neg_lo:[0,1] neg_hi:[0,1]
	s_waitcnt lgkmcnt(0)
	v_pk_mul_f32 v[100:101], v[118:119], v[110:111]
	v_pk_mul_f32 v[98:99], v[98:99], v[110:111] op_sel:[0,1]
	v_pk_fma_f32 v[100:101], v[114:115], v[110:111], v[100:101] op_sel:[0,1,0] op_sel_hi:[1,0,1]
	v_pk_fma_f32 v[98:99], v[102:103], v[110:111], v[98:99] op_sel_hi:[1,0,1] neg_lo:[0,0,1] neg_hi:[0,0,1]
	ds_write2st64_b64 v33, v[112:113], v[116:117] offset1:4
	v_pk_add_f32 v[102:103], v[100:101], v[98:99]
	v_pk_add_f32 v[106:107], v[100:101], v[98:99] neg_lo:[0,1] neg_hi:[0,1]
	v_pk_add_f32 v[98:99], v[98:99], v[100:101] neg_lo:[0,1] neg_hi:[0,1]
	v_pk_mul_f32 v[100:101], v[94:95], v[102:103] op_sel:[1,1] op_sel_hi:[0,1]
	v_mov_b32_e32 v106, v102
	v_pk_fma_f32 v[102:103], v[94:95], v[98:99], v[100:101] neg_lo:[0,0,1] neg_hi:[0,0,1]
	v_pk_fma_f32 v[94:95], v[94:95], v[98:99], v[100:101] op_sel_hi:[1,0,1]
	v_and_b32_e32 v63, 0xf8, v31
	v_mov_b32_e32 v103, v95
	ds_write2st64_b64 v33, v[106:107], v[102:103] offset0:8 offset1:12
	ds_read2st64_b64 v[98:101], v27 offset1:4
	ds_read2st64_b64 v[106:109], v27 offset0:8 offset1:12
	ds_read_b64 v[84:85], v91
	v_sub_f32_e32 v2, v68, v2
	v_mul_f32_e32 v0, v21, v0
	v_mul_f32_e32 v34, v21, v34
	s_waitcnt lgkmcnt(1)
	v_pk_add_f32 v[94:95], v[98:99], v[106:107]
	v_pk_add_f32 v[102:103], v[100:101], v[108:109]
	v_mov_b32_e32 v116, v108
	v_pk_add_f32 v[110:111], v[94:95], v[102:103]
	v_pk_add_f32 v[94:95], v[94:95], v[102:103] neg_lo:[0,1] neg_hi:[0,1]
	ds_read_b64 v[102:103], v65
	s_waitcnt lgkmcnt(1)
	v_pk_mul_f32 v[112:113], v[94:95], v[84:85] op_sel:[1,1] op_sel_hi:[1,0]
	v_mov_b32_e32 v117, v107
	v_pk_fma_f32 v[114:115], v[94:95], v[84:85], v[112:113] neg_lo:[0,0,1] neg_hi:[0,0,1]
	v_pk_fma_f32 v[94:95], v[94:95], v[84:85], v[112:113] op_sel_hi:[0,1,1]
	v_mov_b32_e32 v115, v95
	v_mov_b32_e32 v94, v98
	v_mov_b32_e32 v95, v100
	v_mov_b32_e32 v112, v106
	v_mov_b32_e32 v113, v108
	v_pk_add_f32 v[94:95], v[94:95], v[112:113] neg_lo:[0,1] neg_hi:[0,1]
	v_mov_b32_e32 v112, v100
	v_mov_b32_e32 v113, v99
	v_pk_add_f32 v[112:113], v[112:113], v[116:117] neg_lo:[0,1] neg_hi:[0,1]
	v_pk_mov_b32 v[116:117], v[100:101], v[98:99] op_sel:[1,0]
	v_pk_mov_b32 v[118:119], v[108:109], v[106:107] op_sel:[1,0]
	v_mov_b32_e32 v100, v99
	v_mov_b32_e32 v108, v107
	v_pk_add_f32 v[98:99], v[100:101], v[108:109] neg_lo:[0,1] neg_hi:[0,1]
	v_pk_add_f32 v[116:117], v[116:117], v[118:119] neg_lo:[0,1] neg_hi:[0,1]
	s_waitcnt lgkmcnt(0)
	v_pk_mul_f32 v[98:99], v[98:99], v[102:103] op_sel:[0,1]
	ds_write2st64_b64 v27, v[110:111], v[114:115] offset1:4
	v_pk_fma_f32 v[94:95], v[94:95], v[102:103], v[98:99] op_sel_hi:[1,0,1] neg_lo:[0,0,1] neg_hi:[0,0,1]
	v_pk_mul_f32 v[98:99], v[116:117], v[102:103]
	v_mul_f32_e32 v30, v21, v30
	v_pk_fma_f32 v[98:99], v[112:113], v[102:103], v[98:99] op_sel:[0,1,0] op_sel_hi:[1,0,1]
	v_mul_f32_e32 v86, v21, v89
	v_pk_add_f32 v[100:101], v[98:99], v[94:95]
	v_pk_add_f32 v[102:103], v[98:99], v[94:95] neg_lo:[0,1] neg_hi:[0,1]
	v_pk_add_f32 v[94:95], v[94:95], v[98:99] neg_lo:[0,1] neg_hi:[0,1]
	v_pk_mul_f32 v[98:99], v[84:85], v[100:101] op_sel:[1,1] op_sel_hi:[0,1]
	v_mov_b32_e32 v102, v100
	v_pk_fma_f32 v[100:101], v[84:85], v[94:95], v[98:99] neg_lo:[0,0,1] neg_hi:[0,0,1]
	v_pk_fma_f32 v[84:85], v[84:85], v[94:95], v[98:99] op_sel_hi:[1,0,1]
	v_mul_f32_e32 v26, v21, v26
	v_mov_b32_e32 v101, v85
	ds_write2st64_b64 v27, v[102:103], v[100:101] offset0:8 offset1:12
	v_and_b32_e32 v27, 63, v35
	v_lshlrev_b32_e32 v33, 3, v27
	v_lshl_or_b32 v59, v59, 11, v33
	v_add_u32_e32 v59, 0x50, v59
	s_waitcnt lgkmcnt(0)
	s_barrier
	v_lshlrev_b32_e32 v61, 8, v27
	ds_read2st64_b64 v[98:101], v59 offset1:1
	ds_read2st64_b64 v[106:109], v59 offset0:2 offset1:3
	v_lshlrev_b32_e32 v27, 9, v27
	v_add3_u32 v27, s85, v27, v33
	ds_read_b64 v[84:85], v27
	v_add3_u32 v61, s85, v61, v63
	s_waitcnt lgkmcnt(1)
	v_pk_add_f32 v[94:95], v[98:99], v[106:107]
	v_pk_add_f32 v[102:103], v[100:101], v[108:109]
	v_mov_b32_e32 v116, v108
	v_pk_add_f32 v[110:111], v[94:95], v[102:103]
	v_pk_add_f32 v[94:95], v[94:95], v[102:103] neg_lo:[0,1] neg_hi:[0,1]
	ds_read_b64 v[102:103], v61
	s_waitcnt lgkmcnt(1)
	v_pk_mul_f32 v[112:113], v[94:95], v[84:85] op_sel:[1,1] op_sel_hi:[1,0]
	v_mov_b32_e32 v117, v107
	v_pk_fma_f32 v[114:115], v[94:95], v[84:85], v[112:113] neg_lo:[0,0,1] neg_hi:[0,0,1]
	v_pk_fma_f32 v[94:95], v[94:95], v[84:85], v[112:113] op_sel_hi:[0,1,1]
	v_mov_b32_e32 v115, v95
	v_mov_b32_e32 v94, v98
	v_mov_b32_e32 v95, v100
	v_mov_b32_e32 v112, v106
	v_mov_b32_e32 v113, v108
	v_pk_add_f32 v[94:95], v[94:95], v[112:113] neg_lo:[0,1] neg_hi:[0,1]
	v_mov_b32_e32 v112, v100
	v_mov_b32_e32 v113, v99
	v_pk_add_f32 v[112:113], v[112:113], v[116:117] neg_lo:[0,1] neg_hi:[0,1]
	v_pk_mov_b32 v[116:117], v[100:101], v[98:99] op_sel:[1,0]
	v_pk_mov_b32 v[118:119], v[108:109], v[106:107] op_sel:[1,0]
	v_mov_b32_e32 v100, v99
	v_mov_b32_e32 v108, v107
	v_pk_add_f32 v[98:99], v[100:101], v[108:109] neg_lo:[0,1] neg_hi:[0,1]
	v_pk_add_f32 v[116:117], v[116:117], v[118:119] neg_lo:[0,1] neg_hi:[0,1]
	s_waitcnt lgkmcnt(0)
	v_pk_mul_f32 v[98:99], v[98:99], v[102:103] op_sel:[0,1]
	v_lshl_or_b32 v57, v57, 11, v33
	v_pk_fma_f32 v[94:95], v[94:95], v[102:103], v[98:99] op_sel_hi:[1,0,1] neg_lo:[0,0,1] neg_hi:[0,0,1]
	v_pk_mul_f32 v[98:99], v[116:117], v[102:103]
	ds_write2st64_b64 v59, v[110:111], v[114:115] offset1:1
	v_pk_fma_f32 v[98:99], v[112:113], v[102:103], v[98:99] op_sel:[0,1,0] op_sel_hi:[1,0,1]
	v_add_u32_e32 v57, 0x50, v57
	v_pk_add_f32 v[100:101], v[98:99], v[94:95]
	v_pk_add_f32 v[102:103], v[98:99], v[94:95] neg_lo:[0,1] neg_hi:[0,1]
	v_pk_add_f32 v[94:95], v[94:95], v[98:99] neg_lo:[0,1] neg_hi:[0,1]
	v_pk_mul_f32 v[98:99], v[84:85], v[100:101] op_sel:[1,1] op_sel_hi:[0,1]
	v_mov_b32_e32 v102, v100
	v_pk_fma_f32 v[100:101], v[84:85], v[94:95], v[98:99] neg_lo:[0,0,1] neg_hi:[0,0,1]
	v_pk_fma_f32 v[84:85], v[84:85], v[94:95], v[98:99] op_sel_hi:[1,0,1]
	v_mul_f32_e32 v28, v21, v28
	v_mov_b32_e32 v101, v85
	ds_write2st64_b64 v59, v[102:103], v[100:101] offset0:2 offset1:3
	ds_read2st64_b64 v[98:101], v57 offset1:1
	ds_read2st64_b64 v[106:109], v57 offset0:2 offset1:3
	ds_read_b64 v[82:83], v27
	v_mul_f32_e32 v84, v21, v29
	v_lshl_or_b32 v29, v55, 11, v33
	v_add_u32_e32 v29, 0x50, v29
	s_waitcnt lgkmcnt(1)
	v_pk_add_f32 v[94:95], v[98:99], v[106:107]
	v_pk_add_f32 v[102:103], v[100:101], v[108:109]
	v_mov_b32_e32 v116, v108
	v_pk_add_f32 v[110:111], v[94:95], v[102:103]
	v_pk_add_f32 v[94:95], v[94:95], v[102:103] neg_lo:[0,1] neg_hi:[0,1]
	ds_read_b64 v[102:103], v61
	s_waitcnt lgkmcnt(1)
	v_pk_mul_f32 v[112:113], v[94:95], v[82:83] op_sel:[1,1] op_sel_hi:[1,0]
	v_mov_b32_e32 v117, v107
	v_pk_fma_f32 v[114:115], v[94:95], v[82:83], v[112:113] neg_lo:[0,0,1] neg_hi:[0,0,1]
	v_pk_fma_f32 v[94:95], v[94:95], v[82:83], v[112:113] op_sel_hi:[0,1,1]
	v_mov_b32_e32 v115, v95
	v_mov_b32_e32 v94, v98
	v_mov_b32_e32 v95, v100
	v_mov_b32_e32 v112, v106
	v_mov_b32_e32 v113, v108
	v_pk_add_f32 v[94:95], v[94:95], v[112:113] neg_lo:[0,1] neg_hi:[0,1]
	v_mov_b32_e32 v112, v100
	v_mov_b32_e32 v113, v99
	v_pk_add_f32 v[112:113], v[112:113], v[116:117] neg_lo:[0,1] neg_hi:[0,1]
	v_pk_mov_b32 v[116:117], v[100:101], v[98:99] op_sel:[1,0]
	v_pk_mov_b32 v[118:119], v[108:109], v[106:107] op_sel:[1,0]
	v_mov_b32_e32 v100, v99
	v_mov_b32_e32 v108, v107
	v_pk_add_f32 v[98:99], v[100:101], v[108:109] neg_lo:[0,1] neg_hi:[0,1]
	v_pk_add_f32 v[116:117], v[116:117], v[118:119] neg_lo:[0,1] neg_hi:[0,1]
	s_waitcnt lgkmcnt(0)
	v_pk_mul_f32 v[98:99], v[98:99], v[102:103] op_sel:[0,1]
	ds_write2st64_b64 v57, v[110:111], v[114:115] offset1:1
	v_pk_fma_f32 v[94:95], v[94:95], v[102:103], v[98:99] op_sel_hi:[1,0,1] neg_lo:[0,0,1] neg_hi:[0,0,1]
	v_pk_mul_f32 v[98:99], v[116:117], v[102:103]
	v_sub_f32_e32 v55, v80, v22
	v_pk_fma_f32 v[98:99], v[112:113], v[102:103], v[98:99] op_sel:[0,1,0] op_sel_hi:[1,0,1]
	v_mul_f32_e32 v24, v21, v24
	v_pk_add_f32 v[100:101], v[98:99], v[94:95]
	v_pk_add_f32 v[102:103], v[98:99], v[94:95] neg_lo:[0,1] neg_hi:[0,1]
	v_pk_add_f32 v[94:95], v[94:95], v[98:99] neg_lo:[0,1] neg_hi:[0,1]
	v_pk_mul_f32 v[98:99], v[82:83], v[100:101] op_sel:[1,1] op_sel_hi:[0,1]
	v_mov_b32_e32 v102, v100
	v_pk_fma_f32 v[100:101], v[82:83], v[94:95], v[98:99] neg_lo:[0,0,1] neg_hi:[0,0,1]
	v_pk_fma_f32 v[82:83], v[82:83], v[94:95], v[98:99] op_sel_hi:[1,0,1]
	v_mul_f32_e32 v10, v21, v10
	v_mov_b32_e32 v101, v83
	ds_write2st64_b64 v57, v[102:103], v[100:101] offset0:2 offset1:3
	ds_read2st64_b64 v[98:101], v29 offset1:1
	ds_read2st64_b64 v[106:109], v29 offset0:2 offset1:3
	v_mul_f32_e32 v82, v21, v23
	ds_read_b64 v[22:23], v27
	v_mul_f32_e32 v6, v21, v6
	v_mul_f32_e32 v8, v21, v8
	s_waitcnt lgkmcnt(1)
	v_pk_add_f32 v[80:81], v[98:99], v[106:107]
	v_pk_add_f32 v[94:95], v[100:101], v[108:109]
	v_mov_b32_e32 v114, v108
	v_pk_add_f32 v[102:103], v[80:81], v[94:95]
	v_pk_add_f32 v[80:81], v[80:81], v[94:95] neg_lo:[0,1] neg_hi:[0,1]
	ds_read_b64 v[94:95], v61
	s_waitcnt lgkmcnt(1)
	v_pk_mul_f32 v[110:111], v[80:81], v[22:23] op_sel:[1,1] op_sel_hi:[1,0]
	v_mov_b32_e32 v115, v107
	v_pk_fma_f32 v[112:113], v[80:81], v[22:23], v[110:111] neg_lo:[0,0,1] neg_hi:[0,0,1]
	v_pk_fma_f32 v[80:81], v[80:81], v[22:23], v[110:111] op_sel_hi:[0,1,1]
	v_mov_b32_e32 v113, v81
	v_mov_b32_e32 v80, v98
	v_mov_b32_e32 v81, v100
	v_mov_b32_e32 v110, v106
	v_mov_b32_e32 v111, v108
	v_pk_add_f32 v[80:81], v[80:81], v[110:111] neg_lo:[0,1] neg_hi:[0,1]
	v_mov_b32_e32 v110, v100
	v_mov_b32_e32 v111, v99
	v_pk_add_f32 v[110:111], v[110:111], v[114:115] neg_lo:[0,1] neg_hi:[0,1]
	v_pk_mov_b32 v[114:115], v[100:101], v[98:99] op_sel:[1,0]
	v_pk_mov_b32 v[116:117], v[108:109], v[106:107] op_sel:[1,0]
	v_mov_b32_e32 v100, v99
	v_mov_b32_e32 v108, v107
	v_pk_add_f32 v[98:99], v[100:101], v[108:109] neg_lo:[0,1] neg_hi:[0,1]
	v_pk_add_f32 v[114:115], v[114:115], v[116:117] neg_lo:[0,1] neg_hi:[0,1]
	s_waitcnt lgkmcnt(0)
	v_pk_mul_f32 v[98:99], v[98:99], v[94:95] op_sel:[0,1]
	ds_write2st64_b64 v29, v[102:103], v[112:113] offset1:1
	v_pk_fma_f32 v[80:81], v[80:81], v[94:95], v[98:99] op_sel_hi:[1,0,1] neg_lo:[0,0,1] neg_hi:[0,0,1]
	v_pk_mul_f32 v[98:99], v[114:115], v[94:95]
	v_mul_f32_e32 v2, v21, v2
	v_pk_fma_f32 v[94:95], v[110:111], v[94:95], v[98:99] op_sel:[0,1,0] op_sel_hi:[1,0,1]
	s_add_u32 s30, s0, 0x800
	v_pk_add_f32 v[98:99], v[94:95], v[80:81]
	v_pk_add_f32 v[100:101], v[94:95], v[80:81] neg_lo:[0,1] neg_hi:[0,1]
	v_pk_add_f32 v[80:81], v[80:81], v[94:95] neg_lo:[0,1] neg_hi:[0,1]
	v_pk_mul_f32 v[94:95], v[22:23], v[98:99] op_sel:[1,1] op_sel_hi:[0,1]
	v_mov_b32_e32 v100, v98
	v_pk_fma_f32 v[98:99], v[22:23], v[80:81], v[94:95] neg_lo:[0,0,1] neg_hi:[0,0,1]
	v_pk_fma_f32 v[22:23], v[22:23], v[80:81], v[94:95] op_sel_hi:[1,0,1]
	v_mul_f32_e32 v80, v21, v55
	v_mov_b32_e32 v99, v23
	v_lshl_or_b32 v22, v53, 11, v33
	ds_write2st64_b64 v29, v[100:101], v[98:99] offset0:2 offset1:3
	v_add_u32_e32 v23, 0x50, v22
	ds_read2st64_b64 v[98:101], v23 offset1:1
	ds_read2st64_b64 v[106:109], v23 offset0:2 offset1:3
	ds_read_b64 v[94:95], v27
	v_add_f32_e32 v22, v25, v79
	v_mul_f32_e32 v22, v21, v22
	v_readlane_b32 s6, v249, 54
	s_waitcnt lgkmcnt(1)
	v_pk_add_f32 v[102:103], v[98:99], v[106:107]
	v_pk_add_f32 v[110:111], v[100:101], v[108:109]
	v_mov_b32_e32 v118, v108
	v_pk_add_f32 v[112:113], v[102:103], v[110:111]
	v_pk_add_f32 v[102:103], v[102:103], v[110:111] neg_lo:[0,1] neg_hi:[0,1]
	ds_read_b64 v[110:111], v61
	s_waitcnt lgkmcnt(1)
	v_pk_mul_f32 v[114:115], v[102:103], v[94:95] op_sel:[1,1] op_sel_hi:[1,0]
	v_mov_b32_e32 v119, v107
	v_pk_fma_f32 v[116:117], v[102:103], v[94:95], v[114:115] neg_lo:[0,0,1] neg_hi:[0,0,1]
	v_pk_fma_f32 v[102:103], v[102:103], v[94:95], v[114:115] op_sel_hi:[0,1,1]
	v_mov_b32_e32 v117, v103
	v_mov_b32_e32 v102, v98
	v_mov_b32_e32 v103, v100
	v_mov_b32_e32 v114, v106
	v_mov_b32_e32 v115, v108
	v_pk_add_f32 v[102:103], v[102:103], v[114:115] neg_lo:[0,1] neg_hi:[0,1]
	v_mov_b32_e32 v114, v100
	v_mov_b32_e32 v115, v99
	v_pk_add_f32 v[114:115], v[114:115], v[118:119] neg_lo:[0,1] neg_hi:[0,1]
	v_pk_mov_b32 v[118:119], v[100:101], v[98:99] op_sel:[1,0]
	v_pk_mov_b32 v[120:121], v[108:109], v[106:107] op_sel:[1,0]
	v_mov_b32_e32 v100, v99
	v_mov_b32_e32 v108, v107
	v_pk_add_f32 v[118:119], v[118:119], v[120:121] neg_lo:[0,1] neg_hi:[0,1]
	v_pk_add_f32 v[98:99], v[100:101], v[108:109] neg_lo:[0,1] neg_hi:[0,1]
	s_waitcnt lgkmcnt(0)
	v_pk_mul_f32 v[100:101], v[118:119], v[110:111]
	v_pk_mul_f32 v[98:99], v[98:99], v[110:111] op_sel:[0,1]
	v_pk_fma_f32 v[100:101], v[114:115], v[110:111], v[100:101] op_sel:[0,1,0] op_sel_hi:[1,0,1]
	v_pk_fma_f32 v[98:99], v[102:103], v[110:111], v[98:99] op_sel_hi:[1,0,1] neg_lo:[0,0,1] neg_hi:[0,0,1]
	ds_write2st64_b64 v23, v[112:113], v[116:117] offset1:1
	v_pk_add_f32 v[102:103], v[100:101], v[98:99]
	v_pk_add_f32 v[106:107], v[100:101], v[98:99] neg_lo:[0,1] neg_hi:[0,1]
	v_pk_add_f32 v[98:99], v[98:99], v[100:101] neg_lo:[0,1] neg_hi:[0,1]
	v_pk_mul_f32 v[100:101], v[94:95], v[102:103] op_sel:[1,1] op_sel_hi:[0,1]
	v_mov_b32_e32 v106, v102
	v_pk_fma_f32 v[102:103], v[94:95], v[98:99], v[100:101] neg_lo:[0,0,1] neg_hi:[0,0,1]
	v_pk_fma_f32 v[94:95], v[94:95], v[98:99], v[100:101] op_sel_hi:[1,0,1]
	s_addc_u32 s31, s1, 0
	v_mov_b32_e32 v103, v95
	ds_write2st64_b64 v23, v[106:107], v[102:103] offset0:2 offset1:3
	v_and_b32_e32 v23, 15, v35
	v_and_or_b32 v25, v31, s35, v23
	v_lshl_add_u32 v25, v25, 3, v205
	v_lshlrev_b32_e32 v27, 10, v23
	v_lshlrev_b32_e32 v29, 4, v23
	s_waitcnt lgkmcnt(0)
	s_barrier
	v_add3_u32 v27, s85, v27, v29
	ds_read2_b64 v[98:101], v25 offset1:16
	ds_read2_b64 v[106:109], v25 offset0:32 offset1:48
	v_lshlrev_b32_e32 v29, 11, v23
	v_lshlrev_b32_e32 v33, 5, v23
	v_add3_u32 v29, s85, v29, v33
	ds_read_b64 v[94:95], v29
	s_waitcnt lgkmcnt(1)
	v_pk_add_f32 v[102:103], v[98:99], v[106:107]
	v_pk_add_f32 v[110:111], v[100:101], v[108:109]
	v_mov_b32_e32 v118, v108
	v_pk_add_f32 v[112:113], v[102:103], v[110:111]
	v_pk_add_f32 v[102:103], v[102:103], v[110:111] neg_lo:[0,1] neg_hi:[0,1]
	ds_read_b64 v[110:111], v27
	s_waitcnt lgkmcnt(1)
	v_pk_mul_f32 v[114:115], v[102:103], v[94:95] op_sel:[1,1] op_sel_hi:[1,0]
	v_mov_b32_e32 v119, v107
	v_pk_fma_f32 v[116:117], v[102:103], v[94:95], v[114:115] neg_lo:[0,0,1] neg_hi:[0,0,1]
	v_pk_fma_f32 v[102:103], v[102:103], v[94:95], v[114:115] op_sel_hi:[0,1,1]
	v_mov_b32_e32 v117, v103
	v_mov_b32_e32 v102, v98
	v_mov_b32_e32 v103, v100
	v_mov_b32_e32 v114, v106
	v_mov_b32_e32 v115, v108
	v_pk_add_f32 v[102:103], v[102:103], v[114:115] neg_lo:[0,1] neg_hi:[0,1]
	v_mov_b32_e32 v114, v100
	v_mov_b32_e32 v115, v99
	v_pk_add_f32 v[114:115], v[114:115], v[118:119] neg_lo:[0,1] neg_hi:[0,1]
	v_pk_mov_b32 v[118:119], v[100:101], v[98:99] op_sel:[1,0]
	v_pk_mov_b32 v[120:121], v[108:109], v[106:107] op_sel:[1,0]
	v_mov_b32_e32 v100, v99
	v_mov_b32_e32 v108, v107
	v_pk_add_f32 v[118:119], v[118:119], v[120:121] neg_lo:[0,1] neg_hi:[0,1]
	v_pk_add_f32 v[98:99], v[100:101], v[108:109] neg_lo:[0,1] neg_hi:[0,1]
	s_waitcnt lgkmcnt(0)
	v_pk_mul_f32 v[100:101], v[118:119], v[110:111]
	v_pk_mul_f32 v[98:99], v[98:99], v[110:111] op_sel:[0,1]
	v_pk_fma_f32 v[100:101], v[114:115], v[110:111], v[100:101] op_sel:[0,1,0] op_sel_hi:[1,0,1]
	v_pk_fma_f32 v[98:99], v[102:103], v[110:111], v[98:99] op_sel_hi:[1,0,1] neg_lo:[0,0,1] neg_hi:[0,0,1]
	ds_write2_b64 v25, v[112:113], v[116:117] offset1:16
	v_pk_add_f32 v[102:103], v[100:101], v[98:99]
	v_pk_add_f32 v[106:107], v[100:101], v[98:99] neg_lo:[0,1] neg_hi:[0,1]
	v_pk_add_f32 v[98:99], v[98:99], v[100:101] neg_lo:[0,1] neg_hi:[0,1]
	v_pk_mul_f32 v[100:101], v[94:95], v[102:103] op_sel:[1,1] op_sel_hi:[0,1]
	v_mov_b32_e32 v106, v102
	v_pk_fma_f32 v[102:103], v[94:95], v[98:99], v[100:101] neg_lo:[0,0,1] neg_hi:[0,0,1]
	v_pk_fma_f32 v[94:95], v[94:95], v[98:99], v[100:101] op_sel_hi:[1,0,1]
	v_readlane_b32 s7, v249, 55
	v_mov_b32_e32 v103, v95
	ds_write2_b64 v25, v[106:107], v[102:103] offset0:32 offset1:48
	v_and_or_b32 v25, v37, s35, v23
	v_lshl_add_u32 v25, v25, 3, v205
	ds_read2_b64 v[98:101], v25 offset1:16
	ds_read2_b64 v[106:109], v25 offset0:32 offset1:48
	ds_read_b64 v[78:79], v29
	s_waitcnt lgkmcnt(1)
	v_pk_add_f32 v[94:95], v[98:99], v[106:107]
	v_pk_add_f32 v[102:103], v[100:101], v[108:109]
	v_mov_b32_e32 v116, v108
	v_pk_add_f32 v[110:111], v[94:95], v[102:103]
	v_pk_add_f32 v[94:95], v[94:95], v[102:103] neg_lo:[0,1] neg_hi:[0,1]
	ds_read_b64 v[102:103], v27
	s_waitcnt lgkmcnt(1)
	v_pk_mul_f32 v[112:113], v[94:95], v[78:79] op_sel:[1,1] op_sel_hi:[1,0]
	v_mov_b32_e32 v117, v107
	v_pk_fma_f32 v[114:115], v[94:95], v[78:79], v[112:113] neg_lo:[0,0,1] neg_hi:[0,0,1]
	v_pk_fma_f32 v[94:95], v[94:95], v[78:79], v[112:113] op_sel_hi:[0,1,1]
	v_mov_b32_e32 v115, v95
	v_mov_b32_e32 v94, v98
	v_mov_b32_e32 v95, v100
	v_mov_b32_e32 v112, v106
	v_mov_b32_e32 v113, v108
	v_pk_add_f32 v[94:95], v[94:95], v[112:113] neg_lo:[0,1] neg_hi:[0,1]
	v_mov_b32_e32 v112, v100
	v_mov_b32_e32 v113, v99
	v_pk_add_f32 v[112:113], v[112:113], v[116:117] neg_lo:[0,1] neg_hi:[0,1]
	v_pk_mov_b32 v[116:117], v[100:101], v[98:99] op_sel:[1,0]
	v_pk_mov_b32 v[118:119], v[108:109], v[106:107] op_sel:[1,0]
	v_mov_b32_e32 v100, v99
	v_mov_b32_e32 v108, v107
	v_pk_add_f32 v[98:99], v[100:101], v[108:109] neg_lo:[0,1] neg_hi:[0,1]
	v_pk_add_f32 v[116:117], v[116:117], v[118:119] neg_lo:[0,1] neg_hi:[0,1]
	s_waitcnt lgkmcnt(0)
	v_pk_mul_f32 v[98:99], v[98:99], v[102:103] op_sel:[0,1]
	ds_write2_b64 v25, v[110:111], v[114:115] offset1:16
	v_pk_fma_f32 v[94:95], v[94:95], v[102:103], v[98:99] op_sel_hi:[1,0,1] neg_lo:[0,0,1] neg_hi:[0,0,1]
	v_pk_mul_f32 v[98:99], v[116:117], v[102:103]
	s_nop 0
	v_pk_fma_f32 v[98:99], v[112:113], v[102:103], v[98:99] op_sel:[0,1,0] op_sel_hi:[1,0,1]
	s_nop 0
	v_pk_add_f32 v[100:101], v[98:99], v[94:95]
	v_pk_add_f32 v[102:103], v[98:99], v[94:95] neg_lo:[0,1] neg_hi:[0,1]
	v_pk_add_f32 v[94:95], v[94:95], v[98:99] neg_lo:[0,1] neg_hi:[0,1]
	v_pk_mul_f32 v[98:99], v[78:79], v[100:101] op_sel:[1,1] op_sel_hi:[0,1]
	v_mov_b32_e32 v102, v100
	v_pk_fma_f32 v[100:101], v[78:79], v[94:95], v[98:99] neg_lo:[0,0,1] neg_hi:[0,0,1]
	v_pk_fma_f32 v[78:79], v[78:79], v[94:95], v[98:99] op_sel_hi:[1,0,1]
	s_nop 0
	v_mov_b32_e32 v101, v79
	ds_write2_b64 v25, v[102:103], v[100:101] offset0:32 offset1:48
	v_and_or_b32 v25, v39, s35, v23
	v_lshl_add_u32 v25, v25, 3, v205
	ds_read2_b64 v[98:101], v25 offset1:16
	ds_read2_b64 v[106:109], v25 offset0:32 offset1:48
	ds_read_b64 v[76:77], v29
	v_mul_f32_e32 v78, v21, v11
	v_and_or_b32 v11, v41, s35, v23
	v_lshl_add_u32 v11, v11, 3, v205
	s_waitcnt lgkmcnt(1)
	v_pk_add_f32 v[94:95], v[98:99], v[106:107]
	v_pk_add_f32 v[102:103], v[100:101], v[108:109]
	v_mov_b32_e32 v116, v108
	v_pk_add_f32 v[110:111], v[94:95], v[102:103]
	v_pk_add_f32 v[94:95], v[94:95], v[102:103] neg_lo:[0,1] neg_hi:[0,1]
	ds_read_b64 v[102:103], v27
	s_waitcnt lgkmcnt(1)
	v_pk_mul_f32 v[112:113], v[94:95], v[76:77] op_sel:[1,1] op_sel_hi:[1,0]
	v_mov_b32_e32 v117, v107
	v_pk_fma_f32 v[114:115], v[94:95], v[76:77], v[112:113] neg_lo:[0,0,1] neg_hi:[0,0,1]
	v_pk_fma_f32 v[94:95], v[94:95], v[76:77], v[112:113] op_sel_hi:[0,1,1]
	v_mov_b32_e32 v115, v95
	v_mov_b32_e32 v94, v98
	v_mov_b32_e32 v95, v100
	v_mov_b32_e32 v112, v106
	v_mov_b32_e32 v113, v108
	v_pk_add_f32 v[94:95], v[94:95], v[112:113] neg_lo:[0,1] neg_hi:[0,1]
	v_mov_b32_e32 v112, v100
	v_mov_b32_e32 v113, v99
	v_pk_add_f32 v[112:113], v[112:113], v[116:117] neg_lo:[0,1] neg_hi:[0,1]
	v_pk_mov_b32 v[116:117], v[100:101], v[98:99] op_sel:[1,0]
	v_pk_mov_b32 v[118:119], v[108:109], v[106:107] op_sel:[1,0]
	v_mov_b32_e32 v100, v99
	v_mov_b32_e32 v108, v107
	v_pk_add_f32 v[98:99], v[100:101], v[108:109] neg_lo:[0,1] neg_hi:[0,1]
	v_pk_add_f32 v[116:117], v[116:117], v[118:119] neg_lo:[0,1] neg_hi:[0,1]
	s_waitcnt lgkmcnt(0)
	v_pk_mul_f32 v[98:99], v[98:99], v[102:103] op_sel:[0,1]
	ds_write2_b64 v25, v[110:111], v[114:115] offset1:16
	v_pk_fma_f32 v[94:95], v[94:95], v[102:103], v[98:99] op_sel_hi:[1,0,1] neg_lo:[0,0,1] neg_hi:[0,0,1]
	v_pk_mul_f32 v[98:99], v[116:117], v[102:103]
	v_sub_f32_e32 v23, v74, v12
	v_pk_fma_f32 v[98:99], v[112:113], v[102:103], v[98:99] op_sel:[0,1,0] op_sel_hi:[1,0,1]
	s_nop 0
	v_pk_add_f32 v[100:101], v[98:99], v[94:95]
	v_pk_add_f32 v[102:103], v[98:99], v[94:95] neg_lo:[0,1] neg_hi:[0,1]
	v_pk_add_f32 v[94:95], v[94:95], v[98:99] neg_lo:[0,1] neg_hi:[0,1]
	v_pk_mul_f32 v[98:99], v[76:77], v[100:101] op_sel:[1,1] op_sel_hi:[0,1]
	v_mov_b32_e32 v102, v100
	v_pk_fma_f32 v[100:101], v[76:77], v[94:95], v[98:99] neg_lo:[0,0,1] neg_hi:[0,0,1]
	v_pk_fma_f32 v[76:77], v[76:77], v[94:95], v[98:99] op_sel_hi:[1,0,1]
	s_nop 0
	v_mov_b32_e32 v101, v77
	ds_write2_b64 v25, v[102:103], v[100:101] offset0:32 offset1:48
	ds_read2_b64 v[98:101], v11 offset1:16
	ds_read2_b64 v[106:109], v11 offset0:32 offset1:48
	v_mul_f32_e32 v76, v21, v13
	ds_read_b64 v[12:13], v29
	s_waitcnt lgkmcnt(1)
	v_pk_add_f32 v[74:75], v[98:99], v[106:107]
	v_pk_add_f32 v[94:95], v[100:101], v[108:109]
	v_mov_b32_e32 v114, v108
	v_pk_add_f32 v[102:103], v[74:75], v[94:95]
	v_pk_add_f32 v[74:75], v[74:75], v[94:95] neg_lo:[0,1] neg_hi:[0,1]
	ds_read_b64 v[94:95], v27
	s_waitcnt lgkmcnt(1)
	v_pk_mul_f32 v[110:111], v[74:75], v[12:13] op_sel:[1,1] op_sel_hi:[1,0]
	v_mov_b32_e32 v115, v107
	v_pk_fma_f32 v[112:113], v[74:75], v[12:13], v[110:111] neg_lo:[0,0,1] neg_hi:[0,0,1]
	v_pk_fma_f32 v[74:75], v[74:75], v[12:13], v[110:111] op_sel_hi:[0,1,1]
	v_mov_b32_e32 v113, v75
	v_mov_b32_e32 v74, v98
	v_mov_b32_e32 v75, v100
	v_mov_b32_e32 v110, v106
	v_mov_b32_e32 v111, v108
	v_pk_add_f32 v[74:75], v[74:75], v[110:111] neg_lo:[0,1] neg_hi:[0,1]
	v_mov_b32_e32 v110, v100
	v_mov_b32_e32 v111, v99
	v_pk_add_f32 v[110:111], v[110:111], v[114:115] neg_lo:[0,1] neg_hi:[0,1]
	v_pk_mov_b32 v[114:115], v[100:101], v[98:99] op_sel:[1,0]
	v_pk_mov_b32 v[116:117], v[108:109], v[106:107] op_sel:[1,0]
	v_mov_b32_e32 v100, v99
	v_mov_b32_e32 v108, v107
	v_pk_add_f32 v[98:99], v[100:101], v[108:109] neg_lo:[0,1] neg_hi:[0,1]
	v_pk_add_f32 v[114:115], v[114:115], v[116:117] neg_lo:[0,1] neg_hi:[0,1]
	s_waitcnt lgkmcnt(0)
	v_pk_mul_f32 v[98:99], v[98:99], v[94:95] op_sel:[0,1]
	ds_write2_b64 v11, v[102:103], v[112:113] offset1:16
	v_pk_fma_f32 v[74:75], v[74:75], v[94:95], v[98:99] op_sel_hi:[1,0,1] neg_lo:[0,0,1] neg_hi:[0,0,1]
	v_pk_mul_f32 v[98:99], v[114:115], v[94:95]
	s_nop 0
	v_pk_fma_f32 v[94:95], v[110:111], v[94:95], v[98:99] op_sel:[0,1,0] op_sel_hi:[1,0,1]
	s_nop 0
	v_pk_add_f32 v[98:99], v[94:95], v[74:75]
	v_pk_add_f32 v[100:101], v[94:95], v[74:75] neg_lo:[0,1] neg_hi:[0,1]
	v_pk_add_f32 v[74:75], v[74:75], v[94:95] neg_lo:[0,1] neg_hi:[0,1]
	v_pk_mul_f32 v[94:95], v[12:13], v[98:99] op_sel:[1,1] op_sel_hi:[0,1]
	v_mov_b32_e32 v100, v98
	v_pk_fma_f32 v[98:99], v[12:13], v[74:75], v[94:95] neg_lo:[0,0,1] neg_hi:[0,0,1]
	v_pk_fma_f32 v[12:13], v[12:13], v[74:75], v[94:95] op_sel_hi:[1,0,1]
	s_nop 0
	v_mov_b32_e32 v99, v13
	ds_write2_b64 v11, v[100:101], v[98:99] offset0:32 offset1:48
	v_and_b32_e32 v11, 3, v35
	v_and_or_b32 v12, v31, s5, v11
	v_lshl_add_u32 v25, v12, 3, v205
	v_lshlrev_b32_e32 v12, 12, v11
	v_lshlrev_b32_e32 v13, 6, v11
	s_waitcnt lgkmcnt(0)
	s_barrier
	v_add3_u32 v27, s85, v12, v13
	ds_read2_b64 v[98:101], v25 offset1:4
	ds_read2_b64 v[106:109], v25 offset0:8 offset1:12
	v_lshlrev_b32_e32 v12, 13, v11
	v_lshlrev_b32_e32 v13, 7, v11
	v_add3_u32 v29, s85, v12, v13
	ds_read_b64 v[12:13], v29
	s_waitcnt lgkmcnt(1)
	v_pk_add_f32 v[74:75], v[98:99], v[106:107]
	v_pk_add_f32 v[94:95], v[100:101], v[108:109]
	v_mov_b32_e32 v114, v108
	v_pk_add_f32 v[102:103], v[74:75], v[94:95]
	v_pk_add_f32 v[74:75], v[74:75], v[94:95] neg_lo:[0,1] neg_hi:[0,1]
	ds_read_b64 v[94:95], v27
	s_waitcnt lgkmcnt(1)
	v_pk_mul_f32 v[110:111], v[74:75], v[12:13] op_sel:[1,1] op_sel_hi:[1,0]
	v_mov_b32_e32 v115, v107
	v_pk_fma_f32 v[112:113], v[74:75], v[12:13], v[110:111] neg_lo:[0,0,1] neg_hi:[0,0,1]
	v_pk_fma_f32 v[74:75], v[74:75], v[12:13], v[110:111] op_sel_hi:[0,1,1]
	v_mov_b32_e32 v113, v75
	v_mov_b32_e32 v74, v98
	v_mov_b32_e32 v75, v100
	v_mov_b32_e32 v110, v106
	v_mov_b32_e32 v111, v108
	v_pk_add_f32 v[74:75], v[74:75], v[110:111] neg_lo:[0,1] neg_hi:[0,1]
	v_mov_b32_e32 v110, v100
	v_mov_b32_e32 v111, v99
	v_pk_add_f32 v[110:111], v[110:111], v[114:115] neg_lo:[0,1] neg_hi:[0,1]
	v_pk_mov_b32 v[114:115], v[100:101], v[98:99] op_sel:[1,0]
	v_pk_mov_b32 v[116:117], v[108:109], v[106:107] op_sel:[1,0]
	v_mov_b32_e32 v100, v99
	v_mov_b32_e32 v108, v107
	v_pk_add_f32 v[98:99], v[100:101], v[108:109] neg_lo:[0,1] neg_hi:[0,1]
	v_pk_add_f32 v[114:115], v[114:115], v[116:117] neg_lo:[0,1] neg_hi:[0,1]
	s_waitcnt lgkmcnt(0)
	v_pk_mul_f32 v[98:99], v[98:99], v[94:95] op_sel:[0,1]
	ds_write2_b64 v25, v[102:103], v[112:113] offset1:4
	v_pk_fma_f32 v[74:75], v[74:75], v[94:95], v[98:99] op_sel_hi:[1,0,1] neg_lo:[0,0,1] neg_hi:[0,0,1]
	v_pk_mul_f32 v[98:99], v[114:115], v[94:95]
	s_nop 0
	v_pk_fma_f32 v[94:95], v[110:111], v[94:95], v[98:99] op_sel:[0,1,0] op_sel_hi:[1,0,1]
	s_nop 0
	v_pk_add_f32 v[98:99], v[94:95], v[74:75]
	v_pk_add_f32 v[100:101], v[94:95], v[74:75] neg_lo:[0,1] neg_hi:[0,1]
	v_pk_add_f32 v[74:75], v[74:75], v[94:95] neg_lo:[0,1] neg_hi:[0,1]
	v_pk_mul_f32 v[94:95], v[12:13], v[98:99] op_sel:[1,1] op_sel_hi:[0,1]
	v_mov_b32_e32 v100, v98
	v_pk_fma_f32 v[98:99], v[12:13], v[74:75], v[94:95] neg_lo:[0,0,1] neg_hi:[0,0,1]
	v_pk_fma_f32 v[12:13], v[12:13], v[74:75], v[94:95] op_sel_hi:[1,0,1]
	v_mul_f32_e32 v74, v21, v23
	v_mov_b32_e32 v99, v13
	v_and_or_b32 v12, v37, s5, v11
	ds_write2_b64 v25, v[100:101], v[98:99] offset0:8 offset1:12
	v_lshl_add_u32 v13, v12, 3, v205
	ds_read2_b64 v[98:101], v13 offset1:4
	ds_read2_b64 v[106:109], v13 offset0:8 offset1:12
	ds_read_b64 v[94:95], v29
	v_mul_f32_e32 v12, v21, v7
	v_and_or_b32 v7, v39, s5, v11
	v_lshl_add_u32 v7, v7, 3, v205
	s_waitcnt lgkmcnt(1)
	v_pk_add_f32 v[102:103], v[98:99], v[106:107]
	v_pk_add_f32 v[110:111], v[100:101], v[108:109]
	v_mov_b32_e32 v118, v108
	v_pk_add_f32 v[112:113], v[102:103], v[110:111]
	v_pk_add_f32 v[102:103], v[102:103], v[110:111] neg_lo:[0,1] neg_hi:[0,1]
	ds_read_b64 v[110:111], v27
	s_waitcnt lgkmcnt(1)
	v_pk_mul_f32 v[114:115], v[102:103], v[94:95] op_sel:[1,1] op_sel_hi:[1,0]
	v_mov_b32_e32 v119, v107
	v_pk_fma_f32 v[116:117], v[102:103], v[94:95], v[114:115] neg_lo:[0,0,1] neg_hi:[0,0,1]
	v_pk_fma_f32 v[102:103], v[102:103], v[94:95], v[114:115] op_sel_hi:[0,1,1]
	v_mov_b32_e32 v117, v103
	v_mov_b32_e32 v102, v98
	v_mov_b32_e32 v103, v100
	v_mov_b32_e32 v114, v106
	v_mov_b32_e32 v115, v108
	v_pk_add_f32 v[102:103], v[102:103], v[114:115] neg_lo:[0,1] neg_hi:[0,1]
	v_mov_b32_e32 v114, v100
	v_mov_b32_e32 v115, v99
	v_pk_add_f32 v[114:115], v[114:115], v[118:119] neg_lo:[0,1] neg_hi:[0,1]
	v_pk_mov_b32 v[118:119], v[100:101], v[98:99] op_sel:[1,0]
	v_pk_mov_b32 v[120:121], v[108:109], v[106:107] op_sel:[1,0]
	v_mov_b32_e32 v100, v99
	v_mov_b32_e32 v108, v107
	v_pk_add_f32 v[118:119], v[118:119], v[120:121] neg_lo:[0,1] neg_hi:[0,1]
	v_pk_add_f32 v[98:99], v[100:101], v[108:109] neg_lo:[0,1] neg_hi:[0,1]
	s_waitcnt lgkmcnt(0)
	v_pk_mul_f32 v[100:101], v[118:119], v[110:111]
	v_pk_mul_f32 v[98:99], v[98:99], v[110:111] op_sel:[0,1]
	v_pk_fma_f32 v[100:101], v[114:115], v[110:111], v[100:101] op_sel:[0,1,0] op_sel_hi:[1,0,1]
	v_pk_fma_f32 v[98:99], v[102:103], v[110:111], v[98:99] op_sel_hi:[1,0,1] neg_lo:[0,0,1] neg_hi:[0,0,1]
	ds_write2_b64 v13, v[112:113], v[116:117] offset1:4
	v_pk_add_f32 v[102:103], v[100:101], v[98:99]
	v_pk_add_f32 v[106:107], v[100:101], v[98:99] neg_lo:[0,1] neg_hi:[0,1]
	v_pk_add_f32 v[98:99], v[98:99], v[100:101] neg_lo:[0,1] neg_hi:[0,1]
	v_pk_mul_f32 v[100:101], v[94:95], v[102:103] op_sel:[1,1] op_sel_hi:[0,1]
	v_mov_b32_e32 v106, v102
	v_pk_fma_f32 v[102:103], v[94:95], v[98:99], v[100:101] neg_lo:[0,0,1] neg_hi:[0,0,1]
	v_pk_fma_f32 v[94:95], v[94:95], v[98:99], v[100:101] op_sel_hi:[1,0,1]
	s_nop 0
	v_mov_b32_e32 v103, v95
	ds_write2_b64 v13, v[106:107], v[102:103] offset0:8 offset1:12
	ds_read2_b64 v[98:101], v7 offset1:4
	ds_read2_b64 v[106:109], v7 offset0:8 offset1:12
	ds_read_b64 v[72:73], v29
	s_waitcnt lgkmcnt(1)
	v_pk_add_f32 v[94:95], v[98:99], v[106:107]
	v_pk_add_f32 v[102:103], v[100:101], v[108:109]
	v_mov_b32_e32 v116, v108
	v_pk_add_f32 v[110:111], v[94:95], v[102:103]
	v_pk_add_f32 v[94:95], v[94:95], v[102:103] neg_lo:[0,1] neg_hi:[0,1]
	ds_read_b64 v[102:103], v27
	s_waitcnt lgkmcnt(1)
	v_pk_mul_f32 v[112:113], v[94:95], v[72:73] op_sel:[1,1] op_sel_hi:[1,0]
	v_mov_b32_e32 v117, v107
	v_pk_fma_f32 v[114:115], v[94:95], v[72:73], v[112:113] neg_lo:[0,0,1] neg_hi:[0,0,1]
	v_pk_fma_f32 v[94:95], v[94:95], v[72:73], v[112:113] op_sel_hi:[0,1,1]
	v_mov_b32_e32 v115, v95
	v_mov_b32_e32 v94, v98
	v_mov_b32_e32 v95, v100
	v_mov_b32_e32 v112, v106
	v_mov_b32_e32 v113, v108
	v_pk_add_f32 v[94:95], v[94:95], v[112:113] neg_lo:[0,1] neg_hi:[0,1]
	v_mov_b32_e32 v112, v100
	v_mov_b32_e32 v113, v99
	v_pk_add_f32 v[112:113], v[112:113], v[116:117] neg_lo:[0,1] neg_hi:[0,1]
	v_pk_mov_b32 v[116:117], v[100:101], v[98:99] op_sel:[1,0]
	v_pk_mov_b32 v[118:119], v[108:109], v[106:107] op_sel:[1,0]
	v_mov_b32_e32 v100, v99
	v_mov_b32_e32 v108, v107
	v_pk_add_f32 v[98:99], v[100:101], v[108:109] neg_lo:[0,1] neg_hi:[0,1]
	v_pk_add_f32 v[116:117], v[116:117], v[118:119] neg_lo:[0,1] neg_hi:[0,1]
	s_waitcnt lgkmcnt(0)
	v_pk_mul_f32 v[98:99], v[98:99], v[102:103] op_sel:[0,1]
	ds_write2_b64 v7, v[110:111], v[114:115] offset1:4
	v_pk_fma_f32 v[94:95], v[94:95], v[102:103], v[98:99] op_sel_hi:[1,0,1] neg_lo:[0,0,1] neg_hi:[0,0,1]
	v_pk_mul_f32 v[98:99], v[116:117], v[102:103]
	s_nop 0
	v_pk_fma_f32 v[98:99], v[112:113], v[102:103], v[98:99] op_sel:[0,1,0] op_sel_hi:[1,0,1]
	s_nop 0
	v_pk_add_f32 v[100:101], v[98:99], v[94:95]
	v_pk_add_f32 v[102:103], v[98:99], v[94:95] neg_lo:[0,1] neg_hi:[0,1]
	v_pk_add_f32 v[94:95], v[94:95], v[98:99] neg_lo:[0,1] neg_hi:[0,1]
	v_pk_mul_f32 v[98:99], v[72:73], v[100:101] op_sel:[1,1] op_sel_hi:[0,1]
	v_mov_b32_e32 v102, v100
	v_pk_fma_f32 v[100:101], v[72:73], v[94:95], v[98:99] neg_lo:[0,0,1] neg_hi:[0,0,1]
	v_pk_fma_f32 v[72:73], v[72:73], v[94:95], v[98:99] op_sel_hi:[1,0,1]
	s_nop 0
	v_mov_b32_e32 v101, v73
	ds_write2_b64 v7, v[102:103], v[100:101] offset0:8 offset1:12
	v_and_or_b32 v7, v41, s5, v11
	v_lshl_add_u32 v7, v7, 3, v205
	ds_read2_b64 v[98:101], v7 offset1:4
	ds_read2_b64 v[106:109], v7 offset0:8 offset1:12
	ds_read_b64 v[70:71], v29
	v_mul_f32_e32 v72, v21, v9
	s_waitcnt lgkmcnt(1)
	v_pk_add_f32 v[94:95], v[98:99], v[106:107]
	v_pk_add_f32 v[102:103], v[100:101], v[108:109]
	v_mov_b32_e32 v116, v108
	v_pk_add_f32 v[110:111], v[94:95], v[102:103]
	v_pk_add_f32 v[94:95], v[94:95], v[102:103] neg_lo:[0,1] neg_hi:[0,1]
	ds_read_b64 v[102:103], v27
	s_waitcnt lgkmcnt(1)
	v_pk_mul_f32 v[112:113], v[94:95], v[70:71] op_sel:[1,1] op_sel_hi:[1,0]
	v_mov_b32_e32 v117, v107
	v_pk_fma_f32 v[114:115], v[94:95], v[70:71], v[112:113] neg_lo:[0,0,1] neg_hi:[0,0,1]
	v_pk_fma_f32 v[94:95], v[94:95], v[70:71], v[112:113] op_sel_hi:[0,1,1]
	v_mov_b32_e32 v115, v95
	v_mov_b32_e32 v94, v98
	v_mov_b32_e32 v95, v100
	v_mov_b32_e32 v112, v106
	v_mov_b32_e32 v113, v108
	v_pk_add_f32 v[94:95], v[94:95], v[112:113] neg_lo:[0,1] neg_hi:[0,1]
	v_mov_b32_e32 v112, v100
	v_mov_b32_e32 v113, v99
	v_pk_add_f32 v[112:113], v[112:113], v[116:117] neg_lo:[0,1] neg_hi:[0,1]
	v_pk_mov_b32 v[116:117], v[100:101], v[98:99] op_sel:[1,0]
	v_pk_mov_b32 v[118:119], v[108:109], v[106:107] op_sel:[1,0]
	v_mov_b32_e32 v100, v99
	v_mov_b32_e32 v108, v107
	v_pk_add_f32 v[98:99], v[100:101], v[108:109] neg_lo:[0,1] neg_hi:[0,1]
	v_pk_add_f32 v[116:117], v[116:117], v[118:119] neg_lo:[0,1] neg_hi:[0,1]
	s_waitcnt lgkmcnt(0)
	v_pk_mul_f32 v[98:99], v[98:99], v[102:103] op_sel:[0,1]
	ds_write2_b64 v7, v[110:111], v[114:115] offset1:4
	v_pk_fma_f32 v[94:95], v[94:95], v[102:103], v[98:99] op_sel_hi:[1,0,1] neg_lo:[0,0,1] neg_hi:[0,0,1]
	v_pk_mul_f32 v[98:99], v[116:117], v[102:103]
	s_nop 0
	v_pk_fma_f32 v[98:99], v[112:113], v[102:103], v[98:99] op_sel:[0,1,0] op_sel_hi:[1,0,1]
	s_nop 0
	v_pk_add_f32 v[100:101], v[98:99], v[94:95]
	v_pk_add_f32 v[102:103], v[98:99], v[94:95] neg_lo:[0,1] neg_hi:[0,1]
	v_pk_add_f32 v[94:95], v[94:95], v[98:99] neg_lo:[0,1] neg_hi:[0,1]
	v_pk_mul_f32 v[98:99], v[70:71], v[100:101] op_sel:[1,1] op_sel_hi:[0,1]
	v_mov_b32_e32 v102, v100
	v_pk_fma_f32 v[100:101], v[70:71], v[94:95], v[98:99] neg_lo:[0,0,1] neg_hi:[0,0,1]
	v_pk_fma_f32 v[70:71], v[70:71], v[94:95], v[98:99] op_sel_hi:[1,0,1]
	s_nop 0
	v_mov_b32_e32 v101, v71
	ds_write2_b64 v7, v[102:103], v[100:101] offset0:8 offset1:12
	v_lshl_add_u32 v7, v35, 5, v205
	s_waitcnt lgkmcnt(0)
	s_barrier
	ds_read_b128 v[98:101], v7
	ds_read_b128 v[106:109], v7 offset:16
	v_mul_f32_e32 v70, v21, v3
	v_add_f32_e32 v3, v5, v67
	s_waitcnt lgkmcnt(0)
	v_pk_add_f32 v[68:69], v[98:99], v[106:107]
	v_pk_add_f32 v[94:95], v[100:101], v[108:109]
	s_nop 0
	v_pk_add_f32 v[110:111], v[68:69], v[94:95]
	v_pk_add_f32 v[112:113], v[68:69], v[94:95] neg_lo:[0,1] neg_hi:[0,1]
	ds_write_b128 v7, v[110:113]
	v_pk_add_f32 v[68:69], v[98:99], v[106:107] neg_lo:[0,1] neg_hi:[0,1]
	v_pk_add_f32 v[94:95], v[100:101], v[108:109] neg_lo:[0,1] neg_hi:[0,1]
	ds_read_b128 v[106:109], v7 offset:16384
	ds_read_b128 v[110:113], v7 offset:16400
	v_pk_add_f32 v[102:103], v[68:69], v[94:95] op_sel:[0,1] op_sel_hi:[1,0]
	v_pk_add_f32 v[100:101], v[68:69], v[94:95] op_sel:[0,1] op_sel_hi:[1,0] neg_lo:[0,1] neg_hi:[0,1]
	v_mov_b32_e32 v98, v102
	v_mov_b32_e32 v99, v101
	v_mov_b32_e32 v101, v103
	s_waitcnt lgkmcnt(0)
	v_pk_add_f32 v[68:69], v[106:107], v[110:111]
	v_pk_add_f32 v[94:95], v[108:109], v[112:113]
	ds_write_b128 v7, v[98:101] offset:16
	v_pk_add_f32 v[98:99], v[68:69], v[94:95]
	v_pk_add_f32 v[100:101], v[68:69], v[94:95] neg_lo:[0,1] neg_hi:[0,1]
	ds_write_b128 v7, v[98:101] offset:16384
	v_pk_add_f32 v[68:69], v[106:107], v[110:111] neg_lo:[0,1] neg_hi:[0,1]
	v_pk_add_f32 v[94:95], v[108:109], v[112:113] neg_lo:[0,1] neg_hi:[0,1]
	ds_read_b128 v[106:109], v7 offset:32768
	ds_read_b128 v[110:113], v7 offset:32784
	v_pk_add_f32 v[102:103], v[68:69], v[94:95] op_sel:[0,1] op_sel_hi:[1,0]
	v_pk_add_f32 v[100:101], v[68:69], v[94:95] op_sel:[0,1] op_sel_hi:[1,0] neg_lo:[0,1] neg_hi:[0,1]
	v_mov_b32_e32 v98, v102
	v_mov_b32_e32 v99, v101
	v_mov_b32_e32 v101, v103
	s_waitcnt lgkmcnt(0)
	v_pk_add_f32 v[68:69], v[106:107], v[110:111]
	v_pk_add_f32 v[94:95], v[108:109], v[112:113]
	ds_write_b128 v7, v[98:101] offset:16400
	v_pk_add_f32 v[98:99], v[68:69], v[94:95]
	v_pk_add_f32 v[100:101], v[68:69], v[94:95] neg_lo:[0,1] neg_hi:[0,1]
	ds_write_b128 v7, v[98:101] offset:32768
	v_pk_add_f32 v[68:69], v[106:107], v[110:111] neg_lo:[0,1] neg_hi:[0,1]
	v_pk_add_f32 v[94:95], v[108:109], v[112:113] neg_lo:[0,1] neg_hi:[0,1]
	ds_read_b128 v[106:109], v7 offset:49152
	ds_read_b128 v[110:113], v7 offset:49168
	v_pk_add_f32 v[102:103], v[68:69], v[94:95] op_sel:[0,1] op_sel_hi:[1,0]
	v_pk_add_f32 v[100:101], v[68:69], v[94:95] op_sel:[0,1] op_sel_hi:[1,0] neg_lo:[0,1] neg_hi:[0,1]
	v_mov_b32_e32 v98, v102
	v_mov_b32_e32 v99, v101
	v_mov_b32_e32 v101, v103
	s_waitcnt lgkmcnt(0)
	v_pk_add_f32 v[68:69], v[106:107], v[110:111]
	v_pk_add_f32 v[94:95], v[108:109], v[112:113]
	ds_write_b128 v7, v[98:101] offset:32784
	v_pk_add_f32 v[98:99], v[68:69], v[94:95]
	v_pk_add_f32 v[100:101], v[68:69], v[94:95] neg_lo:[0,1] neg_hi:[0,1]
	v_pk_add_f32 v[68:69], v[106:107], v[110:111] neg_lo:[0,1] neg_hi:[0,1]
	v_pk_add_f32 v[94:95], v[108:109], v[112:113] neg_lo:[0,1] neg_hi:[0,1]
	ds_write_b128 v7, v[98:101] offset:49152
	v_pk_add_f32 v[102:103], v[68:69], v[94:95] op_sel:[0,1] op_sel_hi:[1,0]
	v_pk_add_f32 v[100:101], v[68:69], v[94:95] op_sel:[0,1] op_sel_hi:[1,0] neg_lo:[0,1] neg_hi:[0,1]
	v_mov_b32_e32 v98, v102
	v_mov_b32_e32 v99, v101
	v_mov_b32_e32 v101, v103
	ds_write_b128 v7, v[98:101] offset:49168
	s_waitcnt lgkmcnt(0)
	s_barrier
	ds_read2st64_b64 v[98:101], v148 offset1:8
	v_mul_f32_e32 v94, v21, v3
	v_sub_f32_e32 v3, v66, v4
	ds_read2st64_b64 v[66:69], v148 offset0:16 offset1:24
	v_mul_f32_e32 v102, v21, v3
	s_waitcnt lgkmcnt(1)
	v_pk_mul_f32 v[4:5], v[96:97], v[98:99] op_sel:[0,1] op_sel_hi:[0,0]
	v_pk_fma_f32 v[96:97], v[20:21], v[98:99], v[4:5] neg_lo:[0,0,1] neg_hi:[0,0,1]
	v_pk_fma_f32 v[4:5], v[20:21], v[98:99], v[4:5] op_sel_hi:[0,1,1]
	v_mov_b32_e32 v97, v5
	v_pk_mul_f32 v[4:5], v[38:39], v[100:101] op_sel:[0,1] op_sel_hi:[0,0]
	v_pk_fma_f32 v[20:21], v[0:1], v[100:101], v[4:5] neg_lo:[0,0,1] neg_hi:[0,0,1]
	v_pk_fma_f32 v[4:5], v[0:1], v[100:101], v[4:5] op_sel_hi:[0,1,1]
	v_mov_b32_e32 v21, v5
	s_waitcnt lgkmcnt(0)
	v_pk_mul_f32 v[4:5], v[34:35], v[66:67] op_sel:[0,1] op_sel_hi:[0,0]
	ds_write2st64_b64 v148, v[96:97], v[20:21] offset1:8
	v_pk_fma_f32 v[20:21], v[40:41], v[66:67], v[4:5] neg_lo:[0,0,1] neg_hi:[0,0,1]
	v_pk_fma_f32 v[4:5], v[40:41], v[66:67], v[4:5] op_sel_hi:[0,1,1]
	v_mov_b32_e32 v21, v5
	v_pk_mul_f32 v[4:5], v[36:37], v[68:69] op_sel:[0,1] op_sel_hi:[0,0]
	ds_read2st64_b64 v[34:37], v148 offset0:32 offset1:40
	v_pk_fma_f32 v[38:39], v[92:93], v[68:69], v[4:5] neg_lo:[0,0,1] neg_hi:[0,0,1]
	v_pk_fma_f32 v[4:5], v[92:93], v[68:69], v[4:5] op_sel_hi:[0,1,1]
	v_mov_b32_e32 v39, v5
	ds_write2st64_b64 v148, v[20:21], v[38:39] offset0:16 offset1:24
	ds_read2st64_b64 v[38:41], v148 offset0:48 offset1:56
	s_waitcnt lgkmcnt(2)
	v_pk_mul_f32 v[4:5], v[30:31], v[34:35] op_sel:[0,1] op_sel_hi:[0,0]
	v_pk_fma_f32 v[20:21], v[90:91], v[34:35], v[4:5] neg_lo:[0,0,1] neg_hi:[0,0,1]
	v_pk_fma_f32 v[4:5], v[90:91], v[34:35], v[4:5] op_sel_hi:[0,1,1]
	v_mov_b32_e32 v21, v5
	v_pk_mul_f32 v[4:5], v[86:87], v[36:37] op_sel:[0,1] op_sel_hi:[0,0]
	v_pk_fma_f32 v[30:31], v[88:89], v[36:37], v[4:5] neg_lo:[0,0,1] neg_hi:[0,0,1]
	v_pk_fma_f32 v[4:5], v[88:89], v[36:37], v[4:5] op_sel_hi:[0,1,1]
	v_mov_b32_e32 v31, v5
	s_waitcnt lgkmcnt(0)
	v_pk_mul_f32 v[4:5], v[26:27], v[38:39] op_sel:[0,1] op_sel_hi:[0,0]
	ds_write2st64_b64 v148, v[20:21], v[30:31] offset0:32 offset1:40
	v_pk_fma_f32 v[20:21], v[32:33], v[38:39], v[4:5] neg_lo:[0,0,1] neg_hi:[0,0,1]
	v_pk_fma_f32 v[4:5], v[32:33], v[38:39], v[4:5] op_sel_hi:[0,1,1]
	v_mov_b32_e32 v21, v5
	v_pk_mul_f32 v[4:5], v[28:29], v[40:41] op_sel:[0,1] op_sel_hi:[0,0]
	ds_read2st64_b64 v[26:29], v148 offset0:64 offset1:72
	v_pk_fma_f32 v[30:31], v[84:85], v[40:41], v[4:5] neg_lo:[0,0,1] neg_hi:[0,0,1]
	v_pk_fma_f32 v[4:5], v[84:85], v[40:41], v[4:5] op_sel_hi:[0,1,1]
	v_mov_b32_e32 v31, v5
	ds_write2st64_b64 v148, v[20:21], v[30:31] offset0:48 offset1:56
	s_waitcnt lgkmcnt(1)
	v_pk_mul_f32 v[4:5], v[80:81], v[26:27] op_sel:[0,1] op_sel_hi:[0,0]
	v_pk_fma_f32 v[20:21], v[82:83], v[26:27], v[4:5] neg_lo:[0,0,1] neg_hi:[0,0,1]
	v_pk_fma_f32 v[4:5], v[82:83], v[26:27], v[4:5] op_sel_hi:[0,1,1]
	v_mov_b32_e32 v21, v5
	v_pk_mul_f32 v[4:5], v[24:25], v[28:29] op_sel:[0,1] op_sel_hi:[0,0]
	ds_read2st64_b64 v[24:27], v148 offset0:80 offset1:88
	v_pk_fma_f32 v[30:31], v[22:23], v[28:29], v[4:5] neg_lo:[0,0,1] neg_hi:[0,0,1]
	v_pk_fma_f32 v[4:5], v[22:23], v[28:29], v[4:5] op_sel_hi:[0,1,1]
	v_mov_b32_e32 v31, v5
	ds_write2st64_b64 v148, v[20:21], v[30:31] offset0:64 offset1:72
	ds_read2st64_b64 v[20:23], v148 offset0:96 offset1:104
	s_waitcnt lgkmcnt(2)
	v_pk_mul_f32 v[4:5], v[10:11], v[24:25] op_sel:[0,1] op_sel_hi:[0,0]
	v_pk_fma_f32 v[10:11], v[78:79], v[24:25], v[4:5] neg_lo:[0,0,1] neg_hi:[0,0,1]
	v_pk_fma_f32 v[4:5], v[78:79], v[24:25], v[4:5] op_sel_hi:[0,1,1]
	v_mov_b32_e32 v11, v5
	v_pk_mul_f32 v[4:5], v[74:75], v[26:27] op_sel:[0,1] op_sel_hi:[0,0]
	v_pk_fma_f32 v[24:25], v[76:77], v[26:27], v[4:5] neg_lo:[0,0,1] neg_hi:[0,0,1]
	v_pk_fma_f32 v[4:5], v[76:77], v[26:27], v[4:5] op_sel_hi:[0,1,1]
	v_mov_b32_e32 v25, v5
	s_waitcnt lgkmcnt(0)
	v_pk_mul_f32 v[4:5], v[6:7], v[20:21] op_sel:[0,1] op_sel_hi:[0,0]
	ds_write2st64_b64 v148, v[10:11], v[24:25] offset0:80 offset1:88
	v_pk_fma_f32 v[10:11], v[12:13], v[20:21], v[4:5] neg_lo:[0,0,1] neg_hi:[0,0,1]
	v_pk_fma_f32 v[4:5], v[12:13], v[20:21], v[4:5] op_sel_hi:[0,1,1]
	v_mov_b32_e32 v11, v5
	ds_read2st64_b64 v[4:7], v148 offset0:112 offset1:120
	v_pk_mul_f32 v[8:9], v[8:9], v[22:23] op_sel:[0,1] op_sel_hi:[0,0]
	v_pk_fma_f32 v[12:13], v[72:73], v[22:23], v[8:9] neg_lo:[0,0,1] neg_hi:[0,0,1]
	v_pk_fma_f32 v[8:9], v[72:73], v[22:23], v[8:9] op_sel_hi:[0,1,1]
	v_mov_b32_e32 v13, v9
	s_waitcnt lgkmcnt(0)
	v_pk_mul_f32 v[2:3], v[2:3], v[4:5] op_sel:[0,1] op_sel_hi:[0,0]
	v_pk_fma_f32 v[8:9], v[70:71], v[4:5], v[2:3] neg_lo:[0,0,1] neg_hi:[0,0,1]
	v_pk_fma_f32 v[2:3], v[70:71], v[4:5], v[2:3] op_sel_hi:[0,1,1]
	v_mov_b32_e32 v9, v3
	v_pk_mul_f32 v[2:3], v[102:103], v[6:7] op_sel:[0,1] op_sel_hi:[0,0]
	v_pk_fma_f32 v[4:5], v[94:95], v[6:7], v[2:3] neg_lo:[0,0,1] neg_hi:[0,0,1]
	v_pk_fma_f32 v[2:3], v[94:95], v[6:7], v[2:3] op_sel_hi:[0,1,1]
	v_mov_b32_e32 v5, v3
	v_mov_b32_e32 v0, v135
	ds_write2st64_b64 v148, v[10:11], v[12:13] offset0:96 offset1:104
	ds_write2st64_b64 v148, v[8:9], v[4:5] offset0:112 offset1:120
	s_waitcnt lgkmcnt(0)
	s_barrier
	s_nop 0
	v_lshl_add_u32 v28, v0, 5, v205
	ds_read_b128 v[2:5], v28
	ds_read_b128 v[6:9], v28 offset:16
	s_waitcnt lgkmcnt(1)
	v_pk_add_f32 v[20:21], v[2:3], v[4:5]
	v_pk_add_f32 v[2:3], v[2:3], v[4:5] neg_lo:[0,1] neg_hi:[0,1]
	s_waitcnt lgkmcnt(0)
	v_pk_add_f32 v[4:5], v[6:7], v[8:9] neg_lo:[0,1] neg_hi:[0,1]
	v_pk_add_f32 v[22:23], v[6:7], v[8:9]
	v_pk_add_f32 v[24:25], v[2:3], v[4:5] op_sel:[0,1] op_sel_hi:[1,0] neg_lo:[0,1] neg_hi:[0,1]
	v_pk_add_f32 v[4:5], v[2:3], v[4:5] op_sel:[0,1] op_sel_hi:[1,0]
	v_pk_add_f32 v[10:11], v[20:21], v[22:23]
	v_mov_b32_e32 v12, v24
	v_mov_b32_e32 v13, v5
	ds_write_b128 v28, v[10:13]
	ds_read_b128 v[6:9], v28 offset:16384
	ds_read_b128 v[10:13], v28 offset:16400
	v_pk_add_f32 v[2:3], v[20:21], v[22:23] neg_lo:[0,1] neg_hi:[0,1]
	v_mov_b32_e32 v5, v25
	ds_write_b128 v28, v[2:5] offset:16
	s_waitcnt lgkmcnt(2)
	v_pk_add_f32 v[24:25], v[6:7], v[8:9]
	v_pk_add_f32 v[4:5], v[6:7], v[8:9] neg_lo:[0,1] neg_hi:[0,1]
	s_waitcnt lgkmcnt(1)
	v_pk_add_f32 v[6:7], v[10:11], v[12:13] neg_lo:[0,1] neg_hi:[0,1]
	v_pk_add_f32 v[26:27], v[10:11], v[12:13]
	v_pk_add_f32 v[12:13], v[4:5], v[6:7] op_sel:[0,1] op_sel_hi:[1,0] neg_lo:[0,1] neg_hi:[0,1]
	v_pk_add_f32 v[6:7], v[4:5], v[6:7] op_sel:[0,1] op_sel_hi:[1,0]
	v_pk_add_f32 v[2:3], v[24:25], v[26:27]
	v_mov_b32_e32 v4, v12
	v_mov_b32_e32 v5, v7
	ds_write_b128 v28, v[2:5] offset:16384
	ds_read_b128 v[8:11], v28 offset:32768
	ds_read_b128 v[20:23], v28 offset:32784
	v_pk_add_f32 v[4:5], v[24:25], v[26:27] neg_lo:[0,1] neg_hi:[0,1]
	v_mov_b32_e32 v7, v13
	ds_write_b128 v28, v[4:7] offset:16400
	s_waitcnt lgkmcnt(2)
	v_pk_add_f32 v[4:5], v[8:9], v[10:11] neg_lo:[0,1] neg_hi:[0,1]
	s_waitcnt lgkmcnt(1)
	v_pk_add_f32 v[6:7], v[20:21], v[22:23] neg_lo:[0,1] neg_hi:[0,1]
	v_pk_add_f32 v[12:13], v[8:9], v[10:11]
	v_pk_add_f32 v[24:25], v[20:21], v[22:23]
	v_pk_add_f32 v[26:27], v[4:5], v[6:7] op_sel:[0,1] op_sel_hi:[1,0] neg_lo:[0,1] neg_hi:[0,1]
	v_pk_add_f32 v[6:7], v[4:5], v[6:7] op_sel:[0,1] op_sel_hi:[1,0]
	v_pk_add_f32 v[2:3], v[12:13], v[24:25]
	v_mov_b32_e32 v4, v26
	v_mov_b32_e32 v5, v7
	ds_write_b128 v28, v[2:5] offset:32768
	ds_read_b128 v[8:11], v28 offset:49152
	ds_read_b128 v[20:23], v28 offset:49168
	v_pk_add_f32 v[4:5], v[12:13], v[24:25] neg_lo:[0,1] neg_hi:[0,1]
	v_mov_b32_e32 v7, v27
	ds_write_b128 v28, v[4:7] offset:32784
	s_waitcnt lgkmcnt(2)
	v_pk_add_f32 v[4:5], v[8:9], v[10:11] neg_lo:[0,1] neg_hi:[0,1]
	s_waitcnt lgkmcnt(1)
	v_pk_add_f32 v[6:7], v[20:21], v[22:23] neg_lo:[0,1] neg_hi:[0,1]
	v_pk_add_f32 v[12:13], v[8:9], v[10:11]
	v_pk_add_f32 v[24:25], v[20:21], v[22:23]
	v_pk_add_f32 v[8:9], v[4:5], v[6:7] op_sel:[0,1] op_sel_hi:[1,0] neg_lo:[0,1] neg_hi:[0,1]
	v_pk_add_f32 v[6:7], v[4:5], v[6:7] op_sel:[0,1] op_sel_hi:[1,0]
	v_pk_add_f32 v[2:3], v[12:13], v[24:25]
	v_mov_b32_e32 v4, v8
	v_mov_b32_e32 v5, v7
	ds_write_b128 v28, v[2:5] offset:49152
	v_pk_add_f32 v[4:5], v[12:13], v[24:25] neg_lo:[0,1] neg_hi:[0,1]
	v_mov_b32_e32 v7, v9
	v_and_b32_e32 v9, 3, v0
	v_lshlrev_b32_e32 v8, 2, v0
	ds_write_b128 v28, v[4:7] offset:49168
	v_and_or_b32 v2, v8, s5, v9
	v_lshlrev_b32_e32 v6, 13, v9
	v_lshlrev_b32_e32 v7, 7, v9
	v_lshl_add_u32 v23, v2, 3, v205
	v_add3_u32 v32, s85, v6, v7
	s_waitcnt lgkmcnt(0)
	s_barrier
	ds_read2_b64 v[2:5], v23 offset0:8 offset1:12
	ds_read_b64 v[10:11], v32
	v_lshlrev_b32_e32 v6, 12, v9
	v_lshlrev_b32_e32 v7, 6, v9
	v_add3_u32 v33, s85, v6, v7
	ds_read_b64 v[12:13], v33
	s_waitcnt lgkmcnt(1)
	v_pk_mul_f32 v[6:7], v[4:5], v[10:11]
	v_pk_mul_f32 v[4:5], v[4:5], v[10:11] op_sel:[1,0] op_sel_hi:[0,1]
	v_add_f32_e32 v21, v6, v7
	v_sub_f32_e32 v24, v4, v5
	ds_read2_b64 v[4:7], v23 offset1:4
	v_add_f32_e32 v20, v2, v21
	v_add_f32_e32 v22, v3, v24
	v_sub_f32_e32 v2, v2, v21
	v_sub_f32_e32 v24, v3, v24
	s_waitcnt lgkmcnt(0)
	v_pk_mul_f32 v[26:27], v[6:7], v[10:11] op_sel:[1,1] op_sel_hi:[0,1]
	v_pk_fma_f32 v[28:29], v[6:7], v[10:11], v[26:27]
	v_pk_fma_f32 v[6:7], v[6:7], v[10:11], v[26:27] op_sel_hi:[1,0,1] neg_lo:[0,0,1] neg_hi:[0,0,1]
	v_pk_mul_f32 v[10:11], v[12:13], v[20:21] op_sel_hi:[1,0]
	v_mov_b32_e32 v29, v7
	v_pk_fma_f32 v[20:21], v[12:13], v[22:23], v[10:11] op_sel:[1,0,0] op_sel_hi:[0,1,1]
	v_pk_fma_f32 v[10:11], v[12:13], v[22:23], v[10:11] op_sel:[1,0,0] op_sel_hi:[0,0,1] neg_lo:[0,0,1] neg_hi:[0,0,1]
	v_pk_add_f32 v[6:7], v[4:5], v[28:29]
	v_mov_b32_e32 v21, v11
	v_pk_mul_f32 v[2:3], v[12:13], v[2:3] op_sel:[1,0] op_sel_hi:[0,0]
	v_pk_add_f32 v[10:11], v[6:7], v[20:21]
	v_pk_add_f32 v[6:7], v[6:7], v[20:21] neg_lo:[0,1] neg_hi:[0,1]
	v_pk_fma_f32 v[20:21], v[12:13], v[24:25], v[2:3] neg_lo:[0,0,1] neg_hi:[0,0,1]
	v_pk_fma_f32 v[2:3], v[12:13], v[24:25], v[2:3] op_sel_hi:[1,0,1]
	v_pk_add_f32 v[4:5], v[4:5], v[28:29] neg_lo:[0,1] neg_hi:[0,1]
	v_mov_b32_e32 v21, v3
	v_pk_add_f32 v[2:3], v[4:5], v[20:21] neg_lo:[0,1] neg_hi:[0,1]
	v_pk_add_f32 v[4:5], v[4:5], v[20:21]
	v_mov_b32_e32 v12, v2
	v_mov_b32_e32 v13, v5
	v_mov_b32_e32 v5, v3
	v_add_u32_e32 v2, 0x200, v0
	ds_write2_b64 v23, v[6:7], v[4:5] offset0:8 offset1:12
	v_lshlrev_b32_e32 v7, 2, v2
	v_and_or_b32 v3, v7, s5, v9
	ds_write2_b64 v23, v[10:11], v[12:13] offset1:4
	v_lshl_add_u32 v3, v3, 3, v205
	ds_read2_b64 v[10:13], v3 offset0:8 offset1:12
	ds_read_b64 v[4:5], v32
	ds_read_b64 v[24:25], v33
	s_waitcnt lgkmcnt(1)
	v_pk_mul_f32 v[20:21], v[12:13], v[4:5]
	s_nop 0
	v_add_f32_e32 v26, v20, v21
	ds_read2_b64 v[20:23], v3 offset1:4
	v_pk_mul_f32 v[12:13], v[12:13], v[4:5] op_sel:[1,0] op_sel_hi:[0,1]
	v_sub_f32_e32 v13, v12, v13
	v_add_f32_e32 v6, v10, v26
	v_sub_f32_e32 v10, v10, v26
	s_waitcnt lgkmcnt(0)
	v_pk_mul_f32 v[28:29], v[22:23], v[4:5] op_sel:[1,1] op_sel_hi:[0,1]
	v_add_f32_e32 v12, v11, v13
	v_sub_f32_e32 v26, v11, v13
	v_pk_fma_f32 v[30:31], v[22:23], v[4:5], v[28:29]
	v_pk_fma_f32 v[4:5], v[22:23], v[4:5], v[28:29] op_sel_hi:[1,0,1] neg_lo:[0,0,1] neg_hi:[0,0,1]
	v_pk_mul_f32 v[22:23], v[24:25], v[6:7] op_sel_hi:[1,0]
	v_pk_mul_f32 v[10:11], v[24:25], v[10:11] op_sel:[1,0] op_sel_hi:[0,0]
	v_mov_b32_e32 v31, v5
	v_pk_fma_f32 v[28:29], v[24:25], v[12:13], v[22:23] op_sel:[1,0,0] op_sel_hi:[0,1,1]
	v_pk_fma_f32 v[12:13], v[24:25], v[12:13], v[22:23] op_sel:[1,0,0] op_sel_hi:[0,0,1] neg_lo:[0,0,1] neg_hi:[0,0,1]
	v_pk_fma_f32 v[22:23], v[24:25], v[26:27], v[10:11] neg_lo:[0,0,1] neg_hi:[0,0,1]
	v_pk_fma_f32 v[10:11], v[24:25], v[26:27], v[10:11] op_sel_hi:[1,0,1]
	v_pk_add_f32 v[4:5], v[20:21], v[30:31]
	v_pk_add_f32 v[20:21], v[20:21], v[30:31] neg_lo:[0,1] neg_hi:[0,1]
	v_mov_b32_e32 v23, v11
	v_mov_b32_e32 v29, v13
	v_pk_add_f32 v[10:11], v[20:21], v[22:23] neg_lo:[0,1] neg_hi:[0,1]
	v_pk_add_f32 v[20:21], v[20:21], v[22:23]
	v_pk_add_f32 v[12:13], v[4:5], v[28:29]
	v_pk_add_f32 v[4:5], v[4:5], v[28:29] neg_lo:[0,1] neg_hi:[0,1]
	v_mov_b32_e32 v22, v10
	v_mov_b32_e32 v23, v21
	v_mov_b32_e32 v21, v11
	ds_write2_b64 v3, v[12:13], v[22:23] offset1:4
	ds_write2_b64 v3, v[4:5], v[20:21] offset0:8 offset1:12
	v_add_u32_e32 v3, 0x400, v0
	v_lshlrev_b32_e32 v5, 2, v3
	v_and_or_b32 v4, v5, s5, v9
	v_lshl_add_u32 v34, v4, 3, v205
	ds_read2_b64 v[10:13], v34 offset0:8 offset1:12
	ds_read_b64 v[24:25], v32
	ds_read_b64 v[26:27], v33
	s_waitcnt lgkmcnt(1)
	v_pk_mul_f32 v[20:21], v[12:13], v[24:25]
	s_nop 0
	v_add_f32_e32 v28, v20, v21
	ds_read2_b64 v[20:23], v34 offset1:4
	v_pk_mul_f32 v[12:13], v[12:13], v[24:25] op_sel:[1,0] op_sel_hi:[0,1]
	v_sub_f32_e32 v12, v12, v13
	v_add_f32_e32 v4, v10, v28
	v_sub_f32_e32 v10, v10, v28
	s_waitcnt lgkmcnt(0)
	v_pk_mul_f32 v[28:29], v[22:23], v[24:25] op_sel:[1,1] op_sel_hi:[0,1]
	v_add_f32_e32 v6, v11, v12
	v_pk_fma_f32 v[30:31], v[22:23], v[24:25], v[28:29]
	v_pk_fma_f32 v[22:23], v[22:23], v[24:25], v[28:29] op_sel_hi:[1,0,1] neg_lo:[0,0,1] neg_hi:[0,0,1]
	v_pk_mul_f32 v[24:25], v[26:27], v[4:5] op_sel_hi:[1,0]
	v_mov_b32_e32 v31, v23
	v_pk_fma_f32 v[28:29], v[26:27], v[6:7], v[24:25] op_sel:[1,0,0] op_sel_hi:[0,1,1]
	v_pk_fma_f32 v[24:25], v[26:27], v[6:7], v[24:25] op_sel:[1,0,0] op_sel_hi:[0,0,1] neg_lo:[0,0,1] neg_hi:[0,0,1]
	v_sub_f32_e32 v12, v11, v12
	v_pk_add_f32 v[22:23], v[20:21], v[30:31]
	v_mov_b32_e32 v29, v25
	v_pk_mul_f32 v[10:11], v[26:27], v[10:11] op_sel:[1,0] op_sel_hi:[0,0]
	v_pk_add_f32 v[24:25], v[22:23], v[28:29]
	v_pk_add_f32 v[22:23], v[22:23], v[28:29] neg_lo:[0,1] neg_hi:[0,1]
	v_pk_fma_f32 v[28:29], v[26:27], v[12:13], v[10:11] neg_lo:[0,0,1] neg_hi:[0,0,1]
	v_pk_fma_f32 v[10:11], v[26:27], v[12:13], v[10:11] op_sel_hi:[1,0,1]
	v_pk_add_f32 v[20:21], v[20:21], v[30:31] neg_lo:[0,1] neg_hi:[0,1]
	v_mov_b32_e32 v29, v11
	v_add_u32_e32 v4, 0x600, v0
	v_pk_add_f32 v[10:11], v[20:21], v[28:29] neg_lo:[0,1] neg_hi:[0,1]
	v_pk_add_f32 v[12:13], v[20:21], v[28:29]
	v_lshlrev_b32_e32 v6, 2, v4
	v_mov_b32_e32 v20, v10
	v_mov_b32_e32 v21, v13
	v_mov_b32_e32 v13, v11
	v_and_or_b32 v9, v6, s5, v9
	ds_write2_b64 v34, v[24:25], v[20:21] offset1:4
	ds_write2_b64 v34, v[22:23], v[12:13] offset0:8 offset1:12
	v_lshl_add_u32 v9, v9, 3, v205
	ds_read2_b64 v[10:13], v9 offset0:8 offset1:12
	ds_read_b64 v[24:25], v32
	ds_read_b64 v[26:27], v33
	s_waitcnt lgkmcnt(1)
	v_pk_mul_f32 v[20:21], v[12:13], v[24:25]
	s_nop 0
	v_add_f32_e32 v29, v20, v21
	ds_read2_b64 v[20:23], v9 offset1:4
	v_pk_mul_f32 v[12:13], v[12:13], v[24:25] op_sel:[1,0] op_sel_hi:[0,1]
	v_sub_f32_e32 v13, v12, v13
	v_add_f32_e32 v12, v10, v29
	v_add_f32_e32 v28, v11, v13
	s_waitcnt lgkmcnt(0)
	v_pk_mul_f32 v[32:33], v[22:23], v[24:25] op_sel:[1,1] op_sel_hi:[0,1]
	v_sub_f32_e32 v30, v11, v13
	v_pk_fma_f32 v[34:35], v[22:23], v[24:25], v[32:33]
	v_pk_fma_f32 v[22:23], v[22:23], v[24:25], v[32:33] op_sel_hi:[1,0,1] neg_lo:[0,0,1] neg_hi:[0,0,1]
	v_pk_mul_f32 v[12:13], v[26:27], v[12:13] op_sel_hi:[1,0]
	v_sub_f32_e32 v10, v10, v29
	v_mov_b32_e32 v35, v23
	v_pk_fma_f32 v[24:25], v[26:27], v[28:29], v[12:13] op_sel:[1,0,0] op_sel_hi:[0,1,1]
	v_pk_fma_f32 v[12:13], v[26:27], v[28:29], v[12:13] op_sel:[1,0,0] op_sel_hi:[0,0,1] neg_lo:[0,0,1] neg_hi:[0,0,1]
	v_pk_add_f32 v[22:23], v[20:21], v[34:35]
	v_mov_b32_e32 v25, v13
	v_pk_mul_f32 v[10:11], v[26:27], v[10:11] op_sel:[1,0] op_sel_hi:[0,0]
	v_pk_add_f32 v[12:13], v[22:23], v[24:25]
	v_pk_add_f32 v[22:23], v[22:23], v[24:25] neg_lo:[0,1] neg_hi:[0,1]
	v_pk_fma_f32 v[24:25], v[26:27], v[30:31], v[10:11] neg_lo:[0,0,1] neg_hi:[0,0,1]
	v_pk_fma_f32 v[10:11], v[26:27], v[30:31], v[10:11] op_sel_hi:[1,0,1]
	v_pk_add_f32 v[20:21], v[20:21], v[34:35] neg_lo:[0,1] neg_hi:[0,1]
	v_mov_b32_e32 v25, v11
	v_pk_add_f32 v[10:11], v[20:21], v[24:25] neg_lo:[0,1] neg_hi:[0,1]
	v_pk_add_f32 v[20:21], v[20:21], v[24:25]
	v_mov_b32_e32 v24, v10
	v_mov_b32_e32 v25, v21
	v_mov_b32_e32 v21, v11
	ds_write2_b64 v9, v[12:13], v[24:25] offset1:4
	ds_write2_b64 v9, v[22:23], v[20:21] offset0:8 offset1:12
	v_and_b32_e32 v9, 15, v0
	v_and_or_b32 v10, v8, s35, v9
	v_lshlrev_b32_e32 v20, 11, v9
	v_lshlrev_b32_e32 v21, 5, v9
	v_lshl_add_u32 v29, v10, 3, v205
	v_add3_u32 v31, s85, v20, v21
	s_waitcnt lgkmcnt(0)
	s_barrier
	ds_read2_b64 v[10:13], v29 offset0:32 offset1:48
	ds_read_b64 v[24:25], v31
	v_lshlrev_b32_e32 v20, 10, v9
	v_lshlrev_b32_e32 v21, 4, v9
	v_add3_u32 v36, s85, v20, v21
	ds_read_b64 v[26:27], v36
	s_waitcnt lgkmcnt(1)
	v_pk_mul_f32 v[20:21], v[12:13], v[24:25]
	v_pk_mul_f32 v[12:13], v[12:13], v[24:25] op_sel:[1,0] op_sel_hi:[0,1]
	v_add_f32_e32 v30, v20, v21
	ds_read2_b64 v[20:23], v29 offset1:16
	v_sub_f32_e32 v13, v12, v13
	v_add_f32_e32 v12, v10, v30
	v_add_f32_e32 v28, v11, v13
	v_sub_f32_e32 v10, v10, v30
	s_waitcnt lgkmcnt(0)
	v_pk_mul_f32 v[32:33], v[22:23], v[24:25] op_sel:[1,1] op_sel_hi:[0,1]
	v_sub_f32_e32 v30, v11, v13
	v_pk_fma_f32 v[34:35], v[22:23], v[24:25], v[32:33]
	v_pk_fma_f32 v[22:23], v[22:23], v[24:25], v[32:33] op_sel_hi:[1,0,1] neg_lo:[0,0,1] neg_hi:[0,0,1]
	v_pk_mul_f32 v[12:13], v[26:27], v[12:13] op_sel_hi:[1,0]
	v_mov_b32_e32 v35, v23
	v_pk_fma_f32 v[24:25], v[26:27], v[28:29], v[12:13] op_sel:[1,0,0] op_sel_hi:[0,1,1]
	v_pk_fma_f32 v[12:13], v[26:27], v[28:29], v[12:13] op_sel:[1,0,0] op_sel_hi:[0,0,1] neg_lo:[0,0,1] neg_hi:[0,0,1]
	v_pk_add_f32 v[22:23], v[20:21], v[34:35]
	v_mov_b32_e32 v25, v13
	v_pk_mul_f32 v[10:11], v[26:27], v[10:11] op_sel:[1,0] op_sel_hi:[0,0]
	v_pk_add_f32 v[12:13], v[22:23], v[24:25]
	v_pk_add_f32 v[22:23], v[22:23], v[24:25] neg_lo:[0,1] neg_hi:[0,1]
	v_pk_fma_f32 v[24:25], v[26:27], v[30:31], v[10:11] neg_lo:[0,0,1] neg_hi:[0,0,1]
	v_pk_fma_f32 v[10:11], v[26:27], v[30:31], v[10:11] op_sel_hi:[1,0,1]
	v_pk_add_f32 v[20:21], v[20:21], v[34:35] neg_lo:[0,1] neg_hi:[0,1]
	v_mov_b32_e32 v25, v11
	v_pk_add_f32 v[10:11], v[20:21], v[24:25] neg_lo:[0,1] neg_hi:[0,1]
	v_pk_add_f32 v[20:21], v[20:21], v[24:25]
	v_mov_b32_e32 v24, v10
	v_mov_b32_e32 v25, v21
	v_mov_b32_e32 v21, v11
	v_and_or_b32 v10, v7, s35, v9
	ds_write2_b64 v29, v[12:13], v[24:25] offset1:16
	ds_write2_b64 v29, v[22:23], v[20:21] offset0:32 offset1:48
	v_lshl_add_u32 v29, v10, 3, v205
	ds_read2_b64 v[10:13], v29 offset0:32 offset1:48
	ds_read_b64 v[24:25], v31
	ds_read_b64 v[26:27], v36
	s_waitcnt lgkmcnt(1)
	v_pk_mul_f32 v[20:21], v[12:13], v[24:25]
	s_nop 0
	v_add_f32_e32 v30, v20, v21
	ds_read2_b64 v[20:23], v29 offset1:16
	v_pk_mul_f32 v[12:13], v[12:13], v[24:25] op_sel:[1,0] op_sel_hi:[0,1]
	v_sub_f32_e32 v13, v12, v13
	v_add_f32_e32 v12, v10, v30
	v_add_f32_e32 v28, v11, v13
	s_waitcnt lgkmcnt(0)
	v_pk_mul_f32 v[32:33], v[22:23], v[24:25] op_sel:[1,1] op_sel_hi:[0,1]
	v_sub_f32_e32 v10, v10, v30
	v_sub_f32_e32 v30, v11, v13
	v_pk_fma_f32 v[34:35], v[22:23], v[24:25], v[32:33]
	v_pk_fma_f32 v[22:23], v[22:23], v[24:25], v[32:33] op_sel_hi:[1,0,1] neg_lo:[0,0,1] neg_hi:[0,0,1]
	v_pk_mul_f32 v[12:13], v[26:27], v[12:13] op_sel_hi:[1,0]
	v_mov_b32_e32 v35, v23
	v_pk_fma_f32 v[24:25], v[26:27], v[28:29], v[12:13] op_sel:[1,0,0] op_sel_hi:[0,1,1]
	v_pk_fma_f32 v[12:13], v[26:27], v[28:29], v[12:13] op_sel:[1,0,0] op_sel_hi:[0,0,1] neg_lo:[0,0,1] neg_hi:[0,0,1]
	v_pk_add_f32 v[22:23], v[20:21], v[34:35]
	v_mov_b32_e32 v25, v13
	v_pk_mul_f32 v[10:11], v[26:27], v[10:11] op_sel:[1,0] op_sel_hi:[0,0]
	v_pk_add_f32 v[12:13], v[22:23], v[24:25]
	v_pk_add_f32 v[22:23], v[22:23], v[24:25] neg_lo:[0,1] neg_hi:[0,1]
	v_pk_fma_f32 v[24:25], v[26:27], v[30:31], v[10:11] neg_lo:[0,0,1] neg_hi:[0,0,1]
	v_pk_fma_f32 v[10:11], v[26:27], v[30:31], v[10:11] op_sel_hi:[1,0,1]
	v_pk_add_f32 v[20:21], v[20:21], v[34:35] neg_lo:[0,1] neg_hi:[0,1]
	v_mov_b32_e32 v25, v11
	v_pk_add_f32 v[10:11], v[20:21], v[24:25] neg_lo:[0,1] neg_hi:[0,1]
	v_pk_add_f32 v[20:21], v[20:21], v[24:25]
	v_mov_b32_e32 v24, v10
	v_mov_b32_e32 v25, v21
	v_mov_b32_e32 v21, v11
	v_and_or_b32 v10, v5, s35, v9
	ds_write2_b64 v29, v[12:13], v[24:25] offset1:16
	ds_write2_b64 v29, v[22:23], v[20:21] offset0:32 offset1:48
	v_lshl_add_u32 v29, v10, 3, v205
	ds_read2_b64 v[10:13], v29 offset0:32 offset1:48
	ds_read_b64 v[24:25], v31
	ds_read_b64 v[26:27], v36
	v_and_or_b32 v9, v6, s35, v9
	v_lshl_add_u32 v9, v9, 3, v205
	s_waitcnt lgkmcnt(1)
	v_pk_mul_f32 v[20:21], v[12:13], v[24:25]
	s_nop 0
	v_add_f32_e32 v30, v20, v21
	ds_read2_b64 v[20:23], v29 offset1:16
	v_pk_mul_f32 v[12:13], v[12:13], v[24:25] op_sel:[1,0] op_sel_hi:[0,1]
	v_sub_f32_e32 v13, v12, v13
	v_add_f32_e32 v12, v10, v30
	v_add_f32_e32 v28, v11, v13
	s_waitcnt lgkmcnt(0)
	v_pk_mul_f32 v[32:33], v[22:23], v[24:25] op_sel:[1,1] op_sel_hi:[0,1]
	v_sub_f32_e32 v10, v10, v30
	v_sub_f32_e32 v30, v11, v13
	v_pk_fma_f32 v[34:35], v[22:23], v[24:25], v[32:33]
	v_pk_fma_f32 v[22:23], v[22:23], v[24:25], v[32:33] op_sel_hi:[1,0,1] neg_lo:[0,0,1] neg_hi:[0,0,1]
	v_pk_mul_f32 v[12:13], v[26:27], v[12:13] op_sel_hi:[1,0]
	v_mov_b32_e32 v35, v23
	v_pk_fma_f32 v[24:25], v[26:27], v[28:29], v[12:13] op_sel:[1,0,0] op_sel_hi:[0,1,1]
	v_pk_fma_f32 v[12:13], v[26:27], v[28:29], v[12:13] op_sel:[1,0,0] op_sel_hi:[0,0,1] neg_lo:[0,0,1] neg_hi:[0,0,1]
	v_pk_add_f32 v[22:23], v[20:21], v[34:35]
	v_mov_b32_e32 v25, v13
	v_pk_mul_f32 v[10:11], v[26:27], v[10:11] op_sel:[1,0] op_sel_hi:[0,0]
	v_pk_add_f32 v[12:13], v[22:23], v[24:25]
	v_pk_add_f32 v[22:23], v[22:23], v[24:25] neg_lo:[0,1] neg_hi:[0,1]
	v_pk_fma_f32 v[24:25], v[26:27], v[30:31], v[10:11] neg_lo:[0,0,1] neg_hi:[0,0,1]
	v_pk_fma_f32 v[10:11], v[26:27], v[30:31], v[10:11] op_sel_hi:[1,0,1]
	v_pk_add_f32 v[20:21], v[20:21], v[34:35] neg_lo:[0,1] neg_hi:[0,1]
	v_mov_b32_e32 v25, v11
	v_pk_add_f32 v[10:11], v[20:21], v[24:25] neg_lo:[0,1] neg_hi:[0,1]
	v_pk_add_f32 v[20:21], v[20:21], v[24:25]
	v_mov_b32_e32 v24, v10
	v_mov_b32_e32 v25, v21
	v_mov_b32_e32 v21, v11
	ds_write2_b64 v29, v[12:13], v[24:25] offset1:16
	ds_write2_b64 v29, v[22:23], v[20:21] offset0:32 offset1:48
	ds_read2_b64 v[10:13], v9 offset0:32 offset1:48
	ds_read_b64 v[24:25], v31
	ds_read_b64 v[26:27], v36
	s_waitcnt lgkmcnt(1)
	v_pk_mul_f32 v[20:21], v[12:13], v[24:25]
	s_nop 0
	v_add_f32_e32 v29, v20, v21
	ds_read2_b64 v[20:23], v9 offset1:16
	v_pk_mul_f32 v[12:13], v[12:13], v[24:25] op_sel:[1,0] op_sel_hi:[0,1]
	v_sub_f32_e32 v13, v12, v13
	v_add_f32_e32 v12, v10, v29
	v_add_f32_e32 v28, v11, v13
	s_waitcnt lgkmcnt(0)
	v_pk_mul_f32 v[32:33], v[22:23], v[24:25] op_sel:[1,1] op_sel_hi:[0,1]
	v_sub_f32_e32 v30, v11, v13
	v_pk_fma_f32 v[34:35], v[22:23], v[24:25], v[32:33]
	v_pk_fma_f32 v[22:23], v[22:23], v[24:25], v[32:33] op_sel_hi:[1,0,1] neg_lo:[0,0,1] neg_hi:[0,0,1]
	v_pk_mul_f32 v[12:13], v[26:27], v[12:13] op_sel_hi:[1,0]
	v_sub_f32_e32 v10, v10, v29
	v_mov_b32_e32 v35, v23
	v_pk_fma_f32 v[24:25], v[26:27], v[28:29], v[12:13] op_sel:[1,0,0] op_sel_hi:[0,1,1]
	v_pk_fma_f32 v[12:13], v[26:27], v[28:29], v[12:13] op_sel:[1,0,0] op_sel_hi:[0,0,1] neg_lo:[0,0,1] neg_hi:[0,0,1]
	v_pk_add_f32 v[22:23], v[20:21], v[34:35]
	v_mov_b32_e32 v25, v13
	v_pk_mul_f32 v[10:11], v[26:27], v[10:11] op_sel:[1,0] op_sel_hi:[0,0]
	v_pk_add_f32 v[12:13], v[22:23], v[24:25]
	v_pk_add_f32 v[22:23], v[22:23], v[24:25] neg_lo:[0,1] neg_hi:[0,1]
	v_pk_fma_f32 v[24:25], v[26:27], v[30:31], v[10:11] neg_lo:[0,0,1] neg_hi:[0,0,1]
	v_pk_fma_f32 v[10:11], v[26:27], v[30:31], v[10:11] op_sel_hi:[1,0,1]
	v_pk_add_f32 v[20:21], v[20:21], v[34:35] neg_lo:[0,1] neg_hi:[0,1]
	v_mov_b32_e32 v25, v11
	v_pk_add_f32 v[10:11], v[20:21], v[24:25] neg_lo:[0,1] neg_hi:[0,1]
	v_pk_add_f32 v[20:21], v[20:21], v[24:25]
	v_mov_b32_e32 v24, v10
	v_mov_b32_e32 v25, v21
	v_mov_b32_e32 v21, v11
	ds_write2_b64 v9, v[22:23], v[20:21] offset0:32 offset1:48
	v_and_b32_e32 v20, 63, v0
	ds_write2_b64 v9, v[12:13], v[24:25] offset1:16
	v_ashrrev_i32_e32 v9, 6, v0
	v_lshlrev_b32_e32 v38, 3, v20
	v_lshl_or_b32 v10, v9, 11, v38
	v_lshlrev_b32_e32 v21, 9, v20
	v_add_u32_e32 v31, 0x50, v10
	v_add3_u32 v39, s85, v21, v38
	s_waitcnt lgkmcnt(0)
	s_barrier
	ds_read2st64_b64 v[10:13], v31 offset0:2 offset1:3
	ds_read_b64 v[24:25], v39
	v_lshlrev_b32_e32 v20, 8, v20
	v_and_b32_e32 v21, 0xf8, v8
	v_add3_u32 v40, s85, v20, v21
	ds_read2st64_b64 v[20:23], v31 offset1:1
	ds_read_b64 v[26:27], v40
	s_waitcnt lgkmcnt(2)
	v_pk_mul_f32 v[28:29], v[12:13], v[24:25]
	v_pk_mul_f32 v[12:13], v[12:13], v[24:25] op_sel:[1,0] op_sel_hi:[0,1]
	v_add_f32_e32 v29, v28, v29
	v_sub_f32_e32 v13, v12, v13
	v_add_f32_e32 v12, v10, v29
	s_waitcnt lgkmcnt(1)
	v_pk_mul_f32 v[32:33], v[22:23], v[24:25] op_sel:[1,1] op_sel_hi:[0,1]
	v_add_f32_e32 v28, v11, v13
	v_sub_f32_e32 v30, v11, v13
	v_pk_fma_f32 v[34:35], v[22:23], v[24:25], v[32:33]
	v_pk_fma_f32 v[22:23], v[22:23], v[24:25], v[32:33] op_sel_hi:[1,0,1] neg_lo:[0,0,1] neg_hi:[0,0,1]
	s_waitcnt lgkmcnt(0)
	v_pk_mul_f32 v[12:13], v[26:27], v[12:13] op_sel_hi:[1,0]
	v_sub_f32_e32 v10, v10, v29
	v_mov_b32_e32 v35, v23
	v_pk_fma_f32 v[24:25], v[26:27], v[28:29], v[12:13] op_sel:[1,0,0] op_sel_hi:[0,1,1]
	v_pk_fma_f32 v[12:13], v[26:27], v[28:29], v[12:13] op_sel:[1,0,0] op_sel_hi:[0,0,1] neg_lo:[0,0,1] neg_hi:[0,0,1]
	v_pk_add_f32 v[22:23], v[20:21], v[34:35]
	v_mov_b32_e32 v25, v13
	v_pk_mul_f32 v[10:11], v[26:27], v[10:11] op_sel:[1,0] op_sel_hi:[0,0]
	v_pk_add_f32 v[12:13], v[22:23], v[24:25]
	v_pk_add_f32 v[22:23], v[22:23], v[24:25] neg_lo:[0,1] neg_hi:[0,1]
	v_pk_fma_f32 v[24:25], v[26:27], v[30:31], v[10:11] neg_lo:[0,0,1] neg_hi:[0,0,1]
	v_pk_fma_f32 v[10:11], v[26:27], v[30:31], v[10:11] op_sel_hi:[1,0,1]
	v_pk_add_f32 v[20:21], v[20:21], v[34:35] neg_lo:[0,1] neg_hi:[0,1]
	v_mov_b32_e32 v25, v11
	v_pk_add_f32 v[10:11], v[20:21], v[24:25] neg_lo:[0,1] neg_hi:[0,1]
	v_pk_add_f32 v[20:21], v[20:21], v[24:25]
	v_mov_b32_e32 v24, v10
	v_mov_b32_e32 v25, v21
	v_mov_b32_e32 v21, v11
	v_ashrrev_i32_e32 v10, 6, v2
	ds_write2st64_b64 v31, v[12:13], v[24:25] offset1:1
	ds_write2st64_b64 v31, v[22:23], v[20:21] offset0:2 offset1:3
	v_lshl_or_b32 v11, v10, 11, v38
	v_add_u32_e32 v11, 0x50, v11
	ds_read_b64 v[12:13], v39
	ds_read2st64_b64 v[20:23], v11 offset0:2 offset1:3
	ds_read2st64_b64 v[24:27], v11 offset1:1
	ds_read_b64 v[28:29], v40
	s_waitcnt lgkmcnt(2)
	v_pk_mul_f32 v[30:31], v[22:23], v[12:13]
	s_nop 0
	v_add_f32_e32 v31, v30, v31
	v_pk_mul_f32 v[22:23], v[22:23], v[12:13] op_sel:[1,0] op_sel_hi:[0,1]
	v_sub_f32_e32 v23, v22, v23
	v_add_f32_e32 v22, v20, v31
	s_waitcnt lgkmcnt(1)
	v_pk_mul_f32 v[34:35], v[26:27], v[12:13] op_sel:[1,1] op_sel_hi:[0,1]
	v_add_f32_e32 v30, v21, v23
	v_sub_f32_e32 v32, v21, v23
	v_pk_fma_f32 v[36:37], v[26:27], v[12:13], v[34:35]
	v_pk_fma_f32 v[12:13], v[26:27], v[12:13], v[34:35] op_sel_hi:[1,0,1] neg_lo:[0,0,1] neg_hi:[0,0,1]
	s_waitcnt lgkmcnt(0)
	v_pk_mul_f32 v[22:23], v[28:29], v[22:23] op_sel_hi:[1,0]
	v_sub_f32_e32 v20, v20, v31
	v_mov_b32_e32 v37, v13
	v_pk_fma_f32 v[26:27], v[28:29], v[30:31], v[22:23] op_sel:[1,0,0] op_sel_hi:[0,1,1]
	v_pk_fma_f32 v[22:23], v[28:29], v[30:31], v[22:23] op_sel:[1,0,0] op_sel_hi:[0,0,1] neg_lo:[0,0,1] neg_hi:[0,0,1]
	v_pk_add_f32 v[12:13], v[24:25], v[36:37]
	v_mov_b32_e32 v27, v23
	v_pk_mul_f32 v[20:21], v[28:29], v[20:21] op_sel:[1,0] op_sel_hi:[0,0]
	v_pk_add_f32 v[22:23], v[12:13], v[26:27]
	v_pk_add_f32 v[12:13], v[12:13], v[26:27] neg_lo:[0,1] neg_hi:[0,1]
	v_pk_fma_f32 v[26:27], v[28:29], v[32:33], v[20:21] neg_lo:[0,0,1] neg_hi:[0,0,1]
	v_pk_fma_f32 v[20:21], v[28:29], v[32:33], v[20:21] op_sel_hi:[1,0,1]
	v_pk_add_f32 v[24:25], v[24:25], v[36:37] neg_lo:[0,1] neg_hi:[0,1]
	v_mov_b32_e32 v27, v21
	v_pk_add_f32 v[20:21], v[24:25], v[26:27] neg_lo:[0,1] neg_hi:[0,1]
	v_pk_add_f32 v[24:25], v[24:25], v[26:27]
	v_mov_b32_e32 v26, v20
	v_mov_b32_e32 v27, v25
	v_mov_b32_e32 v25, v21
	ds_write2st64_b64 v11, v[22:23], v[26:27] offset1:1
	ds_write2st64_b64 v11, v[12:13], v[24:25] offset0:2 offset1:3
	v_ashrrev_i32_e32 v11, 6, v3
	v_lshl_or_b32 v12, v11, 11, v38
	v_add_u32_e32 v33, 0x50, v12
	ds_read_b64 v[12:13], v39
	ds_read2st64_b64 v[20:23], v33 offset0:2 offset1:3
	ds_read2st64_b64 v[24:27], v33 offset1:1
	ds_read_b64 v[28:29], v40
	v_lshlrev_b32_e32 v3, 3, v3
	s_waitcnt lgkmcnt(2)
	v_pk_mul_f32 v[30:31], v[22:23], v[12:13]
	s_nop 0
	v_add_f32_e32 v31, v30, v31
	v_pk_mul_f32 v[22:23], v[22:23], v[12:13] op_sel:[1,0] op_sel_hi:[0,1]
	v_sub_f32_e32 v23, v22, v23
	v_add_f32_e32 v22, v20, v31
	s_waitcnt lgkmcnt(1)
	v_pk_mul_f32 v[34:35], v[26:27], v[12:13] op_sel:[1,1] op_sel_hi:[0,1]
	v_add_f32_e32 v30, v21, v23
	v_sub_f32_e32 v32, v21, v23
	v_pk_fma_f32 v[36:37], v[26:27], v[12:13], v[34:35]
	v_pk_fma_f32 v[12:13], v[26:27], v[12:13], v[34:35] op_sel_hi:[1,0,1] neg_lo:[0,0,1] neg_hi:[0,0,1]
	s_waitcnt lgkmcnt(0)
	v_pk_mul_f32 v[22:23], v[28:29], v[22:23] op_sel_hi:[1,0]
	v_sub_f32_e32 v20, v20, v31
	v_mov_b32_e32 v37, v13
	v_pk_fma_f32 v[26:27], v[28:29], v[30:31], v[22:23] op_sel:[1,0,0] op_sel_hi:[0,1,1]
	v_pk_fma_f32 v[22:23], v[28:29], v[30:31], v[22:23] op_sel:[1,0,0] op_sel_hi:[0,0,1] neg_lo:[0,0,1] neg_hi:[0,0,1]
	v_pk_add_f32 v[12:13], v[24:25], v[36:37]
	v_mov_b32_e32 v27, v23
	v_pk_mul_f32 v[20:21], v[28:29], v[20:21] op_sel:[1,0] op_sel_hi:[0,0]
	v_pk_add_f32 v[22:23], v[12:13], v[26:27]
	v_pk_add_f32 v[12:13], v[12:13], v[26:27] neg_lo:[0,1] neg_hi:[0,1]
	v_pk_fma_f32 v[26:27], v[28:29], v[32:33], v[20:21] neg_lo:[0,0,1] neg_hi:[0,0,1]
	v_pk_fma_f32 v[20:21], v[28:29], v[32:33], v[20:21] op_sel_hi:[1,0,1]
	v_pk_add_f32 v[24:25], v[24:25], v[36:37] neg_lo:[0,1] neg_hi:[0,1]
	v_mov_b32_e32 v27, v21
	v_pk_add_f32 v[20:21], v[24:25], v[26:27] neg_lo:[0,1] neg_hi:[0,1]
	v_pk_add_f32 v[24:25], v[24:25], v[26:27]
	v_mov_b32_e32 v26, v20
	v_mov_b32_e32 v27, v25
	v_mov_b32_e32 v25, v21
	ds_write2st64_b64 v33, v[12:13], v[24:25] offset0:2 offset1:3
	v_ashrrev_i32_e32 v12, 6, v4
	ds_write2st64_b64 v33, v[22:23], v[26:27] offset1:1
	v_lshl_or_b32 v13, v12, 11, v38
	v_add_u32_e32 v13, 0x50, v13
	ds_read_b64 v[28:29], v39
	ds_read2st64_b64 v[20:23], v13 offset0:2 offset1:3
	ds_read2st64_b64 v[24:27], v13 offset1:1
	ds_read_b64 v[30:31], v40
	s_waitcnt lgkmcnt(2)
	v_pk_mul_f32 v[32:33], v[22:23], v[28:29]
	s_nop 0
	v_add_f32_e32 v33, v32, v33
	v_pk_mul_f32 v[22:23], v[22:23], v[28:29] op_sel:[1,0] op_sel_hi:[0,1]
	v_sub_f32_e32 v23, v22, v23
	v_add_f32_e32 v22, v20, v33
	s_waitcnt lgkmcnt(1)
	v_pk_mul_f32 v[36:37], v[26:27], v[28:29] op_sel:[1,1] op_sel_hi:[0,1]
	v_add_f32_e32 v32, v21, v23
	v_sub_f32_e32 v34, v21, v23
	v_pk_fma_f32 v[38:39], v[26:27], v[28:29], v[36:37]
	v_pk_fma_f32 v[26:27], v[26:27], v[28:29], v[36:37] op_sel_hi:[1,0,1] neg_lo:[0,0,1] neg_hi:[0,0,1]
	s_waitcnt lgkmcnt(0)
	v_pk_mul_f32 v[22:23], v[30:31], v[22:23] op_sel_hi:[1,0]
	v_sub_f32_e32 v20, v20, v33
	v_mov_b32_e32 v39, v27
	v_pk_fma_f32 v[28:29], v[30:31], v[32:33], v[22:23] op_sel:[1,0,0] op_sel_hi:[0,1,1]
	v_pk_fma_f32 v[22:23], v[30:31], v[32:33], v[22:23] op_sel:[1,0,0] op_sel_hi:[0,0,1] neg_lo:[0,0,1] neg_hi:[0,0,1]
	v_pk_add_f32 v[26:27], v[24:25], v[38:39]
	v_mov_b32_e32 v29, v23
	v_pk_mul_f32 v[20:21], v[30:31], v[20:21] op_sel:[1,0] op_sel_hi:[0,0]
	v_pk_add_f32 v[22:23], v[26:27], v[28:29]
	v_pk_add_f32 v[26:27], v[26:27], v[28:29] neg_lo:[0,1] neg_hi:[0,1]
	v_pk_fma_f32 v[28:29], v[30:31], v[34:35], v[20:21] neg_lo:[0,0,1] neg_hi:[0,0,1]
	v_pk_fma_f32 v[20:21], v[30:31], v[34:35], v[20:21] op_sel_hi:[1,0,1]
	v_pk_add_f32 v[24:25], v[24:25], v[38:39] neg_lo:[0,1] neg_hi:[0,1]
	v_mov_b32_e32 v29, v21
	v_pk_add_f32 v[20:21], v[24:25], v[28:29] neg_lo:[0,1] neg_hi:[0,1]
	v_pk_add_f32 v[24:25], v[24:25], v[28:29]
	v_mov_b32_e32 v28, v20
	v_mov_b32_e32 v29, v25
	v_mov_b32_e32 v25, v21
	ds_write2st64_b64 v13, v[22:23], v[28:29] offset1:1
	ds_write2st64_b64 v13, v[26:27], v[24:25] offset0:2 offset1:3
	v_and_b32_e32 v13, 0xff, v0
	v_lshlrev_b32_e32 v25, 1, v0
	v_and_or_b32 v20, v8, s34, v13
	v_lshlrev_b32_e32 v24, 7, v13
	v_and_b32_e32 v25, 0x1f8, v25
	v_lshl_add_u32 v33, v20, 3, v205
	v_add3_u32 v35, s85, v24, v25
	s_waitcnt lgkmcnt(0)
	s_barrier
	ds_read2st64_b64 v[20:23], v33 offset0:8 offset1:12
	ds_read_b64 v[26:27], v35
	v_lshlrev_b32_e32 v24, 6, v13
	v_and_b32_e32 v25, 0xf8, v0
	v_add3_u32 v40, s85, v24, v25
	ds_read_b64 v[28:29], v40
	s_waitcnt lgkmcnt(1)
	v_pk_mul_f32 v[24:25], v[22:23], v[26:27]
	v_pk_mul_f32 v[22:23], v[22:23], v[26:27] op_sel:[1,0] op_sel_hi:[0,1]
	v_add_f32_e32 v31, v24, v25
	v_sub_f32_e32 v34, v22, v23
	ds_read2st64_b64 v[22:25], v33 offset1:4
	v_add_f32_e32 v30, v20, v31
	v_add_f32_e32 v32, v21, v34
	v_sub_f32_e32 v20, v20, v31
	v_sub_f32_e32 v34, v21, v34
	s_waitcnt lgkmcnt(0)
	v_pk_mul_f32 v[36:37], v[24:25], v[26:27] op_sel:[1,1] op_sel_hi:[0,1]
	v_pk_fma_f32 v[38:39], v[24:25], v[26:27], v[36:37]
	v_pk_fma_f32 v[24:25], v[24:25], v[26:27], v[36:37] op_sel_hi:[1,0,1] neg_lo:[0,0,1] neg_hi:[0,0,1]
	v_pk_mul_f32 v[26:27], v[28:29], v[30:31] op_sel_hi:[1,0]
	v_mov_b32_e32 v39, v25
	v_pk_fma_f32 v[30:31], v[28:29], v[32:33], v[26:27] op_sel:[1,0,0] op_sel_hi:[0,1,1]
	v_pk_fma_f32 v[26:27], v[28:29], v[32:33], v[26:27] op_sel:[1,0,0] op_sel_hi:[0,0,1] neg_lo:[0,0,1] neg_hi:[0,0,1]
	v_pk_add_f32 v[24:25], v[22:23], v[38:39]
	v_mov_b32_e32 v31, v27
	v_pk_mul_f32 v[20:21], v[28:29], v[20:21] op_sel:[1,0] op_sel_hi:[0,0]
	v_pk_add_f32 v[26:27], v[24:25], v[30:31]
	v_pk_add_f32 v[24:25], v[24:25], v[30:31] neg_lo:[0,1] neg_hi:[0,1]
	v_pk_fma_f32 v[30:31], v[28:29], v[34:35], v[20:21] neg_lo:[0,0,1] neg_hi:[0,0,1]
	v_pk_fma_f32 v[20:21], v[28:29], v[34:35], v[20:21] op_sel_hi:[1,0,1]
	v_pk_add_f32 v[22:23], v[22:23], v[38:39] neg_lo:[0,1] neg_hi:[0,1]
	v_mov_b32_e32 v31, v21
	v_pk_add_f32 v[20:21], v[22:23], v[30:31] neg_lo:[0,1] neg_hi:[0,1]
	v_pk_add_f32 v[22:23], v[22:23], v[30:31]
	v_mov_b32_e32 v28, v20
	v_mov_b32_e32 v29, v23
	v_mov_b32_e32 v23, v21
	v_and_or_b32 v20, v7, s34, v13
	ds_write2st64_b64 v33, v[26:27], v[28:29] offset1:4
	ds_write2st64_b64 v33, v[24:25], v[22:23] offset0:8 offset1:12
	v_lshl_add_u32 v33, v20, 3, v205
	ds_read2st64_b64 v[20:23], v33 offset0:8 offset1:12
	ds_read_b64 v[26:27], v35
	ds_read_b64 v[28:29], v40
	s_waitcnt lgkmcnt(1)
	v_pk_mul_f32 v[24:25], v[22:23], v[26:27]
	v_pk_mul_f32 v[22:23], v[22:23], v[26:27] op_sel:[1,0] op_sel_hi:[0,1]
	v_add_f32_e32 v31, v24, v25
	v_sub_f32_e32 v34, v22, v23
	ds_read2st64_b64 v[22:25], v33 offset1:4
	v_add_f32_e32 v30, v20, v31
	v_add_f32_e32 v32, v21, v34
	v_sub_f32_e32 v20, v20, v31
	v_sub_f32_e32 v34, v21, v34
	s_waitcnt lgkmcnt(0)
	v_pk_mul_f32 v[36:37], v[24:25], v[26:27] op_sel:[1,1] op_sel_hi:[0,1]
	v_pk_fma_f32 v[38:39], v[24:25], v[26:27], v[36:37]
	v_pk_fma_f32 v[24:25], v[24:25], v[26:27], v[36:37] op_sel_hi:[1,0,1] neg_lo:[0,0,1] neg_hi:[0,0,1]
	v_pk_mul_f32 v[26:27], v[28:29], v[30:31] op_sel_hi:[1,0]
	v_mov_b32_e32 v39, v25
	v_pk_fma_f32 v[30:31], v[28:29], v[32:33], v[26:27] op_sel:[1,0,0] op_sel_hi:[0,1,1]
	v_pk_fma_f32 v[26:27], v[28:29], v[32:33], v[26:27] op_sel:[1,0,0] op_sel_hi:[0,0,1] neg_lo:[0,0,1] neg_hi:[0,0,1]
	v_pk_add_f32 v[24:25], v[22:23], v[38:39]
	v_mov_b32_e32 v31, v27
	v_pk_mul_f32 v[20:21], v[28:29], v[20:21] op_sel:[1,0] op_sel_hi:[0,0]
	v_pk_add_f32 v[26:27], v[24:25], v[30:31]
	v_pk_add_f32 v[24:25], v[24:25], v[30:31] neg_lo:[0,1] neg_hi:[0,1]
	v_pk_fma_f32 v[30:31], v[28:29], v[34:35], v[20:21] neg_lo:[0,0,1] neg_hi:[0,0,1]
	v_pk_fma_f32 v[20:21], v[28:29], v[34:35], v[20:21] op_sel_hi:[1,0,1]
	v_pk_add_f32 v[22:23], v[22:23], v[38:39] neg_lo:[0,1] neg_hi:[0,1]
	v_mov_b32_e32 v31, v21
	v_pk_add_f32 v[20:21], v[22:23], v[30:31] neg_lo:[0,1] neg_hi:[0,1]
	v_pk_add_f32 v[22:23], v[22:23], v[30:31]
	v_mov_b32_e32 v28, v20
	v_mov_b32_e32 v29, v23
	v_mov_b32_e32 v23, v21
	v_and_or_b32 v20, v5, s34, v13
	ds_write2st64_b64 v33, v[26:27], v[28:29] offset1:4
	ds_write2st64_b64 v33, v[24:25], v[22:23] offset0:8 offset1:12
	v_lshl_add_u32 v33, v20, 3, v205
	ds_read2st64_b64 v[20:23], v33 offset0:8 offset1:12
	ds_read_b64 v[26:27], v35
	ds_read_b64 v[28:29], v40
	v_and_or_b32 v13, v6, s34, v13
	v_lshl_add_u32 v13, v13, 3, v205
	s_waitcnt lgkmcnt(1)
	v_pk_mul_f32 v[24:25], v[22:23], v[26:27]
	v_pk_mul_f32 v[22:23], v[22:23], v[26:27] op_sel:[1,0] op_sel_hi:[0,1]
	v_add_f32_e32 v31, v24, v25
	v_sub_f32_e32 v34, v22, v23
	ds_read2st64_b64 v[22:25], v33 offset1:4
	v_add_f32_e32 v30, v20, v31
	v_add_f32_e32 v32, v21, v34
	v_sub_f32_e32 v20, v20, v31
	v_sub_f32_e32 v34, v21, v34
	s_waitcnt lgkmcnt(0)
	v_pk_mul_f32 v[36:37], v[24:25], v[26:27] op_sel:[1,1] op_sel_hi:[0,1]
	v_pk_fma_f32 v[38:39], v[24:25], v[26:27], v[36:37]
	v_pk_fma_f32 v[24:25], v[24:25], v[26:27], v[36:37] op_sel_hi:[1,0,1] neg_lo:[0,0,1] neg_hi:[0,0,1]
	v_pk_mul_f32 v[26:27], v[28:29], v[30:31] op_sel_hi:[1,0]
	v_mov_b32_e32 v39, v25
	v_pk_fma_f32 v[30:31], v[28:29], v[32:33], v[26:27] op_sel:[1,0,0] op_sel_hi:[0,1,1]
	v_pk_fma_f32 v[26:27], v[28:29], v[32:33], v[26:27] op_sel:[1,0,0] op_sel_hi:[0,0,1] neg_lo:[0,0,1] neg_hi:[0,0,1]
	v_pk_add_f32 v[24:25], v[22:23], v[38:39]
	v_mov_b32_e32 v31, v27
	v_pk_mul_f32 v[20:21], v[28:29], v[20:21] op_sel:[1,0] op_sel_hi:[0,0]
	v_pk_add_f32 v[26:27], v[24:25], v[30:31]
	v_pk_add_f32 v[24:25], v[24:25], v[30:31] neg_lo:[0,1] neg_hi:[0,1]
	v_pk_fma_f32 v[30:31], v[28:29], v[34:35], v[20:21] neg_lo:[0,0,1] neg_hi:[0,0,1]
	v_pk_fma_f32 v[20:21], v[28:29], v[34:35], v[20:21] op_sel_hi:[1,0,1]
	v_pk_add_f32 v[22:23], v[22:23], v[38:39] neg_lo:[0,1] neg_hi:[0,1]
	v_mov_b32_e32 v31, v21
	v_pk_add_f32 v[20:21], v[22:23], v[30:31] neg_lo:[0,1] neg_hi:[0,1]
	v_pk_add_f32 v[22:23], v[22:23], v[30:31]
	v_mov_b32_e32 v28, v20
	v_mov_b32_e32 v29, v23
	v_mov_b32_e32 v23, v21
	ds_write2st64_b64 v33, v[26:27], v[28:29] offset1:4
	ds_write2st64_b64 v33, v[24:25], v[22:23] offset0:8 offset1:12
	ds_read2st64_b64 v[20:23], v13 offset0:8 offset1:12
	ds_read_b64 v[26:27], v35
	ds_read_b64 v[28:29], v40
	s_waitcnt lgkmcnt(1)
	v_pk_mul_f32 v[24:25], v[22:23], v[26:27]
	v_pk_mul_f32 v[22:23], v[22:23], v[26:27] op_sel:[1,0] op_sel_hi:[0,1]
	v_add_f32_e32 v31, v24, v25
	v_sub_f32_e32 v33, v22, v23
	ds_read2st64_b64 v[22:25], v13 offset1:4
	v_add_f32_e32 v30, v20, v31
	v_add_f32_e32 v32, v21, v33
	v_sub_f32_e32 v20, v20, v31
	v_sub_f32_e32 v34, v21, v33
	s_waitcnt lgkmcnt(0)
	v_pk_mul_f32 v[36:37], v[24:25], v[26:27] op_sel:[1,1] op_sel_hi:[0,1]
	v_pk_fma_f32 v[38:39], v[24:25], v[26:27], v[36:37]
	v_pk_fma_f32 v[24:25], v[24:25], v[26:27], v[36:37] op_sel_hi:[1,0,1] neg_lo:[0,0,1] neg_hi:[0,0,1]
	v_pk_mul_f32 v[26:27], v[28:29], v[30:31] op_sel_hi:[1,0]
	v_mov_b32_e32 v39, v25
	v_pk_fma_f32 v[30:31], v[28:29], v[32:33], v[26:27] op_sel:[1,0,0] op_sel_hi:[0,1,1]
	v_pk_fma_f32 v[26:27], v[28:29], v[32:33], v[26:27] op_sel:[1,0,0] op_sel_hi:[0,0,1] neg_lo:[0,0,1] neg_hi:[0,0,1]
	v_pk_add_f32 v[24:25], v[22:23], v[38:39]
	v_mov_b32_e32 v31, v27
	v_pk_mul_f32 v[20:21], v[28:29], v[20:21] op_sel:[1,0] op_sel_hi:[0,0]
	v_pk_add_f32 v[26:27], v[24:25], v[30:31]
	v_pk_add_f32 v[24:25], v[24:25], v[30:31] neg_lo:[0,1] neg_hi:[0,1]
	v_pk_fma_f32 v[30:31], v[28:29], v[34:35], v[20:21] neg_lo:[0,0,1] neg_hi:[0,0,1]
	v_pk_fma_f32 v[20:21], v[28:29], v[34:35], v[20:21] op_sel_hi:[1,0,1]
	v_pk_add_f32 v[22:23], v[22:23], v[38:39] neg_lo:[0,1] neg_hi:[0,1]
	v_mov_b32_e32 v31, v21
	v_pk_add_f32 v[20:21], v[22:23], v[30:31] neg_lo:[0,1] neg_hi:[0,1]
	v_pk_add_f32 v[22:23], v[22:23], v[30:31]
	v_mov_b32_e32 v28, v20
	v_mov_b32_e32 v29, v23
	v_mov_b32_e32 v23, v21
	ds_write2st64_b64 v13, v[26:27], v[28:29] offset1:4
	ds_write2st64_b64 v13, v[24:25], v[22:23] offset0:8 offset1:12
	v_and_b32_e32 v13, 0x3ff, v0
	v_and_or_b32 v8, v8, s26, v13
	v_lshrrev_b32_e32 v24, 1, v0
	v_lshl_add_u32 v33, v8, 3, v205
	v_lshlrev_b32_e32 v8, 5, v13
	v_and_b32_e32 v24, 0x1f8, v24
	v_add3_u32 v38, s85, v8, v24
	s_waitcnt lgkmcnt(0)
	s_barrier
	ds_read2st64_b64 v[20:23], v33 offset0:32 offset1:48
	ds_read_b64 v[26:27], v38
	v_lshrrev_b32_e32 v24, 2, v0
	v_lshlrev_b32_e32 v8, 4, v13
	v_and_b32_e32 v24, 0xf8, v24
	v_add3_u32 v39, s85, v8, v24
	ds_read_b64 v[28:29], v39
	s_waitcnt lgkmcnt(1)
	v_pk_mul_f32 v[24:25], v[22:23], v[26:27]
	v_pk_mul_f32 v[22:23], v[22:23], v[26:27] op_sel:[1,0] op_sel_hi:[0,1]
	v_add_f32_e32 v31, v24, v25
	v_sub_f32_e32 v32, v22, v23
	ds_read2st64_b64 v[22:25], v33 offset1:16
	v_add_f32_e32 v8, v20, v31
	v_sub_f32_e32 v20, v20, v31
	v_add_f32_e32 v30, v21, v32
	v_sub_f32_e32 v32, v21, v32
	s_waitcnt lgkmcnt(0)
	v_pk_mul_f32 v[34:35], v[24:25], v[26:27] op_sel:[1,1] op_sel_hi:[0,1]
	v_pk_fma_f32 v[36:37], v[24:25], v[26:27], v[34:35]
	v_pk_fma_f32 v[24:25], v[24:25], v[26:27], v[34:35] op_sel_hi:[1,0,1] neg_lo:[0,0,1] neg_hi:[0,0,1]
	v_pk_mul_f32 v[26:27], v[28:29], v[8:9] op_sel_hi:[1,0]
	v_pk_mul_f32 v[20:21], v[28:29], v[20:21] op_sel:[1,0] op_sel_hi:[0,0]
	v_mov_b32_e32 v37, v25
	v_pk_fma_f32 v[34:35], v[28:29], v[30:31], v[26:27] op_sel:[1,0,0] op_sel_hi:[0,1,1]
	v_pk_fma_f32 v[26:27], v[28:29], v[30:31], v[26:27] op_sel:[1,0,0] op_sel_hi:[0,0,1] neg_lo:[0,0,1] neg_hi:[0,0,1]
	v_pk_fma_f32 v[30:31], v[28:29], v[32:33], v[20:21] neg_lo:[0,0,1] neg_hi:[0,0,1]
	v_pk_fma_f32 v[20:21], v[28:29], v[32:33], v[20:21] op_sel_hi:[1,0,1]
	v_pk_add_f32 v[24:25], v[22:23], v[36:37]
	v_pk_add_f32 v[22:23], v[22:23], v[36:37] neg_lo:[0,1] neg_hi:[0,1]
	v_mov_b32_e32 v31, v21
	v_mov_b32_e32 v35, v27
	v_pk_add_f32 v[20:21], v[22:23], v[30:31] neg_lo:[0,1] neg_hi:[0,1]
	v_pk_add_f32 v[22:23], v[22:23], v[30:31]
	v_pk_add_f32 v[26:27], v[24:25], v[34:35]
	v_pk_add_f32 v[24:25], v[24:25], v[34:35] neg_lo:[0,1] neg_hi:[0,1]
	v_mov_b32_e32 v29, v23
	v_mov_b32_e32 v23, v21
	ds_write2st64_b64 v33, v[24:25], v[22:23] offset0:32 offset1:48
	v_and_b32_e32 v8, 0x3ff, v2
	v_lshrrev_b32_e32 v25, 1, v2
	v_mov_b32_e32 v28, v20
	v_and_or_b32 v7, v7, s26, v8
	v_lshlrev_b32_e32 v24, 5, v8
	v_and_b32_e32 v25, 0x1f8, v25
	ds_write2st64_b64 v33, v[26:27], v[28:29] offset1:16
	v_lshl_add_u32 v7, v7, 3, v205
	v_add3_u32 v24, s85, v24, v25
	ds_read2st64_b64 v[20:23], v7 offset0:32 offset1:48
	ds_read_b64 v[26:27], v24
	v_lshrrev_b32_e32 v24, 2, v2
	v_lshlrev_b32_e32 v8, 4, v8
	v_and_b32_e32 v24, 0xf8, v24
	v_add3_u32 v8, s85, v8, v24
	s_waitcnt lgkmcnt(0)
	v_pk_mul_f32 v[24:25], v[22:23], v[26:27]
	v_pk_mul_f32 v[22:23], v[22:23], v[26:27] op_sel:[1,0] op_sel_hi:[0,1]
	v_add_f32_e32 v31, v24, v25
	v_sub_f32_e32 v32, v22, v23
	ds_read2st64_b64 v[22:25], v7 offset1:16
	ds_read_b64 v[28:29], v8
	v_add_f32_e32 v8, v20, v31
	v_sub_f32_e32 v20, v20, v31
	v_add_f32_e32 v30, v21, v32
	s_waitcnt lgkmcnt(1)
	v_pk_mul_f32 v[34:35], v[24:25], v[26:27] op_sel:[1,1] op_sel_hi:[0,1]
	v_sub_f32_e32 v32, v21, v32
	v_pk_fma_f32 v[36:37], v[24:25], v[26:27], v[34:35]
	v_pk_fma_f32 v[24:25], v[24:25], v[26:27], v[34:35] op_sel_hi:[1,0,1] neg_lo:[0,0,1] neg_hi:[0,0,1]
	s_waitcnt lgkmcnt(0)
	v_pk_mul_f32 v[26:27], v[28:29], v[8:9] op_sel_hi:[1,0]
	v_pk_mul_f32 v[20:21], v[28:29], v[20:21] op_sel:[1,0] op_sel_hi:[0,0]
	v_mov_b32_e32 v37, v25
	v_pk_fma_f32 v[34:35], v[28:29], v[30:31], v[26:27] op_sel:[1,0,0] op_sel_hi:[0,1,1]
	v_pk_fma_f32 v[26:27], v[28:29], v[30:31], v[26:27] op_sel:[1,0,0] op_sel_hi:[0,0,1] neg_lo:[0,0,1] neg_hi:[0,0,1]
	v_pk_fma_f32 v[30:31], v[28:29], v[32:33], v[20:21] neg_lo:[0,0,1] neg_hi:[0,0,1]
	v_pk_fma_f32 v[20:21], v[28:29], v[32:33], v[20:21] op_sel_hi:[1,0,1]
	v_pk_add_f32 v[24:25], v[22:23], v[36:37]
	v_pk_add_f32 v[22:23], v[22:23], v[36:37] neg_lo:[0,1] neg_hi:[0,1]
	v_mov_b32_e32 v31, v21
	v_mov_b32_e32 v35, v27
	v_pk_add_f32 v[20:21], v[22:23], v[30:31] neg_lo:[0,1] neg_hi:[0,1]
	v_pk_add_f32 v[22:23], v[22:23], v[30:31]
	v_pk_add_f32 v[26:27], v[24:25], v[34:35]
	v_pk_add_f32 v[24:25], v[24:25], v[34:35] neg_lo:[0,1] neg_hi:[0,1]
	v_mov_b32_e32 v28, v20
	v_mov_b32_e32 v29, v23
	v_mov_b32_e32 v23, v21
	v_and_or_b32 v5, v5, s26, v13
	ds_write2st64_b64 v7, v[26:27], v[28:29] offset1:16
	ds_write2st64_b64 v7, v[24:25], v[22:23] offset0:32 offset1:48
	v_lshl_add_u32 v5, v5, 3, v205
	ds_read2st64_b64 v[20:23], v5 offset0:32 offset1:48
	ds_read_b64 v[26:27], v38
	ds_read_b64 v[28:29], v39
	v_lshlrev_b32_e32 v2, 3, v2
	s_waitcnt lgkmcnt(1)
	v_pk_mul_f32 v[24:25], v[22:23], v[26:27]
	v_pk_mul_f32 v[22:23], v[22:23], v[26:27] op_sel:[1,0] op_sel_hi:[0,1]
	v_add_f32_e32 v7, v24, v25
	v_sub_f32_e32 v13, v22, v23
	ds_read2st64_b64 v[22:25], v5 offset1:16
	v_add_f32_e32 v8, v20, v7
	v_sub_f32_e32 v20, v20, v7
	v_add_f32_e32 v30, v21, v13
	v_sub_f32_e32 v32, v21, v13
	s_waitcnt lgkmcnt(0)
	v_pk_mul_f32 v[34:35], v[24:25], v[26:27] op_sel:[1,1] op_sel_hi:[0,1]
	v_pk_fma_f32 v[36:37], v[24:25], v[26:27], v[34:35]
	v_pk_fma_f32 v[24:25], v[24:25], v[26:27], v[34:35] op_sel_hi:[1,0,1] neg_lo:[0,0,1] neg_hi:[0,0,1]
	v_pk_mul_f32 v[26:27], v[28:29], v[8:9] op_sel_hi:[1,0]
	v_pk_mul_f32 v[20:21], v[28:29], v[20:21] op_sel:[1,0] op_sel_hi:[0,0]
	v_mov_b32_e32 v37, v25
	v_pk_fma_f32 v[34:35], v[28:29], v[30:31], v[26:27] op_sel:[1,0,0] op_sel_hi:[0,1,1]
	v_pk_fma_f32 v[26:27], v[28:29], v[30:31], v[26:27] op_sel:[1,0,0] op_sel_hi:[0,0,1] neg_lo:[0,0,1] neg_hi:[0,0,1]
	v_pk_fma_f32 v[30:31], v[28:29], v[32:33], v[20:21] neg_lo:[0,0,1] neg_hi:[0,0,1]
	v_pk_fma_f32 v[20:21], v[28:29], v[32:33], v[20:21] op_sel_hi:[1,0,1]
	v_pk_add_f32 v[24:25], v[22:23], v[36:37]
	v_pk_add_f32 v[22:23], v[22:23], v[36:37] neg_lo:[0,1] neg_hi:[0,1]
	v_mov_b32_e32 v31, v21
	v_mov_b32_e32 v35, v27
	v_pk_add_f32 v[20:21], v[22:23], v[30:31] neg_lo:[0,1] neg_hi:[0,1]
	v_pk_add_f32 v[22:23], v[22:23], v[30:31]
	v_pk_add_f32 v[26:27], v[24:25], v[34:35]
	v_pk_add_f32 v[24:25], v[24:25], v[34:35] neg_lo:[0,1] neg_hi:[0,1]
	v_mov_b32_e32 v28, v20
	v_mov_b32_e32 v29, v23
	v_mov_b32_e32 v23, v21
	ds_write2st64_b64 v5, v[26:27], v[28:29] offset1:16
	ds_write2st64_b64 v5, v[24:25], v[22:23] offset0:32 offset1:48
	v_and_b32_e32 v5, 0x3ff, v4
	v_and_or_b32 v6, v6, s26, v5
	v_lshrrev_b32_e32 v7, 1, v4
	v_lshl_add_u32 v13, v6, 3, v205
	v_lshlrev_b32_e32 v6, 5, v5
	v_and_b32_e32 v7, 0x1f8, v7
	v_add3_u32 v6, s85, v6, v7
	ds_read2st64_b64 v[20:23], v13 offset0:32 offset1:48
	ds_read_b64 v[6:7], v6
	v_lshrrev_b32_e32 v8, 2, v4
	v_lshlrev_b32_e32 v5, 4, v5
	v_and_b32_e32 v8, 0xf8, v8
	v_add3_u32 v5, s85, v5, v8
	ds_read_b64 v[26:27], v5
	s_waitcnt lgkmcnt(1)
	v_pk_mul_f32 v[24:25], v[22:23], v[6:7]
	v_pk_mul_f32 v[22:23], v[22:23], v[6:7] op_sel:[1,0] op_sel_hi:[0,1]
	v_add_f32_e32 v5, v24, v25
	v_sub_f32_e32 v29, v22, v23
	ds_read2st64_b64 v[22:25], v13 offset1:16
	v_add_f32_e32 v8, v20, v5
	v_sub_f32_e32 v20, v20, v5
	v_add_f32_e32 v28, v21, v29
	v_sub_f32_e32 v30, v21, v29
	s_waitcnt lgkmcnt(0)
	v_pk_mul_f32 v[32:33], v[24:25], v[6:7] op_sel:[1,1] op_sel_hi:[0,1]
	v_pk_fma_f32 v[34:35], v[24:25], v[6:7], v[32:33]
	v_pk_fma_f32 v[6:7], v[24:25], v[6:7], v[32:33] op_sel_hi:[1,0,1] neg_lo:[0,0,1] neg_hi:[0,0,1]
	v_pk_mul_f32 v[24:25], v[26:27], v[8:9] op_sel_hi:[1,0]
	v_pk_mul_f32 v[20:21], v[26:27], v[20:21] op_sel:[1,0] op_sel_hi:[0,0]
	v_mov_b32_e32 v35, v7
	v_pk_fma_f32 v[32:33], v[26:27], v[28:29], v[24:25] op_sel:[1,0,0] op_sel_hi:[0,1,1]
	v_pk_fma_f32 v[24:25], v[26:27], v[28:29], v[24:25] op_sel:[1,0,0] op_sel_hi:[0,0,1] neg_lo:[0,0,1] neg_hi:[0,0,1]
	v_pk_fma_f32 v[28:29], v[26:27], v[30:31], v[20:21] neg_lo:[0,0,1] neg_hi:[0,0,1]
	v_pk_fma_f32 v[20:21], v[26:27], v[30:31], v[20:21] op_sel_hi:[1,0,1]
	v_pk_add_f32 v[6:7], v[22:23], v[34:35]
	v_pk_add_f32 v[22:23], v[22:23], v[34:35] neg_lo:[0,1] neg_hi:[0,1]
	v_mov_b32_e32 v29, v21
	v_mov_b32_e32 v33, v25
	v_pk_add_f32 v[20:21], v[22:23], v[28:29] neg_lo:[0,1] neg_hi:[0,1]
	v_pk_add_f32 v[22:23], v[22:23], v[28:29]
	v_pk_add_f32 v[24:25], v[6:7], v[32:33]
	v_pk_add_f32 v[6:7], v[6:7], v[32:33] neg_lo:[0,1] neg_hi:[0,1]
	v_mov_b32_e32 v27, v23
	v_mov_b32_e32 v23, v21
	ds_write2st64_b64 v13, v[6:7], v[22:23] offset0:32 offset1:48
	v_lshlrev_b32_e32 v5, 3, v0
	v_lshlrev_b32_e32 v6, 3, v9
	v_mov_b32_e32 v26, v20
	v_add3_u32 v6, s85, v5, v6
	ds_write2st64_b64 v13, v[24:25], v[26:27] offset1:16
	s_waitcnt lgkmcnt(0)
	s_barrier
	ds_read_b64 v[24:25], v6
	v_add_u32_e32 v30, 0x50, v5
	ds_read2st64_b64 v[6:9], v30 offset0:64 offset1:72
	ds_read2st64_b64 v[20:23], v30 offset1:8
	v_lshlrev_b32_e32 v5, 3, v10
	v_add3_u32 v2, s85, v5, v2
	s_waitcnt lgkmcnt(1)
	v_pk_mul_f32 v[26:27], v[24:25], v[6:7] op_sel:[1,1] op_sel_hi:[1,0]
	s_nop 0
	v_pk_fma_f32 v[28:29], v[24:25], v[6:7], v[26:27]
	v_pk_fma_f32 v[6:7], v[24:25], v[6:7], v[26:27] op_sel_hi:[0,1,1] neg_lo:[0,0,1] neg_hi:[0,0,1]
	v_mov_b32_e32 v29, v7
	s_waitcnt lgkmcnt(0)
	v_pk_add_f32 v[6:7], v[20:21], v[28:29]
	ds_write_b64 v30, v[6:7]
	v_pk_add_f32 v[6:7], v[20:21], v[28:29] neg_lo:[0,1] neg_hi:[0,1]
	ds_write_b64 v30, v[6:7] offset:32768
	ds_read_b64 v[6:7], v2
	v_lshlrev_b32_e32 v2, 3, v11
	v_add3_u32 v2, s85, v2, v3
	s_waitcnt lgkmcnt(0)
	v_pk_mul_f32 v[20:21], v[6:7], v[8:9] op_sel:[1,1] op_sel_hi:[1,0]
	s_nop 0
	v_pk_fma_f32 v[24:25], v[6:7], v[8:9], v[20:21]
	v_pk_fma_f32 v[6:7], v[6:7], v[8:9], v[20:21] op_sel_hi:[0,1,1] neg_lo:[0,0,1] neg_hi:[0,0,1]
	v_mov_b32_e32 v25, v7
	v_pk_add_f32 v[6:7], v[22:23], v[24:25]
	ds_write_b64 v30, v[6:7] offset:4096
	v_pk_add_f32 v[6:7], v[22:23], v[24:25] neg_lo:[0,1] neg_hi:[0,1]
	ds_write_b64 v30, v[6:7] offset:36864
	ds_read_b64 v[2:3], v2
	ds_read2st64_b64 v[6:9], v30 offset0:80 offset1:88
	ds_read2st64_b64 v[20:23], v30 offset0:16 offset1:24
	s_waitcnt lgkmcnt(1)
	v_pk_mul_f32 v[10:11], v[2:3], v[6:7] op_sel:[1,1] op_sel_hi:[1,0]
	s_nop 0
	v_pk_fma_f32 v[24:25], v[2:3], v[6:7], v[10:11]
	v_pk_fma_f32 v[2:3], v[2:3], v[6:7], v[10:11] op_sel_hi:[0,1,1] neg_lo:[0,0,1] neg_hi:[0,0,1]
	v_mov_b32_e32 v25, v3
	s_waitcnt lgkmcnt(0)
	v_pk_add_f32 v[2:3], v[20:21], v[24:25]
	ds_write_b64 v30, v[2:3] offset:8192
	v_pk_add_f32 v[2:3], v[20:21], v[24:25] neg_lo:[0,1] neg_hi:[0,1]
	ds_write_b64 v30, v[2:3] offset:40960
	v_lshlrev_b32_e32 v2, 3, v12
	v_lshlrev_b32_e32 v3, 3, v4
	v_add3_u32 v2, s85, v2, v3
	ds_read_b64 v[2:3], v2
	s_waitcnt lgkmcnt(0)
	v_pk_mul_f32 v[4:5], v[2:3], v[8:9] op_sel:[1,1] op_sel_hi:[1,0]
	s_nop 0
	v_pk_fma_f32 v[6:7], v[2:3], v[8:9], v[4:5]
	v_pk_fma_f32 v[2:3], v[2:3], v[8:9], v[4:5] op_sel_hi:[0,1,1] neg_lo:[0,0,1] neg_hi:[0,0,1]
	v_mov_b32_e32 v7, v3
	v_pk_add_f32 v[2:3], v[22:23], v[6:7]
	ds_write_b64 v30, v[2:3] offset:12288
	v_pk_add_f32 v[2:3], v[22:23], v[6:7] neg_lo:[0,1] neg_hi:[0,1]
	ds_write_b64 v30, v[2:3] offset:45056
	v_add_u32_e32 v2, 0x800, v0
	v_ashrrev_i32_e32 v3, 6, v2
	v_lshlrev_b32_e32 v3, 3, v3
	v_lshlrev_b32_e32 v2, 3, v2
	v_add3_u32 v2, s85, v3, v2
	ds_read_b64 v[10:11], v2
	ds_read2st64_b64 v[2:5], v30 offset0:96 offset1:104
	ds_read2st64_b64 v[6:9], v30 offset0:32 offset1:40
	s_waitcnt lgkmcnt(1)
	v_pk_mul_f32 v[12:13], v[10:11], v[2:3] op_sel:[1,1] op_sel_hi:[1,0]
	s_nop 0
	v_pk_fma_f32 v[20:21], v[10:11], v[2:3], v[12:13]
	v_pk_fma_f32 v[2:3], v[10:11], v[2:3], v[12:13] op_sel_hi:[0,1,1] neg_lo:[0,0,1] neg_hi:[0,0,1]
	v_mov_b32_e32 v21, v3
	s_waitcnt lgkmcnt(0)
	v_pk_add_f32 v[2:3], v[6:7], v[20:21]
	ds_write_b64 v30, v[2:3] offset:16384
	v_pk_add_f32 v[2:3], v[6:7], v[20:21] neg_lo:[0,1] neg_hi:[0,1]
	ds_write_b64 v30, v[2:3] offset:49152
	v_add_u32_e32 v2, 0xa00, v0
	v_ashrrev_i32_e32 v3, 6, v2
	v_lshlrev_b32_e32 v3, 3, v3
	v_lshlrev_b32_e32 v2, 3, v2
	v_add3_u32 v2, s85, v3, v2
	ds_read_b64 v[2:3], v2
	s_waitcnt lgkmcnt(0)
	v_pk_mul_f32 v[6:7], v[2:3], v[4:5] op_sel:[1,1] op_sel_hi:[1,0]
	s_nop 0
	v_pk_fma_f32 v[10:11], v[2:3], v[4:5], v[6:7]
	v_pk_fma_f32 v[2:3], v[2:3], v[4:5], v[6:7] op_sel_hi:[0,1,1] neg_lo:[0,0,1] neg_hi:[0,0,1]
	v_mov_b32_e32 v11, v3
	v_pk_add_f32 v[2:3], v[8:9], v[10:11]
	ds_write_b64 v30, v[2:3] offset:20480
	v_pk_add_f32 v[2:3], v[8:9], v[10:11] neg_lo:[0,1] neg_hi:[0,1]
	ds_write_b64 v30, v[2:3] offset:53248
	v_add_u32_e32 v2, 0xc00, v0
	v_ashrrev_i32_e32 v3, 6, v2
	v_lshlrev_b32_e32 v3, 3, v3
	v_lshlrev_b32_e32 v2, 3, v2
	v_add3_u32 v2, s85, v3, v2
	ds_read_b64 v[10:11], v2
	ds_read2st64_b64 v[2:5], v30 offset0:112 offset1:120
	ds_read2st64_b64 v[6:9], v30 offset0:48 offset1:56
	v_add_u32_e32 v0, 0xe00, v0
	s_waitcnt lgkmcnt(1)
	v_pk_mul_f32 v[12:13], v[10:11], v[2:3] op_sel:[1,1] op_sel_hi:[1,0]
	s_nop 0
	v_pk_fma_f32 v[20:21], v[10:11], v[2:3], v[12:13]
	v_pk_fma_f32 v[2:3], v[10:11], v[2:3], v[12:13] op_sel_hi:[0,1,1] neg_lo:[0,0,1] neg_hi:[0,0,1]
	v_mov_b32_e32 v21, v3
	s_waitcnt lgkmcnt(0)
	v_pk_add_f32 v[2:3], v[6:7], v[20:21]
	ds_write_b64 v30, v[2:3] offset:24576
	v_pk_add_f32 v[2:3], v[6:7], v[20:21] neg_lo:[0,1] neg_hi:[0,1]
	ds_write_b64 v30, v[2:3] offset:57344
	v_ashrrev_i32_e32 v2, 6, v0
	v_lshlrev_b32_e32 v2, 3, v2
	v_lshlrev_b32_e32 v0, 3, v0
	v_add3_u32 v0, s85, v2, v0
	ds_read_b64 v[2:3], v0
	s_waitcnt lgkmcnt(0)
	v_pk_mul_f32 v[6:7], v[2:3], v[4:5] op_sel:[1,1] op_sel_hi:[1,0]
	s_nop 0
	v_pk_fma_f32 v[10:11], v[2:3], v[4:5], v[6:7]
	v_pk_fma_f32 v[2:3], v[2:3], v[4:5], v[6:7] op_sel_hi:[0,1,1] neg_lo:[0,0,1] neg_hi:[0,0,1]
	v_mov_b32_e32 v11, v3
	v_pk_add_f32 v[2:3], v[8:9], v[10:11]
	ds_write_b64 v30, v[2:3] offset:28672
	v_pk_add_f32 v[2:3], v[8:9], v[10:11] neg_lo:[0,1] neg_hi:[0,1]
	ds_write_b64 v30, v[2:3] offset:61440
	s_waitcnt lgkmcnt(0)
	s_barrier
	global_load_dword v31, v1, s[0:1] offset:2048
	global_load_dword v32, v1, s[30:31] offset:3072
	global_load_dword v28, v1, s[24:25] offset:1024
	global_load_dword v29, v1, s[20:21] offset:2048
	s_mul_i32 s21, s6, 0xc000
	v_readlane_b32 s24, v251, 39
	s_mul_hi_i32 s20, s6, 0xc000
	v_readlane_b32 s25, v251, 40
	s_add_u32 s23, s24, s21
	s_addc_u32 s24, s25, s20
	s_add_u32 s20, s23, 0x4000
	s_addc_u32 s21, s24, 0
	v_lshl_add_u64 v[8:9], v[50:51], 2, s[20:21]
	global_load_dword v66, v[8:9], off
	global_load_dword v33, v203, s[0:1]
	ds_read_b64 v[2:3], v148
	s_and_saveexec_b64 s[0:1], s[40:41]
	s_cbranch_execz .LBB0_949
	v_mov_b32_e32 v0, v50
	v_lshl_add_u64 v[4:5], v[0:1], 2, s[20:21]
	global_load_dword v67, v[4:5], off offset:-4
.LBB0_949:
	s_or_b64 exec, exec, s[0:1]
	s_and_saveexec_b64 s[0:1], s[42:43]
	s_cbranch_execz .LBB0_951
	global_load_dword v68, v[8:9], off offset:4
.LBB0_951:
	s_or_b64 exec, exec, s[0:1]
	s_add_u32 s0, s23, 0x8000
	s_addc_u32 s1, s24, 0
	v_lshl_add_u64 v[6:7], v[50:51], 2, s[0:1]
	global_load_dword v69, v[6:7], off
	s_and_saveexec_b64 s[24:25], s[40:41]
	s_cbranch_execz .LBB0_953
	v_mov_b32_e32 v0, v50
	v_lshl_add_u64 v[4:5], v[0:1], 2, s[0:1]
	global_load_dword v70, v[4:5], off offset:-4
.LBB0_953:
	s_or_b64 exec, exec, s[24:25]
	s_and_saveexec_b64 s[24:25], s[42:43]
	s_cbranch_execz .LBB0_955
	global_load_dword v71, v[6:7], off offset:4
.LBB0_955:
	s_or_b64 exec, exec, s[24:25]
	global_load_dword v72, v[8:9], off offset:2048
	ds_read_b64 v[4:5], v148 offset:4096
	s_and_saveexec_b64 s[24:25], s[54:55]
	s_cbranch_execz .LBB0_957
	v_mov_b32_e32 v53, v1
	v_lshl_add_u64 v[10:11], v[52:53], 2, s[20:21]
	global_load_dword v73, v[10:11], off offset:-4
.LBB0_957:
	s_or_b64 exec, exec, s[24:25]
	s_and_saveexec_b64 s[24:25], s[58:59]
	s_cbranch_execz .LBB0_959
	global_load_dword v74, v[8:9], off offset:2052
.LBB0_959:
	s_or_b64 exec, exec, s[24:25]
	global_load_dword v75, v[6:7], off offset:2048
	s_and_saveexec_b64 s[24:25], s[54:55]
	s_cbranch_execz .LBB0_961
	v_mov_b32_e32 v53, v1
	v_lshl_add_u64 v[10:11], v[52:53], 2, s[0:1]
	global_load_dword v76, v[10:11], off offset:-4
.LBB0_961:
	s_or_b64 exec, exec, s[24:25]
	s_and_saveexec_b64 s[24:25], s[58:59]
	s_cbranch_execz .LBB0_963
	global_load_dword v77, v[6:7], off offset:2052
.LBB0_963:
	s_or_b64 exec, exec, s[24:25]
	v_add_co_u32_e32 v10, vcc, 0x1000, v8
	s_nop 1
	v_addc_co_u32_e32 v11, vcc, 0, v9, vcc
	global_load_dword v78, v[10:11], off
	ds_read_b64 v[10:11], v148 offset:8192
	s_and_saveexec_b64 s[24:25], s[36:37]
	s_cbranch_execz .LBB0_965
	v_mov_b32_e32 v55, v1
	v_lshl_add_u64 v[12:13], v[54:55], 2, s[20:21]
	global_load_dword v79, v[12:13], off offset:-4
.LBB0_965:
	s_or_b64 exec, exec, s[24:25]
	s_and_saveexec_b64 s[24:25], s[38:39]
	s_cbranch_execz .LBB0_967
	s_mov_b64 s[16:17], 0x1000
	v_lshl_add_u64 v[12:13], v[8:9], 0, s[16:17]
	global_load_dword v80, v[12:13], off offset:4
.LBB0_967:
	s_or_b64 exec, exec, s[24:25]
	v_add_co_u32_e32 v12, vcc, 0x1000, v6
	s_nop 1
	v_addc_co_u32_e32 v13, vcc, 0, v7, vcc
	global_load_dword v81, v[12:13], off
	s_and_saveexec_b64 s[24:25], s[36:37]
	s_cbranch_execz .LBB0_969
	v_mov_b32_e32 v55, v1
	v_lshl_add_u64 v[12:13], v[54:55], 2, s[0:1]
	global_load_dword v82, v[12:13], off offset:-4
.LBB0_969:
	s_or_b64 exec, exec, s[24:25]
	s_and_saveexec_b64 s[24:25], s[38:39]
	s_cbranch_execz .LBB0_971
	s_mov_b64 s[16:17], 0x1000
	v_lshl_add_u64 v[12:13], v[6:7], 0, s[16:17]
	global_load_dword v83, v[12:13], off offset:4
.LBB0_971:
	s_or_b64 exec, exec, s[24:25]
	v_add_co_u32_e32 v12, vcc, 0x1000, v8
	s_nop 1
	v_addc_co_u32_e32 v13, vcc, 0, v9, vcc
	global_load_dword v84, v[12:13], off offset:2048
	ds_read_b64 v[12:13], v148 offset:12288
	s_and_saveexec_b64 s[24:25], s[44:45]
	s_cbranch_execz .LBB0_973
	v_mov_b32_e32 v57, v1
	v_lshl_add_u64 v[20:21], v[56:57], 2, s[20:21]
	global_load_dword v85, v[20:21], off offset:-4
.LBB0_973:
	s_or_b64 exec, exec, s[24:25]
	s_and_saveexec_b64 s[24:25], s[46:47]
	s_cbranch_execz .LBB0_975
	s_mov_b64 s[16:17], 0x1800
	v_lshl_add_u64 v[20:21], v[8:9], 0, s[16:17]
	global_load_dword v86, v[20:21], off offset:4
.LBB0_975:
	s_or_b64 exec, exec, s[24:25]
	v_add_co_u32_e32 v20, vcc, 0x1000, v6
	s_nop 1
	v_addc_co_u32_e32 v21, vcc, 0, v7, vcc
	global_load_dword v87, v[20:21], off offset:2048
	s_and_saveexec_b64 s[24:25], s[44:45]
	s_cbranch_execz .LBB0_977
	v_mov_b32_e32 v57, v1
	v_lshl_add_u64 v[20:21], v[56:57], 2, s[0:1]
	global_load_dword v88, v[20:21], off offset:-4
.LBB0_977:
	s_or_b64 exec, exec, s[24:25]
	s_and_saveexec_b64 s[24:25], s[46:47]
	s_cbranch_execz .LBB0_979
	s_mov_b64 s[16:17], 0x1800
	v_lshl_add_u64 v[20:21], v[6:7], 0, s[16:17]
	global_load_dword v89, v[20:21], off offset:4
.LBB0_979:
	s_or_b64 exec, exec, s[24:25]
	v_add_co_u32_e32 v20, vcc, 0x2000, v8
	s_nop 1
	v_addc_co_u32_e32 v21, vcc, 0, v9, vcc
	global_load_dword v90, v[20:21], off
	ds_read_b64 v[20:21], v148 offset:16384
	s_and_saveexec_b64 s[24:25], s[48:49]
	s_cbranch_execz .LBB0_981
	v_mov_b32_e32 v59, v1
	v_lshl_add_u64 v[22:23], v[58:59], 2, s[20:21]
	global_load_dword v91, v[22:23], off offset:-4
.LBB0_981:
	s_or_b64 exec, exec, s[24:25]
	s_and_saveexec_b64 s[24:25], s[50:51]
	s_cbranch_execz .LBB0_983
	s_mov_b64 s[16:17], 0x2000
	v_lshl_add_u64 v[22:23], v[8:9], 0, s[16:17]
	global_load_dword v92, v[22:23], off offset:4
.LBB0_983:
	s_or_b64 exec, exec, s[24:25]
	v_add_co_u32_e32 v22, vcc, 0x2000, v6
	s_nop 1
	v_addc_co_u32_e32 v23, vcc, 0, v7, vcc
	global_load_dword v93, v[22:23], off
	s_and_saveexec_b64 s[24:25], s[48:49]
	s_cbranch_execz .LBB0_985
	v_mov_b32_e32 v59, v1
	v_lshl_add_u64 v[22:23], v[58:59], 2, s[0:1]
	global_load_dword v94, v[22:23], off offset:-4
.LBB0_985:
	s_or_b64 exec, exec, s[24:25]
	s_and_saveexec_b64 s[24:25], s[50:51]
	s_cbranch_execz .LBB0_987
	s_mov_b64 s[16:17], 0x2000
	v_lshl_add_u64 v[22:23], v[6:7], 0, s[16:17]
	global_load_dword v95, v[22:23], off offset:4
.LBB0_987:
	s_or_b64 exec, exec, s[24:25]
	v_add_co_u32_e32 v22, vcc, 0x2000, v8
	s_nop 1
	v_addc_co_u32_e32 v23, vcc, 0, v9, vcc
	global_load_dword v96, v[22:23], off offset:2048
	ds_read_b64 v[22:23], v148 offset:20480
	s_and_saveexec_b64 s[24:25], s[52:53]
	s_cbranch_execz .LBB0_989
	v_mov_b32_e32 v61, v1
	v_lshl_add_u64 v[24:25], v[60:61], 2, s[20:21]
	global_load_dword v97, v[24:25], off offset:-4
.LBB0_989:
	s_or_b64 exec, exec, s[24:25]
	s_and_saveexec_b64 s[24:25], s[56:57]
	s_cbranch_execz .LBB0_991
	s_mov_b64 s[16:17], 0x2800
	v_lshl_add_u64 v[24:25], v[8:9], 0, s[16:17]
	global_load_dword v98, v[24:25], off offset:4
.LBB0_991:
	s_or_b64 exec, exec, s[24:25]
	v_add_co_u32_e32 v24, vcc, 0x2000, v6
	s_nop 1
	v_addc_co_u32_e32 v25, vcc, 0, v7, vcc
	global_load_dword v99, v[24:25], off offset:2048
	s_and_saveexec_b64 s[24:25], s[52:53]
	s_cbranch_execz .LBB0_993
	v_mov_b32_e32 v61, v1
	v_lshl_add_u64 v[24:25], v[60:61], 2, s[0:1]
	global_load_dword v100, v[24:25], off offset:-4
.LBB0_993:
	s_or_b64 exec, exec, s[24:25]
	s_and_saveexec_b64 s[24:25], s[56:57]
	s_cbranch_execz .LBB0_995
	s_mov_b64 s[16:17], 0x2800
	v_lshl_add_u64 v[24:25], v[6:7], 0, s[16:17]
	global_load_dword v101, v[24:25], off offset:4
.LBB0_995:
	s_or_b64 exec, exec, s[24:25]
	v_add_co_u32_e32 v24, vcc, 0x3000, v8
	s_nop 1
	v_addc_co_u32_e32 v25, vcc, 0, v9, vcc
	global_load_dword v102, v[24:25], off
	ds_read_b64 v[24:25], v148 offset:24576
	s_and_saveexec_b64 s[24:25], s[60:61]
	s_cbranch_execz .LBB0_997
	v_mov_b32_e32 v63, v1
	v_lshl_add_u64 v[26:27], v[62:63], 2, s[20:21]
	global_load_dword v103, v[26:27], off offset:-4
.LBB0_997:
	s_or_b64 exec, exec, s[24:25]
	s_and_saveexec_b64 s[24:25], s[62:63]
	s_cbranch_execz .LBB0_999
	s_mov_b64 s[16:17], 0x3000
	v_lshl_add_u64 v[26:27], v[8:9], 0, s[16:17]
	global_load_dword v106, v[26:27], off offset:4
.LBB0_999:
	s_or_b64 exec, exec, s[24:25]
	v_add_co_u32_e32 v26, vcc, 0x3000, v6
	s_nop 1
	v_addc_co_u32_e32 v27, vcc, 0, v7, vcc
	global_load_dword v107, v[26:27], off
	s_and_saveexec_b64 s[24:25], s[60:61]
	s_cbranch_execz .LBB0_1001
	v_mov_b32_e32 v63, v1
	v_lshl_add_u64 v[26:27], v[62:63], 2, s[0:1]
	global_load_dword v108, v[26:27], off offset:-4
.LBB0_1001:
	s_or_b64 exec, exec, s[24:25]
	s_and_saveexec_b64 s[24:25], s[62:63]
	s_cbranch_execz .LBB0_1003
	s_mov_b64 s[16:17], 0x3000
	v_lshl_add_u64 v[26:27], v[6:7], 0, s[16:17]
	global_load_dword v109, v[26:27], off offset:4
.LBB0_1003:
	s_or_b64 exec, exec, s[24:25]
	v_add_co_u32_e32 v26, vcc, 0x3000, v8
	s_nop 1
	v_addc_co_u32_e32 v27, vcc, 0, v9, vcc
	global_load_dword v110, v[26:27], off offset:2048
	ds_read_b64 v[26:27], v148 offset:28672
	s_and_saveexec_b64 s[24:25], s[64:65]
	s_cbranch_execz .LBB0_1005
	v_mov_b32_e32 v65, v1
	v_lshl_add_u64 v[58:59], v[64:65], 2, s[20:21]
	global_load_dword v111, v[58:59], off offset:-4
.LBB0_1005:
	s_or_b64 exec, exec, s[24:25]
	s_and_saveexec_b64 s[20:21], s[66:67]
	s_cbranch_execz .LBB0_1007
	s_mov_b64 s[16:17], 0x3800
	v_lshl_add_u64 v[8:9], v[8:9], 0, s[16:17]
	global_load_dword v112, v[8:9], off offset:4
.LBB0_1007:
	s_or_b64 exec, exec, s[20:21]
	v_add_co_u32_e32 v8, vcc, 0x3000, v6
	s_nop 1
	v_addc_co_u32_e32 v9, vcc, 0, v7, vcc
	global_load_dword v113, v[8:9], off offset:2048
	s_and_saveexec_b64 s[20:21], s[64:65]
	s_cbranch_execz .LBB0_1009
	v_mov_b32_e32 v65, v1
	v_lshl_add_u64 v[8:9], v[64:65], 2, s[0:1]
	global_load_dword v114, v[8:9], off offset:-4
.LBB0_1009:
	s_or_b64 exec, exec, s[20:21]
	s_waitcnt vmcnt(0)
	v_fma_f32 v30, v32, v66, v29
	s_and_saveexec_b64 s[98:99], s[40:41]
	v_fmac_f32_e32 v30, v31, v67
	s_or_b64 exec, exec, s[98:99]
	s_and_saveexec_b64 s[98:99], s[42:43]
	v_fmac_f32_e32 v30, v33, v68
	s_or_b64 exec, exec, s[98:99]
	v_fma_f32 v34, v32, v69, v29
	s_and_saveexec_b64 s[98:99], s[40:41]
	v_fmac_f32_e32 v34, v31, v70
	s_or_b64 exec, exec, s[98:99]
	s_and_saveexec_b64 s[98:99], s[42:43]
	v_fmac_f32_e32 v34, v33, v71
	s_or_b64 exec, exec, s[98:99]
	v_fma_f32 v0, v32, v72, v29
	s_and_saveexec_b64 s[98:99], s[54:55]
	v_fmac_f32_e32 v0, v31, v73
	s_or_b64 exec, exec, s[98:99]
	s_and_saveexec_b64 s[98:99], s[58:59]
	v_fmac_f32_e32 v0, v33, v74
	s_or_b64 exec, exec, s[98:99]
	v_fma_f32 v35, v32, v75, v29
	s_and_saveexec_b64 s[98:99], s[54:55]
	v_fmac_f32_e32 v35, v31, v76
	s_or_b64 exec, exec, s[98:99]
	s_and_saveexec_b64 s[98:99], s[58:59]
	v_fmac_f32_e32 v35, v33, v77
	s_or_b64 exec, exec, s[98:99]
	v_fma_f32 v36, v32, v78, v29
	s_and_saveexec_b64 s[98:99], s[36:37]
	v_fmac_f32_e32 v36, v31, v79
	s_or_b64 exec, exec, s[98:99]
	s_and_saveexec_b64 s[98:99], s[38:39]
	v_fmac_f32_e32 v36, v33, v80
	s_or_b64 exec, exec, s[98:99]
	v_fma_f32 v37, v32, v81, v29
	s_and_saveexec_b64 s[98:99], s[36:37]
	v_fmac_f32_e32 v37, v31, v82
	s_or_b64 exec, exec, s[98:99]
	s_and_saveexec_b64 s[98:99], s[38:39]
	v_fmac_f32_e32 v37, v33, v83
	s_or_b64 exec, exec, s[98:99]
	v_fma_f32 v38, v32, v84, v29
	s_and_saveexec_b64 s[98:99], s[44:45]
	v_fmac_f32_e32 v38, v31, v85
	s_or_b64 exec, exec, s[98:99]
	s_and_saveexec_b64 s[98:99], s[46:47]
	v_fmac_f32_e32 v38, v33, v86
	s_or_b64 exec, exec, s[98:99]
	v_fma_f32 v39, v32, v87, v29
	s_and_saveexec_b64 s[98:99], s[44:45]
	v_fmac_f32_e32 v39, v31, v88
	s_or_b64 exec, exec, s[98:99]
	s_and_saveexec_b64 s[98:99], s[46:47]
	v_fmac_f32_e32 v39, v33, v89
	s_or_b64 exec, exec, s[98:99]
	v_fma_f32 v40, v32, v90, v29
	s_and_saveexec_b64 s[98:99], s[48:49]
	v_fmac_f32_e32 v40, v31, v91
	s_or_b64 exec, exec, s[98:99]
	s_and_saveexec_b64 s[98:99], s[50:51]
	v_fmac_f32_e32 v40, v33, v92
	s_or_b64 exec, exec, s[98:99]
	v_fma_f32 v41, v32, v93, v29
	s_and_saveexec_b64 s[98:99], s[48:49]
	v_fmac_f32_e32 v41, v31, v94
	s_or_b64 exec, exec, s[98:99]
	s_and_saveexec_b64 s[98:99], s[50:51]
	v_fmac_f32_e32 v41, v33, v95
	s_or_b64 exec, exec, s[98:99]
	v_fma_f32 v52, v32, v96, v29
	s_and_saveexec_b64 s[98:99], s[52:53]
	v_fmac_f32_e32 v52, v31, v97
	s_or_b64 exec, exec, s[98:99]
	s_and_saveexec_b64 s[98:99], s[56:57]
	v_fmac_f32_e32 v52, v33, v98
	s_or_b64 exec, exec, s[98:99]
	v_fma_f32 v53, v32, v99, v29
	s_and_saveexec_b64 s[98:99], s[52:53]
	v_fmac_f32_e32 v53, v31, v100
	s_or_b64 exec, exec, s[98:99]
	s_and_saveexec_b64 s[98:99], s[56:57]
	v_fmac_f32_e32 v53, v33, v101
	s_or_b64 exec, exec, s[98:99]
	v_fma_f32 v54, v32, v102, v29
	s_and_saveexec_b64 s[98:99], s[60:61]
	v_fmac_f32_e32 v54, v31, v103
	s_or_b64 exec, exec, s[98:99]
	s_and_saveexec_b64 s[98:99], s[62:63]
	v_fmac_f32_e32 v54, v33, v106
	s_or_b64 exec, exec, s[98:99]
	v_fma_f32 v55, v32, v107, v29
	s_and_saveexec_b64 s[98:99], s[60:61]
	v_fmac_f32_e32 v55, v31, v108
	s_or_b64 exec, exec, s[98:99]
	s_and_saveexec_b64 s[98:99], s[62:63]
	v_fmac_f32_e32 v55, v33, v109
	s_or_b64 exec, exec, s[98:99]
	v_fma_f32 v56, v32, v110, v29
	s_and_saveexec_b64 s[98:99], s[64:65]
	v_fmac_f32_e32 v56, v31, v111
	s_or_b64 exec, exec, s[98:99]
	s_and_saveexec_b64 s[98:99], s[66:67]
	v_fmac_f32_e32 v56, v33, v112
	s_or_b64 exec, exec, s[98:99]
	v_fmac_f32_e32 v29, v32, v113
	s_and_saveexec_b64 s[98:99], s[64:65]
	v_fmac_f32_e32 v29, v31, v114
	s_or_b64 exec, exec, s[98:99]
	s_and_saveexec_b64 s[0:1], s[66:67]
	s_cbranch_execz .LBB0_601
	s_mov_b64 s[16:17], 0x3800
	v_lshl_add_u64 v[6:7], v[6:7], 0, s[16:17]
	global_load_dword v6, v[6:7], off offset:4
	s_waitcnt vmcnt(0)
	v_fmac_f32_e32 v29, v33, v6
	s_branch .LBB0_601
